# in-loop LDS-DMA operand loads marked sc1 (bypass the CU L1, served from L2)
# speedup vs baseline: 1.0276x; 1.0007x over previous
; template <bool SWAP, class Epi, bool THIN = false> ...
;     ...
;     for (int st = 0; st < ns; ++st) {
;       asm volatile("s_waitcnt vmcnt(0)" ::: "memory");
;       __builtin_amdgcn_s_barrier();
;       asm volatile("" ::: "memory");
;       if (st + 1 < ns) {
;         char* nb = smem + ((st + 1) & 1) * 65536;
;         const int ko = (st + 1) * 64;
; #pragma unroll
;         for (int i = 0; i < 4; ++i) { GLDS16(A + (size_t)(ap[i] + ko), nb + tid * 16 + i * 8192); GLDS16(Bt + (size_t)(bp[i] + ko), nb + 32768 + tid * 16 + i * 8192); }
;       }
;       const char* sa = smem + (st & 1) * 65536 + (wr * 64 + fr) * 128;
;       const char* sb = smem + (st & 1) * 65536 + 32768 + (wc * 128 + fr) * 128;
;       if constexpr (THIN) {
;         if (wc == 0) {
; #pragma unroll
;           for (int ks = 0; ks < 2; ++ks) {
;             bf16x8 af[4], bf[2];
; #pragma unroll
;             for (int m = 0; m < 4; ++m) af[m] = *(const bf16x8*)(sa + m * 2048 + (((ks * 4 + fq) ^ swz) << 4));
; #pragma unroll
;             for (int n = 0; n < 2; ++n) bf[n] = *(const bf16x8*)(sb + n * 2048 + (((ks * 4 + fq) ^ swz) << 4));
; #pragma unroll
;             for (int m = 0; m < 4; ++m)
; #pragma unroll
;               for (int n = 0; n < 2; ++n)
;                 acc[m][n] = SWAP ? __builtin_amdgcn_mfma_f32_16x16x32_bf16(bf[n], af[m], acc[m][n], 0, 0, 0)
;                                  : __builtin_amdgcn_mfma_f32_16x16x32_bf16(af[m], bf[n], acc[m][n], 0, 0, 0);
;           }
;         }
;       } else {
;       bf16x8 afA[4], afB[4], bfb[2][2];
; #pragma unroll
;       for (int m = 0; m < 4; ++m) afA[m] = *(const bf16x8*)(sa + m * 2048 + ((fq ^ swz) << 4));
; #pragma unroll
;       for (int n = 0; n < 2; ++n) bfb[0][n] = *(const bf16x8*)(sb + n * 2048 + ((fq ^ swz) << 4));
; #pragma unroll
;       for (int gq = 0; gq < 8; ++gq) {
;         const int ks = gq >> 2, nh = gq & 3;
;         if (gq < 7) {
;           const int ks2 = (gq + 1) >> 2, nh2 = (gq + 1) & 3;
; #pragma unroll
;           for (int n = 0; n < 2; ++n) bfb[(gq + 1) & 1][n] = *(const bf16x8*)(sb + (nh2 * 2 + n) * 2048 + (((ks2 * 4 + fq) ^ swz) << 4));
;         }
;         if (gq == 3) {
; #pragma unroll
;           for (int m = 0; m < 4; ++m) afB[m] = *(const bf16x8*)(sa + m * 2048 + (((4 + fq) ^ swz) << 4));
;         }
;         __builtin_amdgcn_sched_barrier(0);
; #pragma unroll
.LBB0_339:
	s_add_i32 s8, s7, 0x10000
	s_and_b32 s9, s8, 0x10000
	v_add_u32_e32 v171, s9, v144
	s_nop 0
	v_readfirstlane_b32 s9, v171
	s_waitcnt vmcnt(0)
	s_barrier
	s_and_b32 s7, s7, 0x10000
	v_add_u32_e32 v130, s7, v145
	v_add_u32_e32 v140, v130, v147
	ds_read_b128 v[172:175], v140
	ds_read_b128 v[176:179], v140 offset:2048
	ds_read_b128 v[180:183], v140 offset:4096
	ds_read_b128 v[184:187], v140 offset:6144
	v_or_b32_e32 v140, s7, v146
	v_add_u32_e32 v141, v140, v147
	ds_read_b128 v[188:191], v141 offset:32768
	ds_read_b128 v[192:195], v141 offset:34816
	ds_read_b128 v[196:199], v141 offset:36864
	ds_read_b128 v[200:203], v141 offset:38912
	v_add_u32_e32 v130, v130, v148
	s_waitcnt lgkmcnt(3)
	v_mfma_f32_16x16x32_bf16 v[126:129], v[188:191], v[172:175], v[126:129]
	s_mov_b32 m0, s9
	v_mfma_f32_16x16x32_bf16 v[110:113], v[188:191], v[176:179], v[110:113]
	global_load_lds_dwordx4 v139, s[36:37] sc1
	v_add_u32_e32 v139, 0x80, v139
	v_mfma_f32_16x16x32_bf16 v[82:85], v[188:191], v[180:183], v[82:85]
	v_mfma_f32_16x16x32_bf16 v[50:53], v[188:191], v[184:187], v[50:53]
	ds_read_b128 v[188:191], v141 offset:40960
	ds_read_b128 v[204:207], v141 offset:43008
	s_waitcnt lgkmcnt(4)
	v_mfma_f32_16x16x32_bf16 v[122:125], v[192:195], v[172:175], v[122:125]
	s_add_u32 m0, s9, 0x8000
	v_mfma_f32_16x16x32_bf16 v[106:109], v[192:195], v[176:179], v[106:109]
	global_load_lds_dwordx4 v138, s[22:23] sc1
	v_add_u32_e32 v138, 0x80, v138
	v_mfma_f32_16x16x32_bf16 v[78:81], v[192:195], v[180:183], v[78:81]
	v_mfma_f32_16x16x32_bf16 v[42:45], v[192:195], v[184:187], v[42:45]
	s_waitcnt lgkmcnt(3)
	v_mfma_f32_16x16x32_bf16 v[118:121], v[196:199], v[172:175], v[118:121]
	s_add_u32 m0, s9, 0x2000
	v_mfma_f32_16x16x32_bf16 v[94:97], v[196:199], v[176:179], v[94:97]
	global_load_lds_dwordx4 v137, s[36:37] sc1
	v_add_u32_e32 v137, 0x80, v137
	v_mfma_f32_16x16x32_bf16 v[58:61], v[196:199], v[180:183], v[58:61]
	v_mfma_f32_16x16x32_bf16 v[26:29], v[196:199], v[184:187], v[26:29]
	ds_read_b128 v[192:195], v141 offset:45056
	ds_read_b128 v[196:199], v141 offset:47104
	s_waitcnt lgkmcnt(4)
	v_mfma_f32_16x16x32_bf16 v[114:117], v[200:203], v[172:175], v[114:117]
	s_add_u32 m0, s9, 0xa000
	v_mfma_f32_16x16x32_bf16 v[86:89], v[200:203], v[176:179], v[86:89]
	global_load_lds_dwordx4 v136, s[22:23] sc1
	v_add_u32_e32 v136, 0x80, v136
	v_mfma_f32_16x16x32_bf16 v[54:57], v[200:203], v[180:183], v[54:57]
	v_mfma_f32_16x16x32_bf16 v[22:25], v[200:203], v[184:187], v[22:25]
	v_add_u32_e32 v140, v140, v148
	s_waitcnt lgkmcnt(3)
	v_mfma_f32_16x16x32_bf16 v[102:105], v[188:191], v[172:175], v[102:105]
	ds_read_b128 v[200:203], v140 offset:32768
	ds_read_b128 v[208:211], v140 offset:34816
	s_add_u32 m0, s9, 0x4000
	v_mfma_f32_16x16x32_bf16 v[74:77], v[188:191], v[176:179], v[74:77]
	global_load_lds_dwordx4 v135, s[36:37] sc1
	v_add_u32_e32 v135, 0x80, v135
	v_mfma_f32_16x16x32_bf16 v[46:49], v[188:191], v[180:183], v[46:49]
	v_mfma_f32_16x16x32_bf16 v[10:13], v[188:191], v[184:187], v[10:13]
	ds_read_b128 v[188:191], v130
	ds_read_b128 v[212:215], v130 offset:2048
	ds_read_b128 v[216:219], v130 offset:4096
	ds_read_b128 v[220:223], v130 offset:6144
	s_waitcnt lgkmcnt(8)
	v_mfma_f32_16x16x32_bf16 v[98:101], v[204:207], v[172:175], v[98:101]
	s_add_u32 m0, s9, 0xc000
	v_mfma_f32_16x16x32_bf16 v[66:69], v[204:207], v[176:179], v[66:69]
	global_load_lds_dwordx4 v134, s[22:23] sc1
	v_add_u32_e32 v134, 0x80, v134
	v_mfma_f32_16x16x32_bf16 v[30:33], v[204:207], v[180:183], v[30:33]
	v_mfma_f32_16x16x32_bf16 v[6:9], v[204:207], v[184:187], v[6:9]
	s_waitcnt lgkmcnt(7)
	v_mfma_f32_16x16x32_bf16 v[70:73], v[192:195], v[172:175], v[70:73]
	s_add_u32 m0, s9, 0x6000
	s_waitcnt lgkmcnt(6)
	v_mfma_f32_16x16x32_bf16 v[62:65], v[196:199], v[172:175], v[62:65]
	global_load_lds_dwordx4 v133, s[36:37] sc1
	v_add_u32_e32 v133, 0x80, v133
	v_mfma_f32_16x16x32_bf16 v[38:41], v[192:195], v[176:179], v[38:41]
	v_mfma_f32_16x16x32_bf16 v[34:37], v[196:199], v[176:179], v[34:37]
	ds_read_b128 v[172:175], v140 offset:36864
	ds_read_b128 v[176:179], v140 offset:38912
	v_mfma_f32_16x16x32_bf16 v[18:21], v[192:195], v[180:183], v[18:21]
	s_add_u32 m0, s9, 0xe000
	v_mfma_f32_16x16x32_bf16 v[14:17], v[196:199], v[180:183], v[14:17]
	global_load_lds_dwordx4 v132, s[22:23] sc1
	v_add_u32_e32 v132, 0x80, v132
	v_mfma_f32_16x16x32_bf16 v[2:5], v[192:195], v[184:187], v[2:5]
	v_mfma_f32_16x16x32_bf16 v[90:93], v[196:199], v[184:187], v[90:93]
	ds_read_b128 v[180:183], v140 offset:40960
	ds_read_b128 v[184:187], v140 offset:43008
	s_waitcnt lgkmcnt(7)
	v_mfma_f32_16x16x32_bf16 v[126:129], v[200:203], v[188:191], v[126:129]
	v_mfma_f32_16x16x32_bf16 v[122:125], v[208:211], v[188:191], v[122:125]
	s_waitcnt lgkmcnt(6)
	v_mfma_f32_16x16x32_bf16 v[110:113], v[200:203], v[212:215], v[110:113]
	v_mfma_f32_16x16x32_bf16 v[106:109], v[208:211], v[212:215], v[106:109]
	s_waitcnt lgkmcnt(5)
	v_mfma_f32_16x16x32_bf16 v[82:85], v[200:203], v[216:219], v[82:85]
	v_mfma_f32_16x16x32_bf16 v[78:81], v[208:211], v[216:219], v[78:81]
	s_waitcnt lgkmcnt(4)
	v_mfma_f32_16x16x32_bf16 v[50:53], v[200:203], v[220:223], v[50:53]
	v_mfma_f32_16x16x32_bf16 v[42:45], v[208:211], v[220:223], v[42:45]
	s_waitcnt lgkmcnt(3)
	v_mfma_f32_16x16x32_bf16 v[118:121], v[172:175], v[188:191], v[118:121]
	v_mfma_f32_16x16x32_bf16 v[94:97], v[172:175], v[212:215], v[94:97]
	v_mfma_f32_16x16x32_bf16 v[58:61], v[172:175], v[216:219], v[58:61]
	v_mfma_f32_16x16x32_bf16 v[26:29], v[172:175], v[220:223], v[26:29]
	ds_read_b128 v[172:175], v140 offset:45056
	ds_read_b128 v[192:195], v140 offset:47104
	s_waitcnt lgkmcnt(4)
; template <bool SWAP, class Epi, bool THIN = false> ...
;     ...
;       bf16x8 afA[4], afB[4], bfb[2][2];
; #pragma unroll
;       for (int m = 0; m < 4; ++m) afA[m] = *(const bf16x8*)(sa + m * 2048 + ((fq ^ swz) << 4));
; #pragma unroll
;       for (int n = 0; n < 2; ++n) bfb[0][n] = *(const bf16x8*)(sb + n * 2048 + ((fq ^ swz) << 4));
; #pragma unroll
;       for (int gq = 0; gq < 8; ++gq) {
;         const int ks = gq >> 2, nh = gq & 3;
;         if (gq < 7) {
;           const int ks2 = (gq + 1) >> 2, nh2 = (gq + 1) & 3;
; #pragma unroll
;           for (int n = 0; n < 2; ++n) bfb[(gq + 1) & 1][n] = *(const bf16x8*)(sb + (nh2 * 2 + n) * 2048 + (((ks2 * 4 + fq) ^ swz) << 4));
;         }
;         if (gq == 3) {
; #pragma unroll
;           for (int m = 0; m < 4; ++m) afB[m] = *(const bf16x8*)(sa + m * 2048 + (((4 + fq) ^ swz) << 4));
;         }
;         __builtin_amdgcn_sched_barrier(0);
; #pragma unroll
;         for (int m = 0; m < 4; ++m)
; #pragma unroll
;           for (int n = 0; n < 2; ++n) {
;             const bf16x8 av = ks ? afB[m] : afA[m];
;             acc[m][nh * 2 + n] = SWAP ? __builtin_amdgcn_mfma_f32_16x16x32_bf16(bfb[gq & 1][n], av, acc[m][nh * 2 + n], 0, 0, 0)
;                                       : __builtin_amdgcn_mfma_f32_16x16x32_bf16(av, bfb[gq & 1][n], acc[m][nh * 2 + n], 0, 0, 0);
;           }
;       }
;       }
;     }
;     __syncthreads();
	v_mfma_f32_16x16x32_bf16 v[114:117], v[176:179], v[188:191], v[114:117]
	v_mfma_f32_16x16x32_bf16 v[86:89], v[176:179], v[212:215], v[86:89]
	v_mfma_f32_16x16x32_bf16 v[54:57], v[176:179], v[216:219], v[54:57]
	v_mfma_f32_16x16x32_bf16 v[22:25], v[176:179], v[220:223], v[22:25]
	s_waitcnt lgkmcnt(3)
	v_mfma_f32_16x16x32_bf16 v[102:105], v[180:183], v[188:191], v[102:105]
	s_waitcnt lgkmcnt(2)
	v_mfma_f32_16x16x32_bf16 v[98:101], v[184:187], v[188:191], v[98:101]
	v_mfma_f32_16x16x32_bf16 v[74:77], v[180:183], v[212:215], v[74:77]
	v_mfma_f32_16x16x32_bf16 v[66:69], v[184:187], v[212:215], v[66:69]
	v_mfma_f32_16x16x32_bf16 v[46:49], v[180:183], v[216:219], v[46:49]
	v_mfma_f32_16x16x32_bf16 v[30:33], v[184:187], v[216:219], v[30:33]
	v_mfma_f32_16x16x32_bf16 v[10:13], v[180:183], v[220:223], v[10:13]
	v_mfma_f32_16x16x32_bf16 v[6:9], v[184:187], v[220:223], v[6:9]
	s_waitcnt lgkmcnt(1)
	v_mfma_f32_16x16x32_bf16 v[70:73], v[172:175], v[188:191], v[70:73]
	s_add_i32 s6, s6, 64
	s_cmpk_eq_i32 s6, 0x3c0
	s_mov_b32 s7, s8
	s_waitcnt lgkmcnt(0)
	v_mfma_f32_16x16x32_bf16 v[62:65], v[192:195], v[188:191], v[62:65]
	v_mfma_f32_16x16x32_bf16 v[38:41], v[172:175], v[212:215], v[38:41]
	v_mfma_f32_16x16x32_bf16 v[34:37], v[192:195], v[212:215], v[34:37]
	v_mfma_f32_16x16x32_bf16 v[18:21], v[172:175], v[216:219], v[18:21]
	v_mfma_f32_16x16x32_bf16 v[14:17], v[192:195], v[216:219], v[14:17]
	v_mfma_f32_16x16x32_bf16 v[2:5], v[172:175], v[220:223], v[2:5]
	v_mfma_f32_16x16x32_bf16 v[90:93], v[192:195], v[220:223], v[90:93]
	s_cbranch_scc0 .LBB0_339
	s_waitcnt vmcnt(0)
	s_barrier
	v_add_u32_e32 v130, v159, v147
	ds_read_b128 v[132:135], v130
	ds_read_b128 v[136:139], v130 offset:2048
	ds_read_b128 v[172:175], v130 offset:4096
	ds_read_b128 v[176:179], v130 offset:6144
	v_add_u32_e32 v130, v160, v147
	ds_read_b128 v[180:183], v130
	ds_read_b128 v[184:187], v130 offset:2048
	ds_read_b128 v[188:191], v130 offset:4096
	ds_read_b128 v[192:195], v130 offset:6144
	s_waitcnt lgkmcnt(0)
	v_mfma_f32_16x16x32_bf16 v[126:129], v[180:183], v[132:135], v[126:129]
	v_mfma_f32_16x16x32_bf16 v[110:113], v[180:183], v[136:139], v[110:113]
	v_mfma_f32_16x16x32_bf16 v[82:85], v[180:183], v[172:175], v[82:85]
	v_mfma_f32_16x16x32_bf16 v[50:53], v[180:183], v[176:179], v[50:53]
	ds_read_b128 v[180:183], v130 offset:8192
	ds_read_b128 v[196:199], v130 offset:10240
	v_mfma_f32_16x16x32_bf16 v[122:125], v[184:187], v[132:135], v[122:125]
	v_mfma_f32_16x16x32_bf16 v[106:109], v[184:187], v[136:139], v[106:109]
	v_mfma_f32_16x16x32_bf16 v[78:81], v[184:187], v[172:175], v[78:81]
	v_mfma_f32_16x16x32_bf16 v[42:45], v[184:187], v[176:179], v[42:45]
	v_mfma_f32_16x16x32_bf16 v[118:121], v[188:191], v[132:135], v[118:121]
	v_mfma_f32_16x16x32_bf16 v[184:187], v[188:191], v[136:139], v[94:97]
	v_mfma_f32_16x16x32_bf16 v[204:207], v[188:191], v[172:175], v[58:61]
	v_mfma_f32_16x16x32_bf16 v[208:211], v[192:195], v[172:175], v[54:57]
	v_mfma_f32_16x16x32_bf16 v[188:191], v[188:191], v[176:179], v[26:29]
	s_nop 2
	ds_read_b128 v[26:29], v130 offset:12288
	ds_read_b128 v[54:57], v130 offset:14336
	v_mfma_f32_16x16x32_bf16 v[114:117], v[192:195], v[132:135], v[114:117]
	v_mfma_f32_16x16x32_bf16 v[200:203], v[192:195], v[136:139], v[86:89]
	v_mfma_f32_16x16x32_bf16 v[192:195], v[192:195], v[176:179], v[22:25]
	v_add_u32_e32 v130, v160, v148
	s_waitcnt lgkmcnt(0)
	v_mfma_f32_16x16x32_bf16 v[212:215], v[196:199], v[172:175], v[30:33]
	ds_read_b128 v[22:25], v130
	ds_read_b128 v[86:89], v130 offset:2048
	s_nop 0
	v_add_u32_e32 v30, v159, v148
	v_mfma_f32_16x16x32_bf16 v[102:105], v[180:183], v[132:135], v[102:105]
	v_mfma_f32_16x16x32_bf16 v[74:77], v[180:183], v[136:139], v[74:77]
	v_mfma_f32_16x16x32_bf16 v[46:49], v[180:183], v[172:175], v[46:49]
	v_mfma_f32_16x16x32_bf16 v[10:13], v[180:183], v[176:179], v[10:13]
	ds_read_b128 v[180:183], v30
	ds_read_b128 v[216:219], v30 offset:2048
	ds_read_b128 v[220:223], v30 offset:4096
	ds_read_b128 v[224:227], v30 offset:6144
	v_mfma_f32_16x16x32_bf16 v[98:101], v[196:199], v[132:135], v[98:101]
	v_mfma_f32_16x16x32_bf16 v[66:69], v[196:199], v[136:139], v[66:69]
	v_mfma_f32_16x16x32_bf16 v[6:9], v[196:199], v[176:179], v[6:9]
	v_mfma_f32_16x16x32_bf16 v[196:199], v[26:29], v[172:175], v[18:21]
	v_mfma_f32_16x16x32_bf16 v[172:175], v[54:57], v[172:175], v[14:17]
	s_nop 2
	ds_read_b128 v[14:17], v130 offset:4096
	ds_read_b128 v[18:21], v130 offset:6144
	v_mfma_f32_16x16x32_bf16 v[70:73], v[26:29], v[132:135], v[70:73]
	v_mfma_f32_16x16x32_bf16 v[132:135], v[54:57], v[132:135], v[62:65]
	v_mfma_f32_16x16x32_bf16 v[38:41], v[26:29], v[136:139], v[38:41]
	v_mfma_f32_16x16x32_bf16 v[34:37], v[54:57], v[136:139], v[34:37]
	v_mfma_f32_16x16x32_bf16 v[2:5], v[26:29], v[176:179], v[2:5]
	v_mfma_f32_16x16x32_bf16 v[176:179], v[54:57], v[176:179], v[90:93]
	ds_read_b128 v[136:139], v130 offset:8192
	ds_read_b128 v[228:231], v130 offset:10240
	s_waitcnt lgkmcnt(0)
	v_mfma_f32_16x16x32_bf16 v[126:129], v[22:25], v[180:183], v[126:129]
	v_mfma_f32_16x16x32_bf16 v[122:125], v[86:89], v[180:183], v[122:125]
	v_mfma_f32_16x16x32_bf16 v[94:97], v[22:25], v[216:219], v[110:113]
	v_mfma_f32_16x16x32_bf16 v[90:93], v[86:89], v[216:219], v[106:109]
	v_mfma_f32_16x16x32_bf16 v[62:65], v[22:25], v[220:223], v[82:85]
	v_mfma_f32_16x16x32_bf16 v[58:61], v[86:89], v[220:223], v[78:81]
	v_mfma_f32_16x16x32_bf16 v[30:33], v[22:25], v[224:227], v[50:53]
	v_mfma_f32_16x16x32_bf16 v[26:29], v[86:89], v[224:227], v[42:45]
	v_mfma_f32_16x16x32_bf16 v[86:89], v[14:17], v[216:219], v[184:187]
	v_mfma_f32_16x16x32_bf16 v[22:25], v[14:17], v[224:227], v[188:191]
	s_nop 1
	ds_read_b128 v[184:187], v130 offset:12288
	ds_read_b128 v[188:191], v130 offset:14336
	v_mfma_f32_16x16x32_bf16 v[118:121], v[14:17], v[180:183], v[118:121]
	v_mfma_f32_16x16x32_bf16 v[114:117], v[18:21], v[180:183], v[114:117]
	v_mfma_f32_16x16x32_bf16 v[82:85], v[18:21], v[216:219], v[200:203]
	v_mfma_f32_16x16x32_bf16 v[54:57], v[14:17], v[220:223], v[204:207]
	v_mfma_f32_16x16x32_bf16 v[50:53], v[18:21], v[220:223], v[208:211]
	v_mfma_f32_16x16x32_bf16 v[18:21], v[18:21], v[224:227], v[192:195]
	v_mfma_f32_16x16x32_bf16 v[110:113], v[136:139], v[180:183], v[102:105]
	v_mfma_f32_16x16x32_bf16 v[106:109], v[228:231], v[180:183], v[98:101]
	v_mfma_f32_16x16x32_bf16 v[78:81], v[136:139], v[216:219], v[74:77]
	v_mfma_f32_16x16x32_bf16 v[74:77], v[228:231], v[216:219], v[66:69]
	v_mfma_f32_16x16x32_bf16 v[46:49], v[136:139], v[220:223], v[46:49]
	v_mfma_f32_16x16x32_bf16 v[42:45], v[228:231], v[220:223], v[212:215]
	v_mfma_f32_16x16x32_bf16 v[14:17], v[136:139], v[224:227], v[10:13]
	v_mfma_f32_16x16x32_bf16 v[6:9], v[228:231], v[224:227], v[6:9]
	s_nop 1
	v_mov_b32_e32 v10, v1
	s_waitcnt vmcnt(0) lgkmcnt(0)
	s_barrier
; __device__ __forceinline__ int get_tid512() { int t = threadIdx.x; asm volatile("" : "+v"(t)); return t; }
; __device__ __forceinline__ unsigned pack2(float a, float b) { unsigned r; asm("v_cvt_pk_bf16_f32 %0, %1, %2" : "=v"(r) : "v"(a), "v"(b)); return r; }
;   __device__ __forceinline__ float c4(int g, int rig, int col, f32x4 v) const {
;     ...
;     uint2 u; u.x = pack2(v[0], v[1]); u.y = pack2(v[2], v[3]);
;     *(uint2*)(out + row * ld + col) = u;
;     return v[0] * v[0] + v[1] * v[1] + v[2] * v[2] + v[3] * v[3];
; template <bool SWAP, class Epi, bool THIN = false> ...
;     ...
;     const int te = get_tid512();
;     const int fr_e = te & 15, fq_e = (te & 63) >> 4, wr_e = te >> 7, wc_e = (te >> 6) & 1;
;     const int sub = 2 * mt + (wr_e >> 1);
;     const int g = sub / tpg, ti = sub - g * tpg;
;     const int rig0 = ti * step - halo;
;     const int rw = (wr_e & 1) * 64;
;     if constexpr (Epi::KIND == 0) {
; #pragma unroll
;       for (int m = 0; m < 4; ++m) {
;         const int rig = rig0 + rw + m * 16 + fr_e;
;         if constexpr (Epi::ROWSUM) {
;           float ss = 0.f;
; #pragma unroll
;           for (int n = 0; n < 8; ++n) {
;             const int col = nt * 256 + wc_e * 128 + n * 16 + fq_e * 4;
;             if (col < N) ss += epi.c4(g, rig, col, acc[m][n]);
;           }
;           ss += __shfl_xor(ss, 16); ss += __shfl_xor(ss, 32);
;           if (fq_e == 0) epi.rowsum(g, rig, nt * 2 + wc_e, ss);
	v_mfma_f32_16x16x32_bf16 v[98:101], v[188:191], v[180:183], v[132:135]
	v_ashrrev_i32_e32 v11, 8, v10
	v_add_u32_e32 v11, s5, v11
	v_ashrrev_i32_e32 v12, 31, v11
	v_lshrrev_b32_e32 v12, 28, v12
	v_add_u32_e32 v12, v11, v12
	v_ashrrev_i32_e32 v138, 4, v12
	v_and_b32_e32 v132, 15, v10
	v_bfe_u32 v130, v10, 4, 2
	v_bfe_u32 v171, v10, 6, 1
	v_lshlrev_b32_e32 v12, 11, v138
	v_lshlrev_b32_e32 v11, 7, v11
	v_lshrrev_b32_e32 v10, 1, v10
	v_sub_u32_e32 v133, v11, v12
	v_and_b32_e32 v135, 64, v10
	v_lshlrev_b32_e32 v134, 7, v171
	v_mfma_f32_16x16x32_bf16 v[10:13], v[184:187], v[224:227], v[2:5]
	v_ashrrev_i32_e32 v139, 31, v138
	v_or3_b32 v132, v133, v135, v132
	v_ashrrev_i32_e32 v133, 31, v132
	v_lshlrev_b32_e32 v2, 2, v130
	v_mfma_f32_16x16x32_bf16 v[102:105], v[184:187], v[180:183], v[70:73]
	v_or3_b32 v134, v134, v2, s4
	v_lshlrev_b64 v[136:137], 21, v[138:139]
	v_cmp_gt_i32_e32 vcc, s29, v134
	v_mfma_f32_16x16x32_bf16 v[70:73], v[184:187], v[216:219], v[38:41]
	v_lshlrev_b64 v[140:141], 10, v[132:133]
	v_ashrrev_i32_e32 v135, 31, v134
	v_lshl_add_u64 v[136:137], s[38:39], 0, v[136:137]
	v_mfma_f32_16x16x32_bf16 v[66:69], v[188:191], v[216:219], v[34:37]
	v_mfma_f32_16x16x32_bf16 v[38:41], v[184:187], v[220:223], v[196:199]
	v_mfma_f32_16x16x32_bf16 v[34:37], v[188:191], v[220:223], v[172:175]
	v_mfma_f32_16x16x32_bf16 v[2:5], v[188:191], v[224:227], v[176:179]
	s_nop 1
	v_mov_b32_e32 v172, 0
	s_and_saveexec_b64 s[4:5], vcc
	s_cbranch_execz .LBB0_342
	v_cvt_pk_bf16_f32 v172, v126, v127
	v_pk_mul_f32 v[126:127], v[126:127], v[126:127]
	v_cvt_pk_bf16_f32 v173, v128, v129
	v_lshl_add_u64 v[174:175], v[136:137], 0, v[140:141]
	v_pk_mul_f32 v[128:129], v[128:129], v[128:129]
	v_add_f32_e32 v126, v126, v127
	v_lshl_add_u64 v[174:175], v[134:135], 1, v[174:175]
	v_add_f32_e32 v126, v128, v126
	global_store_dwordx2 v[174:175], v[172:173], off
	v_add_f32_e32 v172, v129, v126

; template <bool SWAP, class Epi, bool THIN = false> ...
;     ...
;     for (int st = 0; st < ns; ++st) {
;       asm volatile("s_waitcnt vmcnt(0)" ::: "memory");
;       __builtin_amdgcn_s_barrier();
;       asm volatile("" ::: "memory");
;       if (st + 1 < ns) {
;         char* nb = smem + ((st + 1) & 1) * 65536;
;         const int ko = (st + 1) * 64;
; #pragma unroll
;         for (int i = 0; i < 4; ++i) { GLDS16(A + (size_t)(ap[i] + ko), nb + tid * 16 + i * 8192); GLDS16(Bt + (size_t)(bp[i] + ko), nb + 32768 + tid * 16 + i * 8192); }
;       }
;       const char* sa = smem + (st & 1) * 65536 + (wr * 64 + fr) * 128;
;       const char* sb = smem + (st & 1) * 65536 + 32768 + (wc * 128 + fr) * 128;
;       if constexpr (THIN) {
;         if (wc == 0) {
; #pragma unroll
;           for (int ks = 0; ks < 2; ++ks) {
;             bf16x8 af[4], bf[2];
; #pragma unroll
;             for (int m = 0; m < 4; ++m) af[m] = *(const bf16x8*)(sa + m * 2048 + (((ks * 4 + fq) ^ swz) << 4));
; #pragma unroll
;             for (int n = 0; n < 2; ++n) bf[n] = *(const bf16x8*)(sb + n * 2048 + (((ks * 4 + fq) ^ swz) << 4));
; #pragma unroll
;             for (int m = 0; m < 4; ++m)
; #pragma unroll
;               for (int n = 0; n < 2; ++n)
;                 acc[m][n] = SWAP ? __builtin_amdgcn_mfma_f32_16x16x32_bf16(bf[n], af[m], acc[m][n], 0, 0, 0)
;                                  : __builtin_amdgcn_mfma_f32_16x16x32_bf16(af[m], bf[n], acc[m][n], 0, 0, 0);
;           }
;         }
;       } else {
;       bf16x8 afA[4], afB[4], bfb[2][2];
; #pragma unroll
;       for (int m = 0; m < 4; ++m) afA[m] = *(const bf16x8*)(sa + m * 2048 + ((fq ^ swz) << 4));
; #pragma unroll
;       for (int n = 0; n < 2; ++n) bfb[0][n] = *(const bf16x8*)(sb + n * 2048 + ((fq ^ swz) << 4));
; #pragma unroll
;       for (int gq = 0; gq < 8; ++gq) {
;         const int ks = gq >> 2, nh = gq & 3;
;         if (gq < 7) {
;           const int ks2 = (gq + 1) >> 2, nh2 = (gq + 1) & 3;
; #pragma unroll
;           for (int n = 0; n < 2; ++n) bfb[(gq + 1) & 1][n] = *(const bf16x8*)(sb + (nh2 * 2 + n) * 2048 + (((ks2 * 4 + fq) ^ swz) << 4));
;         }
;         if (gq == 3) {
; #pragma unroll
;           for (int m = 0; m < 4; ++m) afB[m] = *(const bf16x8*)(sa + m * 2048 + (((4 + fq) ^ swz) << 4));
;         }
;         __builtin_amdgcn_sched_barrier(0);
; #pragma unroll
.LBB0_418:
	s_add_i32 s8, s7, 0x10000
	s_and_b32 s9, s8, 0x10000
	v_add_u32_e32 v170, s9, v138
	s_nop 0
	v_readfirstlane_b32 s9, v170
	s_waitcnt vmcnt(0)
	s_barrier
	s_and_b32 s7, s7, 0x10000
	v_or_b32_e32 v204, s7, v140
	v_add_u32_e32 v205, v204, v141
	v_add_u32_e32 v130, s7, v139
	v_add_u32_e32 v180, v130, v141
	ds_read_b128 v[168:171], v180
	ds_read_b128 v[172:175], v180 offset:2048
	ds_read_b128 v[176:179], v180 offset:4096
	ds_read_b128 v[180:183], v180 offset:6144
	ds_read_b128 v[184:187], v205 offset:32768
	ds_read_b128 v[188:191], v205 offset:34816
	ds_read_b128 v[192:195], v205 offset:36864
	ds_read_b128 v[196:199], v205 offset:38912
	v_add_u32_e32 v130, v130, v142
	s_waitcnt lgkmcnt(3)
	v_mfma_f32_16x16x32_bf16 v[126:129], v[184:187], v[168:171], v[126:129]
	s_mov_b32 m0, s9
	v_mfma_f32_16x16x32_bf16 v[110:113], v[184:187], v[172:175], v[110:113]
	global_load_lds_dwordx4 v167, s[36:37] sc1
	v_add_u32_e32 v167, 0x80, v167
	v_mfma_f32_16x16x32_bf16 v[82:85], v[184:187], v[176:179], v[82:85]
	v_mfma_f32_16x16x32_bf16 v[50:53], v[184:187], v[180:183], v[50:53]
	ds_read_b128 v[184:187], v205 offset:40960
	ds_read_b128 v[200:203], v205 offset:43008
	s_waitcnt lgkmcnt(4)
	v_mfma_f32_16x16x32_bf16 v[122:125], v[188:191], v[168:171], v[122:125]
	s_add_u32 m0, s9, 0x8000
	v_mfma_f32_16x16x32_bf16 v[106:109], v[188:191], v[172:175], v[106:109]
	global_load_lds_dwordx4 v166, s[38:39] sc1
	v_add_u32_e32 v166, 0x80, v166
	v_mfma_f32_16x16x32_bf16 v[78:81], v[188:191], v[176:179], v[78:81]
	v_mfma_f32_16x16x32_bf16 v[42:45], v[188:191], v[180:183], v[42:45]
	s_waitcnt lgkmcnt(3)
	v_mfma_f32_16x16x32_bf16 v[118:121], v[192:195], v[168:171], v[118:121]
	s_add_u32 m0, s9, 0x2000
	v_mfma_f32_16x16x32_bf16 v[94:97], v[192:195], v[172:175], v[94:97]
	global_load_lds_dwordx4 v165, s[36:37] sc1
	v_add_u32_e32 v165, 0x80, v165
	v_mfma_f32_16x16x32_bf16 v[58:61], v[192:195], v[176:179], v[58:61]
	v_mfma_f32_16x16x32_bf16 v[26:29], v[192:195], v[180:183], v[26:29]
	ds_read_b128 v[188:191], v205 offset:45056
	ds_read_b128 v[192:195], v205 offset:47104
	s_waitcnt lgkmcnt(4)
	v_mfma_f32_16x16x32_bf16 v[114:117], v[196:199], v[168:171], v[114:117]
	s_add_u32 m0, s9, 0xa000
	v_mfma_f32_16x16x32_bf16 v[86:89], v[196:199], v[172:175], v[86:89]
	global_load_lds_dwordx4 v164, s[38:39] sc1
	v_add_u32_e32 v164, 0x80, v164
	v_mfma_f32_16x16x32_bf16 v[54:57], v[196:199], v[176:179], v[54:57]
	v_mfma_f32_16x16x32_bf16 v[22:25], v[196:199], v[180:183], v[22:25]
	v_add_u32_e32 v220, v204, v142
	s_waitcnt lgkmcnt(3)
	v_mfma_f32_16x16x32_bf16 v[102:105], v[184:187], v[168:171], v[102:105]
	ds_read_b128 v[196:199], v220 offset:32768
	ds_read_b128 v[204:207], v220 offset:34816
	s_add_u32 m0, s9, 0x4000
	v_mfma_f32_16x16x32_bf16 v[74:77], v[184:187], v[172:175], v[74:77]
	global_load_lds_dwordx4 v135, s[36:37] sc1
	v_add_u32_e32 v135, 0x80, v135
	v_mfma_f32_16x16x32_bf16 v[46:49], v[184:187], v[176:179], v[46:49]
	v_mfma_f32_16x16x32_bf16 v[10:13], v[184:187], v[180:183], v[10:13]
	ds_read_b128 v[184:187], v130
	ds_read_b128 v[208:211], v130 offset:2048
	ds_read_b128 v[212:215], v130 offset:4096
	ds_read_b128 v[216:219], v130 offset:6144
	s_waitcnt lgkmcnt(8)
	v_mfma_f32_16x16x32_bf16 v[98:101], v[200:203], v[168:171], v[98:101]
	s_add_u32 m0, s9, 0xc000
	v_mfma_f32_16x16x32_bf16 v[66:69], v[200:203], v[172:175], v[66:69]
	global_load_lds_dwordx4 v134, s[38:39] sc1
	v_add_u32_e32 v134, 0x80, v134
	v_mfma_f32_16x16x32_bf16 v[30:33], v[200:203], v[176:179], v[30:33]
	v_mfma_f32_16x16x32_bf16 v[6:9], v[200:203], v[180:183], v[6:9]
	s_waitcnt lgkmcnt(7)
	v_mfma_f32_16x16x32_bf16 v[70:73], v[188:191], v[168:171], v[70:73]
	s_add_u32 m0, s9, 0x6000
	s_waitcnt lgkmcnt(6)
	v_mfma_f32_16x16x32_bf16 v[62:65], v[192:195], v[168:171], v[62:65]
	global_load_lds_dwordx4 v133, s[36:37] sc1
	v_add_u32_e32 v133, 0x80, v133
	v_mfma_f32_16x16x32_bf16 v[38:41], v[188:191], v[172:175], v[38:41]
	v_mfma_f32_16x16x32_bf16 v[34:37], v[192:195], v[172:175], v[34:37]
	ds_read_b128 v[168:171], v220 offset:36864
	ds_read_b128 v[172:175], v220 offset:38912
	v_mfma_f32_16x16x32_bf16 v[18:21], v[188:191], v[176:179], v[18:21]
	s_add_u32 m0, s9, 0xe000
	v_mfma_f32_16x16x32_bf16 v[14:17], v[192:195], v[176:179], v[14:17]
	global_load_lds_dwordx4 v132, s[38:39] sc1
	v_add_u32_e32 v132, 0x80, v132
	v_mfma_f32_16x16x32_bf16 v[2:5], v[188:191], v[180:183], v[2:5]
	v_mfma_f32_16x16x32_bf16 v[90:93], v[192:195], v[180:183], v[90:93]
	ds_read_b128 v[176:179], v220 offset:40960
	ds_read_b128 v[180:183], v220 offset:43008
	s_waitcnt lgkmcnt(7)
	v_mfma_f32_16x16x32_bf16 v[126:129], v[196:199], v[184:187], v[126:129]
	v_mfma_f32_16x16x32_bf16 v[122:125], v[204:207], v[184:187], v[122:125]
	s_waitcnt lgkmcnt(6)
	v_mfma_f32_16x16x32_bf16 v[110:113], v[196:199], v[208:211], v[110:113]
	v_mfma_f32_16x16x32_bf16 v[106:109], v[204:207], v[208:211], v[106:109]
	s_waitcnt lgkmcnt(5)
	v_mfma_f32_16x16x32_bf16 v[82:85], v[196:199], v[212:215], v[82:85]
	v_mfma_f32_16x16x32_bf16 v[78:81], v[204:207], v[212:215], v[78:81]
	s_waitcnt lgkmcnt(4)
	v_mfma_f32_16x16x32_bf16 v[50:53], v[196:199], v[216:219], v[50:53]
	v_mfma_f32_16x16x32_bf16 v[42:45], v[204:207], v[216:219], v[42:45]
	s_waitcnt lgkmcnt(3)
	v_mfma_f32_16x16x32_bf16 v[118:121], v[168:171], v[184:187], v[118:121]
	v_mfma_f32_16x16x32_bf16 v[94:97], v[168:171], v[208:211], v[94:97]
	v_mfma_f32_16x16x32_bf16 v[58:61], v[168:171], v[212:215], v[58:61]
	v_mfma_f32_16x16x32_bf16 v[26:29], v[168:171], v[216:219], v[26:29]
	ds_read_b128 v[168:171], v220 offset:45056
	ds_read_b128 v[188:191], v220 offset:47104
	s_waitcnt lgkmcnt(4)
; template <bool SWAP, class Epi, bool THIN = false> ...
;     ...
;       bf16x8 afA[4], afB[4], bfb[2][2];
; #pragma unroll
;       for (int m = 0; m < 4; ++m) afA[m] = *(const bf16x8*)(sa + m * 2048 + ((fq ^ swz) << 4));
; #pragma unroll
;       for (int n = 0; n < 2; ++n) bfb[0][n] = *(const bf16x8*)(sb + n * 2048 + ((fq ^ swz) << 4));
; #pragma unroll
;       for (int gq = 0; gq < 8; ++gq) {
;         const int ks = gq >> 2, nh = gq & 3;
;         if (gq < 7) {
;           const int ks2 = (gq + 1) >> 2, nh2 = (gq + 1) & 3;
; #pragma unroll
;           for (int n = 0; n < 2; ++n) bfb[(gq + 1) & 1][n] = *(const bf16x8*)(sb + (nh2 * 2 + n) * 2048 + (((ks2 * 4 + fq) ^ swz) << 4));
;         }
;         if (gq == 3) {
; #pragma unroll
;           for (int m = 0; m < 4; ++m) afB[m] = *(const bf16x8*)(sa + m * 2048 + (((4 + fq) ^ swz) << 4));
;         }
;         __builtin_amdgcn_sched_barrier(0);
; #pragma unroll
;         for (int m = 0; m < 4; ++m)
; #pragma unroll
;           for (int n = 0; n < 2; ++n) {
;             const bf16x8 av = ks ? afB[m] : afA[m];
;             acc[m][nh * 2 + n] = SWAP ? __builtin_amdgcn_mfma_f32_16x16x32_bf16(bfb[gq & 1][n], av, acc[m][nh * 2 + n], 0, 0, 0)
;                                       : __builtin_amdgcn_mfma_f32_16x16x32_bf16(av, bfb[gq & 1][n], acc[m][nh * 2 + n], 0, 0, 0);
;           }
;       }
;       }
;     }
;     __syncthreads();
	v_mfma_f32_16x16x32_bf16 v[114:117], v[172:175], v[184:187], v[114:117]
	v_mfma_f32_16x16x32_bf16 v[86:89], v[172:175], v[208:211], v[86:89]
	v_mfma_f32_16x16x32_bf16 v[54:57], v[172:175], v[212:215], v[54:57]
	v_mfma_f32_16x16x32_bf16 v[22:25], v[172:175], v[216:219], v[22:25]
	s_waitcnt lgkmcnt(3)
	v_mfma_f32_16x16x32_bf16 v[102:105], v[176:179], v[184:187], v[102:105]
	s_waitcnt lgkmcnt(2)
	v_mfma_f32_16x16x32_bf16 v[98:101], v[180:183], v[184:187], v[98:101]
	v_mfma_f32_16x16x32_bf16 v[74:77], v[176:179], v[208:211], v[74:77]
	v_mfma_f32_16x16x32_bf16 v[66:69], v[180:183], v[208:211], v[66:69]
	v_mfma_f32_16x16x32_bf16 v[46:49], v[176:179], v[212:215], v[46:49]
	v_mfma_f32_16x16x32_bf16 v[30:33], v[180:183], v[212:215], v[30:33]
	v_mfma_f32_16x16x32_bf16 v[10:13], v[176:179], v[216:219], v[10:13]
	v_mfma_f32_16x16x32_bf16 v[6:9], v[180:183], v[216:219], v[6:9]
	s_waitcnt lgkmcnt(1)
	v_mfma_f32_16x16x32_bf16 v[70:73], v[168:171], v[184:187], v[70:73]
	s_add_i32 s6, s6, 64
	s_cmpk_eq_i32 s6, 0x3c0
	s_mov_b32 s7, s8
	s_waitcnt lgkmcnt(0)
	v_mfma_f32_16x16x32_bf16 v[62:65], v[188:191], v[184:187], v[62:65]
	v_mfma_f32_16x16x32_bf16 v[38:41], v[168:171], v[208:211], v[38:41]
	v_mfma_f32_16x16x32_bf16 v[34:37], v[188:191], v[208:211], v[34:37]
	v_mfma_f32_16x16x32_bf16 v[18:21], v[168:171], v[212:215], v[18:21]
	v_mfma_f32_16x16x32_bf16 v[14:17], v[188:191], v[212:215], v[14:17]
	v_mfma_f32_16x16x32_bf16 v[2:5], v[168:171], v[216:219], v[2:5]
	v_mfma_f32_16x16x32_bf16 v[90:93], v[188:191], v[216:219], v[90:93]
	s_cbranch_scc0 .LBB0_418
	s_waitcnt vmcnt(0)
	s_barrier
	v_add_u32_e32 v130, v153, v141
	ds_read_b128 v[132:135], v130
	ds_read_b128 v[164:167], v130 offset:2048
	ds_read_b128 v[168:171], v130 offset:4096
	ds_read_b128 v[172:175], v130 offset:6144
	v_add_u32_e32 v130, v154, v141
	ds_read_b128 v[176:179], v130
	ds_read_b128 v[180:183], v130 offset:2048
	ds_read_b128 v[184:187], v130 offset:4096
	ds_read_b128 v[188:191], v130 offset:6144
	s_waitcnt lgkmcnt(0)
	v_mfma_f32_16x16x32_bf16 v[126:129], v[176:179], v[132:135], v[126:129]
	v_mfma_f32_16x16x32_bf16 v[110:113], v[176:179], v[164:167], v[110:113]
	v_mfma_f32_16x16x32_bf16 v[82:85], v[176:179], v[168:171], v[82:85]
	v_mfma_f32_16x16x32_bf16 v[50:53], v[176:179], v[172:175], v[50:53]
	ds_read_b128 v[176:179], v130 offset:8192
	ds_read_b128 v[192:195], v130 offset:10240
	v_mfma_f32_16x16x32_bf16 v[122:125], v[180:183], v[132:135], v[122:125]
	v_mfma_f32_16x16x32_bf16 v[106:109], v[180:183], v[164:167], v[106:109]
	v_mfma_f32_16x16x32_bf16 v[78:81], v[180:183], v[168:171], v[78:81]
	v_mfma_f32_16x16x32_bf16 v[42:45], v[180:183], v[172:175], v[42:45]
	v_mfma_f32_16x16x32_bf16 v[118:121], v[184:187], v[132:135], v[118:121]
	v_mfma_f32_16x16x32_bf16 v[180:183], v[184:187], v[164:167], v[94:97]
	v_mfma_f32_16x16x32_bf16 v[200:203], v[184:187], v[168:171], v[58:61]
	v_mfma_f32_16x16x32_bf16 v[204:207], v[188:191], v[168:171], v[54:57]
	v_mfma_f32_16x16x32_bf16 v[184:187], v[184:187], v[172:175], v[26:29]
	s_nop 2
	ds_read_b128 v[26:29], v130 offset:12288
	ds_read_b128 v[54:57], v130 offset:14336
	v_mfma_f32_16x16x32_bf16 v[114:117], v[188:191], v[132:135], v[114:117]
	v_mfma_f32_16x16x32_bf16 v[196:199], v[188:191], v[164:167], v[86:89]
	v_mfma_f32_16x16x32_bf16 v[188:191], v[188:191], v[172:175], v[22:25]
	v_add_u32_e32 v130, v154, v142
	s_waitcnt lgkmcnt(0)
	v_mfma_f32_16x16x32_bf16 v[208:211], v[192:195], v[168:171], v[30:33]
	ds_read_b128 v[22:25], v130
	ds_read_b128 v[86:89], v130 offset:2048
	s_nop 0
	v_add_u32_e32 v30, v153, v142
	v_mfma_f32_16x16x32_bf16 v[102:105], v[176:179], v[132:135], v[102:105]
	v_mfma_f32_16x16x32_bf16 v[74:77], v[176:179], v[164:167], v[74:77]
	v_mfma_f32_16x16x32_bf16 v[46:49], v[176:179], v[168:171], v[46:49]
	v_mfma_f32_16x16x32_bf16 v[10:13], v[176:179], v[172:175], v[10:13]
	ds_read_b128 v[176:179], v30
	ds_read_b128 v[212:215], v30 offset:2048
	ds_read_b128 v[216:219], v30 offset:4096
	ds_read_b128 v[220:223], v30 offset:6144
	v_mfma_f32_16x16x32_bf16 v[98:101], v[192:195], v[132:135], v[98:101]
	v_mfma_f32_16x16x32_bf16 v[66:69], v[192:195], v[164:167], v[66:69]
	v_mfma_f32_16x16x32_bf16 v[6:9], v[192:195], v[172:175], v[6:9]
	v_mfma_f32_16x16x32_bf16 v[38:41], v[26:29], v[164:167], v[38:41]
	v_mfma_f32_16x16x32_bf16 v[34:37], v[54:57], v[164:167], v[34:37]
	v_mfma_f32_16x16x32_bf16 v[192:195], v[26:29], v[168:171], v[18:21]
	v_mfma_f32_16x16x32_bf16 v[166:169], v[54:57], v[168:171], v[14:17]
	s_nop 2
	ds_read_b128 v[14:17], v130 offset:4096
	ds_read_b128 v[18:21], v130 offset:6144
	v_mfma_f32_16x16x32_bf16 v[70:73], v[26:29], v[132:135], v[70:73]
	v_mfma_f32_16x16x32_bf16 v[132:135], v[54:57], v[132:135], v[62:65]
	v_mfma_f32_16x16x32_bf16 v[2:5], v[26:29], v[172:175], v[2:5]
	v_mfma_f32_16x16x32_bf16 v[170:173], v[54:57], v[172:175], v[90:93]
	ds_read_b128 v[224:227], v130 offset:8192
	ds_read_b128 v[228:231], v130 offset:10240
	s_waitcnt lgkmcnt(0)
	v_mfma_f32_16x16x32_bf16 v[126:129], v[22:25], v[176:179], v[126:129]
	v_mfma_f32_16x16x32_bf16 v[122:125], v[86:89], v[176:179], v[122:125]
	v_mfma_f32_16x16x32_bf16 v[94:97], v[22:25], v[212:215], v[110:113]
	v_mfma_f32_16x16x32_bf16 v[90:93], v[86:89], v[212:215], v[106:109]
	v_mfma_f32_16x16x32_bf16 v[62:65], v[22:25], v[216:219], v[82:85]
	v_mfma_f32_16x16x32_bf16 v[58:61], v[86:89], v[216:219], v[78:81]
	v_mfma_f32_16x16x32_bf16 v[30:33], v[22:25], v[220:223], v[50:53]
	v_mfma_f32_16x16x32_bf16 v[26:29], v[86:89], v[220:223], v[42:45]
	v_mfma_f32_16x16x32_bf16 v[86:89], v[14:17], v[212:215], v[180:183]
	v_mfma_f32_16x16x32_bf16 v[22:25], v[14:17], v[220:223], v[184:187]
	s_nop 1
	ds_read_b128 v[180:183], v130 offset:12288
	ds_read_b128 v[184:187], v130 offset:14336
	v_mfma_f32_16x16x32_bf16 v[118:121], v[14:17], v[176:179], v[118:121]
	v_mfma_f32_16x16x32_bf16 v[114:117], v[18:21], v[176:179], v[114:117]
	v_mfma_f32_16x16x32_bf16 v[82:85], v[18:21], v[212:215], v[196:199]
	v_mfma_f32_16x16x32_bf16 v[54:57], v[14:17], v[216:219], v[200:203]
	v_mfma_f32_16x16x32_bf16 v[50:53], v[18:21], v[216:219], v[204:207]
	v_mfma_f32_16x16x32_bf16 v[18:21], v[18:21], v[220:223], v[188:191]
	v_mfma_f32_16x16x32_bf16 v[110:113], v[224:227], v[176:179], v[102:105]
	v_mfma_f32_16x16x32_bf16 v[106:109], v[228:231], v[176:179], v[98:101]
	v_mfma_f32_16x16x32_bf16 v[78:81], v[224:227], v[212:215], v[74:77]
	v_mfma_f32_16x16x32_bf16 v[74:77], v[228:231], v[212:215], v[66:69]
	v_mfma_f32_16x16x32_bf16 v[46:49], v[224:227], v[216:219], v[46:49]
	v_mfma_f32_16x16x32_bf16 v[42:45], v[228:231], v[216:219], v[208:211]
	v_mfma_f32_16x16x32_bf16 v[14:17], v[224:227], v[220:223], v[10:13]
	v_mfma_f32_16x16x32_bf16 v[10:13], v[228:231], v[220:223], v[6:9]
	s_nop 2
	v_mov_b32_e32 v6, v1
	s_waitcnt vmcnt(0) lgkmcnt(0)
	s_barrier
; __device__ __forceinline__ int get_tid512() { int t = threadIdx.x; asm volatile("" : "+v"(t)); return t; }
; __device__ __forceinline__ unsigned pack2(float a, float b) { unsigned r; asm("v_cvt_pk_bf16_f32 %0, %1, %2" : "=v"(r) : "v"(a), "v"(b)); return r; }
;   __device__ __forceinline__ float c4(int g, int rig, int col, f32x4 v) const {
;     ...
;     uint2 u; u.x = pack2(v[0], v[1]); u.y = pack2(v[2], v[3]);
;     *(uint2*)(out + row * ld + col) = u;
;     return v[0] * v[0] + v[1] * v[1] + v[2] * v[2] + v[3] * v[3];
; template <bool SWAP, class Epi, bool THIN = false> ...
;     ...
;     const int te = get_tid512();
;     const int fr_e = te & 15, fq_e = (te & 63) >> 4, wr_e = te >> 7, wc_e = (te >> 6) & 1;
;     const int sub = 2 * mt + (wr_e >> 1);
;     const int g = sub / tpg, ti = sub - g * tpg;
;     const int rig0 = ti * step - halo;
;     const int rw = (wr_e & 1) * 64;
;     if constexpr (Epi::KIND == 0) {
; #pragma unroll
;       for (int m = 0; m < 4; ++m) {
;         const int rig = rig0 + rw + m * 16 + fr_e;
;         if constexpr (Epi::ROWSUM) {
;           float ss = 0.f;
; #pragma unroll
;           for (int n = 0; n < 8; ++n) {
;             const int col = nt * 256 + wc_e * 128 + n * 16 + fq_e * 4;
;             if (col < N) ss += epi.c4(g, rig, col, acc[m][n]);
;           }
;           ss += __shfl_xor(ss, 16); ss += __shfl_xor(ss, 32);
;           if (fq_e == 0) epi.rowsum(g, rig, nt * 2 + wc_e, ss);
	v_mfma_f32_16x16x32_bf16 v[98:101], v[184:187], v[176:179], v[132:135]
	v_ashrrev_i32_e32 v7, 8, v6
	v_add_u32_e32 v7, s5, v7
	v_mul_hi_i32 v8, v7, s23
	v_lshrrev_b32_e32 v9, 31, v8
	v_ashrrev_i32_e32 v8, 2, v8
	v_add_u32_e32 v130, v8, v9
	v_and_b32_e32 v132, 15, v6
	v_bfe_u32 v164, v6, 4, 2
	v_bfe_u32 v165, v6, 6, 1
	v_mul_lo_u32 v8, v130, s24
	v_lshrrev_b32_e32 v6, 1, v6
	v_mfma_f32_16x16x32_bf16 v[102:105], v[180:183], v[176:179], v[70:73]
	v_add_lshl_u32 v133, v8, v7, 7
	v_and_b32_e32 v135, 64, v6
	v_lshlrev_b32_e32 v134, 7, v165
	v_mfma_f32_16x16x32_bf16 v[70:73], v[180:183], v[212:215], v[38:41]
	v_or3_b32 v132, v133, v135, v132
	v_ashrrev_i32_e32 v133, 31, v132
	v_mfma_f32_16x16x32_bf16 v[66:69], v[184:187], v[212:215], v[34:37]
	v_mfma_f32_16x16x32_bf16 v[38:41], v[180:183], v[216:219], v[192:195]
	v_mfma_f32_16x16x32_bf16 v[34:37], v[184:187], v[216:219], v[166:169]
	v_mfma_f32_16x16x32_bf16 v[6:9], v[180:183], v[220:223], v[2:5]
	s_nop 1
	v_lshlrev_b32_e32 v166, 2, v164
	v_or3_b32 v134, v134, v166, s4
	v_cmp_gt_i32_e32 vcc, s27, v134
	v_mfma_f32_16x16x32_bf16 v[2:5], v[184:187], v[220:223], v[170:173]
	v_mov_b32_e32 v166, 0
	v_ashrrev_i32_e32 v135, 31, v134
	s_and_saveexec_b64 s[4:5], vcc
	s_cbranch_execz .LBB0_421
	v_mad_i64_i32 v[166:167], s[6:7], v130, s25, v[132:133]
	v_mov_b64_e32 v[170:171], s[30:31]
	v_cvt_pk_bf16_f32 v168, v126, v127
	v_mad_u64_u32 v[170:171], s[6:7], v166, s28, v[170:171]
	v_pk_mul_f32 v[126:127], v[126:127], v[126:127]
	v_cvt_pk_bf16_f32 v169, v128, v129
	v_mad_i32_i24 v171, v167, s28, v171
	v_pk_mul_f32 v[128:129], v[128:129], v[128:129]
	v_add_f32_e32 v126, v126, v127
	v_lshl_add_u64 v[166:167], v[134:135], 1, v[170:171]
	v_add_f32_e32 v126, v128, v126
	global_store_dwordx2 v[166:167], v[168:169], off
	v_add_f32_e32 v166, v129, v126

; template <bool SWAP, class Epi, bool THIN = false> ...
;     ...
;     for (int st = 0; st < ns; ++st) {
;       asm volatile("s_waitcnt vmcnt(0)" ::: "memory");
;       __builtin_amdgcn_s_barrier();
;       asm volatile("" ::: "memory");
;       if (st + 1 < ns) {
;         char* nb = smem + ((st + 1) & 1) * 65536;
;         const int ko = (st + 1) * 64;
; #pragma unroll
;         for (int i = 0; i < 4; ++i) { GLDS16(A + (size_t)(ap[i] + ko), nb + tid * 16 + i * 8192); GLDS16(Bt + (size_t)(bp[i] + ko), nb + 32768 + tid * 16 + i * 8192); }
;       }
;       const char* sa = smem + (st & 1) * 65536 + (wr * 64 + fr) * 128;
;       const char* sb = smem + (st & 1) * 65536 + 32768 + (wc * 128 + fr) * 128;
;       if constexpr (THIN) {
;         if (wc == 0) {
; #pragma unroll
;           for (int ks = 0; ks < 2; ++ks) {
;             bf16x8 af[4], bf[2];
; #pragma unroll
;             for (int m = 0; m < 4; ++m) af[m] = *(const bf16x8*)(sa + m * 2048 + (((ks * 4 + fq) ^ swz) << 4));
; #pragma unroll
;             for (int n = 0; n < 2; ++n) bf[n] = *(const bf16x8*)(sb + n * 2048 + (((ks * 4 + fq) ^ swz) << 4));
; #pragma unroll
;             for (int m = 0; m < 4; ++m)
; #pragma unroll
;               for (int n = 0; n < 2; ++n)
;                 acc[m][n] = SWAP ? __builtin_amdgcn_mfma_f32_16x16x32_bf16(bf[n], af[m], acc[m][n], 0, 0, 0)
;                                  : __builtin_amdgcn_mfma_f32_16x16x32_bf16(af[m], bf[n], acc[m][n], 0, 0, 0);
;           }
;         }
;       } else {
;       bf16x8 afA[4], afB[4], bfb[2][2];
; #pragma unroll
;       for (int m = 0; m < 4; ++m) afA[m] = *(const bf16x8*)(sa + m * 2048 + ((fq ^ swz) << 4));
; #pragma unroll
;       for (int n = 0; n < 2; ++n) bfb[0][n] = *(const bf16x8*)(sb + n * 2048 + ((fq ^ swz) << 4));
; #pragma unroll
;       for (int gq = 0; gq < 8; ++gq) {
;         const int ks = gq >> 2, nh = gq & 3;
;         if (gq < 7) {
;           const int ks2 = (gq + 1) >> 2, nh2 = (gq + 1) & 3;
; #pragma unroll
;           for (int n = 0; n < 2; ++n) bfb[(gq + 1) & 1][n] = *(const bf16x8*)(sb + (nh2 * 2 + n) * 2048 + (((ks2 * 4 + fq) ^ swz) << 4));
;         }
;         if (gq == 3) {
; #pragma unroll
;           for (int m = 0; m < 4; ++m) afB[m] = *(const bf16x8*)(sa + m * 2048 + (((4 + fq) ^ swz) << 4));
;         }
;         __builtin_amdgcn_sched_barrier(0);
; #pragma unroll
.LBB0_2116:
	s_add_i32 s8, s7, 0x10000
	s_and_b32 s9, s8, 0x10000
	v_add_u32_e32 v169, s9, v144
	s_nop 0
	v_readfirstlane_b32 s9, v169
	s_waitcnt vmcnt(0)
	s_barrier
	s_and_b32 s7, s7, 0x10000
	v_add_u32_e32 v130, s7, v145
	v_add_u32_e32 v140, v130, v147
	ds_read_b128 v[170:173], v140
	ds_read_b128 v[174:177], v140 offset:2048
	ds_read_b128 v[178:181], v140 offset:4096
	ds_read_b128 v[182:185], v140 offset:6144
	v_or_b32_e32 v140, s7, v146
	v_add_u32_e32 v141, v140, v147
	ds_read_b128 v[186:189], v141 offset:32768
	ds_read_b128 v[190:193], v141 offset:34816
	ds_read_b128 v[194:197], v141 offset:36864
	ds_read_b128 v[198:201], v141 offset:38912
	v_add_u32_e32 v130, v130, v148
	s_waitcnt lgkmcnt(3)
	v_mfma_f32_16x16x32_bf16 v[126:129], v[186:189], v[170:173], v[126:129]
	s_mov_b32 m0, s9
	v_mfma_f32_16x16x32_bf16 v[110:113], v[186:189], v[174:177], v[110:113]
	global_load_lds_dwordx4 v139, s[18:19] sc1
	v_add_u32_e32 v139, 0x80, v139
	v_mfma_f32_16x16x32_bf16 v[82:85], v[186:189], v[178:181], v[82:85]
	v_mfma_f32_16x16x32_bf16 v[50:53], v[186:189], v[182:185], v[50:53]
	ds_read_b128 v[186:189], v141 offset:40960
	ds_read_b128 v[202:205], v141 offset:43008
	s_waitcnt lgkmcnt(4)
	v_mfma_f32_16x16x32_bf16 v[122:125], v[190:193], v[170:173], v[122:125]
	s_add_u32 m0, s9, 0x8000
	v_mfma_f32_16x16x32_bf16 v[106:109], v[190:193], v[174:177], v[106:109]
	global_load_lds_dwordx4 v138, s[24:25] sc1
	v_add_u32_e32 v138, 0x80, v138
	v_mfma_f32_16x16x32_bf16 v[78:81], v[190:193], v[178:181], v[78:81]
	v_mfma_f32_16x16x32_bf16 v[42:45], v[190:193], v[182:185], v[42:45]
	s_waitcnt lgkmcnt(3)
	v_mfma_f32_16x16x32_bf16 v[118:121], v[194:197], v[170:173], v[118:121]
	s_add_u32 m0, s9, 0x2000
	v_mfma_f32_16x16x32_bf16 v[94:97], v[194:197], v[174:177], v[94:97]
	global_load_lds_dwordx4 v137, s[18:19] sc1
	v_add_u32_e32 v137, 0x80, v137
	v_mfma_f32_16x16x32_bf16 v[58:61], v[194:197], v[178:181], v[58:61]
	v_mfma_f32_16x16x32_bf16 v[26:29], v[194:197], v[182:185], v[26:29]
	ds_read_b128 v[190:193], v141 offset:45056
	ds_read_b128 v[194:197], v141 offset:47104
	s_waitcnt lgkmcnt(4)
	v_mfma_f32_16x16x32_bf16 v[114:117], v[198:201], v[170:173], v[114:117]
	s_add_u32 m0, s9, 0xa000
	v_mfma_f32_16x16x32_bf16 v[86:89], v[198:201], v[174:177], v[86:89]
	global_load_lds_dwordx4 v136, s[24:25] sc1
	v_add_u32_e32 v136, 0x80, v136
	v_mfma_f32_16x16x32_bf16 v[54:57], v[198:201], v[178:181], v[54:57]
	v_mfma_f32_16x16x32_bf16 v[22:25], v[198:201], v[182:185], v[22:25]
	v_add_u32_e32 v140, v140, v148
	s_waitcnt lgkmcnt(3)
	v_mfma_f32_16x16x32_bf16 v[102:105], v[186:189], v[170:173], v[102:105]
	ds_read_b128 v[198:201], v140 offset:32768
	ds_read_b128 v[206:209], v140 offset:34816
	s_add_u32 m0, s9, 0x4000
	v_mfma_f32_16x16x32_bf16 v[74:77], v[186:189], v[174:177], v[74:77]
	global_load_lds_dwordx4 v135, s[18:19] sc1
	v_add_u32_e32 v135, 0x80, v135
	v_mfma_f32_16x16x32_bf16 v[46:49], v[186:189], v[178:181], v[46:49]
	v_mfma_f32_16x16x32_bf16 v[10:13], v[186:189], v[182:185], v[10:13]
	ds_read_b128 v[186:189], v130
	ds_read_b128 v[210:213], v130 offset:2048
	ds_read_b128 v[214:217], v130 offset:4096
	ds_read_b128 v[218:221], v130 offset:6144
	s_waitcnt lgkmcnt(8)
	v_mfma_f32_16x16x32_bf16 v[98:101], v[202:205], v[170:173], v[98:101]
	s_add_u32 m0, s9, 0xc000
	v_mfma_f32_16x16x32_bf16 v[66:69], v[202:205], v[174:177], v[66:69]
	global_load_lds_dwordx4 v134, s[24:25] sc1
	v_add_u32_e32 v134, 0x80, v134
	v_mfma_f32_16x16x32_bf16 v[30:33], v[202:205], v[178:181], v[30:33]
	v_mfma_f32_16x16x32_bf16 v[6:9], v[202:205], v[182:185], v[6:9]
	s_waitcnt lgkmcnt(7)
	v_mfma_f32_16x16x32_bf16 v[70:73], v[190:193], v[170:173], v[70:73]
	s_add_u32 m0, s9, 0x6000
	s_waitcnt lgkmcnt(6)
	v_mfma_f32_16x16x32_bf16 v[62:65], v[194:197], v[170:173], v[62:65]
	global_load_lds_dwordx4 v133, s[18:19] sc1
	v_add_u32_e32 v133, 0x80, v133
	v_mfma_f32_16x16x32_bf16 v[38:41], v[190:193], v[174:177], v[38:41]
	v_mfma_f32_16x16x32_bf16 v[34:37], v[194:197], v[174:177], v[34:37]
	ds_read_b128 v[170:173], v140 offset:36864
	ds_read_b128 v[174:177], v140 offset:38912
	v_mfma_f32_16x16x32_bf16 v[18:21], v[190:193], v[178:181], v[18:21]
	s_add_u32 m0, s9, 0xe000
	v_mfma_f32_16x16x32_bf16 v[14:17], v[194:197], v[178:181], v[14:17]
	global_load_lds_dwordx4 v132, s[24:25] sc1
	v_add_u32_e32 v132, 0x80, v132
	v_mfma_f32_16x16x32_bf16 v[2:5], v[190:193], v[182:185], v[2:5]
	v_mfma_f32_16x16x32_bf16 v[90:93], v[194:197], v[182:185], v[90:93]
	ds_read_b128 v[178:181], v140 offset:40960
	ds_read_b128 v[182:185], v140 offset:43008
	s_waitcnt lgkmcnt(7)
	v_mfma_f32_16x16x32_bf16 v[126:129], v[198:201], v[186:189], v[126:129]
	v_mfma_f32_16x16x32_bf16 v[122:125], v[206:209], v[186:189], v[122:125]
	s_waitcnt lgkmcnt(6)
	v_mfma_f32_16x16x32_bf16 v[110:113], v[198:201], v[210:213], v[110:113]
	v_mfma_f32_16x16x32_bf16 v[106:109], v[206:209], v[210:213], v[106:109]
	s_waitcnt lgkmcnt(5)
	v_mfma_f32_16x16x32_bf16 v[82:85], v[198:201], v[214:217], v[82:85]
	v_mfma_f32_16x16x32_bf16 v[78:81], v[206:209], v[214:217], v[78:81]
	s_waitcnt lgkmcnt(4)
	v_mfma_f32_16x16x32_bf16 v[50:53], v[198:201], v[218:221], v[50:53]
	v_mfma_f32_16x16x32_bf16 v[42:45], v[206:209], v[218:221], v[42:45]
	s_waitcnt lgkmcnt(3)
	v_mfma_f32_16x16x32_bf16 v[118:121], v[170:173], v[186:189], v[118:121]
	v_mfma_f32_16x16x32_bf16 v[94:97], v[170:173], v[210:213], v[94:97]
	v_mfma_f32_16x16x32_bf16 v[58:61], v[170:173], v[214:217], v[58:61]
	v_mfma_f32_16x16x32_bf16 v[26:29], v[170:173], v[218:221], v[26:29]
	ds_read_b128 v[170:173], v140 offset:45056
	ds_read_b128 v[190:193], v140 offset:47104
	s_waitcnt lgkmcnt(4)
; template <bool SWAP, class Epi, bool THIN = false> ...
;     ...
;       bf16x8 afA[4], afB[4], bfb[2][2];
; #pragma unroll
;       for (int m = 0; m < 4; ++m) afA[m] = *(const bf16x8*)(sa + m * 2048 + ((fq ^ swz) << 4));
; #pragma unroll
;       for (int n = 0; n < 2; ++n) bfb[0][n] = *(const bf16x8*)(sb + n * 2048 + ((fq ^ swz) << 4));
; #pragma unroll
;       for (int gq = 0; gq < 8; ++gq) {
;         const int ks = gq >> 2, nh = gq & 3;
;         if (gq < 7) {
;           const int ks2 = (gq + 1) >> 2, nh2 = (gq + 1) & 3;
; #pragma unroll
;           for (int n = 0; n < 2; ++n) bfb[(gq + 1) & 1][n] = *(const bf16x8*)(sb + (nh2 * 2 + n) * 2048 + (((ks2 * 4 + fq) ^ swz) << 4));
;         }
;         if (gq == 3) {
; #pragma unroll
;           for (int m = 0; m < 4; ++m) afB[m] = *(const bf16x8*)(sa + m * 2048 + (((4 + fq) ^ swz) << 4));
;         }
;         __builtin_amdgcn_sched_barrier(0);
; #pragma unroll
;         for (int m = 0; m < 4; ++m)
; #pragma unroll
;           for (int n = 0; n < 2; ++n) {
;             const bf16x8 av = ks ? afB[m] : afA[m];
;             acc[m][nh * 2 + n] = SWAP ? __builtin_amdgcn_mfma_f32_16x16x32_bf16(bfb[gq & 1][n], av, acc[m][nh * 2 + n], 0, 0, 0)
;                                       : __builtin_amdgcn_mfma_f32_16x16x32_bf16(av, bfb[gq & 1][n], acc[m][nh * 2 + n], 0, 0, 0);
;           }
;       }
;       }
;     }
;     __syncthreads();
	v_mfma_f32_16x16x32_bf16 v[114:117], v[174:177], v[186:189], v[114:117]
	v_mfma_f32_16x16x32_bf16 v[86:89], v[174:177], v[210:213], v[86:89]
	v_mfma_f32_16x16x32_bf16 v[54:57], v[174:177], v[214:217], v[54:57]
	v_mfma_f32_16x16x32_bf16 v[22:25], v[174:177], v[218:221], v[22:25]
	s_waitcnt lgkmcnt(3)
	v_mfma_f32_16x16x32_bf16 v[102:105], v[178:181], v[186:189], v[102:105]
	s_waitcnt lgkmcnt(2)
	v_mfma_f32_16x16x32_bf16 v[98:101], v[182:185], v[186:189], v[98:101]
	v_mfma_f32_16x16x32_bf16 v[74:77], v[178:181], v[210:213], v[74:77]
	v_mfma_f32_16x16x32_bf16 v[66:69], v[182:185], v[210:213], v[66:69]
	v_mfma_f32_16x16x32_bf16 v[46:49], v[178:181], v[214:217], v[46:49]
	v_mfma_f32_16x16x32_bf16 v[30:33], v[182:185], v[214:217], v[30:33]
	v_mfma_f32_16x16x32_bf16 v[10:13], v[178:181], v[218:221], v[10:13]
	v_mfma_f32_16x16x32_bf16 v[6:9], v[182:185], v[218:221], v[6:9]
	s_waitcnt lgkmcnt(1)
	v_mfma_f32_16x16x32_bf16 v[70:73], v[170:173], v[186:189], v[70:73]
	s_add_i32 s6, s6, 64
	s_cmpk_eq_i32 s6, 0x3c0
	s_mov_b32 s7, s8
	s_waitcnt lgkmcnt(0)
	v_mfma_f32_16x16x32_bf16 v[62:65], v[190:193], v[186:189], v[62:65]
	v_mfma_f32_16x16x32_bf16 v[38:41], v[170:173], v[210:213], v[38:41]
	v_mfma_f32_16x16x32_bf16 v[34:37], v[190:193], v[210:213], v[34:37]
	v_mfma_f32_16x16x32_bf16 v[18:21], v[170:173], v[214:217], v[18:21]
	v_mfma_f32_16x16x32_bf16 v[14:17], v[190:193], v[214:217], v[14:17]
	v_mfma_f32_16x16x32_bf16 v[2:5], v[170:173], v[218:221], v[2:5]
	v_mfma_f32_16x16x32_bf16 v[90:93], v[190:193], v[218:221], v[90:93]
	s_cbranch_scc0 .LBB0_2116
	s_waitcnt vmcnt(0)
	s_barrier
	v_add_u32_e32 v130, v159, v147
	ds_read_b128 v[132:135], v130
	ds_read_b128 v[136:139], v130 offset:2048
	ds_read_b128 v[170:173], v130 offset:4096
	ds_read_b128 v[174:177], v130 offset:6144
	v_add_u32_e32 v130, v160, v147
	ds_read_b128 v[178:181], v130
	ds_read_b128 v[182:185], v130 offset:2048
	ds_read_b128 v[186:189], v130 offset:4096
	ds_read_b128 v[190:193], v130 offset:6144
	s_waitcnt lgkmcnt(0)
	v_mfma_f32_16x16x32_bf16 v[126:129], v[178:181], v[132:135], v[126:129]
	v_mfma_f32_16x16x32_bf16 v[110:113], v[178:181], v[136:139], v[110:113]
	v_mfma_f32_16x16x32_bf16 v[82:85], v[178:181], v[170:173], v[82:85]
	v_mfma_f32_16x16x32_bf16 v[50:53], v[178:181], v[174:177], v[50:53]
	ds_read_b128 v[178:181], v130 offset:8192
	ds_read_b128 v[194:197], v130 offset:10240
	v_mfma_f32_16x16x32_bf16 v[122:125], v[182:185], v[132:135], v[122:125]
	v_mfma_f32_16x16x32_bf16 v[106:109], v[182:185], v[136:139], v[106:109]
	v_mfma_f32_16x16x32_bf16 v[78:81], v[182:185], v[170:173], v[78:81]
	v_mfma_f32_16x16x32_bf16 v[42:45], v[182:185], v[174:177], v[42:45]
	v_mfma_f32_16x16x32_bf16 v[118:121], v[186:189], v[132:135], v[118:121]
	v_mfma_f32_16x16x32_bf16 v[182:185], v[186:189], v[136:139], v[94:97]
	v_mfma_f32_16x16x32_bf16 v[202:205], v[186:189], v[170:173], v[58:61]
	v_mfma_f32_16x16x32_bf16 v[206:209], v[190:193], v[170:173], v[54:57]
	v_mfma_f32_16x16x32_bf16 v[186:189], v[186:189], v[174:177], v[26:29]
	s_nop 2
	ds_read_b128 v[26:29], v130 offset:12288
	ds_read_b128 v[54:57], v130 offset:14336
	v_mfma_f32_16x16x32_bf16 v[114:117], v[190:193], v[132:135], v[114:117]
	v_mfma_f32_16x16x32_bf16 v[198:201], v[190:193], v[136:139], v[86:89]
	v_mfma_f32_16x16x32_bf16 v[190:193], v[190:193], v[174:177], v[22:25]
	v_add_u32_e32 v130, v160, v148
	s_waitcnt lgkmcnt(0)
	v_mfma_f32_16x16x32_bf16 v[210:213], v[194:197], v[170:173], v[30:33]
	ds_read_b128 v[22:25], v130
	ds_read_b128 v[86:89], v130 offset:2048
	s_nop 0
	v_add_u32_e32 v30, v159, v148
	v_mfma_f32_16x16x32_bf16 v[102:105], v[178:181], v[132:135], v[102:105]
	v_mfma_f32_16x16x32_bf16 v[74:77], v[178:181], v[136:139], v[74:77]
	v_mfma_f32_16x16x32_bf16 v[46:49], v[178:181], v[170:173], v[46:49]
	v_mfma_f32_16x16x32_bf16 v[10:13], v[178:181], v[174:177], v[10:13]
	ds_read_b128 v[178:181], v30
	ds_read_b128 v[214:217], v30 offset:2048
	ds_read_b128 v[218:221], v30 offset:4096
	ds_read_b128 v[222:225], v30 offset:6144
	v_mfma_f32_16x16x32_bf16 v[98:101], v[194:197], v[132:135], v[98:101]
	v_mfma_f32_16x16x32_bf16 v[66:69], v[194:197], v[136:139], v[66:69]
	v_mfma_f32_16x16x32_bf16 v[6:9], v[194:197], v[174:177], v[6:9]
	v_mfma_f32_16x16x32_bf16 v[38:41], v[26:29], v[136:139], v[38:41]
	v_mfma_f32_16x16x32_bf16 v[34:37], v[54:57], v[136:139], v[34:37]
	v_mfma_f32_16x16x32_bf16 v[136:139], v[26:29], v[170:173], v[18:21]
	v_mfma_f32_16x16x32_bf16 v[170:173], v[54:57], v[170:173], v[14:17]
	s_nop 2
	ds_read_b128 v[14:17], v130 offset:4096
	ds_read_b128 v[18:21], v130 offset:6144
	v_mfma_f32_16x16x32_bf16 v[70:73], v[26:29], v[132:135], v[70:73]
	v_mfma_f32_16x16x32_bf16 v[132:135], v[54:57], v[132:135], v[62:65]
	v_mfma_f32_16x16x32_bf16 v[2:5], v[26:29], v[174:177], v[2:5]
	v_mfma_f32_16x16x32_bf16 v[174:177], v[54:57], v[174:177], v[90:93]
	ds_read_b128 v[194:197], v130 offset:8192
	ds_read_b128 v[226:229], v130 offset:10240
	s_waitcnt lgkmcnt(0)
	v_mfma_f32_16x16x32_bf16 v[126:129], v[22:25], v[178:181], v[126:129]
	v_mfma_f32_16x16x32_bf16 v[122:125], v[86:89], v[178:181], v[122:125]
	v_mfma_f32_16x16x32_bf16 v[94:97], v[22:25], v[214:217], v[110:113]
	v_mfma_f32_16x16x32_bf16 v[90:93], v[86:89], v[214:217], v[106:109]
	v_mfma_f32_16x16x32_bf16 v[62:65], v[22:25], v[218:221], v[82:85]
	v_mfma_f32_16x16x32_bf16 v[58:61], v[86:89], v[218:221], v[78:81]
	v_mfma_f32_16x16x32_bf16 v[30:33], v[22:25], v[222:225], v[50:53]
	v_mfma_f32_16x16x32_bf16 v[26:29], v[86:89], v[222:225], v[42:45]
	v_mfma_f32_16x16x32_bf16 v[86:89], v[14:17], v[214:217], v[182:185]
	v_mfma_f32_16x16x32_bf16 v[22:25], v[14:17], v[222:225], v[186:189]
	s_nop 1
	ds_read_b128 v[182:185], v130 offset:12288
	ds_read_b128 v[186:189], v130 offset:14336
	v_mfma_f32_16x16x32_bf16 v[118:121], v[14:17], v[178:181], v[118:121]
	v_mfma_f32_16x16x32_bf16 v[114:117], v[18:21], v[178:181], v[114:117]
	v_mfma_f32_16x16x32_bf16 v[82:85], v[18:21], v[214:217], v[198:201]
	v_mfma_f32_16x16x32_bf16 v[54:57], v[14:17], v[218:221], v[202:205]
	v_mfma_f32_16x16x32_bf16 v[50:53], v[18:21], v[218:221], v[206:209]
	v_mfma_f32_16x16x32_bf16 v[18:21], v[18:21], v[222:225], v[190:193]
	v_mfma_f32_16x16x32_bf16 v[110:113], v[194:197], v[178:181], v[102:105]
	v_mfma_f32_16x16x32_bf16 v[106:109], v[226:229], v[178:181], v[98:101]
	v_mfma_f32_16x16x32_bf16 v[78:81], v[194:197], v[214:217], v[74:77]
	v_mfma_f32_16x16x32_bf16 v[74:77], v[226:229], v[214:217], v[66:69]
	v_mfma_f32_16x16x32_bf16 v[46:49], v[194:197], v[218:221], v[46:49]
	v_mfma_f32_16x16x32_bf16 v[42:45], v[226:229], v[218:221], v[210:213]
	v_mfma_f32_16x16x32_bf16 v[14:17], v[194:197], v[222:225], v[10:13]
	v_mfma_f32_16x16x32_bf16 v[6:9], v[226:229], v[222:225], v[6:9]
	v_mov_b32_e32 v130, v1
	s_waitcnt vmcnt(0) lgkmcnt(0)
	s_barrier
; __device__ __forceinline__ unsigned pack2(float a, float b) { unsigned r; asm("v_cvt_pk_bf16_f32 %0, %1, %2" : "=v"(r) : "v"(a), "v"(b)); return r; }
; __device__ __forceinline__ float bf2f(bf16_t h) { return __uint_as_float(((unsigned)h) << 16); }
;   __device__ __forceinline__ void c4(int g, int rig, int col, f32x4 v) const {
;     const size_t o = ((size_t)g * 2048 + rig) * 1024 + col;
;     f32x4 bs;
;     if (BASE_F32) bs = __builtin_nontemporal_load((const f32x4*)((const float*)base + o));
;     else {
;       const uint2 u = *(const uint2*)((const bf16_t*)base + o);
;       bs[0] = bf2f((bf16_t)(u.x & 0xffff)); bs[1] = bf2f((bf16_t)(u.x >> 16)); bs[2] = bf2f((bf16_t)(u.y & 0xffff)); bs[3] = bf2f((bf16_t)(u.y >> 16));
;     }
;     const f32x4 gt = *(const f32x4*)(gate + (size_t)g * 6144 + col);
;     f32x4 bi = {0.f, 0.f, 0.f, 0.f};
;     if (bias) bi = *(const f32x4*)(bias + col);
;     f32x4 r;
; #pragma unroll
;     for (int j = 0; j < 4; ++j) r[j] = bs[j] + gt[j] * (v[j] + bi[j]);
;     uint2 w; w.x = pack2(r[0], r[1]); w.y = pack2(r[2], r[3]);
;     *(uint2*)(X16 + o) = w;
;   }
; template <bool SWAP, class Epi, bool THIN = false> ...
;     ...
;     if constexpr (Epi::KIND == 0) {
; #pragma unroll
;       for (int m = 0; m < 4; ++m) {
;         const int rig = rig0 + rw + m * 16 + fr_e;
;         if constexpr (Epi::ROWSUM) {
;           float ss = 0.f;
; #pragma unroll
;           for (int n = 0; n < 8; ++n) {
;             const int col = nt * 256 + wc_e * 128 + n * 16 + fq_e * 4;
;             if (col < N) ss += epi.c4(g, rig, col, acc[m][n]);
;           }
;           ss += __shfl_xor(ss, 16); ss += __shfl_xor(ss, 32);
;           if (fq_e == 0) epi.rowsum(g, rig, nt * 2 + wc_e, ss);
;         } else {
; #pragma unroll
;           for (int n = 0; n < 8; ++n) {
;             const int col = nt * 256 + wc_e * 128 + n * 16 + fq_e * 4;
;             if (col < N) epi.c4(g, rig, col, acc[m][n]);
	v_mfma_f32_16x16x32_bf16 v[98:101], v[186:189], v[178:181], v[132:135]
	v_ashrrev_i32_e32 v11, 8, v130
	v_add_u32_e32 v11, s5, v11
	v_ashrrev_i32_e32 v12, 31, v11
	v_lshrrev_b32_e32 v12, 28, v12
	v_add_u32_e32 v12, v11, v12
	v_ashrrev_i32_e32 v134, 4, v12
	v_lshlrev_b32_e32 v12, 11, v134
	v_lshlrev_b32_e32 v11, 7, v11
	v_sub_u32_e32 v11, v11, v12
	v_lshrrev_b32_e32 v12, 1, v130
	v_and_b32_e32 v10, 15, v130
	v_and_b32_e32 v12, 64, v12
	v_mfma_f32_16x16x32_bf16 v[102:105], v[182:185], v[178:181], v[70:73]
	v_ashrrev_i32_e32 v135, 31, v134
	v_mfma_f32_16x16x32_bf16 v[70:73], v[182:185], v[214:217], v[38:41]
	v_mfma_f32_16x16x32_bf16 v[38:41], v[182:185], v[218:221], v[136:139]
	s_nop 2
	v_or3_b32 v136, v11, v12, v10
	v_lshlrev_b32_e32 v10, 1, v130
	v_and_b32_e32 v132, 0x80, v10
	v_mfma_f32_16x16x32_bf16 v[10:13], v[182:185], v[222:225], v[2:5]
	v_ashrrev_i32_e32 v137, 31, v136
	v_lshlrev_b64 v[138:139], 21, v[134:135]
	v_lshlrev_b64 v[140:141], 10, v[136:137]
	v_lshrrev_b32_e32 v2, 2, v130
	v_and_b32_e32 v2, 12, v2
	v_mfma_f32_16x16x32_bf16 v[66:69], v[186:189], v[214:217], v[34:37]
	v_or3_b32 v132, v2, v132, s4
	v_mad_i64_i32 v[134:135], s[4:5], v134, s33, 0
	v_mfma_f32_16x16x32_bf16 v[34:37], v[186:189], v[218:221], v[170:173]
	v_lshl_add_u64 v[140:141], v[140:141], 0, v[138:139]
	v_cmp_gt_i32_e32 vcc, s34, v132
	v_ashrrev_i32_e32 v133, 31, v132
	v_mfma_f32_16x16x32_bf16 v[2:5], v[186:189], v[222:225], v[174:177]
	v_lshl_add_u64 v[134:135], s[26:27], 0, v[134:135]
	v_lshl_add_u64 v[168:169], v[132:133], 2, v[134:135]
	global_load_dwordx4 v[180:183], v[168:169], off
	global_load_dwordx4 v[184:187], v[168:169], off offset:64
	global_load_dwordx4 v[188:191], v[168:169], off offset:128
	global_load_dwordx4 v[192:195], v[168:169], off offset:192
	global_load_dwordx4 v[196:199], v[168:169], off offset:256
	global_load_dwordx4 v[200:203], v[168:169], off offset:320
	global_load_dwordx4 v[204:207], v[168:169], off offset:384
	global_load_dwordx4 v[208:211], v[168:169], off offset:448
	v_lshl_add_u64 v[178:179], v[140:141], 0, v[132:133]
	v_lshl_add_u64 v[244:245], v[140:141], 0, v[132:133]
	v_lshl_add_u64 v[244:245], v[244:245], 2, s[22:23]
	global_load_dwordx4 v[212:215], v[244:245], off nt
	global_load_dwordx4 v[216:219], v[244:245], off offset:64 nt
	global_load_dwordx4 v[220:223], v[244:245], off offset:128 nt
	global_load_dwordx4 v[224:227], v[244:245], off offset:192 nt
	global_load_dwordx4 v[228:231], v[244:245], off offset:256 nt
	global_load_dwordx4 v[232:235], v[244:245], off offset:320 nt
	global_load_dwordx4 v[236:239], v[244:245], off offset:384 nt
	global_load_dwordx4 v[240:243], v[244:245], off offset:448 nt
	s_nop 0
	v_add_f32_e32 v126, 0, v126
	v_add_f32_e32 v127, 0, v127
	v_add_f32_e32 v128, 0, v128
	v_add_f32_e32 v129, 0, v129
	s_waitcnt vmcnt(7)
	v_fma_f32 v126, v126, v180, v212
	v_fma_f32 v127, v127, v181, v213
	v_fma_f32 v128, v128, v182, v214
	v_fma_f32 v177, v129, v183, v215
	v_cvt_pk_bf16_f32 v126, v126, v127
	v_cvt_pk_bf16_f32 v127, v128, v177
	v_lshl_add_u64 v[128:129], v[178:179], 1, s[20:21]
	global_store_dwordx2 v[128:129], v[126:127], off
	v_or_b32_e32 v126, 16, v132
	v_lshl_add_u64 v[174:175], v[140:141], 0, v[132:133]
	s_nop 0
	v_add_f32_e32 v122, 0, v122
	v_add_f32_e32 v123, 0, v123
	v_add_f32_e32 v124, 0, v124
	v_add_f32_e32 v125, 0, v125
	s_waitcnt vmcnt(7)
	v_fma_f32 v122, v122, v184, v216
	v_fma_f32 v123, v123, v185, v217
	v_fma_f32 v124, v124, v186, v218
	v_fma_f32 v173, v125, v187, v219
	v_cvt_pk_bf16_f32 v122, v122, v123
	v_cvt_pk_bf16_f32 v123, v124, v173
	v_lshl_add_u64 v[124:125], v[174:175], 1, s[20:21]
	global_store_dwordx2 v[124:125], v[122:123], off offset:32
	v_or_b32_e32 v122, 32, v132
	v_lshl_add_u64 v[170:171], v[140:141], 0, v[132:133]
	s_nop 0
	v_add_f32_e32 v118, 0, v118
	v_add_f32_e32 v119, 0, v119
	v_add_f32_e32 v120, 0, v120
	v_add_f32_e32 v121, 0, v121
	s_waitcnt vmcnt(7)
	v_fma_f32 v118, v118, v188, v220
	v_fma_f32 v119, v119, v189, v221
	v_fma_f32 v120, v120, v190, v222
	v_fma_f32 v129, v121, v191, v223
	v_cvt_pk_bf16_f32 v118, v118, v119
	v_cvt_pk_bf16_f32 v119, v120, v129
	v_lshl_add_u64 v[120:121], v[170:171], 1, s[20:21]
	global_store_dwordx2 v[120:121], v[118:119], off offset:64
	v_or_b32_e32 v118, 48, v132
	v_lshl_add_u64 v[126:127], v[140:141], 0, v[132:133]
	s_nop 0
	v_add_f32_e32 v114, 0, v114
	v_add_f32_e32 v115, 0, v115
	v_add_f32_e32 v116, 0, v116
	v_add_f32_e32 v117, 0, v117
	s_waitcnt vmcnt(7)
	v_fma_f32 v114, v114, v192, v224
	v_fma_f32 v115, v115, v193, v225
	v_fma_f32 v116, v116, v194, v226
	v_fma_f32 v125, v117, v195, v227
	v_cvt_pk_bf16_f32 v114, v114, v115
	v_cvt_pk_bf16_f32 v115, v116, v125
	v_lshl_add_u64 v[116:117], v[126:127], 1, s[20:21]
	global_store_dwordx2 v[116:117], v[114:115], off offset:96
	v_or_b32_e32 v114, 64, v132
	v_lshl_add_u64 v[122:123], v[140:141], 0, v[132:133]
	s_nop 0
	v_add_f32_e32 v110, 0, v110
	v_add_f32_e32 v111, 0, v111
	v_add_f32_e32 v112, 0, v112
	v_add_f32_e32 v113, 0, v113
	s_waitcnt vmcnt(7)
	v_fma_f32 v110, v110, v196, v228
	v_fma_f32 v111, v111, v197, v229
	v_fma_f32 v112, v112, v198, v230
	v_fma_f32 v121, v113, v199, v231
	v_cvt_pk_bf16_f32 v110, v110, v111
	v_cvt_pk_bf16_f32 v111, v112, v121
	v_lshl_add_u64 v[112:113], v[122:123], 1, s[20:21]
	global_store_dwordx2 v[112:113], v[110:111], off offset:128
	v_or_b32_e32 v110, 0x50, v132
	v_lshl_add_u64 v[118:119], v[140:141], 0, v[132:133]
	s_nop 0
	v_add_f32_e32 v106, 0, v106
	v_add_f32_e32 v107, 0, v107
	v_add_f32_e32 v108, 0, v108
	v_add_f32_e32 v109, 0, v109
	s_waitcnt vmcnt(7)
; __device__ __forceinline__ unsigned pack2(float a, float b) { unsigned r; asm("v_cvt_pk_bf16_f32 %0, %1, %2" : "=v"(r) : "v"(a), "v"(b)); return r; }
; __device__ __forceinline__ float bf2f(bf16_t h) { return __uint_as_float(((unsigned)h) << 16); }
;   __device__ __forceinline__ void c4(int g, int rig, int col, f32x4 v) const {
;     const size_t o = ((size_t)g * 2048 + rig) * 1024 + col;
;     f32x4 bs;
;     if (BASE_F32) bs = __builtin_nontemporal_load((const f32x4*)((const float*)base + o));
;     else {
;       const uint2 u = *(const uint2*)((const bf16_t*)base + o);
;       bs[0] = bf2f((bf16_t)(u.x & 0xffff)); bs[1] = bf2f((bf16_t)(u.x >> 16)); bs[2] = bf2f((bf16_t)(u.y & 0xffff)); bs[3] = bf2f((bf16_t)(u.y >> 16));
;     }
;     const f32x4 gt = *(const f32x4*)(gate + (size_t)g * 6144 + col);
;     f32x4 bi = {0.f, 0.f, 0.f, 0.f};
;     if (bias) bi = *(const f32x4*)(bias + col);
;     f32x4 r;
; #pragma unroll
;     for (int j = 0; j < 4; ++j) r[j] = bs[j] + gt[j] * (v[j] + bi[j]);
;     uint2 w; w.x = pack2(r[0], r[1]); w.y = pack2(r[2], r[3]);
;     *(uint2*)(X16 + o) = w;
;   }
; template <bool SWAP, class Epi, bool THIN = false> ...
;     ...
;     if constexpr (Epi::KIND == 0) {
; #pragma unroll
;       for (int m = 0; m < 4; ++m) {
;         const int rig = rig0 + rw + m * 16 + fr_e;
;         if constexpr (Epi::ROWSUM) {
;           float ss = 0.f;
; #pragma unroll
;           for (int n = 0; n < 8; ++n) {
;             const int col = nt * 256 + wc_e * 128 + n * 16 + fq_e * 4;
;             if (col < N) ss += epi.c4(g, rig, col, acc[m][n]);
;           }
;           ss += __shfl_xor(ss, 16); ss += __shfl_xor(ss, 32);
;           if (fq_e == 0) epi.rowsum(g, rig, nt * 2 + wc_e, ss);
;         } else {
; #pragma unroll
;           for (int n = 0; n < 8; ++n) {
;             const int col = nt * 256 + wc_e * 128 + n * 16 + fq_e * 4;
;             if (col < N) epi.c4(g, rig, col, acc[m][n]);
	v_fma_f32 v106, v106, v200, v232
	v_fma_f32 v107, v107, v201, v233
	v_fma_f32 v108, v108, v202, v234
	v_fma_f32 v117, v109, v203, v235
	v_cvt_pk_bf16_f32 v106, v106, v107
	v_cvt_pk_bf16_f32 v107, v108, v117
	v_lshl_add_u64 v[108:109], v[118:119], 1, s[20:21]
	global_store_dwordx2 v[108:109], v[106:107], off offset:160
	v_or_b32_e32 v106, 0x60, v132
	v_lshl_add_u64 v[114:115], v[140:141], 0, v[132:133]
	s_nop 0
	v_add_f32_e32 v102, 0, v102
	v_add_f32_e32 v103, 0, v103
	v_add_f32_e32 v104, 0, v104
	v_add_f32_e32 v105, 0, v105
	s_waitcnt vmcnt(7)
	v_fma_f32 v102, v102, v204, v236
	v_fma_f32 v103, v103, v205, v237
	v_fma_f32 v104, v104, v206, v238
	v_fma_f32 v113, v105, v207, v239
	v_cvt_pk_bf16_f32 v102, v102, v103
	v_cvt_pk_bf16_f32 v103, v104, v113
	v_lshl_add_u64 v[104:105], v[114:115], 1, s[20:21]
	global_store_dwordx2 v[104:105], v[102:103], off offset:192
	v_or_b32_e32 v102, 0x70, v132
	v_lshl_add_u64 v[110:111], v[140:141], 0, v[132:133]
	s_nop 0
	v_add_f32_e32 v98, 0, v98
	v_add_f32_e32 v99, 0, v99
	v_add_f32_e32 v100, 0, v100
	v_add_f32_e32 v101, 0, v101
	s_waitcnt vmcnt(7)
	v_fma_f32 v98, v98, v208, v240
	v_fma_f32 v99, v99, v209, v241
	v_fma_f32 v100, v100, v210, v242
	v_fma_f32 v109, v101, v211, v243
	v_cvt_pk_bf16_f32 v98, v98, v99
	v_cvt_pk_bf16_f32 v99, v100, v109
	v_lshl_add_u64 v[100:101], v[110:111], 1, s[20:21]
	global_store_dwordx2 v[100:101], v[98:99], off offset:224
	v_or_b32_e32 v98, 16, v136
	v_ashrrev_i32_e32 v99, 31, v98
	v_lshlrev_b64 v[98:99], 10, v[98:99]
	v_lshl_add_u64 v[98:99], v[98:99], 0, v[138:139]
	v_lshl_add_u64 v[108:109], v[98:99], 0, v[132:133]
	v_lshl_add_u64 v[244:245], v[98:99], 0, v[132:133]
	v_lshl_add_u64 v[244:245], v[244:245], 2, s[22:23]
	global_load_dwordx4 v[212:215], v[244:245], off nt
	global_load_dwordx4 v[216:219], v[244:245], off offset:64 nt
	global_load_dwordx4 v[220:223], v[244:245], off offset:128 nt
	global_load_dwordx4 v[224:227], v[244:245], off offset:192 nt
	global_load_dwordx4 v[228:231], v[244:245], off offset:256 nt
	global_load_dwordx4 v[232:235], v[244:245], off offset:320 nt
	global_load_dwordx4 v[236:239], v[244:245], off offset:384 nt
	global_load_dwordx4 v[240:243], v[244:245], off offset:448 nt
	s_nop 0
	v_add_f32_e32 v94, 0, v94
	v_add_f32_e32 v95, 0, v95
	v_add_f32_e32 v96, 0, v96
	v_add_f32_e32 v97, 0, v97
	s_waitcnt vmcnt(7)
	v_fma_f32 v94, v94, v180, v212
	v_fma_f32 v95, v95, v181, v213
	v_fma_f32 v96, v96, v182, v214
	v_fma_f32 v107, v97, v183, v215
	v_cvt_pk_bf16_f32 v94, v94, v95
	v_cvt_pk_bf16_f32 v95, v96, v107
	v_lshl_add_u64 v[96:97], v[108:109], 1, s[20:21]
	global_store_dwordx2 v[96:97], v[94:95], off
	v_lshl_add_u64 v[104:105], v[98:99], 0, v[132:133]
	s_nop 0
	v_add_f32_e32 v90, 0, v90
	v_add_f32_e32 v91, 0, v91
	v_add_f32_e32 v92, 0, v92
	v_add_f32_e32 v93, 0, v93
	s_waitcnt vmcnt(7)
	v_fma_f32 v90, v90, v184, v216
	v_fma_f32 v91, v91, v185, v217
	v_fma_f32 v92, v92, v186, v218
	v_fma_f32 v103, v93, v187, v219
	v_cvt_pk_bf16_f32 v90, v90, v91
	v_cvt_pk_bf16_f32 v91, v92, v103
	v_lshl_add_u64 v[92:93], v[104:105], 1, s[20:21]
	global_store_dwordx2 v[92:93], v[90:91], off offset:32
	v_lshl_add_u64 v[100:101], v[98:99], 0, v[132:133]
	s_nop 0
	v_add_f32_e32 v86, 0, v86
	v_add_f32_e32 v87, 0, v87
	v_add_f32_e32 v88, 0, v88
	v_add_f32_e32 v89, 0, v89
	s_waitcnt vmcnt(7)
	v_fma_f32 v86, v86, v188, v220
	v_fma_f32 v87, v87, v189, v221
	v_fma_f32 v88, v88, v190, v222
	v_fma_f32 v97, v89, v191, v223
	v_cvt_pk_bf16_f32 v86, v86, v87
	v_cvt_pk_bf16_f32 v87, v88, v97
	v_lshl_add_u64 v[88:89], v[100:101], 1, s[20:21]
	global_store_dwordx2 v[88:89], v[86:87], off offset:64
	v_lshl_add_u64 v[94:95], v[98:99], 0, v[132:133]
	s_nop 0
	v_add_f32_e32 v82, 0, v82
	v_add_f32_e32 v83, 0, v83
	v_add_f32_e32 v84, 0, v84
	v_add_f32_e32 v85, 0, v85
	s_waitcnt vmcnt(7)
	v_fma_f32 v82, v82, v192, v224
	v_fma_f32 v83, v83, v193, v225
	v_fma_f32 v84, v84, v194, v226
	v_fma_f32 v93, v85, v195, v227
	v_cvt_pk_bf16_f32 v82, v82, v83
	v_cvt_pk_bf16_f32 v83, v84, v93
	v_lshl_add_u64 v[84:85], v[94:95], 1, s[20:21]
	global_store_dwordx2 v[84:85], v[82:83], off offset:96
	v_lshl_add_u64 v[90:91], v[98:99], 0, v[132:133]
	s_nop 0
	v_add_f32_e32 v78, 0, v78
	v_add_f32_e32 v79, 0, v79
	v_add_f32_e32 v80, 0, v80
	v_add_f32_e32 v81, 0, v81
	s_waitcnt vmcnt(7)
	v_fma_f32 v78, v78, v196, v228
	v_fma_f32 v79, v79, v197, v229
	v_fma_f32 v80, v80, v198, v230
	v_fma_f32 v89, v81, v199, v231
	v_cvt_pk_bf16_f32 v78, v78, v79
	v_cvt_pk_bf16_f32 v79, v80, v89
	v_lshl_add_u64 v[80:81], v[90:91], 1, s[20:21]
	global_store_dwordx2 v[80:81], v[78:79], off offset:128
	v_lshl_add_u64 v[86:87], v[98:99], 0, v[132:133]
	s_nop 0
	v_add_f32_e32 v74, 0, v74
	v_add_f32_e32 v75, 0, v75
	v_add_f32_e32 v76, 0, v76
	v_add_f32_e32 v77, 0, v77
	s_waitcnt vmcnt(7)
	v_fma_f32 v74, v74, v200, v232
	v_fma_f32 v75, v75, v201, v233
	v_fma_f32 v76, v76, v202, v234
	v_fma_f32 v85, v77, v203, v235
	v_cvt_pk_bf16_f32 v74, v74, v75
	v_cvt_pk_bf16_f32 v75, v76, v85
	v_lshl_add_u64 v[76:77], v[86:87], 1, s[20:21]
	global_store_dwordx2 v[76:77], v[74:75], off offset:160
	v_lshl_add_u64 v[82:83], v[98:99], 0, v[132:133]
	v_add_f32_e32 v70, 0, v70
	v_add_f32_e32 v71, 0, v71
	v_add_f32_e32 v72, 0, v72
	v_add_f32_e32 v73, 0, v73
	s_waitcnt vmcnt(7)
	v_fma_f32 v70, v70, v204, v236
	v_fma_f32 v71, v71, v205, v237
	v_fma_f32 v72, v72, v206, v238
	v_fma_f32 v81, v73, v207, v239
	v_cvt_pk_bf16_f32 v70, v70, v71
	v_cvt_pk_bf16_f32 v71, v72, v81
	v_lshl_add_u64 v[72:73], v[82:83], 1, s[20:21]
	global_store_dwordx2 v[72:73], v[70:71], off offset:192
	v_lshl_add_u64 v[78:79], v[98:99], 0, v[132:133]
	v_add_f32_e32 v66, 0, v66
	v_add_f32_e32 v67, 0, v67
	v_add_f32_e32 v68, 0, v68
	v_add_f32_e32 v69, 0, v69
	s_waitcnt vmcnt(7)
; __device__ __forceinline__ unsigned pack2(float a, float b) { unsigned r; asm("v_cvt_pk_bf16_f32 %0, %1, %2" : "=v"(r) : "v"(a), "v"(b)); return r; }
; __device__ __forceinline__ float bf2f(bf16_t h) { return __uint_as_float(((unsigned)h) << 16); }
;   __device__ __forceinline__ void c4(int g, int rig, int col, f32x4 v) const {
;     const size_t o = ((size_t)g * 2048 + rig) * 1024 + col;
;     f32x4 bs;
;     if (BASE_F32) bs = __builtin_nontemporal_load((const f32x4*)((const float*)base + o));
;     else {
;       const uint2 u = *(const uint2*)((const bf16_t*)base + o);
;       bs[0] = bf2f((bf16_t)(u.x & 0xffff)); bs[1] = bf2f((bf16_t)(u.x >> 16)); bs[2] = bf2f((bf16_t)(u.y & 0xffff)); bs[3] = bf2f((bf16_t)(u.y >> 16));
;     }
;     const f32x4 gt = *(const f32x4*)(gate + (size_t)g * 6144 + col);
;     f32x4 bi = {0.f, 0.f, 0.f, 0.f};
;     if (bias) bi = *(const f32x4*)(bias + col);
;     f32x4 r;
; #pragma unroll
;     for (int j = 0; j < 4; ++j) r[j] = bs[j] + gt[j] * (v[j] + bi[j]);
;     uint2 w; w.x = pack2(r[0], r[1]); w.y = pack2(r[2], r[3]);
;     *(uint2*)(X16 + o) = w;
;   }
; template <bool SWAP, class Epi, bool THIN = false> ...
;     ...
;     if constexpr (Epi::KIND == 0) {
; #pragma unroll
;       for (int m = 0; m < 4; ++m) {
;         const int rig = rig0 + rw + m * 16 + fr_e;
;         if constexpr (Epi::ROWSUM) {
;           float ss = 0.f;
; #pragma unroll
;           for (int n = 0; n < 8; ++n) {
;             const int col = nt * 256 + wc_e * 128 + n * 16 + fq_e * 4;
;             if (col < N) ss += epi.c4(g, rig, col, acc[m][n]);
;           }
;           ss += __shfl_xor(ss, 16); ss += __shfl_xor(ss, 32);
;           if (fq_e == 0) epi.rowsum(g, rig, nt * 2 + wc_e, ss);
;         } else {
; #pragma unroll
;           for (int n = 0; n < 8; ++n) {
;             const int col = nt * 256 + wc_e * 128 + n * 16 + fq_e * 4;
;             if (col < N) epi.c4(g, rig, col, acc[m][n]);
	v_fma_f32 v66, v66, v208, v240
	v_fma_f32 v67, v67, v209, v241
	v_fma_f32 v68, v68, v210, v242
	v_fma_f32 v77, v69, v211, v243
	v_cvt_pk_bf16_f32 v66, v66, v67
	v_cvt_pk_bf16_f32 v67, v68, v77
	v_lshl_add_u64 v[68:69], v[78:79], 1, s[20:21]
	global_store_dwordx2 v[68:69], v[66:67], off offset:224
	v_or_b32_e32 v66, 32, v136
	v_ashrrev_i32_e32 v67, 31, v66
	v_lshlrev_b64 v[66:67], 10, v[66:67]
	v_lshl_add_u64 v[66:67], v[66:67], 0, v[138:139]
	v_lshl_add_u64 v[76:77], v[66:67], 0, v[132:133]
	v_lshl_add_u64 v[244:245], v[66:67], 0, v[132:133]
	v_lshl_add_u64 v[244:245], v[244:245], 2, s[22:23]
	global_load_dwordx4 v[212:215], v[244:245], off nt
	global_load_dwordx4 v[216:219], v[244:245], off offset:64 nt
	global_load_dwordx4 v[220:223], v[244:245], off offset:128 nt
	global_load_dwordx4 v[224:227], v[244:245], off offset:192 nt
	global_load_dwordx4 v[228:231], v[244:245], off offset:256 nt
	global_load_dwordx4 v[232:235], v[244:245], off offset:320 nt
	global_load_dwordx4 v[236:239], v[244:245], off offset:384 nt
	global_load_dwordx4 v[240:243], v[244:245], off offset:448 nt
	v_add_f32_e32 v62, 0, v62
	v_add_f32_e32 v63, 0, v63
	v_add_f32_e32 v64, 0, v64
	v_add_f32_e32 v65, 0, v65
	s_waitcnt vmcnt(7)
	v_fma_f32 v62, v62, v180, v212
	v_fma_f32 v63, v63, v181, v213
	v_fma_f32 v64, v64, v182, v214
	v_fma_f32 v75, v65, v183, v215
	v_cvt_pk_bf16_f32 v62, v62, v63
	v_cvt_pk_bf16_f32 v63, v64, v75
	v_lshl_add_u64 v[64:65], v[76:77], 1, s[20:21]
	global_store_dwordx2 v[64:65], v[62:63], off
	v_lshl_add_u64 v[72:73], v[66:67], 0, v[132:133]
	v_add_f32_e32 v58, 0, v58
	v_add_f32_e32 v59, 0, v59
	v_add_f32_e32 v60, 0, v60
	v_add_f32_e32 v61, 0, v61
	s_waitcnt vmcnt(7)
	v_fma_f32 v58, v58, v184, v216
	v_fma_f32 v59, v59, v185, v217
	v_fma_f32 v60, v60, v186, v218
	v_fma_f32 v71, v61, v187, v219
	v_cvt_pk_bf16_f32 v58, v58, v59
	v_cvt_pk_bf16_f32 v59, v60, v71
	v_lshl_add_u64 v[60:61], v[72:73], 1, s[20:21]
	global_store_dwordx2 v[60:61], v[58:59], off offset:32
	v_lshl_add_u64 v[68:69], v[66:67], 0, v[132:133]
	v_add_f32_e32 v54, 0, v54
	v_add_f32_e32 v55, 0, v55
	v_add_f32_e32 v56, 0, v56
	v_add_f32_e32 v57, 0, v57
	s_waitcnt vmcnt(7)
	v_fma_f32 v54, v54, v188, v220
	v_fma_f32 v55, v55, v189, v221
	v_fma_f32 v56, v56, v190, v222
	v_fma_f32 v65, v57, v191, v223
	v_cvt_pk_bf16_f32 v54, v54, v55
	v_cvt_pk_bf16_f32 v55, v56, v65
	v_lshl_add_u64 v[56:57], v[68:69], 1, s[20:21]
	global_store_dwordx2 v[56:57], v[54:55], off offset:64
	v_lshl_add_u64 v[62:63], v[66:67], 0, v[132:133]
	v_add_f32_e32 v50, 0, v50
	v_add_f32_e32 v51, 0, v51
	v_add_f32_e32 v52, 0, v52
	v_add_f32_e32 v53, 0, v53
	s_waitcnt vmcnt(7)
	v_fma_f32 v50, v50, v192, v224
	v_fma_f32 v51, v51, v193, v225
	v_fma_f32 v52, v52, v194, v226
	v_fma_f32 v61, v53, v195, v227
	v_cvt_pk_bf16_f32 v50, v50, v51
	v_cvt_pk_bf16_f32 v51, v52, v61
	v_lshl_add_u64 v[52:53], v[62:63], 1, s[20:21]
	global_store_dwordx2 v[52:53], v[50:51], off offset:96
	v_lshl_add_u64 v[58:59], v[66:67], 0, v[132:133]
	v_add_f32_e32 v46, 0, v46
	v_add_f32_e32 v47, 0, v47
	v_add_f32_e32 v48, 0, v48
	v_add_f32_e32 v49, 0, v49
	s_waitcnt vmcnt(7)
	v_fma_f32 v46, v46, v196, v228
	v_fma_f32 v47, v47, v197, v229
	v_fma_f32 v48, v48, v198, v230
	v_fma_f32 v57, v49, v199, v231
	v_cvt_pk_bf16_f32 v46, v46, v47
	v_cvt_pk_bf16_f32 v47, v48, v57
	v_lshl_add_u64 v[48:49], v[58:59], 1, s[20:21]
	global_store_dwordx2 v[48:49], v[46:47], off offset:128
	v_lshl_add_u64 v[54:55], v[66:67], 0, v[132:133]
	v_add_f32_e32 v42, 0, v42
	v_add_f32_e32 v43, 0, v43
	v_add_f32_e32 v44, 0, v44
	v_add_f32_e32 v45, 0, v45
	s_waitcnt vmcnt(7)
	v_fma_f32 v42, v42, v200, v232
	v_fma_f32 v43, v43, v201, v233
	v_fma_f32 v44, v44, v202, v234
	v_fma_f32 v53, v45, v203, v235
	v_cvt_pk_bf16_f32 v42, v42, v43
	v_cvt_pk_bf16_f32 v43, v44, v53
	v_lshl_add_u64 v[44:45], v[54:55], 1, s[20:21]
	global_store_dwordx2 v[44:45], v[42:43], off offset:160
	v_lshl_add_u64 v[50:51], v[66:67], 0, v[132:133]
	v_add_f32_e32 v38, 0, v38
	v_add_f32_e32 v39, 0, v39
	v_add_f32_e32 v40, 0, v40
	v_add_f32_e32 v41, 0, v41
	s_waitcnt vmcnt(7)
	v_fma_f32 v38, v38, v204, v236
	v_fma_f32 v39, v39, v205, v237
	v_fma_f32 v40, v40, v206, v238
	v_fma_f32 v49, v41, v207, v239
	v_cvt_pk_bf16_f32 v38, v38, v39
	v_cvt_pk_bf16_f32 v39, v40, v49
	v_lshl_add_u64 v[40:41], v[50:51], 1, s[20:21]
	global_store_dwordx2 v[40:41], v[38:39], off offset:192
	v_lshl_add_u64 v[46:47], v[66:67], 0, v[132:133]
	v_add_f32_e32 v34, 0, v34
	v_add_f32_e32 v35, 0, v35
	v_add_f32_e32 v36, 0, v36
	v_add_f32_e32 v37, 0, v37
	s_waitcnt vmcnt(7)
; __device__ __forceinline__ unsigned pack2(float a, float b) { unsigned r; asm("v_cvt_pk_bf16_f32 %0, %1, %2" : "=v"(r) : "v"(a), "v"(b)); return r; }
; __device__ __forceinline__ float bf2f(bf16_t h) { return __uint_as_float(((unsigned)h) << 16); }
;   __device__ __forceinline__ void c4(int g, int rig, int col, f32x4 v) const {
;     const size_t o = ((size_t)g * 2048 + rig) * 1024 + col;
;     f32x4 bs;
;     if (BASE_F32) bs = __builtin_nontemporal_load((const f32x4*)((const float*)base + o));
;     else {
;       const uint2 u = *(const uint2*)((const bf16_t*)base + o);
;       bs[0] = bf2f((bf16_t)(u.x & 0xffff)); bs[1] = bf2f((bf16_t)(u.x >> 16)); bs[2] = bf2f((bf16_t)(u.y & 0xffff)); bs[3] = bf2f((bf16_t)(u.y >> 16));
;     }
;     const f32x4 gt = *(const f32x4*)(gate + (size_t)g * 6144 + col);
;     f32x4 bi = {0.f, 0.f, 0.f, 0.f};
;     if (bias) bi = *(const f32x4*)(bias + col);
;     f32x4 r;
; #pragma unroll
;     for (int j = 0; j < 4; ++j) r[j] = bs[j] + gt[j] * (v[j] + bi[j]);
;     uint2 w; w.x = pack2(r[0], r[1]); w.y = pack2(r[2], r[3]);
;     *(uint2*)(X16 + o) = w;
;   }
; template <bool SWAP, class Epi, bool THIN = false> ...
;     ...
;     if constexpr (Epi::KIND == 0) {
; #pragma unroll
;       for (int m = 0; m < 4; ++m) {
;         const int rig = rig0 + rw + m * 16 + fr_e;
;         if constexpr (Epi::ROWSUM) {
;           float ss = 0.f;
; #pragma unroll
;           for (int n = 0; n < 8; ++n) {
;             const int col = nt * 256 + wc_e * 128 + n * 16 + fq_e * 4;
;             if (col < N) ss += epi.c4(g, rig, col, acc[m][n]);
;           }
;           ss += __shfl_xor(ss, 16); ss += __shfl_xor(ss, 32);
;           if (fq_e == 0) epi.rowsum(g, rig, nt * 2 + wc_e, ss);
;         } else {
; #pragma unroll
;           for (int n = 0; n < 8; ++n) {
;             const int col = nt * 256 + wc_e * 128 + n * 16 + fq_e * 4;
;             if (col < N) epi.c4(g, rig, col, acc[m][n]);
	v_fma_f32 v34, v34, v208, v240
	v_fma_f32 v35, v35, v209, v241
	v_fma_f32 v36, v36, v210, v242
	v_fma_f32 v45, v37, v211, v243
	v_cvt_pk_bf16_f32 v34, v34, v35
	v_cvt_pk_bf16_f32 v35, v36, v45
	v_lshl_add_u64 v[36:37], v[46:47], 1, s[20:21]
	global_store_dwordx2 v[36:37], v[34:35], off offset:224
	v_or_b32_e32 v34, 48, v136
	v_ashrrev_i32_e32 v35, 31, v34
	v_lshlrev_b64 v[34:35], 10, v[34:35]
	v_lshl_add_u64 v[34:35], v[34:35], 0, v[138:139]
	v_lshl_add_u64 v[44:45], v[34:35], 0, v[132:133]
	v_lshl_add_u64 v[244:245], v[34:35], 0, v[132:133]
	v_lshl_add_u64 v[244:245], v[244:245], 2, s[22:23]
	global_load_dwordx4 v[212:215], v[244:245], off nt
	global_load_dwordx4 v[216:219], v[244:245], off offset:64 nt
	global_load_dwordx4 v[220:223], v[244:245], off offset:128 nt
	global_load_dwordx4 v[224:227], v[244:245], off offset:192 nt
	global_load_dwordx4 v[228:231], v[244:245], off offset:256 nt
	global_load_dwordx4 v[232:235], v[244:245], off offset:320 nt
	global_load_dwordx4 v[236:239], v[244:245], off offset:384 nt
	global_load_dwordx4 v[240:243], v[244:245], off offset:448 nt
	v_add_f32_e32 v30, 0, v30
	v_add_f32_e32 v31, 0, v31
	v_add_f32_e32 v32, 0, v32
	v_add_f32_e32 v33, 0, v33
	s_waitcnt vmcnt(7)
	v_fma_f32 v30, v30, v180, v212
	v_fma_f32 v31, v31, v181, v213
	v_fma_f32 v32, v32, v182, v214
	v_fma_f32 v43, v33, v183, v215
	v_cvt_pk_bf16_f32 v30, v30, v31
	v_cvt_pk_bf16_f32 v31, v32, v43
	v_lshl_add_u64 v[32:33], v[44:45], 1, s[20:21]
	global_store_dwordx2 v[32:33], v[30:31], off
	v_lshl_add_u64 v[40:41], v[34:35], 0, v[132:133]
	v_add_f32_e32 v26, 0, v26
	v_add_f32_e32 v27, 0, v27
	v_add_f32_e32 v28, 0, v28
	v_add_f32_e32 v29, 0, v29
	s_waitcnt vmcnt(7)
	v_fma_f32 v26, v26, v184, v216
	v_fma_f32 v27, v27, v185, v217
	v_fma_f32 v28, v28, v186, v218
	v_fma_f32 v39, v29, v187, v219
	v_cvt_pk_bf16_f32 v26, v26, v27
	v_cvt_pk_bf16_f32 v27, v28, v39
	v_lshl_add_u64 v[28:29], v[40:41], 1, s[20:21]
	global_store_dwordx2 v[28:29], v[26:27], off offset:32
	v_lshl_add_u64 v[36:37], v[34:35], 0, v[132:133]
	v_add_f32_e32 v22, 0, v22
	v_add_f32_e32 v23, 0, v23
	v_add_f32_e32 v24, 0, v24
	v_add_f32_e32 v25, 0, v25
	s_waitcnt vmcnt(7)
	v_fma_f32 v22, v22, v188, v220
	v_fma_f32 v23, v23, v189, v221
	v_fma_f32 v24, v24, v190, v222
	v_fma_f32 v33, v25, v191, v223
	v_cvt_pk_bf16_f32 v22, v22, v23
	v_cvt_pk_bf16_f32 v23, v24, v33
	v_lshl_add_u64 v[24:25], v[36:37], 1, s[20:21]
	global_store_dwordx2 v[24:25], v[22:23], off offset:64
	v_lshl_add_u64 v[30:31], v[34:35], 0, v[132:133]
	v_add_f32_e32 v18, 0, v18
	v_add_f32_e32 v19, 0, v19
	v_add_f32_e32 v20, 0, v20
	v_add_f32_e32 v21, 0, v21
	s_waitcnt vmcnt(7)
	v_fma_f32 v18, v18, v192, v224
	v_fma_f32 v19, v19, v193, v225
	v_fma_f32 v20, v20, v194, v226
	v_fma_f32 v29, v21, v195, v227
	v_cvt_pk_bf16_f32 v18, v18, v19
	v_cvt_pk_bf16_f32 v19, v20, v29
	v_lshl_add_u64 v[20:21], v[30:31], 1, s[20:21]
	global_store_dwordx2 v[20:21], v[18:19], off offset:96
	v_lshl_add_u64 v[26:27], v[34:35], 0, v[132:133]
	v_add_f32_e32 v14, 0, v14
	v_add_f32_e32 v15, 0, v15
	v_add_f32_e32 v16, 0, v16
	v_add_f32_e32 v17, 0, v17
	s_waitcnt vmcnt(7)
	v_fma_f32 v14, v14, v196, v228
	v_fma_f32 v15, v15, v197, v229
	v_fma_f32 v16, v16, v198, v230
	v_fma_f32 v25, v17, v199, v231
	v_cvt_pk_bf16_f32 v14, v14, v15
	v_cvt_pk_bf16_f32 v15, v16, v25
	v_lshl_add_u64 v[16:17], v[26:27], 1, s[20:21]
	global_store_dwordx2 v[16:17], v[14:15], off offset:128
	v_lshl_add_u64 v[22:23], v[34:35], 0, v[132:133]
	v_add_f32_e32 v6, 0, v6
	v_add_f32_e32 v7, 0, v7
	v_add_f32_e32 v8, 0, v8
	v_add_f32_e32 v9, 0, v9
	s_waitcnt vmcnt(7)
	v_fma_f32 v6, v6, v200, v232
	v_fma_f32 v7, v7, v201, v233
	v_fma_f32 v8, v8, v202, v234
	v_fma_f32 v21, v9, v203, v235
	v_cvt_pk_bf16_f32 v6, v6, v7
	v_cvt_pk_bf16_f32 v7, v8, v21
	v_lshl_add_u64 v[8:9], v[22:23], 1, s[20:21]
	global_store_dwordx2 v[8:9], v[6:7], off offset:160
	v_lshl_add_u64 v[18:19], v[34:35], 0, v[132:133]
	v_add_f32_e32 v10, 0, v10
	v_add_f32_e32 v11, 0, v11
	v_add_f32_e32 v12, 0, v12
	v_add_f32_e32 v13, 0, v13
	s_waitcnt vmcnt(7)
	v_fma_f32 v6, v10, v204, v236
	v_fma_f32 v7, v11, v205, v237
	v_fma_f32 v8, v12, v206, v238
	v_fma_f32 v17, v13, v207, v239
	v_cvt_pk_bf16_f32 v6, v6, v7
	v_cvt_pk_bf16_f32 v7, v8, v17
	v_lshl_add_u64 v[8:9], v[18:19], 1, s[20:21]
	global_store_dwordx2 v[8:9], v[6:7], off offset:192
	v_lshl_add_u64 v[14:15], v[34:35], 0, v[132:133]
	v_add_f32_e32 v2, 0, v2
	v_add_f32_e32 v3, 0, v3
	v_add_f32_e32 v4, 0, v4
	v_add_f32_e32 v5, 0, v5
	s_waitcnt vmcnt(7)
	v_fma_f32 v2, v2, v208, v240
	v_fma_f32 v3, v3, v209, v241
	v_fma_f32 v4, v4, v210, v242
	v_fma_f32 v13, v5, v211, v243
	v_cvt_pk_bf16_f32 v2, v2, v3
	v_cvt_pk_bf16_f32 v3, v4, v13
	v_lshl_add_u64 v[4:5], v[14:15], 1, s[20:21]
	global_store_dwordx2 v[4:5], v[2:3], off offset:224
	s_branch .LBB0_2114

; template <bool SWAP, class Epi, bool THIN = false> ...
;     ...
;     for (int st = 0; st < ns; ++st) {
;       asm volatile("s_waitcnt vmcnt(0)" ::: "memory");
;       __builtin_amdgcn_s_barrier();
;       asm volatile("" ::: "memory");
;       if (st + 1 < ns) {
;         char* nb = smem + ((st + 1) & 1) * 65536;
;         const int ko = (st + 1) * 64;
; #pragma unroll
;         for (int i = 0; i < 4; ++i) { GLDS16(A + (size_t)(ap[i] + ko), nb + tid * 16 + i * 8192); GLDS16(Bt + (size_t)(bp[i] + ko), nb + 32768 + tid * 16 + i * 8192); }
;       }
;       const char* sa = smem + (st & 1) * 65536 + (wr * 64 + fr) * 128;
;       const char* sb = smem + (st & 1) * 65536 + 32768 + (wc * 128 + fr) * 128;
;       if constexpr (THIN) {
;         if (wc == 0) {
; #pragma unroll
;           for (int ks = 0; ks < 2; ++ks) {
;             bf16x8 af[4], bf[2];
; #pragma unroll
;             for (int m = 0; m < 4; ++m) af[m] = *(const bf16x8*)(sa + m * 2048 + (((ks * 4 + fq) ^ swz) << 4));
; #pragma unroll
;             for (int n = 0; n < 2; ++n) bf[n] = *(const bf16x8*)(sb + n * 2048 + (((ks * 4 + fq) ^ swz) << 4));
; #pragma unroll
;             for (int m = 0; m < 4; ++m)
; #pragma unroll
;               for (int n = 0; n < 2; ++n)
;                 acc[m][n] = SWAP ? __builtin_amdgcn_mfma_f32_16x16x32_bf16(bf[n], af[m], acc[m][n], 0, 0, 0)
;                                  : __builtin_amdgcn_mfma_f32_16x16x32_bf16(af[m], bf[n], acc[m][n], 0, 0, 0);
;           }
;         }
;       } else {
;       bf16x8 afA[4], afB[4], bfb[2][2];
; #pragma unroll
;       for (int m = 0; m < 4; ++m) afA[m] = *(const bf16x8*)(sa + m * 2048 + ((fq ^ swz) << 4));
; #pragma unroll
;       for (int n = 0; n < 2; ++n) bfb[0][n] = *(const bf16x8*)(sb + n * 2048 + ((fq ^ swz) << 4));
; #pragma unroll
;       for (int gq = 0; gq < 8; ++gq) {
;         const int ks = gq >> 2, nh = gq & 3;
;         if (gq < 7) {
;           const int ks2 = (gq + 1) >> 2, nh2 = (gq + 1) & 3;
; #pragma unroll
;           for (int n = 0; n < 2; ++n) bfb[(gq + 1) & 1][n] = *(const bf16x8*)(sb + (nh2 * 2 + n) * 2048 + (((ks2 * 4 + fq) ^ swz) << 4));
;         }
;         if (gq == 3) {
; #pragma unroll
;           for (int m = 0; m < 4; ++m) afB[m] = *(const bf16x8*)(sa + m * 2048 + (((4 + fq) ^ swz) << 4));
;         }
;         __builtin_amdgcn_sched_barrier(0);
; #pragma unroll
.LBB0_2334:
	s_add_i32 s8, s7, 0x10000
	s_and_b32 s9, s8, 0x10000
	v_add_u32_e32 v170, s9, v135
	s_nop 0
	v_readfirstlane_b32 s9, v170
	s_waitcnt vmcnt(0)
	s_barrier
	s_and_b32 s7, s7, 0x10000
	v_or_b32_e32 v204, s7, v139
	v_add_u32_e32 v205, v204, v140
	v_add_u32_e32 v136, s7, v138
	v_add_u32_e32 v180, v136, v140
	ds_read_b128 v[168:171], v180
	ds_read_b128 v[172:175], v180 offset:2048
	ds_read_b128 v[176:179], v180 offset:4096
	ds_read_b128 v[180:183], v180 offset:6144
	ds_read_b128 v[184:187], v205 offset:32768
	ds_read_b128 v[188:191], v205 offset:34816
	ds_read_b128 v[192:195], v205 offset:36864
	ds_read_b128 v[196:199], v205 offset:38912
	v_add_u32_e32 v136, v136, v141
	s_waitcnt lgkmcnt(3)
	v_mfma_f32_16x16x32_bf16 v[126:129], v[184:187], v[168:171], v[126:129]
	s_mov_b32 m0, s9
	v_mfma_f32_16x16x32_bf16 v[110:113], v[184:187], v[172:175], v[110:113]
	global_load_lds_dwordx4 v167, s[16:17] sc1
	v_add_u32_e32 v167, 0x80, v167
	v_mfma_f32_16x16x32_bf16 v[82:85], v[184:187], v[176:179], v[82:85]
	v_mfma_f32_16x16x32_bf16 v[50:53], v[184:187], v[180:183], v[50:53]
	ds_read_b128 v[184:187], v205 offset:40960
	ds_read_b128 v[200:203], v205 offset:43008
	s_waitcnt lgkmcnt(4)
	v_mfma_f32_16x16x32_bf16 v[122:125], v[188:191], v[168:171], v[122:125]
	s_add_u32 m0, s9, 0x8000
	v_mfma_f32_16x16x32_bf16 v[106:109], v[188:191], v[172:175], v[106:109]
	global_load_lds_dwordx4 v166, s[18:19] sc1
	v_add_u32_e32 v166, 0x80, v166
	v_mfma_f32_16x16x32_bf16 v[78:81], v[188:191], v[176:179], v[78:81]
	v_mfma_f32_16x16x32_bf16 v[42:45], v[188:191], v[180:183], v[42:45]
	s_waitcnt lgkmcnt(3)
	v_mfma_f32_16x16x32_bf16 v[118:121], v[192:195], v[168:171], v[118:121]
	s_add_u32 m0, s9, 0x2000
	v_mfma_f32_16x16x32_bf16 v[94:97], v[192:195], v[172:175], v[94:97]
	global_load_lds_dwordx4 v165, s[16:17] sc1
	v_add_u32_e32 v165, 0x80, v165
	v_mfma_f32_16x16x32_bf16 v[58:61], v[192:195], v[176:179], v[58:61]
	v_mfma_f32_16x16x32_bf16 v[26:29], v[192:195], v[180:183], v[26:29]
	ds_read_b128 v[188:191], v205 offset:45056
	ds_read_b128 v[192:195], v205 offset:47104
	s_waitcnt lgkmcnt(4)
	v_mfma_f32_16x16x32_bf16 v[114:117], v[196:199], v[168:171], v[114:117]
	s_add_u32 m0, s9, 0xa000
	v_mfma_f32_16x16x32_bf16 v[90:93], v[196:199], v[172:175], v[90:93]
	global_load_lds_dwordx4 v164, s[18:19] sc1
	v_add_u32_e32 v164, 0x80, v164
	v_mfma_f32_16x16x32_bf16 v[54:57], v[196:199], v[176:179], v[54:57]
	v_mfma_f32_16x16x32_bf16 v[22:25], v[196:199], v[180:183], v[22:25]
	v_add_u32_e32 v220, v204, v141
	s_waitcnt lgkmcnt(3)
	v_mfma_f32_16x16x32_bf16 v[102:105], v[184:187], v[168:171], v[102:105]
	ds_read_b128 v[196:199], v220 offset:32768
	ds_read_b128 v[204:207], v220 offset:34816
	s_add_u32 m0, s9, 0x4000
	v_mfma_f32_16x16x32_bf16 v[74:77], v[184:187], v[172:175], v[74:77]
	global_load_lds_dwordx4 v163, s[16:17] sc1
	v_add_u32_e32 v163, 0x80, v163
	v_mfma_f32_16x16x32_bf16 v[46:49], v[184:187], v[176:179], v[46:49]
	v_mfma_f32_16x16x32_bf16 v[10:13], v[184:187], v[180:183], v[10:13]
	ds_read_b128 v[184:187], v136
	ds_read_b128 v[208:211], v136 offset:2048
	ds_read_b128 v[212:215], v136 offset:4096
	ds_read_b128 v[216:219], v136 offset:6144
	s_waitcnt lgkmcnt(8)
	v_mfma_f32_16x16x32_bf16 v[98:101], v[200:203], v[168:171], v[98:101]
	s_add_u32 m0, s9, 0xc000
	v_mfma_f32_16x16x32_bf16 v[66:69], v[200:203], v[172:175], v[66:69]
	global_load_lds_dwordx4 v162, s[18:19] sc1
	v_add_u32_e32 v162, 0x80, v162
	v_mfma_f32_16x16x32_bf16 v[30:33], v[200:203], v[176:179], v[30:33]
	v_mfma_f32_16x16x32_bf16 v[6:9], v[200:203], v[180:183], v[6:9]
	s_waitcnt lgkmcnt(7)
	v_mfma_f32_16x16x32_bf16 v[70:73], v[188:191], v[168:171], v[70:73]
	s_add_u32 m0, s9, 0x6000
	s_waitcnt lgkmcnt(6)
	v_mfma_f32_16x16x32_bf16 v[62:65], v[192:195], v[168:171], v[62:65]
	global_load_lds_dwordx4 v161, s[16:17] sc1
	v_add_u32_e32 v161, 0x80, v161
	v_mfma_f32_16x16x32_bf16 v[38:41], v[188:191], v[172:175], v[38:41]
	v_mfma_f32_16x16x32_bf16 v[34:37], v[192:195], v[172:175], v[34:37]
	ds_read_b128 v[168:171], v220 offset:36864
	ds_read_b128 v[172:175], v220 offset:38912
	v_mfma_f32_16x16x32_bf16 v[18:21], v[188:191], v[176:179], v[18:21]
	s_add_u32 m0, s9, 0xe000
	v_mfma_f32_16x16x32_bf16 v[14:17], v[192:195], v[176:179], v[14:17]
	global_load_lds_dwordx4 v160, s[18:19] sc1
	v_add_u32_e32 v160, 0x80, v160
	v_mfma_f32_16x16x32_bf16 v[2:5], v[188:191], v[180:183], v[2:5]
	v_mfma_f32_16x16x32_bf16 v[86:89], v[192:195], v[180:183], v[86:89]
	ds_read_b128 v[176:179], v220 offset:40960
	ds_read_b128 v[180:183], v220 offset:43008
	s_waitcnt lgkmcnt(7)
	v_mfma_f32_16x16x32_bf16 v[126:129], v[196:199], v[184:187], v[126:129]
	v_mfma_f32_16x16x32_bf16 v[122:125], v[204:207], v[184:187], v[122:125]
	s_waitcnt lgkmcnt(6)
	v_mfma_f32_16x16x32_bf16 v[110:113], v[196:199], v[208:211], v[110:113]
	v_mfma_f32_16x16x32_bf16 v[106:109], v[204:207], v[208:211], v[106:109]
	s_waitcnt lgkmcnt(5)
	v_mfma_f32_16x16x32_bf16 v[82:85], v[196:199], v[212:215], v[82:85]
	v_mfma_f32_16x16x32_bf16 v[78:81], v[204:207], v[212:215], v[78:81]
	s_waitcnt lgkmcnt(4)
	v_mfma_f32_16x16x32_bf16 v[50:53], v[196:199], v[216:219], v[50:53]
	v_mfma_f32_16x16x32_bf16 v[42:45], v[204:207], v[216:219], v[42:45]
	s_waitcnt lgkmcnt(3)
	v_mfma_f32_16x16x32_bf16 v[118:121], v[168:171], v[184:187], v[118:121]
	v_mfma_f32_16x16x32_bf16 v[94:97], v[168:171], v[208:211], v[94:97]
	v_mfma_f32_16x16x32_bf16 v[58:61], v[168:171], v[212:215], v[58:61]
	v_mfma_f32_16x16x32_bf16 v[26:29], v[168:171], v[216:219], v[26:29]
	ds_read_b128 v[168:171], v220 offset:45056
	ds_read_b128 v[188:191], v220 offset:47104
	s_waitcnt lgkmcnt(4)
; template <bool SWAP, class Epi, bool THIN = false> ...
;     ...
;       bf16x8 afA[4], afB[4], bfb[2][2];
; #pragma unroll
;       for (int m = 0; m < 4; ++m) afA[m] = *(const bf16x8*)(sa + m * 2048 + ((fq ^ swz) << 4));
; #pragma unroll
;       for (int n = 0; n < 2; ++n) bfb[0][n] = *(const bf16x8*)(sb + n * 2048 + ((fq ^ swz) << 4));
; #pragma unroll
;       for (int gq = 0; gq < 8; ++gq) {
;         const int ks = gq >> 2, nh = gq & 3;
;         if (gq < 7) {
;           const int ks2 = (gq + 1) >> 2, nh2 = (gq + 1) & 3;
; #pragma unroll
;           for (int n = 0; n < 2; ++n) bfb[(gq + 1) & 1][n] = *(const bf16x8*)(sb + (nh2 * 2 + n) * 2048 + (((ks2 * 4 + fq) ^ swz) << 4));
;         }
;         if (gq == 3) {
; #pragma unroll
;           for (int m = 0; m < 4; ++m) afB[m] = *(const bf16x8*)(sa + m * 2048 + (((4 + fq) ^ swz) << 4));
;         }
;         __builtin_amdgcn_sched_barrier(0);
; #pragma unroll
;         for (int m = 0; m < 4; ++m)
; #pragma unroll
;           for (int n = 0; n < 2; ++n) {
;             const bf16x8 av = ks ? afB[m] : afA[m];
;             acc[m][nh * 2 + n] = SWAP ? __builtin_amdgcn_mfma_f32_16x16x32_bf16(bfb[gq & 1][n], av, acc[m][nh * 2 + n], 0, 0, 0)
;                                       : __builtin_amdgcn_mfma_f32_16x16x32_bf16(av, bfb[gq & 1][n], acc[m][nh * 2 + n], 0, 0, 0);
;           }
;       }
;       }
;     }
;     __syncthreads();
	v_mfma_f32_16x16x32_bf16 v[114:117], v[172:175], v[184:187], v[114:117]
	v_mfma_f32_16x16x32_bf16 v[90:93], v[172:175], v[208:211], v[90:93]
	v_mfma_f32_16x16x32_bf16 v[54:57], v[172:175], v[212:215], v[54:57]
	v_mfma_f32_16x16x32_bf16 v[22:25], v[172:175], v[216:219], v[22:25]
	s_waitcnt lgkmcnt(3)
	v_mfma_f32_16x16x32_bf16 v[102:105], v[176:179], v[184:187], v[102:105]
	s_waitcnt lgkmcnt(2)
	v_mfma_f32_16x16x32_bf16 v[98:101], v[180:183], v[184:187], v[98:101]
	v_mfma_f32_16x16x32_bf16 v[74:77], v[176:179], v[208:211], v[74:77]
	v_mfma_f32_16x16x32_bf16 v[66:69], v[180:183], v[208:211], v[66:69]
	v_mfma_f32_16x16x32_bf16 v[46:49], v[176:179], v[212:215], v[46:49]
	v_mfma_f32_16x16x32_bf16 v[30:33], v[180:183], v[212:215], v[30:33]
	v_mfma_f32_16x16x32_bf16 v[10:13], v[176:179], v[216:219], v[10:13]
	v_mfma_f32_16x16x32_bf16 v[6:9], v[180:183], v[216:219], v[6:9]
	s_waitcnt lgkmcnt(1)
	v_mfma_f32_16x16x32_bf16 v[70:73], v[168:171], v[184:187], v[70:73]
	s_add_i32 s5, s5, 64
	s_cmpk_eq_i32 s5, 0x3c0
	s_mov_b32 s7, s8
	s_waitcnt lgkmcnt(0)
	v_mfma_f32_16x16x32_bf16 v[62:65], v[188:191], v[184:187], v[62:65]
	v_mfma_f32_16x16x32_bf16 v[38:41], v[168:171], v[208:211], v[38:41]
	v_mfma_f32_16x16x32_bf16 v[34:37], v[188:191], v[208:211], v[34:37]
	v_mfma_f32_16x16x32_bf16 v[18:21], v[168:171], v[212:215], v[18:21]
	v_mfma_f32_16x16x32_bf16 v[14:17], v[188:191], v[212:215], v[14:17]
	v_mfma_f32_16x16x32_bf16 v[2:5], v[168:171], v[216:219], v[2:5]
	v_mfma_f32_16x16x32_bf16 v[86:89], v[188:191], v[216:219], v[86:89]
	s_cbranch_scc0 .LBB0_2334
	s_waitcnt vmcnt(0)
	s_barrier
	v_add_u32_e32 v136, v150, v140
	ds_read_b128 v[160:163], v136
	ds_read_b128 v[164:167], v136 offset:2048
	ds_read_b128 v[168:171], v136 offset:4096
	ds_read_b128 v[172:175], v136 offset:6144
	v_add_u32_e32 v136, v151, v140
	ds_read_b128 v[176:179], v136
	ds_read_b128 v[180:183], v136 offset:2048
	ds_read_b128 v[184:187], v136 offset:4096
	ds_read_b128 v[188:191], v136 offset:6144
	s_waitcnt lgkmcnt(0)
	v_mfma_f32_16x16x32_bf16 v[126:129], v[176:179], v[160:163], v[126:129]
	v_mfma_f32_16x16x32_bf16 v[110:113], v[176:179], v[164:167], v[110:113]
	v_mfma_f32_16x16x32_bf16 v[82:85], v[176:179], v[168:171], v[82:85]
	v_mfma_f32_16x16x32_bf16 v[50:53], v[176:179], v[172:175], v[50:53]
	ds_read_b128 v[176:179], v136 offset:8192
	ds_read_b128 v[192:195], v136 offset:10240
	v_mfma_f32_16x16x32_bf16 v[122:125], v[180:183], v[160:163], v[122:125]
	v_mfma_f32_16x16x32_bf16 v[106:109], v[180:183], v[164:167], v[106:109]
	v_mfma_f32_16x16x32_bf16 v[78:81], v[180:183], v[168:171], v[78:81]
	v_mfma_f32_16x16x32_bf16 v[42:45], v[180:183], v[172:175], v[42:45]
	v_mfma_f32_16x16x32_bf16 v[118:121], v[184:187], v[160:163], v[118:121]
	v_mfma_f32_16x16x32_bf16 v[94:97], v[184:187], v[164:167], v[94:97]
	v_mfma_f32_16x16x32_bf16 v[58:61], v[184:187], v[168:171], v[58:61]
	v_mfma_f32_16x16x32_bf16 v[26:29], v[184:187], v[172:175], v[26:29]
	ds_read_b128 v[180:183], v136 offset:12288
	ds_read_b128 v[184:187], v136 offset:14336
	v_mfma_f32_16x16x32_bf16 v[114:117], v[188:191], v[160:163], v[114:117]
	v_mfma_f32_16x16x32_bf16 v[90:93], v[188:191], v[164:167], v[90:93]
	v_mfma_f32_16x16x32_bf16 v[54:57], v[188:191], v[168:171], v[54:57]
	v_mfma_f32_16x16x32_bf16 v[22:25], v[188:191], v[172:175], v[22:25]
	v_add_u32_e32 v136, v151, v141
	v_add_u32_e32 v208, v150, v141
	s_waitcnt lgkmcnt(0)
	v_mfma_f32_16x16x32_bf16 v[102:105], v[176:179], v[160:163], v[102:105]
	v_mfma_f32_16x16x32_bf16 v[74:77], v[176:179], v[164:167], v[74:77]
	v_mfma_f32_16x16x32_bf16 v[188:191], v[192:195], v[164:167], v[66:69]
	v_mfma_f32_16x16x32_bf16 v[196:199], v[176:179], v[168:171], v[46:49]
	s_nop 2
	ds_read_b128 v[46:49], v136
	ds_read_b128 v[66:69], v136 offset:2048
	v_mfma_f32_16x16x32_bf16 v[10:13], v[176:179], v[172:175], v[10:13]
	ds_read_b128 v[176:179], v208
	ds_read_b128 v[200:203], v208 offset:2048
	ds_read_b128 v[204:207], v208 offset:4096
	ds_read_b128 v[208:211], v208 offset:6144
	v_mfma_f32_16x16x32_bf16 v[98:101], v[192:195], v[160:163], v[98:101]
	v_mfma_f32_16x16x32_bf16 v[30:33], v[192:195], v[168:171], v[30:33]
	v_mfma_f32_16x16x32_bf16 v[6:9], v[192:195], v[172:175], v[6:9]
	v_mfma_f32_16x16x32_bf16 v[192:195], v[180:183], v[164:167], v[38:41]
	v_mfma_f32_16x16x32_bf16 v[164:167], v[184:187], v[164:167], v[34:37]
	v_mfma_f32_16x16x32_bf16 v[18:21], v[180:183], v[168:171], v[18:21]
	v_mfma_f32_16x16x32_bf16 v[168:171], v[184:187], v[168:171], v[14:17]
	s_nop 2
	ds_read_b128 v[14:17], v136 offset:4096
	ds_read_b128 v[34:37], v136 offset:6144
	v_mfma_f32_16x16x32_bf16 v[70:73], v[180:183], v[160:163], v[70:73]
	v_mfma_f32_16x16x32_bf16 v[2:5], v[180:183], v[172:175], v[2:5]
	v_mfma_f32_16x16x32_bf16 v[160:163], v[184:187], v[160:163], v[62:65]
	v_mfma_f32_16x16x32_bf16 v[86:89], v[184:187], v[172:175], v[86:89]
	s_waitcnt lgkmcnt(0)
	v_mfma_f32_16x16x32_bf16 v[172:175], v[46:49], v[208:211], v[50:53]
	s_nop 2
	ds_read_b128 v[50:53], v136 offset:8192
	ds_read_b128 v[180:183], v136 offset:10240
	v_mfma_f32_16x16x32_bf16 v[126:129], v[46:49], v[176:179], v[126:129]
	v_mfma_f32_16x16x32_bf16 v[122:125], v[66:69], v[176:179], v[122:125]
	v_mfma_f32_16x16x32_bf16 v[110:113], v[46:49], v[200:203], v[110:113]
	v_mfma_f32_16x16x32_bf16 v[106:109], v[66:69], v[200:203], v[106:109]
	v_mfma_f32_16x16x32_bf16 v[82:85], v[46:49], v[204:207], v[82:85]
	v_mfma_f32_16x16x32_bf16 v[78:81], v[66:69], v[204:207], v[78:81]
	v_mfma_f32_16x16x32_bf16 v[184:187], v[66:69], v[208:211], v[42:45]
	ds_read_b128 v[224:227], v136 offset:12288
	ds_read_b128 v[228:231], v136 offset:14336
	v_mfma_f32_16x16x32_bf16 v[118:121], v[14:17], v[176:179], v[118:121]
	v_mfma_f32_16x16x32_bf16 v[114:117], v[34:37], v[176:179], v[114:117]
	v_mfma_f32_16x16x32_bf16 v[94:97], v[14:17], v[200:203], v[94:97]
	v_mfma_f32_16x16x32_bf16 v[90:93], v[34:37], v[200:203], v[90:93]
	v_mfma_f32_16x16x32_bf16 v[212:215], v[14:17], v[204:207], v[58:61]
	v_mfma_f32_16x16x32_bf16 v[216:219], v[34:37], v[204:207], v[54:57]
	v_mfma_f32_16x16x32_bf16 v[220:223], v[14:17], v[208:211], v[26:29]
	v_mfma_f32_16x16x32_bf16 v[66:69], v[34:37], v[208:211], v[22:25]
	s_waitcnt lgkmcnt(0)
	v_mfma_f32_16x16x32_bf16 v[38:41], v[180:183], v[204:207], v[30:33]
	v_mfma_f32_16x16x32_bf16 v[62:65], v[50:53], v[176:179], v[102:105]
	v_mfma_f32_16x16x32_bf16 v[46:49], v[180:183], v[176:179], v[98:101]
	v_mfma_f32_16x16x32_bf16 v[58:61], v[50:53], v[200:203], v[74:77]
	v_mfma_f32_16x16x32_bf16 v[42:45], v[180:183], v[200:203], v[188:191]
	v_mfma_f32_16x16x32_bf16 v[54:57], v[50:53], v[204:207], v[196:199]
	v_mfma_f32_16x16x32_bf16 v[50:53], v[50:53], v[208:211], v[10:13]
	v_mfma_f32_16x16x32_bf16 v[34:37], v[180:183], v[208:211], v[6:9]
	s_nop 2
	v_mov_b32_e32 v8, v1
	s_waitcnt vmcnt(0)
	v_mfma_f32_16x16x32_bf16 v[30:33], v[224:227], v[176:179], v[70:73]
	s_barrier
; __device__ __forceinline__ unsigned pack2(float a, float b) { unsigned r; asm("v_cvt_pk_bf16_f32 %0, %1, %2" : "=v"(r) : "v"(a), "v"(b)); return r; }
; template <bool SWAP, class Epi, bool THIN = false> ...
;     ...
;     } else {
;       bf16_t* Zw = (bf16_t*)smem + ((wr_e >> 1) * 2 + wc_e) * (128 * 132);
;       const int nt2w = nt * 2 + wc_e;
; #pragma unroll
;       for (int n = 0; n < 8; ++n) {
;         const int cl = n * 16 + fq_e * 4;
;         f32x4 b4 = {0.f, 0.f, 0.f, 0.f};
;         if (epi.pre_bias) b4 = *(const f32x4*)(epi.pre_bias + epi.norig(nt2w, cl));
; #pragma unroll
;         for (int m = 0; m < 4; ++m) {
;           const int rl = rw + m * 16 + fr_e;
;           const int pos = rig0 + rl;
;           const bool ok = pos >= 0 && pos < grows;
;           f32x4 vv = acc[m][n] + b4;
;           if (!ok) vv = (f32x4){0.f, 0.f, 0.f, 0.f};
;           uint2 u; u.x = pack2(vv[0], vv[1]); u.y = pack2(vv[2], vv[3]);
;           *(uint2*)(Zw + rl * 132 + cl) = u;
;         }
;       }
;       __syncthreads();
	v_mfma_f32_16x16x32_bf16 v[22:25], v[224:227], v[204:207], v[18:21]
	s_nop 0
	v_ashrrev_i32_e32 v71, 8, v8
	v_add_u32_e32 v6, s4, v71
	v_mul_hi_i32 v7, v6, s26
	v_lshrrev_b32_e32 v9, 31, v7
	v_ashrrev_i32_e32 v7, 3, v7
	v_add_u32_e32 v70, v7, v9
	v_and_b32_e32 v73, 15, v8
	v_mad_u64_u32 v[6:7], s[4:5], v70, s27, v[6:7]
	v_lshrrev_b32_e32 v75, 1, v8
	v_bfe_u32 v74, v8, 6, 1
	v_mul_lo_u32 v72, v6, s28
	v_and_or_b32 v73, v75, 64, v73
	v_add_u32_e32 v98, v72, v73
	v_lshl_or_b32 v74, v71, 1, v74
	v_mul_lo_u32 v74, v74, s29
	v_add_u32_e32 v99, -1, v98
	v_mfma_f32_16x16x32_bf16 v[18:21], v[224:227], v[208:211], v[2:5]
	v_add_f32_e64 v76, v126, 0
	v_add_f32_e64 v77, v127, 0
	v_cmp_gt_u32_e32 vcc, s30, v99
	s_lshl_b32 s24, s6, 7
	v_mfma_f32_16x16x32_bf16 v[2:5], v[228:231], v[208:211], v[86:89]
	v_add_f32_e64 v84, v84, 0
	v_add_f32_e64 v85, v85, 0
	v_pk_add_f32 v[82:83], v[82:83], 0 op_sel_hi:[1,0]
	v_pk_add_f32 v[66:67], v[66:67], 0 op_sel_hi:[1,0]
	v_and_or_b32 v86, v75, 24, v74
	v_pk_add_f32 v[74:75], v[128:129], 0 op_sel_hi:[1,0]
	v_add_u32_e32 v88, 15, v98
	v_cndmask_b32_e32 v87, 0, v74, vcc
	v_cndmask_b32_e32 v75, 0, v75, vcc
	v_cndmask_b32_e32 v74, 0, v76, vcc
	v_cndmask_b32_e32 v76, 0, v77, vcc
	v_cvt_pk_bf16_f32 v74, v74, v76
	v_cvt_pk_bf16_f32 v75, v87, v75
	v_mad_u32_u24 v73, v73, s31, v86
	v_pk_add_f32 v[76:77], v[112:113], 0 op_sel_hi:[1,0]
	v_pk_add_f32 v[86:87], v[110:111], 0 op_sel_hi:[1,0]
	v_cmp_gt_u32_e64 s[4:5], s30, v88
	v_mfma_f32_16x16x32_bf16 v[26:29], v[224:227], v[200:203], v[192:195]
	v_add_f32_e64 v62, v62, 0
	v_add_f32_e64 v63, v63, 0
	v_cndmask_b32_e64 v88, 0, v76, s[4:5]
	v_cndmask_b32_e64 v76, 0, v86, s[4:5]
	v_cndmask_b32_e64 v86, 0, v87, s[4:5]
	v_cvt_pk_bf16_f32 v76, v76, v86
	v_add_u32_e32 v86, 31, v98
	v_cndmask_b32_e64 v77, 0, v77, s[4:5]
	v_cmp_gt_u32_e64 s[6:7], s30, v86
	v_cvt_pk_bf16_f32 v77, v88, v77
	v_add_u32_e32 v88, 47, v98
	v_pk_add_f32 v[86:87], v[172:173], 0 op_sel_hi:[1,0]
	v_cndmask_b32_e64 v84, 0, v84, s[6:7]
	v_cndmask_b32_e64 v85, 0, v85, s[6:7]
	v_cndmask_b32_e64 v82, 0, v82, s[6:7]
	v_cndmask_b32_e64 v83, 0, v83, s[6:7]
	v_cvt_pk_bf16_f32 v82, v82, v83
	v_cvt_pk_bf16_f32 v83, v84, v85
	v_pk_add_f32 v[84:85], v[174:175], 0 op_sel_hi:[1,0]
	v_cmp_gt_u32_e64 s[8:9], s30, v88
	v_mfma_f32_16x16x32_bf16 v[14:17], v[228:231], v[176:179], v[160:163]
	v_add_f32_e64 v28, v28, 0
	v_add_f32_e64 v29, v29, 0
	v_cndmask_b32_e64 v88, 0, v84, s[8:9]
	v_cndmask_b32_e64 v85, 0, v85, s[8:9]
	v_cndmask_b32_e64 v84, 0, v86, s[8:9]
	v_cndmask_b32_e64 v86, 0, v87, s[8:9]
	v_cvt_pk_bf16_f32 v84, v84, v86
	v_cvt_pk_bf16_f32 v85, v88, v85
	v_pk_add_f32 v[86:87], v[124:125], 0 op_sel_hi:[1,0]
	v_pk_add_f32 v[88:89], v[122:123], 0 op_sel_hi:[1,0]
	v_cndmask_b32_e32 v98, 0, v86, vcc
	v_cndmask_b32_e32 v87, 0, v87, vcc
	v_cndmask_b32_e32 v86, 0, v88, vcc
	v_cndmask_b32_e32 v88, 0, v89, vcc
	v_cvt_pk_bf16_f32 v86, v86, v88
	v_cvt_pk_bf16_f32 v87, v98, v87
	ds_write2_b64 v73, v[74:75], v[86:87] offset1:4
	v_pk_add_f32 v[74:75], v[108:109], 0 op_sel_hi:[1,0]
	v_pk_add_f32 v[86:87], v[106:107], 0 op_sel_hi:[1,0]
	v_cndmask_b32_e64 v88, 0, v74, s[4:5]
	v_cndmask_b32_e64 v75, 0, v75, s[4:5]
	v_cndmask_b32_e64 v74, 0, v86, s[4:5]
	v_cndmask_b32_e64 v86, 0, v87, s[4:5]
	v_cvt_pk_bf16_f32 v74, v74, v86
	v_cvt_pk_bf16_f32 v75, v88, v75
	v_add_u32_e32 v86, 0x1000, v73
	ds_write2_b64 v86, v[76:77], v[74:75] offset0:16 offset1:20
	v_pk_add_f32 v[74:75], v[80:81], 0 op_sel_hi:[1,0]
	v_pk_add_f32 v[76:77], v[78:79], 0 op_sel_hi:[1,0]
	v_cndmask_b32_e64 v78, 0, v74, s[6:7]
	v_cndmask_b32_e64 v75, 0, v75, s[6:7]
	v_cndmask_b32_e64 v74, 0, v76, s[6:7]
	v_cndmask_b32_e64 v76, 0, v77, s[6:7]
	v_cvt_pk_bf16_f32 v74, v74, v76
	v_cvt_pk_bf16_f32 v75, v78, v75
	v_add_u32_e32 v87, 0x2000, v73
	ds_write2_b64 v87, v[82:83], v[74:75] offset0:32 offset1:36
	v_pk_add_f32 v[74:75], v[186:187], 0 op_sel_hi:[1,0]
	v_pk_add_f32 v[76:77], v[184:185], 0 op_sel_hi:[1,0]
	v_cndmask_b32_e64 v78, 0, v74, s[8:9]
	v_cndmask_b32_e64 v75, 0, v75, s[8:9]
	v_cndmask_b32_e64 v74, 0, v76, s[8:9]
	v_cndmask_b32_e64 v76, 0, v77, s[8:9]
	v_cvt_pk_bf16_f32 v74, v74, v76
	v_cvt_pk_bf16_f32 v75, v78, v75
	v_add_u32_e32 v88, 0x3000, v73
	ds_write2_b64 v88, v[84:85], v[74:75] offset0:48 offset1:52
	v_pk_add_f32 v[74:75], v[120:121], 0 op_sel_hi:[1,0]
	v_pk_add_f32 v[76:77], v[118:119], 0 op_sel_hi:[1,0]
	v_cndmask_b32_e32 v78, 0, v74, vcc
	v_cndmask_b32_e32 v75, 0, v75, vcc
	v_cndmask_b32_e32 v74, 0, v76, vcc
	v_cndmask_b32_e32 v76, 0, v77, vcc
	v_cvt_pk_bf16_f32 v74, v74, v76
	v_cvt_pk_bf16_f32 v75, v78, v75
	v_pk_add_f32 v[76:77], v[96:97], 0 op_sel_hi:[1,0]
	v_pk_add_f32 v[78:79], v[94:95], 0 op_sel_hi:[1,0]
	v_cndmask_b32_e64 v80, 0, v76, s[4:5]
	v_cndmask_b32_e64 v77, 0, v77, s[4:5]
	v_cndmask_b32_e64 v76, 0, v78, s[4:5]
	v_cndmask_b32_e64 v78, 0, v79, s[4:5]
	v_cvt_pk_bf16_f32 v76, v76, v78
	v_cvt_pk_bf16_f32 v77, v80, v77
	v_pk_add_f32 v[78:79], v[214:215], 0 op_sel_hi:[1,0]
	v_pk_add_f32 v[80:81], v[212:213], 0 op_sel_hi:[1,0]
	v_cndmask_b32_e64 v82, 0, v78, s[6:7]
	v_cndmask_b32_e64 v79, 0, v79, s[6:7]
	v_cndmask_b32_e64 v78, 0, v80, s[6:7]
	v_cndmask_b32_e64 v80, 0, v81, s[6:7]
	v_cvt_pk_bf16_f32 v78, v78, v80
	v_cvt_pk_bf16_f32 v79, v82, v79
	v_pk_add_f32 v[80:81], v[222:223], 0 op_sel_hi:[1,0]
	v_pk_add_f32 v[82:83], v[220:221], 0 op_sel_hi:[1,0]
	v_cndmask_b32_e64 v84, 0, v80, s[8:9]
	v_cndmask_b32_e64 v81, 0, v81, s[8:9]
	v_cndmask_b32_e64 v80, 0, v82, s[8:9]
	v_cndmask_b32_e64 v82, 0, v83, s[8:9]
	v_cvt_pk_bf16_f32 v80, v80, v82
	v_cvt_pk_bf16_f32 v81, v84, v81
	v_pk_add_f32 v[82:83], v[116:117], 0 op_sel_hi:[1,0]
	v_pk_add_f32 v[84:85], v[114:115], 0 op_sel_hi:[1,0]
; __device__ __forceinline__ unsigned pack2(float a, float b) { unsigned r; asm("v_cvt_pk_bf16_f32 %0, %1, %2" : "=v"(r) : "v"(a), "v"(b)); return r; }
; template <bool SWAP, class Epi, bool THIN = false> ...
;     ...
;     } else {
;       bf16_t* Zw = (bf16_t*)smem + ((wr_e >> 1) * 2 + wc_e) * (128 * 132);
;       const int nt2w = nt * 2 + wc_e;
; #pragma unroll
;       for (int n = 0; n < 8; ++n) {
;         const int cl = n * 16 + fq_e * 4;
;         f32x4 b4 = {0.f, 0.f, 0.f, 0.f};
;         if (epi.pre_bias) b4 = *(const f32x4*)(epi.pre_bias + epi.norig(nt2w, cl));
; #pragma unroll
;         for (int m = 0; m < 4; ++m) {
;           const int rl = rw + m * 16 + fr_e;
;           const int pos = rig0 + rl;
;           const bool ok = pos >= 0 && pos < grows;
;           f32x4 vv = acc[m][n] + b4;
;           if (!ok) vv = (f32x4){0.f, 0.f, 0.f, 0.f};
;           uint2 u; u.x = pack2(vv[0], vv[1]); u.y = pack2(vv[2], vv[3]);
;           *(uint2*)(Zw + rl * 132 + cl) = u;
;         }
;       }
;       __syncthreads();
	v_cndmask_b32_e32 v89, 0, v82, vcc
	v_cndmask_b32_e32 v83, 0, v83, vcc
	v_cndmask_b32_e32 v82, 0, v84, vcc
	v_mfma_f32_16x16x32_bf16 v[10:13], v[228:231], v[200:203], v[164:167]
	v_cndmask_b32_e32 v84, 0, v85, vcc
	v_cvt_pk_bf16_f32 v82, v82, v84
	v_cvt_pk_bf16_f32 v83, v89, v83
	v_mfma_f32_16x16x32_bf16 v[6:9], v[228:231], v[204:207], v[168:171]
	ds_write2_b64 v73, v[74:75], v[82:83] offset0:8 offset1:12
	v_pk_add_f32 v[74:75], v[92:93], 0 op_sel_hi:[1,0]
	v_pk_add_f32 v[82:83], v[90:91], 0 op_sel_hi:[1,0]
	v_cndmask_b32_e64 v84, 0, v74, s[4:5]
	v_cndmask_b32_e64 v75, 0, v75, s[4:5]
	v_cndmask_b32_e64 v74, 0, v82, s[4:5]
	v_cndmask_b32_e64 v82, 0, v83, s[4:5]
	v_cvt_pk_bf16_f32 v74, v74, v82
	v_cvt_pk_bf16_f32 v75, v84, v75
	v_pk_add_f32 v[26:27], v[26:27], 0 op_sel_hi:[1,0]
	ds_write2_b64 v86, v[76:77], v[74:75] offset0:24 offset1:28
	v_pk_add_f32 v[74:75], v[218:219], 0 op_sel_hi:[1,0]
	v_pk_add_f32 v[76:77], v[216:217], 0 op_sel_hi:[1,0]
	v_pk_add_f32 v[58:59], v[58:59], 0 op_sel_hi:[1,0]
	v_pk_add_f32 v[54:55], v[54:55], 0 op_sel_hi:[1,0]
	v_pk_add_f32 v[50:51], v[50:51], 0 op_sel_hi:[1,0]
	v_pk_add_f32 v[46:47], v[46:47], 0 op_sel_hi:[1,0]
	v_pk_add_f32 v[42:43], v[42:43], 0 op_sel_hi:[1,0]
	v_pk_add_f32 v[38:39], v[38:39], 0 op_sel_hi:[1,0]
	v_pk_add_f32 v[34:35], v[34:35], 0 op_sel_hi:[1,0]
	v_pk_add_f32 v[30:31], v[30:31], 0 op_sel_hi:[1,0]
	v_cndmask_b32_e64 v28, 0, v28, s[4:5]
	v_cndmask_b32_e64 v26, 0, v26, s[4:5]
	v_cndmask_b32_e64 v27, 0, v27, s[4:5]
	v_pk_add_f32 v[22:23], v[22:23], 0 op_sel_hi:[1,0]
	v_pk_add_f32 v[18:19], v[18:19], 0 op_sel_hi:[1,0]
	v_pk_add_f32 v[14:15], v[14:15], 0 op_sel_hi:[1,0]
	v_pk_add_f32 v[10:11], v[10:11], 0 op_sel_hi:[1,0]
	v_pk_add_f32 v[6:7], v[6:7], 0 op_sel_hi:[1,0]
	v_pk_add_f32 v[2:3], v[2:3], 0 op_sel_hi:[1,0]
	v_cndmask_b32_e64 v82, 0, v74, s[6:7]
	v_cndmask_b32_e64 v75, 0, v75, s[6:7]
	v_cndmask_b32_e64 v74, 0, v76, s[6:7]
	v_pk_add_f32 v[68:69], v[68:69], 0 op_sel_hi:[1,0]
	v_cndmask_b32_e64 v66, 0, v66, s[8:9]
	v_cndmask_b32_e64 v67, 0, v67, s[8:9]
	v_pk_add_f32 v[64:65], v[64:65], 0 op_sel_hi:[1,0]
	v_cndmask_b32_e32 v62, 0, v62, vcc
	v_cndmask_b32_e32 v63, 0, v63, vcc
	v_pk_add_f32 v[60:61], v[60:61], 0 op_sel_hi:[1,0]
	v_cndmask_b32_e64 v58, 0, v58, s[4:5]
	v_cndmask_b32_e64 v59, 0, v59, s[4:5]
	v_pk_add_f32 v[56:57], v[56:57], 0 op_sel_hi:[1,0]
	v_cndmask_b32_e64 v54, 0, v54, s[6:7]
	v_cndmask_b32_e64 v55, 0, v55, s[6:7]
	v_pk_add_f32 v[52:53], v[52:53], 0 op_sel_hi:[1,0]
	v_cndmask_b32_e64 v50, 0, v50, s[8:9]
	v_cndmask_b32_e64 v51, 0, v51, s[8:9]
	v_pk_add_f32 v[48:49], v[48:49], 0 op_sel_hi:[1,0]
	v_cndmask_b32_e32 v46, 0, v46, vcc
	v_cndmask_b32_e32 v47, 0, v47, vcc
	v_pk_add_f32 v[44:45], v[44:45], 0 op_sel_hi:[1,0]
	v_cndmask_b32_e64 v42, 0, v42, s[4:5]
	v_cndmask_b32_e64 v43, 0, v43, s[4:5]
	v_pk_add_f32 v[40:41], v[40:41], 0 op_sel_hi:[1,0]
	v_cndmask_b32_e64 v38, 0, v38, s[6:7]
	v_cndmask_b32_e64 v39, 0, v39, s[6:7]
	v_pk_add_f32 v[36:37], v[36:37], 0 op_sel_hi:[1,0]
	v_cndmask_b32_e64 v34, 0, v34, s[8:9]
	v_cndmask_b32_e64 v35, 0, v35, s[8:9]
	v_pk_add_f32 v[32:33], v[32:33], 0 op_sel_hi:[1,0]
	v_cndmask_b32_e32 v30, 0, v30, vcc
	v_cndmask_b32_e32 v31, 0, v31, vcc
	v_cndmask_b32_e64 v29, 0, v29, s[4:5]
	v_cvt_pk_bf16_f32 v26, v26, v27
	v_cvt_pk_bf16_f32 v27, v28, v29
	v_pk_add_f32 v[24:25], v[24:25], 0 op_sel_hi:[1,0]
	v_cndmask_b32_e64 v22, 0, v22, s[6:7]
	v_cndmask_b32_e64 v23, 0, v23, s[6:7]
	v_pk_add_f32 v[20:21], v[20:21], 0 op_sel_hi:[1,0]
	v_cndmask_b32_e64 v18, 0, v18, s[8:9]
	v_cndmask_b32_e64 v19, 0, v19, s[8:9]
	v_pk_add_f32 v[16:17], v[16:17], 0 op_sel_hi:[1,0]
	v_cndmask_b32_e32 v14, 0, v14, vcc
	v_cndmask_b32_e32 v15, 0, v15, vcc
	v_pk_add_f32 v[12:13], v[12:13], 0 op_sel_hi:[1,0]
	v_cndmask_b32_e64 v10, 0, v10, s[4:5]
	v_cndmask_b32_e64 v11, 0, v11, s[4:5]
	v_pk_add_f32 v[8:9], v[8:9], 0 op_sel_hi:[1,0]
	v_cndmask_b32_e64 v6, 0, v6, s[6:7]
	v_cndmask_b32_e64 v7, 0, v7, s[6:7]
	v_pk_add_f32 v[4:5], v[4:5], 0 op_sel_hi:[1,0]
	v_cndmask_b32_e64 v2, 0, v2, s[8:9]
	v_cndmask_b32_e64 v3, 0, v3, s[8:9]
	v_mov_b32_e32 v28, v142
	v_cndmask_b32_e64 v76, 0, v77, s[6:7]
	v_cvt_pk_bf16_f32 v74, v74, v76
	v_cvt_pk_bf16_f32 v75, v82, v75
	ds_write2_b64 v87, v[78:79], v[74:75] offset0:40 offset1:44
	v_cndmask_b32_e64 v68, 0, v68, s[8:9]
	v_cndmask_b32_e64 v69, 0, v69, s[8:9]
	v_cvt_pk_bf16_f32 v66, v66, v67
	v_cvt_pk_bf16_f32 v67, v68, v69
	ds_write2_b64 v88, v[80:81], v[66:67] offset0:56 offset1:60
	v_cndmask_b32_e32 v64, 0, v64, vcc
	v_cndmask_b32_e32 v65, 0, v65, vcc
	v_cvt_pk_bf16_f32 v62, v62, v63
	v_cvt_pk_bf16_f32 v63, v64, v65
	v_cndmask_b32_e64 v60, 0, v60, s[4:5]
	v_cndmask_b32_e64 v61, 0, v61, s[4:5]
	v_cvt_pk_bf16_f32 v58, v58, v59
	v_cvt_pk_bf16_f32 v59, v60, v61
	v_cndmask_b32_e64 v56, 0, v56, s[6:7]
	v_cndmask_b32_e64 v57, 0, v57, s[6:7]
	v_cvt_pk_bf16_f32 v54, v54, v55
	v_cvt_pk_bf16_f32 v55, v56, v57
	v_cndmask_b32_e64 v52, 0, v52, s[8:9]
	v_cndmask_b32_e64 v53, 0, v53, s[8:9]
	v_cvt_pk_bf16_f32 v50, v50, v51
	v_cvt_pk_bf16_f32 v51, v52, v53
	v_cndmask_b32_e32 v48, 0, v48, vcc
	v_cndmask_b32_e32 v49, 0, v49, vcc
	v_cvt_pk_bf16_f32 v46, v46, v47
	v_cvt_pk_bf16_f32 v47, v48, v49
	ds_write2_b64 v73, v[62:63], v[46:47] offset0:16 offset1:20
	v_cndmask_b32_e64 v44, 0, v44, s[4:5]
	v_cndmask_b32_e64 v45, 0, v45, s[4:5]
	v_cvt_pk_bf16_f32 v42, v42, v43
	v_cvt_pk_bf16_f32 v43, v44, v45
	ds_write2_b64 v86, v[58:59], v[42:43] offset0:32 offset1:36
	v_cndmask_b32_e64 v40, 0, v40, s[6:7]
	v_cndmask_b32_e64 v41, 0, v41, s[6:7]
	v_cvt_pk_bf16_f32 v38, v38, v39
; __device__ __forceinline__ unsigned pack2(float a, float b) { unsigned r; asm("v_cvt_pk_bf16_f32 %0, %1, %2" : "=v"(r) : "v"(a), "v"(b)); return r; }
;   template <class F>
;   __device__ __forceinline__ void finish(const bf16_t* Z, int g, int rig0, int nt, F&& pre) const {
;     ...
;     if (MODE == 0 || nt < 8) {
;       if (MODE == 0) {
;         const int f2 = (tid & 31) * 2, q8 = tid >> 5;
;         const int q0 = 1 + 16 * q8, q1 = (q0 + 16 < 127) ? q0 + 16 : 127;
;         const int na = norig(nt, f2), ng = norig(nt, 64 + f2);
;         const f32x2 a0 = *(const f32x2*)(cw + na), a1 = *(const f32x2*)(cw + NC + na), a2 = *(const f32x2*)(cw + 2 * NC + na), ab = *(const f32x2*)(cb + na);
;         const f32x2 g0 = *(const f32x2*)(cw + ng), g1 = *(const f32x2*)(cw + NC + ng), g2 = *(const f32x2*)(cw + 2 * NC + ng), gb = *(const f32x2*)(cb + ng);
;         pre();
;         f32x2 am = ldz(Z, q0 - 1, f2), ac = ldz(Z, q0, f2);
;         f32x2 gm = ldz(Z, q0 - 1, 64 + f2), gc = ldz(Z, q0, 64 + f2);
; template <bool SWAP, class Epi, bool THIN = false> ...
;     ...
;           f32x4 vv = acc[m][n] + b4;
;           if (!ok) vv = (f32x4){0.f, 0.f, 0.f, 0.f};
;           uint2 u; u.x = pack2(vv[0], vv[1]); u.y = pack2(vv[2], vv[3]);
;           *(uint2*)(Zw + rl * 132 + cl) = u;
;         }
;       }
;       __syncthreads();
;       {
;         auto no_pre = []() {};
;         const bf16_t* Zr = (const bf16_t*)smem + ((wr_e >> 1) * 2) * (128 * 132);
;         epi.finish(Zr, g, rig0, nt * 2, no_pre);
	v_cvt_pk_bf16_f32 v39, v40, v41
	ds_write2_b64 v87, v[54:55], v[38:39] offset0:48 offset1:52
	v_cndmask_b32_e64 v36, 0, v36, s[8:9]
	v_cndmask_b32_e64 v37, 0, v37, s[8:9]
	v_cvt_pk_bf16_f32 v34, v34, v35
	v_cvt_pk_bf16_f32 v35, v36, v37
	ds_write2_b64 v88, v[50:51], v[34:35] offset0:64 offset1:68
	v_cndmask_b32_e32 v32, 0, v32, vcc
	v_cndmask_b32_e32 v33, 0, v33, vcc
	v_cvt_pk_bf16_f32 v30, v30, v31
	v_cvt_pk_bf16_f32 v31, v32, v33
	v_cndmask_b32_e64 v24, 0, v24, s[6:7]
	v_cndmask_b32_e64 v25, 0, v25, s[6:7]
	v_cvt_pk_bf16_f32 v22, v22, v23
	v_cvt_pk_bf16_f32 v23, v24, v25
	v_cndmask_b32_e64 v20, 0, v20, s[8:9]
	v_cndmask_b32_e64 v21, 0, v21, s[8:9]
	v_cvt_pk_bf16_f32 v18, v18, v19
	v_cvt_pk_bf16_f32 v19, v20, v21
	v_cndmask_b32_e32 v16, 0, v16, vcc
	v_cndmask_b32_e32 v17, 0, v17, vcc
	v_cvt_pk_bf16_f32 v14, v14, v15
	v_cvt_pk_bf16_f32 v15, v16, v17
	ds_write2_b64 v73, v[30:31], v[14:15] offset0:24 offset1:28
	v_cndmask_b32_e64 v12, 0, v12, s[4:5]
	v_cndmask_b32_e64 v13, 0, v13, s[4:5]
	v_cvt_pk_bf16_f32 v10, v10, v11
	v_cvt_pk_bf16_f32 v11, v12, v13
	ds_write2_b64 v86, v[26:27], v[10:11] offset0:40 offset1:44
	v_cndmask_b32_e64 v8, 0, v8, s[6:7]
	v_cndmask_b32_e64 v9, 0, v9, s[6:7]
	v_cvt_pk_bf16_f32 v6, v6, v7
	v_cvt_pk_bf16_f32 v7, v8, v9
	ds_write2_b64 v87, v[22:23], v[6:7] offset0:56 offset1:60
	v_cndmask_b32_e64 v4, 0, v4, s[8:9]
	v_cndmask_b32_e64 v5, 0, v5, s[8:9]
	v_cvt_pk_bf16_f32 v2, v2, v3
	v_cvt_pk_bf16_f32 v3, v4, v5
	ds_write2_b64 v88, v[18:19], v[2:3] offset0:72 offset1:76
	s_waitcnt lgkmcnt(0)
	s_barrier
	s_nop 0
	v_ashrrev_i32_e32 v29, 1, v28
	v_and_b32_e32 v38, -16, v29
	v_min_i32_e32 v2, 0x6e, v38
	v_or_b32_e32 v20, 1, v38
	v_add_u32_e32 v3, 17, v2
	v_cmp_ge_i32_e32 vcc, v20, v3
	s_and_saveexec_b64 s[4:5], vcc
	s_xor_b64 s[4:5], exec, s[4:5]
	s_ashr_i32 s25, s24, 31
	s_or_saveexec_b64 s[4:5], s[4:5]
	v_mul_i32_i24_e32 v2, 0x10800, v71
	v_mov_b64_e32 v[22:23], s[24:25]
	v_ashrrev_i32_e32 v71, 31, v70
	s_xor_b64 exec, exec, s[4:5]
	s_cbranch_execz .LBB0_2345
	v_lshlrev_b32_e32 v4, 1, v28
	v_and_b32_e32 v21, 62, v4
	v_or_b32_e32 v4, s24, v21
	s_add_i32 s6, s24, 0xb00
	v_ashrrev_i32_e32 v5, 31, v4
	v_or_b32_e32 v12, s6, v21
	v_lshlrev_b64 v[10:11], 2, v[4:5]
	v_lshl_add_u64 v[14:15], s[12:13], 0, v[10:11]
	v_lshl_add_u64 v[18:19], s[22:23], 0, v[10:11]
	v_ashrrev_i32_e32 v13, 31, v12
	v_lshl_add_u64 v[16:17], s[20:21], 0, v[10:11]
	global_load_dwordx2 v[4:5], v[14:15], off
	global_load_dwordx2 v[6:7], v[16:17], off
	global_load_dwordx2 v[8:9], v[18:19], off
	v_lshlrev_b64 v[18:19], 2, v[12:13]
	v_lshl_add_u64 v[10:11], s[14:15], 0, v[10:11]
	v_lshl_add_u64 v[22:23], s[12:13], 0, v[18:19]
	global_load_dwordx2 v[10:11], v[10:11], off
	v_lshl_add_u64 v[24:25], s[20:21], 0, v[18:19]
	v_lshl_add_u64 v[26:27], s[22:23], 0, v[18:19]
	global_load_dwordx2 v[12:13], v[22:23], off
	global_load_dwordx2 v[14:15], v[24:25], off
	global_load_dwordx2 v[16:17], v[26:27], off
	v_lshl_add_u64 v[18:19], s[14:15], 0, v[18:19]
	global_load_dwordx2 v[18:19], v[18:19], off
	s_ashr_i32 s25, s24, 31
	v_mov_b64_e32 v[106:107], s[24:25]
	v_mov_b32_e32 v117, 0
	v_lshlrev_b32_e32 v88, 1, v142
	v_and_b32_e32 v116, 62, v88
	v_add3_u32 v88, v116, s24, 64
	s_add_i32 s38, s24, 0xb40
	v_ashrrev_i32_e32 v89, 31, v88
	v_lshl_add_u64 v[90:91], v[116:117], 0, v[106:107]
	v_or_b32_e32 v96, s38, v116
	v_lshlrev_b64 v[94:95], 2, v[90:91]
	v_lshlrev_b64 v[88:89], 2, v[88:89]
	v_lshl_add_u64 v[98:99], s[12:13], 0, v[94:95]
	v_lshl_add_u64 v[102:103], s[22:23], 0, v[88:89]
	v_ashrrev_i32_e32 v97, 31, v96
	v_lshl_add_u64 v[100:101], s[20:21], 0, v[88:89]
	global_load_dwordx2 v[88:89], v[98:99], off offset:256
	global_load_dwordx2 v[90:91], v[100:101], off
	global_load_dwordx2 v[92:93], v[102:103], off
	v_lshlrev_b64 v[102:103], 2, v[96:97]
	v_lshl_add_u64 v[94:95], s[14:15], 0, v[94:95]
	v_lshl_add_u64 v[108:109], s[12:13], 0, v[102:103]
	global_load_dwordx2 v[94:95], v[94:95], off offset:256
	v_lshl_add_u64 v[110:111], s[20:21], 0, v[102:103]
	v_lshl_add_u64 v[114:115], s[22:23], 0, v[102:103]
	global_load_dwordx2 v[96:97], v[108:109], off
	global_load_dwordx2 v[98:99], v[110:111], off
	global_load_dwordx2 v[100:101], v[114:115], off
	v_lshl_add_u64 v[102:103], s[14:15], 0, v[102:103]
	global_load_dwordx2 v[102:103], v[102:103], off
	v_lshlrev_b32_e32 v136, 1, v21
	v_mul_lo_u32 v22, v38, s31
	v_mul_lo_u32 v20, v20, s31
	v_add3_u32 v22, v2, v22, v136
	v_add3_u32 v20, v2, v20, v136
	ds_read2_b32 v[22:23], v22 offset1:32
	ds_read2_b32 v[20:21], v20 offset1:32
	s_ashr_i32 s25, s24, 31
	s_lshl_b64 s[6:7], s[24:25], 1
	s_add_u32 s6, s10, s6
	s_addc_u32 s7, s11, s7
	v_lshrrev_b32_e32 v29, 4, v29
	v_and_b32_e32 v28, 31, v28
	s_waitcnt lgkmcnt(1)
	v_lshlrev_b32_e32 v32, 16, v23
	v_and_b32_e32 v33, 0xffff0000, v23
	v_lshlrev_b32_e32 v34, 16, v22
	v_and_b32_e32 v35, 0xffff0000, v22
	v_lshl_add_u64 v[22:23], s[6:7], 0, v[136:137]
	v_mad_u64_u32 v[30:31], s[6:7], v29, s33, v[2:3]
	v_lshlrev_b32_e32 v28, 2, v28
	s_waitcnt lgkmcnt(0)
	v_lshlrev_b32_e32 v24, 16, v21
	v_and_b32_e32 v25, 0xffff0000, v21
	v_lshlrev_b32_e32 v26, 16, v20
	v_and_b32_e32 v27, 0xffff0000, v20
	v_lshlrev_b64 v[20:21], 11, v[70:71]
	v_add3_u32 v39, v30, v28, s34
	s_mov_b32 s98, 0x1600
	s_mov_b32 s99, 0
	v_add_u32_e32 v48, v72, v38
	v_ashrrev_i32_e32 v49, 31, v48
	v_lshl_add_u64 v[48:49], v[20:21], 0, v[48:49]
	v_mad_u64_u32 v[50:51], s[38:39], v48, s35, v[22:23]
	v_mad_i32_i24 v51, v49, s35, v51
	s_mov_b64 s[6:7], 0
	s_waitcnt vmcnt(0)
	ds_read2_b32 v[44:45], v39 offset1:32
	s_branch .LBB0_2340

; template <bool SWAP, class Epi, bool THIN = false> ...
;     ...
;     for (int st = 0; st < ns; ++st) {
;       asm volatile("s_waitcnt vmcnt(0)" ::: "memory");
;       __builtin_amdgcn_s_barrier();
;       asm volatile("" ::: "memory");
;       if (st + 1 < ns) {
;         char* nb = smem + ((st + 1) & 1) * 65536;
;         const int ko = (st + 1) * 64;
; #pragma unroll
;         for (int i = 0; i < 4; ++i) { GLDS16(A + (size_t)(ap[i] + ko), nb + tid * 16 + i * 8192); GLDS16(Bt + (size_t)(bp[i] + ko), nb + 32768 + tid * 16 + i * 8192); }
;       }
;       const char* sa = smem + (st & 1) * 65536 + (wr * 64 + fr) * 128;
;       const char* sb = smem + (st & 1) * 65536 + 32768 + (wc * 128 + fr) * 128;
;       if constexpr (THIN) {
;         if (wc == 0) {
; #pragma unroll
;           for (int ks = 0; ks < 2; ++ks) {
;             bf16x8 af[4], bf[2];
; #pragma unroll
;             for (int m = 0; m < 4; ++m) af[m] = *(const bf16x8*)(sa + m * 2048 + (((ks * 4 + fq) ^ swz) << 4));
; #pragma unroll
;             for (int n = 0; n < 2; ++n) bf[n] = *(const bf16x8*)(sb + n * 2048 + (((ks * 4 + fq) ^ swz) << 4));
; #pragma unroll
;             for (int m = 0; m < 4; ++m)
; #pragma unroll
;               for (int n = 0; n < 2; ++n)
;                 acc[m][n] = SWAP ? __builtin_amdgcn_mfma_f32_16x16x32_bf16(bf[n], af[m], acc[m][n], 0, 0, 0)
;                                  : __builtin_amdgcn_mfma_f32_16x16x32_bf16(af[m], bf[n], acc[m][n], 0, 0, 0);
;           }
;         }
;       } else {
;       bf16x8 afA[4], afB[4], bfb[2][2];
; #pragma unroll
;       for (int m = 0; m < 4; ++m) afA[m] = *(const bf16x8*)(sa + m * 2048 + ((fq ^ swz) << 4));
; #pragma unroll
;       for (int n = 0; n < 2; ++n) bfb[0][n] = *(const bf16x8*)(sb + n * 2048 + ((fq ^ swz) << 4));
; #pragma unroll
;       for (int gq = 0; gq < 8; ++gq) {
;         const int ks = gq >> 2, nh = gq & 3;
;         if (gq < 7) {
;           const int ks2 = (gq + 1) >> 2, nh2 = (gq + 1) & 3;
; #pragma unroll
;           for (int n = 0; n < 2; ++n) bfb[(gq + 1) & 1][n] = *(const bf16x8*)(sb + (nh2 * 2 + n) * 2048 + (((ks2 * 4 + fq) ^ swz) << 4));
;         }
;         if (gq == 3) {
; #pragma unroll
;           for (int m = 0; m < 4; ++m) afB[m] = *(const bf16x8*)(sa + m * 2048 + (((4 + fq) ^ swz) << 4));
;         }
;         __builtin_amdgcn_sched_barrier(0);
; #pragma unroll
.LBB0_2429:
	s_add_i32 s9, s7, 0x10000
	s_and_b32 s8, s9, 0x10000
	v_add_u32_e32 v139, s8, v144
	s_nop 0
	v_readfirstlane_b32 s10, v139
	s_waitcnt vmcnt(0)
	s_barrier
	s_and_b32 s7, s7, 0x10000
	v_add_u32_e32 v130, s7, v145
	v_add_u32_e32 v139, v130, v147
	ds_read_b128 v[168:171], v139
	ds_read_b128 v[172:175], v139 offset:2048
	ds_read_b128 v[176:179], v139 offset:4096
	ds_read_b128 v[180:183], v139 offset:6144
	v_or_b32_e32 v139, s7, v146
	v_add_u32_e32 v141, v139, v147
	ds_read_b128 v[184:187], v141 offset:32768
	ds_read_b128 v[188:191], v141 offset:34816
	ds_read_b128 v[192:195], v141 offset:36864
	ds_read_b128 v[196:199], v141 offset:38912
	v_add_u32_e32 v130, v130, v148
	s_waitcnt lgkmcnt(3)
	v_mfma_f32_16x16x32_bf16 v[126:129], v[184:187], v[168:171], v[126:129]
	s_mov_b32 m0, s10
	v_mfma_f32_16x16x32_bf16 v[110:113], v[184:187], v[172:175], v[110:113]
	global_load_lds_dwordx4 v138, s[22:23] sc1
	v_add_u32_e32 v138, 0x80, v138
	v_mfma_f32_16x16x32_bf16 v[82:85], v[184:187], v[176:179], v[82:85]
	v_mfma_f32_16x16x32_bf16 v[50:53], v[184:187], v[180:183], v[50:53]
	ds_read_b128 v[184:187], v141 offset:40960
	ds_read_b128 v[200:203], v141 offset:43008
	s_waitcnt lgkmcnt(4)
	v_mfma_f32_16x16x32_bf16 v[122:125], v[188:191], v[168:171], v[122:125]
	s_add_u32 m0, s10, 0x8000
	v_mfma_f32_16x16x32_bf16 v[106:109], v[188:191], v[172:175], v[106:109]
	global_load_lds_dwordx4 v137, s[18:19] sc1
	v_add_u32_e32 v137, 0x80, v137
	v_mfma_f32_16x16x32_bf16 v[78:81], v[188:191], v[176:179], v[78:81]
	v_mfma_f32_16x16x32_bf16 v[38:41], v[188:191], v[180:183], v[38:41]
	s_waitcnt lgkmcnt(3)
	v_mfma_f32_16x16x32_bf16 v[118:121], v[192:195], v[168:171], v[118:121]
	s_add_u32 m0, s10, 0x2000
	v_mfma_f32_16x16x32_bf16 v[94:97], v[192:195], v[172:175], v[94:97]
	global_load_lds_dwordx4 v136, s[22:23] sc1
	v_add_u32_e32 v136, 0x80, v136
	v_mfma_f32_16x16x32_bf16 v[58:61], v[192:195], v[176:179], v[58:61]
	v_mfma_f32_16x16x32_bf16 v[26:29], v[192:195], v[180:183], v[26:29]
	ds_read_b128 v[188:191], v141 offset:45056
	ds_read_b128 v[192:195], v141 offset:47104
	s_waitcnt lgkmcnt(4)
	v_mfma_f32_16x16x32_bf16 v[114:117], v[196:199], v[168:171], v[114:117]
	s_add_u32 m0, s10, 0xa000
	v_mfma_f32_16x16x32_bf16 v[86:89], v[196:199], v[172:175], v[86:89]
	global_load_lds_dwordx4 v135, s[18:19] sc1
	v_add_u32_e32 v135, 0x80, v135
	v_mfma_f32_16x16x32_bf16 v[54:57], v[196:199], v[176:179], v[54:57]
	v_mfma_f32_16x16x32_bf16 v[22:25], v[196:199], v[180:183], v[22:25]
	v_add_u32_e32 v139, v139, v148
	s_waitcnt lgkmcnt(3)
	v_mfma_f32_16x16x32_bf16 v[102:105], v[184:187], v[168:171], v[102:105]
	ds_read_b128 v[196:199], v139 offset:32768
	ds_read_b128 v[204:207], v139 offset:34816
	s_add_u32 m0, s10, 0x4000
	v_mfma_f32_16x16x32_bf16 v[74:77], v[184:187], v[172:175], v[74:77]
	global_load_lds_dwordx4 v134, s[22:23] sc1
	v_add_u32_e32 v134, 0x80, v134
	v_mfma_f32_16x16x32_bf16 v[46:49], v[184:187], v[176:179], v[46:49]
	v_mfma_f32_16x16x32_bf16 v[10:13], v[184:187], v[180:183], v[10:13]
	ds_read_b128 v[184:187], v130
	ds_read_b128 v[208:211], v130 offset:2048
	ds_read_b128 v[212:215], v130 offset:4096
	ds_read_b128 v[216:219], v130 offset:6144
	s_waitcnt lgkmcnt(8)
	v_mfma_f32_16x16x32_bf16 v[98:101], v[200:203], v[168:171], v[98:101]
	s_add_u32 m0, s10, 0xc000
	v_mfma_f32_16x16x32_bf16 v[66:69], v[200:203], v[172:175], v[66:69]
	global_load_lds_dwordx4 v133, s[18:19] sc1
	v_add_u32_e32 v133, 0x80, v133
	v_mfma_f32_16x16x32_bf16 v[34:37], v[200:203], v[176:179], v[34:37]
	v_mfma_f32_16x16x32_bf16 v[6:9], v[200:203], v[180:183], v[6:9]
	s_waitcnt lgkmcnt(7)
	v_mfma_f32_16x16x32_bf16 v[70:73], v[188:191], v[168:171], v[70:73]
	s_add_u32 m0, s10, 0x6000
	s_waitcnt lgkmcnt(6)
	v_mfma_f32_16x16x32_bf16 v[62:65], v[192:195], v[168:171], v[62:65]
	global_load_lds_dwordx4 v132, s[22:23] sc1
	v_add_u32_e32 v132, 0x80, v132
	v_mfma_f32_16x16x32_bf16 v[42:45], v[188:191], v[172:175], v[42:45]
	v_mfma_f32_16x16x32_bf16 v[30:33], v[192:195], v[172:175], v[30:33]
	ds_read_b128 v[168:171], v139 offset:36864
	ds_read_b128 v[172:175], v139 offset:38912
	v_mfma_f32_16x16x32_bf16 v[18:21], v[188:191], v[176:179], v[18:21]
	s_add_u32 m0, s10, 0xe000
	v_mfma_f32_16x16x32_bf16 v[14:17], v[192:195], v[176:179], v[14:17]
	global_load_lds_dwordx4 v140, s[18:19] sc1
	v_add_u32_e32 v140, 0x80, v140
	v_mfma_f32_16x16x32_bf16 v[2:5], v[188:191], v[180:183], v[2:5]
	v_mfma_f32_16x16x32_bf16 v[90:93], v[192:195], v[180:183], v[90:93]
	ds_read_b128 v[176:179], v139 offset:40960
	ds_read_b128 v[180:183], v139 offset:43008
	s_waitcnt lgkmcnt(7)
	v_mfma_f32_16x16x32_bf16 v[126:129], v[196:199], v[184:187], v[126:129]
	v_mfma_f32_16x16x32_bf16 v[122:125], v[204:207], v[184:187], v[122:125]
	s_waitcnt lgkmcnt(6)
	v_mfma_f32_16x16x32_bf16 v[110:113], v[196:199], v[208:211], v[110:113]
	v_mfma_f32_16x16x32_bf16 v[106:109], v[204:207], v[208:211], v[106:109]
	s_waitcnt lgkmcnt(5)
	v_mfma_f32_16x16x32_bf16 v[82:85], v[196:199], v[212:215], v[82:85]
	v_mfma_f32_16x16x32_bf16 v[78:81], v[204:207], v[212:215], v[78:81]
	s_waitcnt lgkmcnt(4)
	v_mfma_f32_16x16x32_bf16 v[50:53], v[196:199], v[216:219], v[50:53]
	v_mfma_f32_16x16x32_bf16 v[38:41], v[204:207], v[216:219], v[38:41]
	s_waitcnt lgkmcnt(3)
	v_mfma_f32_16x16x32_bf16 v[118:121], v[168:171], v[184:187], v[118:121]
	v_mfma_f32_16x16x32_bf16 v[94:97], v[168:171], v[208:211], v[94:97]
	v_mfma_f32_16x16x32_bf16 v[58:61], v[168:171], v[212:215], v[58:61]
	v_mfma_f32_16x16x32_bf16 v[26:29], v[168:171], v[216:219], v[26:29]
	ds_read_b128 v[168:171], v139 offset:45056
	ds_read_b128 v[188:191], v139 offset:47104
	s_waitcnt lgkmcnt(4)
; template <bool SWAP, class Epi, bool THIN = false> ...
;     ...
;       bf16x8 afA[4], afB[4], bfb[2][2];
; #pragma unroll
;       for (int m = 0; m < 4; ++m) afA[m] = *(const bf16x8*)(sa + m * 2048 + ((fq ^ swz) << 4));
; #pragma unroll
;       for (int n = 0; n < 2; ++n) bfb[0][n] = *(const bf16x8*)(sb + n * 2048 + ((fq ^ swz) << 4));
; #pragma unroll
;       for (int gq = 0; gq < 8; ++gq) {
;         const int ks = gq >> 2, nh = gq & 3;
;         if (gq < 7) {
;           const int ks2 = (gq + 1) >> 2, nh2 = (gq + 1) & 3;
; #pragma unroll
;           for (int n = 0; n < 2; ++n) bfb[(gq + 1) & 1][n] = *(const bf16x8*)(sb + (nh2 * 2 + n) * 2048 + (((ks2 * 4 + fq) ^ swz) << 4));
;         }
;         if (gq == 3) {
; #pragma unroll
;           for (int m = 0; m < 4; ++m) afB[m] = *(const bf16x8*)(sa + m * 2048 + (((4 + fq) ^ swz) << 4));
;         }
;         __builtin_amdgcn_sched_barrier(0);
; #pragma unroll
;         for (int m = 0; m < 4; ++m)
; #pragma unroll
;           for (int n = 0; n < 2; ++n) {
;             const bf16x8 av = ks ? afB[m] : afA[m];
;             acc[m][nh * 2 + n] = SWAP ? __builtin_amdgcn_mfma_f32_16x16x32_bf16(bfb[gq & 1][n], av, acc[m][nh * 2 + n], 0, 0, 0)
;                                       : __builtin_amdgcn_mfma_f32_16x16x32_bf16(av, bfb[gq & 1][n], acc[m][nh * 2 + n], 0, 0, 0);
;           }
;       }
;       }
;     }
;     __syncthreads();
	v_mfma_f32_16x16x32_bf16 v[114:117], v[172:175], v[184:187], v[114:117]
	v_mfma_f32_16x16x32_bf16 v[86:89], v[172:175], v[208:211], v[86:89]
	v_mfma_f32_16x16x32_bf16 v[54:57], v[172:175], v[212:215], v[54:57]
	v_mfma_f32_16x16x32_bf16 v[22:25], v[172:175], v[216:219], v[22:25]
	s_waitcnt lgkmcnt(3)
	v_mfma_f32_16x16x32_bf16 v[102:105], v[176:179], v[184:187], v[102:105]
	s_waitcnt lgkmcnt(2)
	v_mfma_f32_16x16x32_bf16 v[98:101], v[180:183], v[184:187], v[98:101]
	v_mfma_f32_16x16x32_bf16 v[74:77], v[176:179], v[208:211], v[74:77]
	v_mfma_f32_16x16x32_bf16 v[66:69], v[180:183], v[208:211], v[66:69]
	v_mfma_f32_16x16x32_bf16 v[46:49], v[176:179], v[212:215], v[46:49]
	v_mfma_f32_16x16x32_bf16 v[34:37], v[180:183], v[212:215], v[34:37]
	v_mfma_f32_16x16x32_bf16 v[10:13], v[176:179], v[216:219], v[10:13]
	v_mfma_f32_16x16x32_bf16 v[6:9], v[180:183], v[216:219], v[6:9]
	s_waitcnt lgkmcnt(1)
	v_mfma_f32_16x16x32_bf16 v[70:73], v[168:171], v[184:187], v[70:73]
	s_add_i32 s6, s6, 64
	s_cmpk_eq_i32 s6, 0xac0
	s_mov_b32 s7, s9
	s_waitcnt lgkmcnt(0)
	v_mfma_f32_16x16x32_bf16 v[62:65], v[188:191], v[184:187], v[62:65]
	v_mfma_f32_16x16x32_bf16 v[42:45], v[168:171], v[208:211], v[42:45]
	v_mfma_f32_16x16x32_bf16 v[30:33], v[188:191], v[208:211], v[30:33]
	v_mfma_f32_16x16x32_bf16 v[18:21], v[168:171], v[212:215], v[18:21]
	v_mfma_f32_16x16x32_bf16 v[14:17], v[188:191], v[212:215], v[14:17]
	v_mfma_f32_16x16x32_bf16 v[2:5], v[168:171], v[216:219], v[2:5]
	v_mfma_f32_16x16x32_bf16 v[90:93], v[188:191], v[216:219], v[90:93]
	s_cbranch_scc0 .LBB0_2429
	v_add_u32_e32 v130, s8, v145
	s_waitcnt vmcnt(0)
	s_barrier
	v_add_u32_e32 v140, v130, v147
	ds_read_b128 v[132:135], v140
	ds_read_b128 v[136:139], v140 offset:2048
	ds_read_b128 v[168:171], v140 offset:4096
	ds_read_b128 v[172:175], v140 offset:6144
	v_add_u32_e32 v140, s8, v146
	v_add_u32_e32 v141, v140, v147
	ds_read_b128 v[176:179], v141 offset:32768
	ds_read_b128 v[180:183], v141 offset:34816
	ds_read_b128 v[184:187], v141 offset:36864
	ds_read_b128 v[188:191], v141 offset:38912
	v_add_u32_e32 v130, v130, v148
	s_waitcnt lgkmcnt(0)
	v_mfma_f32_16x16x32_bf16 v[126:129], v[176:179], v[132:135], v[126:129]
	v_mfma_f32_16x16x32_bf16 v[110:113], v[176:179], v[136:139], v[110:113]
	v_mfma_f32_16x16x32_bf16 v[82:85], v[176:179], v[168:171], v[82:85]
	v_mfma_f32_16x16x32_bf16 v[50:53], v[176:179], v[172:175], v[50:53]
	ds_read_b128 v[176:179], v141 offset:40960
	ds_read_b128 v[192:195], v141 offset:43008
	v_mfma_f32_16x16x32_bf16 v[122:125], v[180:183], v[132:135], v[122:125]
	v_mfma_f32_16x16x32_bf16 v[106:109], v[180:183], v[136:139], v[106:109]
	v_mfma_f32_16x16x32_bf16 v[78:81], v[180:183], v[168:171], v[78:81]
	v_mfma_f32_16x16x32_bf16 v[38:41], v[180:183], v[172:175], v[38:41]
	v_mfma_f32_16x16x32_bf16 v[118:121], v[184:187], v[132:135], v[118:121]
	v_mfma_f32_16x16x32_bf16 v[180:183], v[184:187], v[136:139], v[94:97]
	v_mfma_f32_16x16x32_bf16 v[200:203], v[184:187], v[168:171], v[58:61]
	v_mfma_f32_16x16x32_bf16 v[204:207], v[188:191], v[168:171], v[54:57]
	v_mfma_f32_16x16x32_bf16 v[184:187], v[184:187], v[172:175], v[26:29]
	s_nop 2
	ds_read_b128 v[26:29], v141 offset:45056
	ds_read_b128 v[54:57], v141 offset:47104
	v_mfma_f32_16x16x32_bf16 v[114:117], v[188:191], v[132:135], v[114:117]
	v_mfma_f32_16x16x32_bf16 v[196:199], v[188:191], v[136:139], v[86:89]
	v_mfma_f32_16x16x32_bf16 v[188:191], v[188:191], v[172:175], v[22:25]
	v_add_u32_e32 v140, v140, v148
	s_waitcnt lgkmcnt(0)
	v_mfma_f32_16x16x32_bf16 v[102:105], v[176:179], v[132:135], v[102:105]
	ds_read_b128 v[22:25], v140 offset:32768
	ds_read_b128 v[86:89], v140 offset:34816
	v_mfma_f32_16x16x32_bf16 v[74:77], v[176:179], v[136:139], v[74:77]
	v_mfma_f32_16x16x32_bf16 v[46:49], v[176:179], v[168:171], v[46:49]
	v_mfma_f32_16x16x32_bf16 v[10:13], v[176:179], v[172:175], v[10:13]
	ds_read_b128 v[176:179], v130
	ds_read_b128 v[208:211], v130 offset:2048
	ds_read_b128 v[212:215], v130 offset:4096
	ds_read_b128 v[216:219], v130 offset:6144
	v_mfma_f32_16x16x32_bf16 v[98:101], v[192:195], v[132:135], v[98:101]
	v_mfma_f32_16x16x32_bf16 v[66:69], v[192:195], v[136:139], v[66:69]
	v_mfma_f32_16x16x32_bf16 v[34:37], v[192:195], v[168:171], v[34:37]
	v_mfma_f32_16x16x32_bf16 v[6:9], v[192:195], v[172:175], v[6:9]
	v_mfma_f32_16x16x32_bf16 v[220:223], v[26:29], v[168:171], v[18:21]
	v_mfma_f32_16x16x32_bf16 v[168:171], v[54:57], v[168:171], v[14:17]
	s_nop 2
	ds_read_b128 v[14:17], v140 offset:36864
	ds_read_b128 v[18:21], v140 offset:38912
	v_mfma_f32_16x16x32_bf16 v[70:73], v[26:29], v[132:135], v[70:73]
	v_mfma_f32_16x16x32_bf16 v[132:135], v[54:57], v[132:135], v[62:65]
	v_mfma_f32_16x16x32_bf16 v[192:195], v[26:29], v[136:139], v[42:45]
	v_mfma_f32_16x16x32_bf16 v[136:139], v[54:57], v[136:139], v[30:33]
	v_mfma_f32_16x16x32_bf16 v[2:5], v[26:29], v[172:175], v[2:5]
	v_mfma_f32_16x16x32_bf16 v[172:175], v[54:57], v[172:175], v[90:93]
	ds_read_b128 v[224:227], v140 offset:40960
	ds_read_b128 v[228:231], v140 offset:43008
	s_waitcnt lgkmcnt(0)
	v_mfma_f32_16x16x32_bf16 v[126:129], v[22:25], v[176:179], v[126:129]
	v_mfma_f32_16x16x32_bf16 v[122:125], v[86:89], v[176:179], v[122:125]
	v_mfma_f32_16x16x32_bf16 v[94:97], v[22:25], v[208:211], v[110:113]
	v_mfma_f32_16x16x32_bf16 v[90:93], v[86:89], v[208:211], v[106:109]
	v_mfma_f32_16x16x32_bf16 v[62:65], v[22:25], v[212:215], v[82:85]
	v_mfma_f32_16x16x32_bf16 v[58:61], v[86:89], v[212:215], v[78:81]
	v_mfma_f32_16x16x32_bf16 v[30:33], v[22:25], v[216:219], v[50:53]
	v_mfma_f32_16x16x32_bf16 v[26:29], v[86:89], v[216:219], v[38:41]
	v_mfma_f32_16x16x32_bf16 v[86:89], v[14:17], v[208:211], v[180:183]
	v_mfma_f32_16x16x32_bf16 v[22:25], v[14:17], v[216:219], v[184:187]
	s_nop 1
	ds_read_b128 v[180:183], v140 offset:45056
	ds_read_b128 v[184:187], v140 offset:47104
	v_mfma_f32_16x16x32_bf16 v[118:121], v[14:17], v[176:179], v[118:121]
	v_mfma_f32_16x16x32_bf16 v[114:117], v[18:21], v[176:179], v[114:117]
	v_mfma_f32_16x16x32_bf16 v[82:85], v[18:21], v[208:211], v[196:199]
	v_mfma_f32_16x16x32_bf16 v[54:57], v[14:17], v[212:215], v[200:203]
	v_mfma_f32_16x16x32_bf16 v[50:53], v[18:21], v[212:215], v[204:207]
	v_mfma_f32_16x16x32_bf16 v[18:21], v[18:21], v[216:219], v[188:191]
	v_mfma_f32_16x16x32_bf16 v[110:113], v[224:227], v[176:179], v[102:105]
	v_mfma_f32_16x16x32_bf16 v[106:109], v[228:231], v[176:179], v[98:101]
	v_mfma_f32_16x16x32_bf16 v[78:81], v[224:227], v[208:211], v[74:77]
	v_mfma_f32_16x16x32_bf16 v[74:77], v[228:231], v[208:211], v[66:69]
	v_mfma_f32_16x16x32_bf16 v[46:49], v[224:227], v[212:215], v[46:49]
	v_mfma_f32_16x16x32_bf16 v[42:45], v[228:231], v[212:215], v[34:37]
	v_mfma_f32_16x16x32_bf16 v[14:17], v[224:227], v[216:219], v[10:13]
	v_mfma_f32_16x16x32_bf16 v[10:13], v[228:231], v[216:219], v[6:9]
	v_mov_b32_e32 v130, v1
	s_waitcnt vmcnt(0) lgkmcnt(0)
	s_barrier
; __device__ __forceinline__ unsigned pack2(float a, float b) { unsigned r; asm("v_cvt_pk_bf16_f32 %0, %1, %2" : "=v"(r) : "v"(a), "v"(b)); return r; }
; __device__ __forceinline__ float bf2f(bf16_t h) { return __uint_as_float(((unsigned)h) << 16); }
;   __device__ __forceinline__ void c4(int g, int rig, int col, f32x4 v) const {
;     const size_t o = ((size_t)g * 2048 + rig) * 1024 + col;
;     f32x4 bs;
;     if (BASE_F32) bs = __builtin_nontemporal_load((const f32x4*)((const float*)base + o));
;     else {
;       const uint2 u = *(const uint2*)((const bf16_t*)base + o);
;       bs[0] = bf2f((bf16_t)(u.x & 0xffff)); bs[1] = bf2f((bf16_t)(u.x >> 16)); bs[2] = bf2f((bf16_t)(u.y & 0xffff)); bs[3] = bf2f((bf16_t)(u.y >> 16));
;     }
;     const f32x4 gt = *(const f32x4*)(gate + (size_t)g * 6144 + col);
;     f32x4 bi = {0.f, 0.f, 0.f, 0.f};
;     if (bias) bi = *(const f32x4*)(bias + col);
;     f32x4 r;
; #pragma unroll
;     for (int j = 0; j < 4; ++j) r[j] = bs[j] + gt[j] * (v[j] + bi[j]);
;     uint2 w; w.x = pack2(r[0], r[1]); w.y = pack2(r[2], r[3]);
;     *(uint2*)(X16 + o) = w;
;   }
; template <bool SWAP, class Epi, bool THIN = false> ...
;     ...
;     if constexpr (Epi::KIND == 0) {
; #pragma unroll
;       for (int m = 0; m < 4; ++m) {
;         const int rig = rig0 + rw + m * 16 + fr_e;
;         if constexpr (Epi::ROWSUM) {
;           float ss = 0.f;
; #pragma unroll
;           for (int n = 0; n < 8; ++n) {
;             const int col = nt * 256 + wc_e * 128 + n * 16 + fq_e * 4;
;             if (col < N) ss += epi.c4(g, rig, col, acc[m][n]);
;           }
;           ss += __shfl_xor(ss, 16); ss += __shfl_xor(ss, 32);
;           if (fq_e == 0) epi.rowsum(g, rig, nt * 2 + wc_e, ss);
;         } else {
; #pragma unroll
;           for (int n = 0; n < 8; ++n) {
;             const int col = nt * 256 + wc_e * 128 + n * 16 + fq_e * 4;
;             if (col < N) epi.c4(g, rig, col, acc[m][n]);
	v_mfma_f32_16x16x32_bf16 v[98:101], v[184:187], v[176:179], v[132:135]
	v_ashrrev_i32_e32 v7, 8, v130
	v_add_u32_e32 v7, s5, v7
	v_ashrrev_i32_e32 v8, 31, v7
	v_lshrrev_b32_e32 v8, 28, v8
	v_add_u32_e32 v8, v7, v8
	v_ashrrev_i32_e32 v134, 4, v8
	v_lshlrev_b32_e32 v8, 11, v134
	v_lshlrev_b32_e32 v7, 7, v7
	v_sub_u32_e32 v7, v7, v8
	v_lshrrev_b32_e32 v8, 1, v130
	v_and_b32_e32 v6, 15, v130
	v_and_b32_e32 v8, 64, v8
	v_mfma_f32_16x16x32_bf16 v[66:69], v[184:187], v[208:211], v[136:139]
	v_ashrrev_i32_e32 v135, 31, v134
	s_nop 1
	v_or3_b32 v136, v7, v8, v6
	v_lshlrev_b32_e32 v6, 1, v130
	v_and_b32_e32 v132, 0x80, v6
	v_mfma_f32_16x16x32_bf16 v[6:9], v[180:183], v[216:219], v[2:5]
	v_ashrrev_i32_e32 v137, 31, v136
	v_lshlrev_b64 v[138:139], 21, v[134:135]
	v_lshlrev_b64 v[140:141], 10, v[136:137]
	v_lshrrev_b32_e32 v2, 2, v130
	v_and_b32_e32 v2, 12, v2
	v_mfma_f32_16x16x32_bf16 v[102:105], v[180:183], v[176:179], v[70:73]
	v_or3_b32 v132, v2, v132, s4
	v_mad_i64_i32 v[134:135], s[4:5], v134, s31, 0
	v_mfma_f32_16x16x32_bf16 v[70:73], v[180:183], v[208:211], v[192:195]
	v_lshl_add_u64 v[140:141], v[140:141], 0, v[138:139]
	v_cmp_gt_i32_e32 vcc, s34, v132
	v_ashrrev_i32_e32 v133, 31, v132
	v_mfma_f32_16x16x32_bf16 v[38:41], v[180:183], v[212:215], v[220:223]
	v_lshl_add_u64 v[134:135], s[24:25], 0, v[134:135]
	v_lshl_add_u64 v[140:141], v[140:141], 1, s[20:21]
	v_mfma_f32_16x16x32_bf16 v[34:37], v[184:187], v[212:215], v[168:171]
	v_mfma_f32_16x16x32_bf16 v[2:5], v[184:187], v[216:219], v[172:175]
	v_lshl_add_u64 v[218:219], v[132:133], 2, v[134:135]
	global_load_dwordx4 v[198:201], v[218:219], off
	global_load_dwordx4 v[202:205], v[218:219], off offset:64
	global_load_dwordx4 v[206:209], v[218:219], off offset:128
	global_load_dwordx4 v[210:213], v[218:219], off offset:192
	global_load_dwordx4 v[214:217], v[218:219], off offset:256
	global_load_dwordx4 v[224:227], v[218:219], off offset:320
	global_load_dwordx4 v[228:231], v[218:219], off offset:384
	global_load_dwordx4 v[232:235], v[218:219], off offset:448
	s_nop 0
	v_lshl_add_u64 v[172:173], v[132:133], 1, v[140:141]
	v_lshl_add_u64 v[196:197], v[132:133], 1, v[140:141]
	global_load_dwordx2 v[176:177], v[196:197], off
	global_load_dwordx2 v[178:179], v[196:197], off offset:32
	global_load_dwordx2 v[180:181], v[196:197], off offset:64
	global_load_dwordx2 v[182:183], v[196:197], off offset:96
	global_load_dwordx2 v[184:185], v[196:197], off offset:128
	global_load_dwordx2 v[186:187], v[196:197], off offset:160
	global_load_dwordx2 v[188:189], v[196:197], off offset:192
	global_load_dwordx2 v[190:191], v[196:197], off offset:224
	v_add_f32_e32 v126, 0, v126
	v_add_f32_e32 v127, 0, v127
	v_add_f32_e32 v128, 0, v128
	v_add_f32_e32 v129, 0, v129
	s_waitcnt vmcnt(7)
	v_lshlrev_b32_e32 v130, 16, v176
	v_and_b32_e32 v137, 0xffff0000, v176
	v_lshlrev_b32_e32 v167, 16, v177
	v_and_b32_e32 v174, 0xffff0000, v177
	v_fmac_f32_e32 v130, v126, v198
	v_fmac_f32_e32 v137, v127, v199
	v_fmac_f32_e32 v167, v128, v200
	v_fmac_f32_e32 v174, v129, v201
	v_cvt_pk_bf16_f32 v126, v130, v137
	v_cvt_pk_bf16_f32 v127, v167, v174
	global_store_dwordx2 v[172:173], v[126:127], off
	v_or_b32_e32 v126, 16, v132
	v_lshl_add_u64 v[168:169], v[132:133], 1, v[140:141]
	v_add_f32_e32 v122, 0, v122
	v_add_f32_e32 v123, 0, v123
	v_add_f32_e32 v124, 0, v124
	v_add_f32_e32 v125, 0, v125
	s_waitcnt vmcnt(7)
	v_lshlrev_b32_e32 v130, 16, v178
	v_and_b32_e32 v137, 0xffff0000, v178
	v_lshlrev_b32_e32 v167, 16, v179
	v_and_b32_e32 v170, 0xffff0000, v179
	v_fmac_f32_e32 v130, v122, v202
	v_fmac_f32_e32 v137, v123, v203
	v_fmac_f32_e32 v167, v124, v204
	v_fmac_f32_e32 v170, v125, v205
	v_cvt_pk_bf16_f32 v122, v130, v137
	v_cvt_pk_bf16_f32 v123, v167, v170
	global_store_dwordx2 v[168:169], v[122:123], off offset:32
	v_or_b32_e32 v122, 32, v132
	v_lshl_add_u64 v[126:127], v[132:133], 1, v[140:141]
	v_add_f32_e32 v118, 0, v118
	v_add_f32_e32 v119, 0, v119
	v_add_f32_e32 v120, 0, v120
	v_add_f32_e32 v121, 0, v121
	s_waitcnt vmcnt(7)
	v_lshlrev_b32_e32 v130, 16, v180
	v_and_b32_e32 v128, 0xffff0000, v180
	v_lshlrev_b32_e32 v137, 16, v181
	v_and_b32_e32 v129, 0xffff0000, v181
	v_fmac_f32_e32 v130, v118, v206
	v_fmac_f32_e32 v128, v119, v207
	v_fmac_f32_e32 v137, v120, v208
	v_fmac_f32_e32 v129, v121, v209
	v_cvt_pk_bf16_f32 v118, v130, v128
	v_cvt_pk_bf16_f32 v119, v137, v129
	global_store_dwordx2 v[126:127], v[118:119], off offset:64
	v_or_b32_e32 v118, 48, v132
	v_lshl_add_u64 v[122:123], v[132:133], 1, v[140:141]
	v_add_f32_e32 v114, 0, v114
	v_add_f32_e32 v115, 0, v115
	v_add_f32_e32 v116, 0, v116
	v_add_f32_e32 v117, 0, v117
	s_waitcnt vmcnt(7)
	v_lshlrev_b32_e32 v126, 16, v182
	v_and_b32_e32 v124, 0xffff0000, v182
	v_lshlrev_b32_e32 v127, 16, v183
	v_and_b32_e32 v125, 0xffff0000, v183
	v_fmac_f32_e32 v126, v114, v210
	v_fmac_f32_e32 v124, v115, v211
	v_fmac_f32_e32 v127, v116, v212
	v_fmac_f32_e32 v125, v117, v213
	v_cvt_pk_bf16_f32 v114, v126, v124
	v_cvt_pk_bf16_f32 v115, v127, v125
	global_store_dwordx2 v[122:123], v[114:115], off offset:96
	v_or_b32_e32 v114, 64, v132
	v_lshl_add_u64 v[118:119], v[132:133], 1, v[140:141]
	v_add_f32_e32 v110, 0, v110
	v_add_f32_e32 v111, 0, v111
	v_add_f32_e32 v112, 0, v112
	v_add_f32_e32 v113, 0, v113
	s_waitcnt vmcnt(7)
	v_lshlrev_b32_e32 v122, 16, v184
	v_and_b32_e32 v120, 0xffff0000, v184
	v_lshlrev_b32_e32 v123, 16, v185
	v_and_b32_e32 v121, 0xffff0000, v185
	v_fmac_f32_e32 v122, v110, v214
	v_fmac_f32_e32 v120, v111, v215
	v_fmac_f32_e32 v123, v112, v216
	v_fmac_f32_e32 v121, v113, v217
	v_cvt_pk_bf16_f32 v110, v122, v120
	v_cvt_pk_bf16_f32 v111, v123, v121
	global_store_dwordx2 v[118:119], v[110:111], off offset:128
	v_or_b32_e32 v110, 0x50, v132
	v_lshl_add_u64 v[114:115], v[132:133], 1, v[140:141]
	v_add_f32_e32 v106, 0, v106
	v_add_f32_e32 v107, 0, v107
	v_add_f32_e32 v108, 0, v108
	v_add_f32_e32 v109, 0, v109
	s_waitcnt vmcnt(7)
; __device__ __forceinline__ unsigned pack2(float a, float b) { unsigned r; asm("v_cvt_pk_bf16_f32 %0, %1, %2" : "=v"(r) : "v"(a), "v"(b)); return r; }
; __device__ __forceinline__ float bf2f(bf16_t h) { return __uint_as_float(((unsigned)h) << 16); }
;   __device__ __forceinline__ void c4(int g, int rig, int col, f32x4 v) const {
;     const size_t o = ((size_t)g * 2048 + rig) * 1024 + col;
;     f32x4 bs;
;     if (BASE_F32) bs = __builtin_nontemporal_load((const f32x4*)((const float*)base + o));
;     else {
;       const uint2 u = *(const uint2*)((const bf16_t*)base + o);
;       bs[0] = bf2f((bf16_t)(u.x & 0xffff)); bs[1] = bf2f((bf16_t)(u.x >> 16)); bs[2] = bf2f((bf16_t)(u.y & 0xffff)); bs[3] = bf2f((bf16_t)(u.y >> 16));
;     }
;     const f32x4 gt = *(const f32x4*)(gate + (size_t)g * 6144 + col);
;     f32x4 bi = {0.f, 0.f, 0.f, 0.f};
;     if (bias) bi = *(const f32x4*)(bias + col);
;     f32x4 r;
; #pragma unroll
;     for (int j = 0; j < 4; ++j) r[j] = bs[j] + gt[j] * (v[j] + bi[j]);
;     uint2 w; w.x = pack2(r[0], r[1]); w.y = pack2(r[2], r[3]);
;     *(uint2*)(X16 + o) = w;
;   }
; template <bool SWAP, class Epi, bool THIN = false> ...
;     ...
;     if constexpr (Epi::KIND == 0) {
; #pragma unroll
;       for (int m = 0; m < 4; ++m) {
;         const int rig = rig0 + rw + m * 16 + fr_e;
;         if constexpr (Epi::ROWSUM) {
;           float ss = 0.f;
; #pragma unroll
;           for (int n = 0; n < 8; ++n) {
;             const int col = nt * 256 + wc_e * 128 + n * 16 + fq_e * 4;
;             if (col < N) ss += epi.c4(g, rig, col, acc[m][n]);
;           }
;           ss += __shfl_xor(ss, 16); ss += __shfl_xor(ss, 32);
;           if (fq_e == 0) epi.rowsum(g, rig, nt * 2 + wc_e, ss);
;         } else {
; #pragma unroll
;           for (int n = 0; n < 8; ++n) {
;             const int col = nt * 256 + wc_e * 128 + n * 16 + fq_e * 4;
;             if (col < N) epi.c4(g, rig, col, acc[m][n]);
	v_lshlrev_b32_e32 v118, 16, v186
	v_and_b32_e32 v116, 0xffff0000, v186
	v_lshlrev_b32_e32 v119, 16, v187
	v_and_b32_e32 v117, 0xffff0000, v187
	v_fmac_f32_e32 v118, v106, v224
	v_fmac_f32_e32 v116, v107, v225
	v_fmac_f32_e32 v119, v108, v226
	v_fmac_f32_e32 v117, v109, v227
	v_cvt_pk_bf16_f32 v106, v118, v116
	v_cvt_pk_bf16_f32 v107, v119, v117
	global_store_dwordx2 v[114:115], v[106:107], off offset:160
	v_or_b32_e32 v106, 0x60, v132
	v_lshl_add_u64 v[110:111], v[132:133], 1, v[140:141]
	v_add_f32_e32 v102, 0, v102
	v_add_f32_e32 v103, 0, v103
	v_add_f32_e32 v104, 0, v104
	v_add_f32_e32 v105, 0, v105
	s_waitcnt vmcnt(7)
	v_lshlrev_b32_e32 v114, 16, v188
	v_and_b32_e32 v112, 0xffff0000, v188
	v_lshlrev_b32_e32 v115, 16, v189
	v_and_b32_e32 v113, 0xffff0000, v189
	v_fmac_f32_e32 v114, v102, v228
	v_fmac_f32_e32 v112, v103, v229
	v_fmac_f32_e32 v115, v104, v230
	v_fmac_f32_e32 v113, v105, v231
	v_cvt_pk_bf16_f32 v102, v114, v112
	v_cvt_pk_bf16_f32 v103, v115, v113
	global_store_dwordx2 v[110:111], v[102:103], off offset:192
	v_or_b32_e32 v102, 0x70, v132
	v_lshl_add_u64 v[106:107], v[132:133], 1, v[140:141]
	v_add_f32_e32 v98, 0, v98
	v_add_f32_e32 v99, 0, v99
	v_add_f32_e32 v100, 0, v100
	v_add_f32_e32 v101, 0, v101
	s_waitcnt vmcnt(7)
	v_lshlrev_b32_e32 v110, 16, v190
	v_and_b32_e32 v108, 0xffff0000, v190
	v_lshlrev_b32_e32 v111, 16, v191
	v_and_b32_e32 v109, 0xffff0000, v191
	v_fmac_f32_e32 v110, v98, v232
	v_fmac_f32_e32 v108, v99, v233
	v_fmac_f32_e32 v111, v100, v234
	v_fmac_f32_e32 v109, v101, v235
	v_cvt_pk_bf16_f32 v98, v110, v108
	v_cvt_pk_bf16_f32 v99, v111, v109
	global_store_dwordx2 v[106:107], v[98:99], off offset:224
	v_or_b32_e32 v98, 16, v136
	v_ashrrev_i32_e32 v99, 31, v98
	v_lshlrev_b64 v[98:99], 10, v[98:99]
	v_lshl_add_u64 v[98:99], v[98:99], 0, v[138:139]
	v_lshl_add_u64 v[98:99], v[98:99], 1, s[20:21]
	v_lshl_add_u64 v[104:105], v[132:133], 1, v[98:99]
	v_lshl_add_u64 v[196:197], v[132:133], 1, v[98:99]
	global_load_dwordx2 v[176:177], v[196:197], off
	global_load_dwordx2 v[178:179], v[196:197], off offset:32
	global_load_dwordx2 v[180:181], v[196:197], off offset:64
	global_load_dwordx2 v[182:183], v[196:197], off offset:96
	global_load_dwordx2 v[184:185], v[196:197], off offset:128
	global_load_dwordx2 v[186:187], v[196:197], off offset:160
	global_load_dwordx2 v[188:189], v[196:197], off offset:192
	global_load_dwordx2 v[190:191], v[196:197], off offset:224
	v_add_f32_e32 v94, 0, v94
	v_add_f32_e32 v95, 0, v95
	v_add_f32_e32 v96, 0, v96
	v_add_f32_e32 v97, 0, v97
	s_waitcnt vmcnt(7)
	v_lshlrev_b32_e32 v108, 16, v176
	v_and_b32_e32 v106, 0xffff0000, v176
	v_lshlrev_b32_e32 v109, 16, v177
	v_and_b32_e32 v107, 0xffff0000, v177
	v_fmac_f32_e32 v108, v94, v198
	v_fmac_f32_e32 v106, v95, v199
	v_fmac_f32_e32 v109, v96, v200
	v_fmac_f32_e32 v107, v97, v201
	v_cvt_pk_bf16_f32 v94, v108, v106
	v_cvt_pk_bf16_f32 v95, v109, v107
	global_store_dwordx2 v[104:105], v[94:95], off
	v_lshl_add_u64 v[100:101], v[132:133], 1, v[98:99]
	v_add_f32_e32 v90, 0, v90
	v_add_f32_e32 v91, 0, v91
	v_add_f32_e32 v92, 0, v92
	v_add_f32_e32 v93, 0, v93
	s_waitcnt vmcnt(7)
	v_lshlrev_b32_e32 v104, 16, v178
	v_and_b32_e32 v102, 0xffff0000, v178
	v_lshlrev_b32_e32 v105, 16, v179
	v_and_b32_e32 v103, 0xffff0000, v179
	v_fmac_f32_e32 v104, v90, v202
	v_fmac_f32_e32 v102, v91, v203
	v_fmac_f32_e32 v105, v92, v204
	v_fmac_f32_e32 v103, v93, v205
	v_cvt_pk_bf16_f32 v90, v104, v102
	v_cvt_pk_bf16_f32 v91, v105, v103
	global_store_dwordx2 v[100:101], v[90:91], off offset:32
	v_lshl_add_u64 v[94:95], v[132:133], 1, v[98:99]
	v_add_f32_e32 v86, 0, v86
	v_add_f32_e32 v87, 0, v87
	v_add_f32_e32 v88, 0, v88
	v_add_f32_e32 v89, 0, v89
	s_waitcnt vmcnt(7)
	v_lshlrev_b32_e32 v100, 16, v180
	v_and_b32_e32 v96, 0xffff0000, v180
	v_lshlrev_b32_e32 v101, 16, v181
	v_and_b32_e32 v97, 0xffff0000, v181
	v_fmac_f32_e32 v100, v86, v206
	v_fmac_f32_e32 v96, v87, v207
	v_fmac_f32_e32 v101, v88, v208
	v_fmac_f32_e32 v97, v89, v209
	v_cvt_pk_bf16_f32 v86, v100, v96
	v_cvt_pk_bf16_f32 v87, v101, v97
	global_store_dwordx2 v[94:95], v[86:87], off offset:64
	v_lshl_add_u64 v[90:91], v[132:133], 1, v[98:99]
	v_add_f32_e32 v82, 0, v82
	v_add_f32_e32 v83, 0, v83
	v_add_f32_e32 v84, 0, v84
	v_add_f32_e32 v85, 0, v85
	s_waitcnt vmcnt(7)
	v_lshlrev_b32_e32 v94, 16, v182
	v_and_b32_e32 v92, 0xffff0000, v182
	v_lshlrev_b32_e32 v95, 16, v183
	v_and_b32_e32 v93, 0xffff0000, v183
	v_fmac_f32_e32 v94, v82, v210
	v_fmac_f32_e32 v92, v83, v211
	v_fmac_f32_e32 v95, v84, v212
	v_fmac_f32_e32 v93, v85, v213
	v_cvt_pk_bf16_f32 v82, v94, v92
	v_cvt_pk_bf16_f32 v83, v95, v93
	global_store_dwordx2 v[90:91], v[82:83], off offset:96
	v_lshl_add_u64 v[86:87], v[132:133], 1, v[98:99]
	v_add_f32_e32 v78, 0, v78
	v_add_f32_e32 v79, 0, v79
	v_add_f32_e32 v80, 0, v80
	v_add_f32_e32 v81, 0, v81
	s_waitcnt vmcnt(7)
	v_lshlrev_b32_e32 v90, 16, v184
	v_and_b32_e32 v88, 0xffff0000, v184
	v_lshlrev_b32_e32 v91, 16, v185
	v_and_b32_e32 v89, 0xffff0000, v185
	v_fmac_f32_e32 v90, v78, v214
	v_fmac_f32_e32 v88, v79, v215
	v_fmac_f32_e32 v91, v80, v216
	v_fmac_f32_e32 v89, v81, v217
	v_cvt_pk_bf16_f32 v78, v90, v88
	v_cvt_pk_bf16_f32 v79, v91, v89
	global_store_dwordx2 v[86:87], v[78:79], off offset:128
	v_lshl_add_u64 v[82:83], v[132:133], 1, v[98:99]
	v_add_f32_e32 v74, 0, v74
	v_add_f32_e32 v75, 0, v75
	v_add_f32_e32 v76, 0, v76
	v_add_f32_e32 v77, 0, v77
	s_waitcnt vmcnt(7)
; __device__ __forceinline__ unsigned pack2(float a, float b) { unsigned r; asm("v_cvt_pk_bf16_f32 %0, %1, %2" : "=v"(r) : "v"(a), "v"(b)); return r; }
; __device__ __forceinline__ float bf2f(bf16_t h) { return __uint_as_float(((unsigned)h) << 16); }
;   __device__ __forceinline__ void c4(int g, int rig, int col, f32x4 v) const {
;     const size_t o = ((size_t)g * 2048 + rig) * 1024 + col;
;     f32x4 bs;
;     if (BASE_F32) bs = __builtin_nontemporal_load((const f32x4*)((const float*)base + o));
;     else {
;       const uint2 u = *(const uint2*)((const bf16_t*)base + o);
;       bs[0] = bf2f((bf16_t)(u.x & 0xffff)); bs[1] = bf2f((bf16_t)(u.x >> 16)); bs[2] = bf2f((bf16_t)(u.y & 0xffff)); bs[3] = bf2f((bf16_t)(u.y >> 16));
;     }
;     const f32x4 gt = *(const f32x4*)(gate + (size_t)g * 6144 + col);
;     f32x4 bi = {0.f, 0.f, 0.f, 0.f};
;     if (bias) bi = *(const f32x4*)(bias + col);
;     f32x4 r;
; #pragma unroll
;     for (int j = 0; j < 4; ++j) r[j] = bs[j] + gt[j] * (v[j] + bi[j]);
;     uint2 w; w.x = pack2(r[0], r[1]); w.y = pack2(r[2], r[3]);
;     *(uint2*)(X16 + o) = w;
;   }
; template <bool SWAP, class Epi, bool THIN = false> ...
;     ...
;         } else {
; #pragma unroll
;           for (int n = 0; n < 8; ++n) {
;             const int col = nt * 256 + wc_e * 128 + n * 16 + fq_e * 4;
;             if (col < N) epi.c4(g, rig, col, acc[m][n]);
;           }
	v_lshlrev_b32_e32 v86, 16, v186
	v_and_b32_e32 v84, 0xffff0000, v186
	v_lshlrev_b32_e32 v87, 16, v187
	v_and_b32_e32 v85, 0xffff0000, v187
	v_fmac_f32_e32 v86, v74, v224
	v_fmac_f32_e32 v84, v75, v225
	v_fmac_f32_e32 v87, v76, v226
	v_fmac_f32_e32 v85, v77, v227
	v_cvt_pk_bf16_f32 v74, v86, v84
	v_cvt_pk_bf16_f32 v75, v87, v85
	global_store_dwordx2 v[82:83], v[74:75], off offset:160
	v_lshl_add_u64 v[78:79], v[132:133], 1, v[98:99]
	v_add_f32_e32 v70, 0, v70
	v_add_f32_e32 v71, 0, v71
	v_add_f32_e32 v72, 0, v72
	v_add_f32_e32 v73, 0, v73
	s_waitcnt vmcnt(7)
	v_lshlrev_b32_e32 v82, 16, v188
	v_and_b32_e32 v80, 0xffff0000, v188
	v_lshlrev_b32_e32 v83, 16, v189
	v_and_b32_e32 v81, 0xffff0000, v189
	v_fmac_f32_e32 v82, v70, v228
	v_fmac_f32_e32 v80, v71, v229
	v_fmac_f32_e32 v83, v72, v230
	v_fmac_f32_e32 v81, v73, v231
	v_cvt_pk_bf16_f32 v70, v82, v80
	v_cvt_pk_bf16_f32 v71, v83, v81
	global_store_dwordx2 v[78:79], v[70:71], off offset:192
	v_lshl_add_u64 v[74:75], v[132:133], 1, v[98:99]
	v_add_f32_e32 v66, 0, v66
	v_add_f32_e32 v67, 0, v67
	v_add_f32_e32 v68, 0, v68
	v_add_f32_e32 v69, 0, v69
	s_waitcnt vmcnt(7)
	v_lshlrev_b32_e32 v78, 16, v190
	v_and_b32_e32 v76, 0xffff0000, v190
	v_lshlrev_b32_e32 v79, 16, v191
	v_and_b32_e32 v77, 0xffff0000, v191
	v_fmac_f32_e32 v78, v66, v232
	v_fmac_f32_e32 v76, v67, v233
	v_fmac_f32_e32 v79, v68, v234
	v_fmac_f32_e32 v77, v69, v235
	v_cvt_pk_bf16_f32 v66, v78, v76
	v_cvt_pk_bf16_f32 v67, v79, v77
	global_store_dwordx2 v[74:75], v[66:67], off offset:224
	v_or_b32_e32 v66, 32, v136
	v_ashrrev_i32_e32 v67, 31, v66
	v_lshlrev_b64 v[66:67], 10, v[66:67]
	v_lshl_add_u64 v[66:67], v[66:67], 0, v[138:139]
	v_lshl_add_u64 v[66:67], v[66:67], 1, s[20:21]
	v_lshl_add_u64 v[72:73], v[132:133], 1, v[66:67]
	v_lshl_add_u64 v[196:197], v[132:133], 1, v[66:67]
	global_load_dwordx2 v[176:177], v[196:197], off
	global_load_dwordx2 v[178:179], v[196:197], off offset:32
	global_load_dwordx2 v[180:181], v[196:197], off offset:64
	global_load_dwordx2 v[182:183], v[196:197], off offset:96
	global_load_dwordx2 v[184:185], v[196:197], off offset:128
	global_load_dwordx2 v[186:187], v[196:197], off offset:160
	global_load_dwordx2 v[188:189], v[196:197], off offset:192
	global_load_dwordx2 v[190:191], v[196:197], off offset:224
	v_add_f32_e32 v62, 0, v62
	v_add_f32_e32 v63, 0, v63
	v_add_f32_e32 v64, 0, v64
	v_add_f32_e32 v65, 0, v65
	s_waitcnt vmcnt(7)
	v_lshlrev_b32_e32 v76, 16, v176
	v_and_b32_e32 v74, 0xffff0000, v176
	v_lshlrev_b32_e32 v77, 16, v177
	v_and_b32_e32 v75, 0xffff0000, v177
	v_fmac_f32_e32 v76, v62, v198
	v_fmac_f32_e32 v74, v63, v199
	v_fmac_f32_e32 v77, v64, v200
	v_fmac_f32_e32 v75, v65, v201
	v_cvt_pk_bf16_f32 v62, v76, v74
	v_cvt_pk_bf16_f32 v63, v77, v75
	global_store_dwordx2 v[72:73], v[62:63], off
	v_lshl_add_u64 v[68:69], v[132:133], 1, v[66:67]
	v_add_f32_e32 v58, 0, v58
	v_add_f32_e32 v59, 0, v59
	v_add_f32_e32 v60, 0, v60
	v_add_f32_e32 v61, 0, v61
	s_waitcnt vmcnt(7)
	v_lshlrev_b32_e32 v72, 16, v178
	v_and_b32_e32 v70, 0xffff0000, v178
	v_lshlrev_b32_e32 v73, 16, v179
	v_and_b32_e32 v71, 0xffff0000, v179
	v_fmac_f32_e32 v72, v58, v202
	v_fmac_f32_e32 v70, v59, v203
	v_fmac_f32_e32 v73, v60, v204
	v_fmac_f32_e32 v71, v61, v205
	v_cvt_pk_bf16_f32 v58, v72, v70
	v_cvt_pk_bf16_f32 v59, v73, v71
	global_store_dwordx2 v[68:69], v[58:59], off offset:32
	v_lshl_add_u64 v[62:63], v[132:133], 1, v[66:67]
	v_add_f32_e32 v54, 0, v54
	v_add_f32_e32 v55, 0, v55
	v_add_f32_e32 v56, 0, v56
	v_add_f32_e32 v57, 0, v57
	s_waitcnt vmcnt(7)
	v_lshlrev_b32_e32 v68, 16, v180
	v_and_b32_e32 v64, 0xffff0000, v180
	v_lshlrev_b32_e32 v69, 16, v181
	v_and_b32_e32 v65, 0xffff0000, v181
	v_fmac_f32_e32 v68, v54, v206
	v_fmac_f32_e32 v64, v55, v207
	v_fmac_f32_e32 v69, v56, v208
	v_fmac_f32_e32 v65, v57, v209
	v_cvt_pk_bf16_f32 v54, v68, v64
	v_cvt_pk_bf16_f32 v55, v69, v65
	global_store_dwordx2 v[62:63], v[54:55], off offset:64
	v_lshl_add_u64 v[58:59], v[132:133], 1, v[66:67]
	v_add_f32_e32 v50, 0, v50
	v_add_f32_e32 v51, 0, v51
	v_add_f32_e32 v52, 0, v52
	v_add_f32_e32 v53, 0, v53
	s_waitcnt vmcnt(7)
	v_lshlrev_b32_e32 v62, 16, v182
	v_and_b32_e32 v60, 0xffff0000, v182
	v_lshlrev_b32_e32 v63, 16, v183
	v_and_b32_e32 v61, 0xffff0000, v183
	v_fmac_f32_e32 v62, v50, v210
	v_fmac_f32_e32 v60, v51, v211
	v_fmac_f32_e32 v63, v52, v212
	v_fmac_f32_e32 v61, v53, v213
	v_cvt_pk_bf16_f32 v50, v62, v60
	v_cvt_pk_bf16_f32 v51, v63, v61
	global_store_dwordx2 v[58:59], v[50:51], off offset:96
	v_lshl_add_u64 v[54:55], v[132:133], 1, v[66:67]
	v_add_f32_e32 v46, 0, v46
	v_add_f32_e32 v47, 0, v47
	v_add_f32_e32 v48, 0, v48
	v_add_f32_e32 v49, 0, v49
	s_waitcnt vmcnt(7)
	v_lshlrev_b32_e32 v58, 16, v184
	v_and_b32_e32 v56, 0xffff0000, v184
	v_lshlrev_b32_e32 v59, 16, v185
	v_and_b32_e32 v57, 0xffff0000, v185
	v_fmac_f32_e32 v58, v46, v214
	v_fmac_f32_e32 v56, v47, v215
	v_fmac_f32_e32 v59, v48, v216
	v_fmac_f32_e32 v57, v49, v217
	v_cvt_pk_bf16_f32 v46, v58, v56
	v_cvt_pk_bf16_f32 v47, v59, v57
	global_store_dwordx2 v[54:55], v[46:47], off offset:128
	v_lshl_add_u64 v[50:51], v[132:133], 1, v[66:67]
	v_add_f32_e32 v42, 0, v42
	v_add_f32_e32 v43, 0, v43
	v_add_f32_e32 v44, 0, v44
	v_add_f32_e32 v45, 0, v45
	s_waitcnt vmcnt(7)
	v_lshlrev_b32_e32 v54, 16, v186
	v_and_b32_e32 v52, 0xffff0000, v186
	v_lshlrev_b32_e32 v55, 16, v187
	v_and_b32_e32 v53, 0xffff0000, v187
	v_fmac_f32_e32 v54, v42, v224
	v_fmac_f32_e32 v52, v43, v225
	v_fmac_f32_e32 v55, v44, v226
	v_fmac_f32_e32 v53, v45, v227
	v_cvt_pk_bf16_f32 v42, v54, v52
	v_cvt_pk_bf16_f32 v43, v55, v53
	global_store_dwordx2 v[50:51], v[42:43], off offset:160
	v_lshl_add_u64 v[46:47], v[132:133], 1, v[66:67]
	v_add_f32_e32 v38, 0, v38
	v_add_f32_e32 v39, 0, v39
	v_add_f32_e32 v40, 0, v40
	v_add_f32_e32 v41, 0, v41
	s_waitcnt vmcnt(7)
; __device__ __forceinline__ unsigned pack2(float a, float b) { unsigned r; asm("v_cvt_pk_bf16_f32 %0, %1, %2" : "=v"(r) : "v"(a), "v"(b)); return r; }
; __device__ __forceinline__ float bf2f(bf16_t h) { return __uint_as_float(((unsigned)h) << 16); }
;   __device__ __forceinline__ void c4(int g, int rig, int col, f32x4 v) const {
;     const size_t o = ((size_t)g * 2048 + rig) * 1024 + col;
;     f32x4 bs;
;     if (BASE_F32) bs = __builtin_nontemporal_load((const f32x4*)((const float*)base + o));
;     else {
;       const uint2 u = *(const uint2*)((const bf16_t*)base + o);
;       bs[0] = bf2f((bf16_t)(u.x & 0xffff)); bs[1] = bf2f((bf16_t)(u.x >> 16)); bs[2] = bf2f((bf16_t)(u.y & 0xffff)); bs[3] = bf2f((bf16_t)(u.y >> 16));
;     }
;     const f32x4 gt = *(const f32x4*)(gate + (size_t)g * 6144 + col);
;     f32x4 bi = {0.f, 0.f, 0.f, 0.f};
;     if (bias) bi = *(const f32x4*)(bias + col);
;     f32x4 r;
; #pragma unroll
;     for (int j = 0; j < 4; ++j) r[j] = bs[j] + gt[j] * (v[j] + bi[j]);
;     uint2 w; w.x = pack2(r[0], r[1]); w.y = pack2(r[2], r[3]);
;     *(uint2*)(X16 + o) = w;
;   }
; template <bool SWAP, class Epi, bool THIN = false> ...
;     ...
;         } else {
; #pragma unroll
;           for (int n = 0; n < 8; ++n) {
;             const int col = nt * 256 + wc_e * 128 + n * 16 + fq_e * 4;
;             if (col < N) epi.c4(g, rig, col, acc[m][n]);
;           }
	v_lshlrev_b32_e32 v50, 16, v188
	v_and_b32_e32 v48, 0xffff0000, v188
	v_lshlrev_b32_e32 v51, 16, v189
	v_and_b32_e32 v49, 0xffff0000, v189
	v_fmac_f32_e32 v50, v38, v228
	v_fmac_f32_e32 v48, v39, v229
	v_fmac_f32_e32 v51, v40, v230
	v_fmac_f32_e32 v49, v41, v231
	v_cvt_pk_bf16_f32 v38, v50, v48
	v_cvt_pk_bf16_f32 v39, v51, v49
	global_store_dwordx2 v[46:47], v[38:39], off offset:192
	v_lshl_add_u64 v[42:43], v[132:133], 1, v[66:67]
	v_add_f32_e32 v34, 0, v34
	v_add_f32_e32 v35, 0, v35
	v_add_f32_e32 v36, 0, v36
	v_add_f32_e32 v37, 0, v37
	s_waitcnt vmcnt(7)
	v_lshlrev_b32_e32 v46, 16, v190
	v_and_b32_e32 v44, 0xffff0000, v190
	v_lshlrev_b32_e32 v47, 16, v191
	v_and_b32_e32 v45, 0xffff0000, v191
	v_fmac_f32_e32 v46, v34, v232
	v_fmac_f32_e32 v44, v35, v233
	v_fmac_f32_e32 v47, v36, v234
	v_fmac_f32_e32 v45, v37, v235
	v_cvt_pk_bf16_f32 v34, v46, v44
	v_cvt_pk_bf16_f32 v35, v47, v45
	global_store_dwordx2 v[42:43], v[34:35], off offset:224
	v_or_b32_e32 v34, 48, v136
	v_ashrrev_i32_e32 v35, 31, v34
	v_lshlrev_b64 v[34:35], 10, v[34:35]
	v_lshl_add_u64 v[34:35], v[34:35], 0, v[138:139]
	v_lshl_add_u64 v[34:35], v[34:35], 1, s[20:21]
	v_lshl_add_u64 v[40:41], v[132:133], 1, v[34:35]
	v_lshl_add_u64 v[196:197], v[132:133], 1, v[34:35]
	global_load_dwordx2 v[176:177], v[196:197], off
	global_load_dwordx2 v[178:179], v[196:197], off offset:32
	global_load_dwordx2 v[180:181], v[196:197], off offset:64
	global_load_dwordx2 v[182:183], v[196:197], off offset:96
	global_load_dwordx2 v[184:185], v[196:197], off offset:128
	global_load_dwordx2 v[186:187], v[196:197], off offset:160
	global_load_dwordx2 v[188:189], v[196:197], off offset:192
	global_load_dwordx2 v[190:191], v[196:197], off offset:224
	v_add_f32_e32 v30, 0, v30
	v_add_f32_e32 v31, 0, v31
	v_add_f32_e32 v32, 0, v32
	v_add_f32_e32 v33, 0, v33
	s_waitcnt vmcnt(7)
	v_lshlrev_b32_e32 v44, 16, v176
	v_and_b32_e32 v42, 0xffff0000, v176
	v_lshlrev_b32_e32 v45, 16, v177
	v_and_b32_e32 v43, 0xffff0000, v177
	v_fmac_f32_e32 v44, v30, v198
	v_fmac_f32_e32 v42, v31, v199
	v_fmac_f32_e32 v45, v32, v200
	v_fmac_f32_e32 v43, v33, v201
	v_cvt_pk_bf16_f32 v30, v44, v42
	v_cvt_pk_bf16_f32 v31, v45, v43
	global_store_dwordx2 v[40:41], v[30:31], off
	v_lshl_add_u64 v[36:37], v[132:133], 1, v[34:35]
	v_add_f32_e32 v26, 0, v26
	v_add_f32_e32 v27, 0, v27
	v_add_f32_e32 v28, 0, v28
	v_add_f32_e32 v29, 0, v29
	s_waitcnt vmcnt(7)
	v_lshlrev_b32_e32 v40, 16, v178
	v_and_b32_e32 v38, 0xffff0000, v178
	v_lshlrev_b32_e32 v41, 16, v179
	v_and_b32_e32 v39, 0xffff0000, v179
	v_fmac_f32_e32 v40, v26, v202
	v_fmac_f32_e32 v38, v27, v203
	v_fmac_f32_e32 v41, v28, v204
	v_fmac_f32_e32 v39, v29, v205
	v_cvt_pk_bf16_f32 v26, v40, v38
	v_cvt_pk_bf16_f32 v27, v41, v39
	global_store_dwordx2 v[36:37], v[26:27], off offset:32
	v_lshl_add_u64 v[30:31], v[132:133], 1, v[34:35]
	v_add_f32_e32 v22, 0, v22
	v_add_f32_e32 v23, 0, v23
	v_add_f32_e32 v24, 0, v24
	v_add_f32_e32 v25, 0, v25
	s_waitcnt vmcnt(7)
	v_lshlrev_b32_e32 v36, 16, v180
	v_and_b32_e32 v32, 0xffff0000, v180
	v_lshlrev_b32_e32 v37, 16, v181
	v_and_b32_e32 v33, 0xffff0000, v181
	v_fmac_f32_e32 v36, v22, v206
	v_fmac_f32_e32 v32, v23, v207
	v_fmac_f32_e32 v37, v24, v208
	v_fmac_f32_e32 v33, v25, v209
	v_cvt_pk_bf16_f32 v22, v36, v32
	v_cvt_pk_bf16_f32 v23, v37, v33
	global_store_dwordx2 v[30:31], v[22:23], off offset:64
	v_lshl_add_u64 v[26:27], v[132:133], 1, v[34:35]
	v_add_f32_e32 v18, 0, v18
	v_add_f32_e32 v19, 0, v19
	v_add_f32_e32 v20, 0, v20
	v_add_f32_e32 v21, 0, v21
	s_waitcnt vmcnt(7)
	v_lshlrev_b32_e32 v30, 16, v182
	v_and_b32_e32 v28, 0xffff0000, v182
	v_lshlrev_b32_e32 v31, 16, v183
	v_and_b32_e32 v29, 0xffff0000, v183
	v_fmac_f32_e32 v30, v18, v210
	v_fmac_f32_e32 v28, v19, v211
	v_fmac_f32_e32 v31, v20, v212
	v_fmac_f32_e32 v29, v21, v213
	v_cvt_pk_bf16_f32 v18, v30, v28
	v_cvt_pk_bf16_f32 v19, v31, v29
	global_store_dwordx2 v[26:27], v[18:19], off offset:96
	v_lshl_add_u64 v[22:23], v[132:133], 1, v[34:35]
	v_add_f32_e32 v14, 0, v14
	v_add_f32_e32 v15, 0, v15
	v_add_f32_e32 v16, 0, v16
	v_add_f32_e32 v17, 0, v17
	s_waitcnt vmcnt(7)
	v_lshlrev_b32_e32 v26, 16, v184
	v_and_b32_e32 v24, 0xffff0000, v184
	v_lshlrev_b32_e32 v27, 16, v185
	v_and_b32_e32 v25, 0xffff0000, v185
	v_fmac_f32_e32 v26, v14, v214
	v_fmac_f32_e32 v24, v15, v215
	v_fmac_f32_e32 v27, v16, v216
	v_fmac_f32_e32 v25, v17, v217
	v_cvt_pk_bf16_f32 v14, v26, v24
	v_cvt_pk_bf16_f32 v15, v27, v25
	global_store_dwordx2 v[22:23], v[14:15], off offset:128
	v_lshl_add_u64 v[18:19], v[132:133], 1, v[34:35]
	v_add_f32_e32 v10, 0, v10
	v_add_f32_e32 v11, 0, v11
	v_add_f32_e32 v12, 0, v12
	v_add_f32_e32 v13, 0, v13
	s_waitcnt vmcnt(7)
	v_lshlrev_b32_e32 v22, 16, v186
	v_and_b32_e32 v20, 0xffff0000, v186
	v_lshlrev_b32_e32 v23, 16, v187
	v_and_b32_e32 v21, 0xffff0000, v187
	v_fmac_f32_e32 v22, v10, v224
	v_fmac_f32_e32 v20, v11, v225
	v_fmac_f32_e32 v23, v12, v226
	v_fmac_f32_e32 v21, v13, v227
	v_cvt_pk_bf16_f32 v10, v22, v20
	v_cvt_pk_bf16_f32 v11, v23, v21
	global_store_dwordx2 v[18:19], v[10:11], off offset:160
	v_lshl_add_u64 v[14:15], v[132:133], 1, v[34:35]
	v_add_f32_e32 v6, 0, v6
	v_add_f32_e32 v7, 0, v7
	v_add_f32_e32 v8, 0, v8
	v_add_f32_e32 v9, 0, v9
	s_waitcnt vmcnt(7)
	v_lshlrev_b32_e32 v18, 16, v188
	v_and_b32_e32 v16, 0xffff0000, v188
	v_lshlrev_b32_e32 v19, 16, v189
	v_and_b32_e32 v17, 0xffff0000, v189
	v_fmac_f32_e32 v18, v6, v228
	v_fmac_f32_e32 v16, v7, v229
	v_fmac_f32_e32 v19, v8, v230
	v_fmac_f32_e32 v17, v9, v231
	v_cvt_pk_bf16_f32 v6, v18, v16
	v_cvt_pk_bf16_f32 v7, v19, v17
	global_store_dwordx2 v[14:15], v[6:7], off offset:192
	v_lshl_add_u64 v[10:11], v[132:133], 1, v[34:35]
	v_add_f32_e32 v2, 0, v2
	v_add_f32_e32 v3, 0, v3
	v_add_f32_e32 v4, 0, v4
	v_add_f32_e32 v5, 0, v5
	s_waitcnt vmcnt(7)
	v_lshlrev_b32_e32 v14, 16, v190
	v_and_b32_e32 v12, 0xffff0000, v190
	v_lshlrev_b32_e32 v15, 16, v191
	v_and_b32_e32 v13, 0xffff0000, v191
	v_fmac_f32_e32 v14, v2, v232
	v_fmac_f32_e32 v12, v3, v233
	v_fmac_f32_e32 v15, v4, v234
	v_fmac_f32_e32 v13, v5, v235
	v_cvt_pk_bf16_f32 v2, v14, v12
	v_cvt_pk_bf16_f32 v3, v15, v13
	global_store_dwordx2 v[10:11], v[2:3], off offset:224
	s_branch .LBB0_2427

; template <bool SWAP, class Epi, bool THIN = false> ...
;     ...
;     for (int st = 0; st < ns; ++st) {
;       asm volatile("s_waitcnt vmcnt(0)" ::: "memory");
;       __builtin_amdgcn_s_barrier();
;       asm volatile("" ::: "memory");
;       if (st + 1 < ns) {
;         char* nb = smem + ((st + 1) & 1) * 65536;
;         const int ko = (st + 1) * 64;
; #pragma unroll
;         for (int i = 0; i < 4; ++i) { GLDS16(A + (size_t)(ap[i] + ko), nb + tid * 16 + i * 8192); GLDS16(Bt + (size_t)(bp[i] + ko), nb + 32768 + tid * 16 + i * 8192); }
;       }
;       const char* sa = smem + (st & 1) * 65536 + (wr * 64 + fr) * 128;
;       const char* sb = smem + (st & 1) * 65536 + 32768 + (wc * 128 + fr) * 128;
;       if constexpr (THIN) {
;         if (wc == 0) {
; #pragma unroll
;           for (int ks = 0; ks < 2; ++ks) {
;             bf16x8 af[4], bf[2];
; #pragma unroll
;             for (int m = 0; m < 4; ++m) af[m] = *(const bf16x8*)(sa + m * 2048 + (((ks * 4 + fq) ^ swz) << 4));
; #pragma unroll
;             for (int n = 0; n < 2; ++n) bf[n] = *(const bf16x8*)(sb + n * 2048 + (((ks * 4 + fq) ^ swz) << 4));
; #pragma unroll
;             for (int m = 0; m < 4; ++m)
; #pragma unroll
;               for (int n = 0; n < 2; ++n)
;                 acc[m][n] = SWAP ? __builtin_amdgcn_mfma_f32_16x16x32_bf16(bf[n], af[m], acc[m][n], 0, 0, 0)
;                                  : __builtin_amdgcn_mfma_f32_16x16x32_bf16(af[m], bf[n], acc[m][n], 0, 0, 0);
;           }
;         }
;       } else {
;       bf16x8 afA[4], afB[4], bfb[2][2];
; #pragma unroll
;       for (int m = 0; m < 4; ++m) afA[m] = *(const bf16x8*)(sa + m * 2048 + ((fq ^ swz) << 4));
; #pragma unroll
;       for (int n = 0; n < 2; ++n) bfb[0][n] = *(const bf16x8*)(sb + n * 2048 + ((fq ^ swz) << 4));
; #pragma unroll
;       for (int gq = 0; gq < 8; ++gq) {
;         const int ks = gq >> 2, nh = gq & 3;
;         if (gq < 7) {
;           const int ks2 = (gq + 1) >> 2, nh2 = (gq + 1) & 3;
; #pragma unroll
;           for (int n = 0; n < 2; ++n) bfb[(gq + 1) & 1][n] = *(const bf16x8*)(sb + (nh2 * 2 + n) * 2048 + (((ks2 * 4 + fq) ^ swz) << 4));
;         }
;         if (gq == 3) {
; #pragma unroll
;           for (int m = 0; m < 4; ++m) afB[m] = *(const bf16x8*)(sa + m * 2048 + (((4 + fq) ^ swz) << 4));
;         }
;         __builtin_amdgcn_sched_barrier(0);
; #pragma unroll
.LBB0_2643:
	s_add_i32 s8, s7, 0x10000
	s_and_b32 s9, s8, 0x10000
	v_add_u32_e32 v167, s9, v142
	s_nop 0
	v_readfirstlane_b32 s9, v167
	s_waitcnt vmcnt(0)
	s_barrier
	s_and_b32 s7, s7, 0x10000
	v_add_u32_e32 v130, s7, v143
	v_add_u32_e32 v167, v130, v145
	ds_read_b128 v[168:171], v167
	ds_read_b128 v[172:175], v167 offset:2048
	ds_read_b128 v[176:179], v167 offset:4096
	ds_read_b128 v[180:183], v167 offset:6144
	v_or_b32_e32 v167, s7, v144
	v_add_u32_e32 v204, v167, v145
	ds_read_b128 v[184:187], v204 offset:32768
	ds_read_b128 v[188:191], v204 offset:34816
	ds_read_b128 v[192:195], v204 offset:36864
	ds_read_b128 v[196:199], v204 offset:38912
	v_add_u32_e32 v130, v130, v146
	s_waitcnt lgkmcnt(3)
	v_mfma_f32_16x16x32_bf16 v[126:129], v[184:187], v[168:171], v[126:129]
	s_mov_b32 m0, s9
	v_mfma_f32_16x16x32_bf16 v[110:113], v[184:187], v[172:175], v[110:113]
	global_load_lds_dwordx4 v139, s[18:19] sc1
	v_add_u32_e32 v139, 0x80, v139
	v_mfma_f32_16x16x32_bf16 v[82:85], v[184:187], v[176:179], v[82:85]
	v_mfma_f32_16x16x32_bf16 v[50:53], v[184:187], v[180:183], v[50:53]
	ds_read_b128 v[184:187], v204 offset:40960
	ds_read_b128 v[200:203], v204 offset:43008
	s_waitcnt lgkmcnt(4)
	v_mfma_f32_16x16x32_bf16 v[122:125], v[188:191], v[168:171], v[122:125]
	s_add_u32 m0, s9, 0x8000
	v_mfma_f32_16x16x32_bf16 v[106:109], v[188:191], v[172:175], v[106:109]
	global_load_lds_dwordx4 v138, s[24:25] sc1
	v_add_u32_e32 v138, 0x80, v138
	v_mfma_f32_16x16x32_bf16 v[78:81], v[188:191], v[176:179], v[78:81]
	v_mfma_f32_16x16x32_bf16 v[42:45], v[188:191], v[180:183], v[42:45]
	s_waitcnt lgkmcnt(3)
	v_mfma_f32_16x16x32_bf16 v[118:121], v[192:195], v[168:171], v[118:121]
	s_add_u32 m0, s9, 0x2000
	v_mfma_f32_16x16x32_bf16 v[94:97], v[192:195], v[172:175], v[94:97]
	global_load_lds_dwordx4 v137, s[18:19] sc1
	v_add_u32_e32 v137, 0x80, v137
	v_mfma_f32_16x16x32_bf16 v[58:61], v[192:195], v[176:179], v[58:61]
	v_mfma_f32_16x16x32_bf16 v[26:29], v[192:195], v[180:183], v[26:29]
	ds_read_b128 v[188:191], v204 offset:45056
	ds_read_b128 v[192:195], v204 offset:47104
	s_waitcnt lgkmcnt(4)
	v_mfma_f32_16x16x32_bf16 v[114:117], v[196:199], v[168:171], v[114:117]
	s_add_u32 m0, s9, 0xa000
	v_mfma_f32_16x16x32_bf16 v[86:89], v[196:199], v[172:175], v[86:89]
	global_load_lds_dwordx4 v136, s[24:25] sc1
	v_add_u32_e32 v136, 0x80, v136
	v_mfma_f32_16x16x32_bf16 v[54:57], v[196:199], v[176:179], v[54:57]
	v_mfma_f32_16x16x32_bf16 v[22:25], v[196:199], v[180:183], v[22:25]
	v_add_u32_e32 v167, v167, v146
	s_waitcnt lgkmcnt(3)
	v_mfma_f32_16x16x32_bf16 v[102:105], v[184:187], v[168:171], v[102:105]
	ds_read_b128 v[196:199], v167 offset:32768
	ds_read_b128 v[204:207], v167 offset:34816
	s_add_u32 m0, s9, 0x4000
	v_mfma_f32_16x16x32_bf16 v[74:77], v[184:187], v[172:175], v[74:77]
	global_load_lds_dwordx4 v135, s[18:19] sc1
	v_add_u32_e32 v135, 0x80, v135
	v_mfma_f32_16x16x32_bf16 v[46:49], v[184:187], v[176:179], v[46:49]
	v_mfma_f32_16x16x32_bf16 v[10:13], v[184:187], v[180:183], v[10:13]
	ds_read_b128 v[184:187], v130
	ds_read_b128 v[208:211], v130 offset:2048
	ds_read_b128 v[212:215], v130 offset:4096
	ds_read_b128 v[216:219], v130 offset:6144
	s_waitcnt lgkmcnt(8)
	v_mfma_f32_16x16x32_bf16 v[98:101], v[200:203], v[168:171], v[98:101]
	s_add_u32 m0, s9, 0xc000
	v_mfma_f32_16x16x32_bf16 v[66:69], v[200:203], v[172:175], v[66:69]
	global_load_lds_dwordx4 v134, s[24:25] sc1
	v_add_u32_e32 v134, 0x80, v134
	v_mfma_f32_16x16x32_bf16 v[30:33], v[200:203], v[176:179], v[30:33]
	v_mfma_f32_16x16x32_bf16 v[6:9], v[200:203], v[180:183], v[6:9]
	s_waitcnt lgkmcnt(7)
	v_mfma_f32_16x16x32_bf16 v[70:73], v[188:191], v[168:171], v[70:73]
	s_add_u32 m0, s9, 0x6000
	s_waitcnt lgkmcnt(6)
	v_mfma_f32_16x16x32_bf16 v[62:65], v[192:195], v[168:171], v[62:65]
	global_load_lds_dwordx4 v133, s[18:19] sc1
	v_add_u32_e32 v133, 0x80, v133
	v_mfma_f32_16x16x32_bf16 v[38:41], v[188:191], v[172:175], v[38:41]
	v_mfma_f32_16x16x32_bf16 v[34:37], v[192:195], v[172:175], v[34:37]
	ds_read_b128 v[168:171], v167 offset:36864
	ds_read_b128 v[172:175], v167 offset:38912
	v_mfma_f32_16x16x32_bf16 v[18:21], v[188:191], v[176:179], v[18:21]
	s_add_u32 m0, s9, 0xe000
	v_mfma_f32_16x16x32_bf16 v[14:17], v[192:195], v[176:179], v[14:17]
	global_load_lds_dwordx4 v132, s[24:25] sc1
	v_add_u32_e32 v132, 0x80, v132
	v_mfma_f32_16x16x32_bf16 v[2:5], v[188:191], v[180:183], v[2:5]
	v_mfma_f32_16x16x32_bf16 v[90:93], v[192:195], v[180:183], v[90:93]
	ds_read_b128 v[176:179], v167 offset:40960
	ds_read_b128 v[180:183], v167 offset:43008
	s_waitcnt lgkmcnt(7)
	v_mfma_f32_16x16x32_bf16 v[126:129], v[196:199], v[184:187], v[126:129]
	v_mfma_f32_16x16x32_bf16 v[122:125], v[204:207], v[184:187], v[122:125]
	s_waitcnt lgkmcnt(6)
	v_mfma_f32_16x16x32_bf16 v[110:113], v[196:199], v[208:211], v[110:113]
	v_mfma_f32_16x16x32_bf16 v[106:109], v[204:207], v[208:211], v[106:109]
	s_waitcnt lgkmcnt(5)
	v_mfma_f32_16x16x32_bf16 v[82:85], v[196:199], v[212:215], v[82:85]
	v_mfma_f32_16x16x32_bf16 v[78:81], v[204:207], v[212:215], v[78:81]
	s_waitcnt lgkmcnt(4)
	v_mfma_f32_16x16x32_bf16 v[50:53], v[196:199], v[216:219], v[50:53]
	v_mfma_f32_16x16x32_bf16 v[42:45], v[204:207], v[216:219], v[42:45]
	s_waitcnt lgkmcnt(3)
	v_mfma_f32_16x16x32_bf16 v[118:121], v[168:171], v[184:187], v[118:121]
	v_mfma_f32_16x16x32_bf16 v[94:97], v[168:171], v[208:211], v[94:97]
	v_mfma_f32_16x16x32_bf16 v[58:61], v[168:171], v[212:215], v[58:61]
	v_mfma_f32_16x16x32_bf16 v[26:29], v[168:171], v[216:219], v[26:29]
	ds_read_b128 v[168:171], v167 offset:45056
	ds_read_b128 v[188:191], v167 offset:47104
	s_waitcnt lgkmcnt(4)
; template <bool SWAP, class Epi, bool THIN = false> ...
;     ...
;       bf16x8 afA[4], afB[4], bfb[2][2];
; #pragma unroll
;       for (int m = 0; m < 4; ++m) afA[m] = *(const bf16x8*)(sa + m * 2048 + ((fq ^ swz) << 4));
; #pragma unroll
;       for (int n = 0; n < 2; ++n) bfb[0][n] = *(const bf16x8*)(sb + n * 2048 + ((fq ^ swz) << 4));
; #pragma unroll
;       for (int gq = 0; gq < 8; ++gq) {
;         const int ks = gq >> 2, nh = gq & 3;
;         if (gq < 7) {
;           const int ks2 = (gq + 1) >> 2, nh2 = (gq + 1) & 3;
; #pragma unroll
;           for (int n = 0; n < 2; ++n) bfb[(gq + 1) & 1][n] = *(const bf16x8*)(sb + (nh2 * 2 + n) * 2048 + (((ks2 * 4 + fq) ^ swz) << 4));
;         }
;         if (gq == 3) {
; #pragma unroll
;           for (int m = 0; m < 4; ++m) afB[m] = *(const bf16x8*)(sa + m * 2048 + (((4 + fq) ^ swz) << 4));
;         }
;         __builtin_amdgcn_sched_barrier(0);
; #pragma unroll
;         for (int m = 0; m < 4; ++m)
; #pragma unroll
;           for (int n = 0; n < 2; ++n) {
;             const bf16x8 av = ks ? afB[m] : afA[m];
;             acc[m][nh * 2 + n] = SWAP ? __builtin_amdgcn_mfma_f32_16x16x32_bf16(bfb[gq & 1][n], av, acc[m][nh * 2 + n], 0, 0, 0)
;                                       : __builtin_amdgcn_mfma_f32_16x16x32_bf16(av, bfb[gq & 1][n], acc[m][nh * 2 + n], 0, 0, 0);
;           }
;       }
;       }
;     }
;     __syncthreads();
	v_mfma_f32_16x16x32_bf16 v[114:117], v[172:175], v[184:187], v[114:117]
	v_mfma_f32_16x16x32_bf16 v[86:89], v[172:175], v[208:211], v[86:89]
	v_mfma_f32_16x16x32_bf16 v[54:57], v[172:175], v[212:215], v[54:57]
	v_mfma_f32_16x16x32_bf16 v[22:25], v[172:175], v[216:219], v[22:25]
	s_waitcnt lgkmcnt(3)
	v_mfma_f32_16x16x32_bf16 v[102:105], v[176:179], v[184:187], v[102:105]
	s_waitcnt lgkmcnt(2)
	v_mfma_f32_16x16x32_bf16 v[98:101], v[180:183], v[184:187], v[98:101]
	v_mfma_f32_16x16x32_bf16 v[74:77], v[176:179], v[208:211], v[74:77]
	v_mfma_f32_16x16x32_bf16 v[66:69], v[180:183], v[208:211], v[66:69]
	v_mfma_f32_16x16x32_bf16 v[46:49], v[176:179], v[212:215], v[46:49]
	v_mfma_f32_16x16x32_bf16 v[30:33], v[180:183], v[212:215], v[30:33]
	v_mfma_f32_16x16x32_bf16 v[10:13], v[176:179], v[216:219], v[10:13]
	v_mfma_f32_16x16x32_bf16 v[6:9], v[180:183], v[216:219], v[6:9]
	s_waitcnt lgkmcnt(1)
	v_mfma_f32_16x16x32_bf16 v[70:73], v[168:171], v[184:187], v[70:73]
	s_add_i32 s6, s6, 64
	s_cmpk_eq_i32 s6, 0x3c0
	s_mov_b32 s7, s8
	s_waitcnt lgkmcnt(0)
	v_mfma_f32_16x16x32_bf16 v[62:65], v[188:191], v[184:187], v[62:65]
	v_mfma_f32_16x16x32_bf16 v[38:41], v[168:171], v[208:211], v[38:41]
	v_mfma_f32_16x16x32_bf16 v[34:37], v[188:191], v[208:211], v[34:37]
	v_mfma_f32_16x16x32_bf16 v[18:21], v[168:171], v[212:215], v[18:21]
	v_mfma_f32_16x16x32_bf16 v[14:17], v[188:191], v[212:215], v[14:17]
	v_mfma_f32_16x16x32_bf16 v[2:5], v[168:171], v[216:219], v[2:5]
	v_mfma_f32_16x16x32_bf16 v[90:93], v[188:191], v[216:219], v[90:93]
	s_cbranch_scc0 .LBB0_2643
	s_waitcnt vmcnt(0)
	s_barrier
	v_add_u32_e32 v130, v157, v145
	ds_read_b128 v[132:135], v130
	ds_read_b128 v[136:139], v130 offset:2048
	ds_read_b128 v[168:171], v130 offset:4096
	ds_read_b128 v[172:175], v130 offset:6144
	v_add_u32_e32 v130, v158, v145
	ds_read_b128 v[176:179], v130
	ds_read_b128 v[180:183], v130 offset:2048
	ds_read_b128 v[184:187], v130 offset:4096
	ds_read_b128 v[188:191], v130 offset:6144
	s_waitcnt lgkmcnt(0)
	v_mfma_f32_16x16x32_bf16 v[126:129], v[176:179], v[132:135], v[126:129]
	v_mfma_f32_16x16x32_bf16 v[110:113], v[176:179], v[136:139], v[110:113]
	v_mfma_f32_16x16x32_bf16 v[82:85], v[176:179], v[168:171], v[82:85]
	v_mfma_f32_16x16x32_bf16 v[50:53], v[176:179], v[172:175], v[50:53]
	ds_read_b128 v[176:179], v130 offset:8192
	ds_read_b128 v[192:195], v130 offset:10240
	v_mfma_f32_16x16x32_bf16 v[122:125], v[180:183], v[132:135], v[122:125]
	v_mfma_f32_16x16x32_bf16 v[106:109], v[180:183], v[136:139], v[106:109]
	v_mfma_f32_16x16x32_bf16 v[78:81], v[180:183], v[168:171], v[78:81]
	v_mfma_f32_16x16x32_bf16 v[42:45], v[180:183], v[172:175], v[42:45]
	v_mfma_f32_16x16x32_bf16 v[118:121], v[184:187], v[132:135], v[118:121]
	v_mfma_f32_16x16x32_bf16 v[180:183], v[184:187], v[136:139], v[94:97]
	v_mfma_f32_16x16x32_bf16 v[200:203], v[184:187], v[168:171], v[58:61]
	v_mfma_f32_16x16x32_bf16 v[204:207], v[188:191], v[168:171], v[54:57]
	v_mfma_f32_16x16x32_bf16 v[184:187], v[184:187], v[172:175], v[26:29]
	s_nop 2
	ds_read_b128 v[26:29], v130 offset:12288
	ds_read_b128 v[54:57], v130 offset:14336
	v_mfma_f32_16x16x32_bf16 v[114:117], v[188:191], v[132:135], v[114:117]
	v_mfma_f32_16x16x32_bf16 v[196:199], v[188:191], v[136:139], v[86:89]
	v_mfma_f32_16x16x32_bf16 v[188:191], v[188:191], v[172:175], v[22:25]
	v_add_u32_e32 v130, v158, v146
	s_waitcnt lgkmcnt(0)
	v_mfma_f32_16x16x32_bf16 v[208:211], v[192:195], v[168:171], v[30:33]
	ds_read_b128 v[22:25], v130
	ds_read_b128 v[86:89], v130 offset:2048
	s_nop 0
	v_add_u32_e32 v30, v157, v146
	v_mfma_f32_16x16x32_bf16 v[102:105], v[176:179], v[132:135], v[102:105]
	v_mfma_f32_16x16x32_bf16 v[74:77], v[176:179], v[136:139], v[74:77]
	v_mfma_f32_16x16x32_bf16 v[46:49], v[176:179], v[168:171], v[46:49]
	v_mfma_f32_16x16x32_bf16 v[10:13], v[176:179], v[172:175], v[10:13]
	ds_read_b128 v[176:179], v30
	ds_read_b128 v[212:215], v30 offset:2048
	ds_read_b128 v[216:219], v30 offset:4096
	ds_read_b128 v[220:223], v30 offset:6144
	v_mfma_f32_16x16x32_bf16 v[98:101], v[192:195], v[132:135], v[98:101]
	v_mfma_f32_16x16x32_bf16 v[66:69], v[192:195], v[136:139], v[66:69]
	v_mfma_f32_16x16x32_bf16 v[6:9], v[192:195], v[172:175], v[6:9]
	v_mfma_f32_16x16x32_bf16 v[224:227], v[26:29], v[136:139], v[38:41]
	v_mfma_f32_16x16x32_bf16 v[34:37], v[54:57], v[136:139], v[34:37]
	v_mfma_f32_16x16x32_bf16 v[136:139], v[26:29], v[168:171], v[18:21]
	v_mfma_f32_16x16x32_bf16 v[168:171], v[54:57], v[168:171], v[14:17]
	s_nop 2
	ds_read_b128 v[14:17], v130 offset:4096
	ds_read_b128 v[18:21], v130 offset:6144
	v_mfma_f32_16x16x32_bf16 v[192:195], v[26:29], v[132:135], v[70:73]
	v_mfma_f32_16x16x32_bf16 v[132:135], v[54:57], v[132:135], v[62:65]
	v_mfma_f32_16x16x32_bf16 v[2:5], v[26:29], v[172:175], v[2:5]
	v_mfma_f32_16x16x32_bf16 v[172:175], v[54:57], v[172:175], v[90:93]
	ds_read_b128 v[228:231], v130 offset:8192
	ds_read_b128 v[232:235], v130 offset:10240
	s_waitcnt lgkmcnt(0)
	v_mfma_f32_16x16x32_bf16 v[126:129], v[22:25], v[176:179], v[126:129]
	v_mfma_f32_16x16x32_bf16 v[122:125], v[86:89], v[176:179], v[122:125]
	v_mfma_f32_16x16x32_bf16 v[94:97], v[22:25], v[212:215], v[110:113]
	v_mfma_f32_16x16x32_bf16 v[90:93], v[86:89], v[212:215], v[106:109]
	v_mfma_f32_16x16x32_bf16 v[62:65], v[22:25], v[216:219], v[82:85]
	v_mfma_f32_16x16x32_bf16 v[58:61], v[86:89], v[216:219], v[78:81]
	v_mfma_f32_16x16x32_bf16 v[30:33], v[22:25], v[220:223], v[50:53]
	v_mfma_f32_16x16x32_bf16 v[26:29], v[86:89], v[220:223], v[42:45]
	v_mfma_f32_16x16x32_bf16 v[86:89], v[14:17], v[212:215], v[180:183]
	v_mfma_f32_16x16x32_bf16 v[22:25], v[14:17], v[220:223], v[184:187]
	s_nop 1
	ds_read_b128 v[180:183], v130 offset:12288
	ds_read_b128 v[184:187], v130 offset:14336
	v_mfma_f32_16x16x32_bf16 v[118:121], v[14:17], v[176:179], v[118:121]
	v_mfma_f32_16x16x32_bf16 v[114:117], v[18:21], v[176:179], v[114:117]
	v_mfma_f32_16x16x32_bf16 v[82:85], v[18:21], v[212:215], v[196:199]
	v_mfma_f32_16x16x32_bf16 v[54:57], v[14:17], v[216:219], v[200:203]
	v_mfma_f32_16x16x32_bf16 v[50:53], v[18:21], v[216:219], v[204:207]
	v_mfma_f32_16x16x32_bf16 v[18:21], v[18:21], v[220:223], v[188:191]
	v_mfma_f32_16x16x32_bf16 v[110:113], v[228:231], v[176:179], v[102:105]
	v_mfma_f32_16x16x32_bf16 v[106:109], v[232:235], v[176:179], v[98:101]
	v_mfma_f32_16x16x32_bf16 v[78:81], v[228:231], v[212:215], v[74:77]
	v_mfma_f32_16x16x32_bf16 v[70:73], v[232:235], v[212:215], v[66:69]
	v_mfma_f32_16x16x32_bf16 v[46:49], v[228:231], v[216:219], v[46:49]
	v_mfma_f32_16x16x32_bf16 v[38:41], v[232:235], v[216:219], v[208:211]
	v_mfma_f32_16x16x32_bf16 v[14:17], v[228:231], v[220:223], v[10:13]
	v_mfma_f32_16x16x32_bf16 v[6:9], v[232:235], v[220:223], v[6:9]
	v_mov_b32_e32 v130, v1
	s_waitcnt vmcnt(0) lgkmcnt(0)
	s_barrier
; __device__ __forceinline__ int get_tid512() { int t = threadIdx.x; asm volatile("" : "+v"(t)); return t; }
; __device__ __forceinline__ unsigned pack2(float a, float b) { unsigned r; asm("v_cvt_pk_bf16_f32 %0, %1, %2" : "=v"(r) : "v"(a), "v"(b)); return r; }
;   __device__ __forceinline__ void c4(int g, int rig, int col, f32x4 v) const {
;     const size_t row = (size_t)g * 2048 + rig;
;     const f32x4 b4 = *(const f32x4*)(bias + col);
;     uint2 u; u.x = pack2(v[0] + b4[0], v[1] + b4[1]); u.y = pack2(v[2] + b4[2], v[3] + b4[3]);
;     *(uint2*)(out + row * ld + col) = u;
;   }
; template <bool SWAP, class Epi, bool THIN = false> ...
;     ...
;     __syncthreads();
;     const int te = get_tid512();
;     const int fr_e = te & 15, fq_e = (te & 63) >> 4, wr_e = te >> 7, wc_e = (te >> 6) & 1;
;     const int sub = 2 * mt + (wr_e >> 1);
;     const int g = sub / tpg, ti = sub - g * tpg;
;     const int rig0 = ti * step - halo;
;     const int rw = (wr_e & 1) * 64;
;     if constexpr (Epi::KIND == 0) {
; #pragma unroll
;       for (int m = 0; m < 4; ++m) {
;         const int rig = rig0 + rw + m * 16 + fr_e;
;         if constexpr (Epi::ROWSUM) {
;           float ss = 0.f;
; #pragma unroll
;           for (int n = 0; n < 8; ++n) {
;             const int col = nt * 256 + wc_e * 128 + n * 16 + fq_e * 4;
;             if (col < N) ss += epi.c4(g, rig, col, acc[m][n]);
;           }
;           ss += __shfl_xor(ss, 16); ss += __shfl_xor(ss, 32);
;           if (fq_e == 0) epi.rowsum(g, rig, nt * 2 + wc_e, ss);
;         } else {
; #pragma unroll
;           for (int n = 0; n < 8; ++n) {
;             const int col = nt * 256 + wc_e * 128 + n * 16 + fq_e * 4;
;             if (col < N) epi.c4(g, rig, col, acc[m][n]);
;           }
	v_mfma_f32_16x16x32_bf16 v[102:105], v[180:183], v[176:179], v[192:195]
	v_ashrrev_i32_e32 v11, 8, v130
	v_add_u32_e32 v11, s5, v11
	v_ashrrev_i32_e32 v12, 31, v11
	v_lshrrev_b32_e32 v12, 28, v12
	v_add_u32_e32 v12, v11, v12
	v_mfma_f32_16x16x32_bf16 v[98:101], v[184:187], v[176:179], v[132:135]
	v_ashrrev_i32_e32 v176, 4, v12
	v_lshlrev_b32_e32 v12, 11, v176
	v_lshlrev_b32_e32 v11, 7, v11
	v_sub_u32_e32 v11, v11, v12
	v_lshrrev_b32_e32 v12, 1, v130
	v_and_b32_e32 v10, 15, v130
	v_and_b32_e32 v12, 64, v12
	v_or3_b32 v134, v11, v12, v10
	v_lshlrev_b32_e32 v10, 1, v130
	v_and_b32_e32 v132, 0x80, v10
	v_mfma_f32_16x16x32_bf16 v[10:13], v[180:183], v[220:223], v[2:5]
	v_ashrrev_i32_e32 v177, 31, v176
	v_ashrrev_i32_e32 v135, 31, v134
	s_nop 0
	v_lshrrev_b32_e32 v2, 2, v130
	v_and_b32_e32 v2, 12, v2
	v_mfma_f32_16x16x32_bf16 v[74:77], v[180:183], v[212:215], v[224:227]
	v_or3_b32 v132, v2, v132, s4
	v_cmp_gt_i32_e32 vcc, s31, v132
	v_ashrrev_i32_e32 v133, 31, v132
	v_mfma_f32_16x16x32_bf16 v[66:69], v[184:187], v[212:215], v[34:37]
	v_mfma_f32_16x16x32_bf16 v[42:45], v[180:183], v[216:219], v[136:139]
	v_mfma_f32_16x16x32_bf16 v[34:37], v[184:187], v[216:219], v[168:171]
	s_nop 1
	v_lshlrev_b64 v[136:137], 11, v[176:177]
	v_lshl_add_u64 v[138:139], v[136:137], 0, v[134:135]
	v_lshlrev_b64 v[138:139], 11, v[138:139]
	v_mfma_f32_16x16x32_bf16 v[2:5], v[184:187], v[220:223], v[172:175]
	v_lshl_add_u64 v[138:139], s[20:21], 0, v[138:139]
	v_lshl_add_u64 v[188:189], v[132:133], 2, s[22:23]
	global_load_dwordx4 v[196:199], v[188:189], off
	global_load_dwordx4 v[200:203], v[188:189], off offset:64
	global_load_dwordx4 v[204:207], v[188:189], off offset:128
	global_load_dwordx4 v[208:211], v[188:189], off offset:192
	global_load_dwordx4 v[228:231], v[188:189], off offset:256
	global_load_dwordx4 v[232:235], v[188:189], off offset:320
	global_load_dwordx4 v[236:239], v[188:189], off offset:384
	global_load_dwordx4 v[240:243], v[188:189], off offset:448
	s_waitcnt vmcnt(0)
	v_add_f32_e32 v126, v126, v196
	v_add_f32_e32 v127, v127, v197
	v_add_f32_e32 v128, v128, v198
	v_add_f32_e32 v129, v129, v199
	v_cvt_pk_bf16_f32 v126, v126, v127
	v_cvt_pk_bf16_f32 v127, v128, v129
	v_lshl_add_u64 v[128:129], v[132:133], 1, v[138:139]
	global_store_dwordx2 v[128:129], v[126:127], off
	v_or_b32_e32 v126, 16, v132
	v_add_f32_e32 v122, v122, v200
	v_add_f32_e32 v123, v123, v201
	v_add_f32_e32 v124, v124, v202
	v_add_f32_e32 v125, v125, v203
	v_cvt_pk_bf16_f32 v122, v122, v123
	v_cvt_pk_bf16_f32 v123, v124, v125
	v_lshl_add_u64 v[124:125], v[132:133], 1, v[138:139]
	global_store_dwordx2 v[124:125], v[122:123], off offset:32
	v_or_b32_e32 v122, 32, v132
	v_add_f32_e32 v118, v118, v204
	v_add_f32_e32 v119, v119, v205
	v_add_f32_e32 v120, v120, v206
	v_add_f32_e32 v121, v121, v207
	v_cvt_pk_bf16_f32 v118, v118, v119
	v_cvt_pk_bf16_f32 v119, v120, v121
	v_lshl_add_u64 v[120:121], v[132:133], 1, v[138:139]
	global_store_dwordx2 v[120:121], v[118:119], off offset:64
	v_or_b32_e32 v118, 48, v132
	v_add_f32_e32 v114, v114, v208
	v_add_f32_e32 v115, v115, v209
	v_add_f32_e32 v116, v116, v210
	v_add_f32_e32 v117, v117, v211
	v_cvt_pk_bf16_f32 v114, v114, v115
	v_cvt_pk_bf16_f32 v115, v116, v117
	v_lshl_add_u64 v[116:117], v[132:133], 1, v[138:139]
	global_store_dwordx2 v[116:117], v[114:115], off offset:96
	v_or_b32_e32 v114, 64, v132
	v_add_f32_e32 v110, v110, v228
	v_add_f32_e32 v111, v111, v229
	v_add_f32_e32 v112, v112, v230
	v_add_f32_e32 v113, v113, v231
	v_cvt_pk_bf16_f32 v110, v110, v111
	v_cvt_pk_bf16_f32 v111, v112, v113
	v_lshl_add_u64 v[112:113], v[132:133], 1, v[138:139]
	global_store_dwordx2 v[112:113], v[110:111], off offset:128
	v_or_b32_e32 v110, 0x50, v132
	v_add_f32_e32 v106, v106, v232
	v_add_f32_e32 v107, v107, v233
	v_add_f32_e32 v108, v108, v234
	v_add_f32_e32 v109, v109, v235
	v_cvt_pk_bf16_f32 v106, v106, v107
	v_cvt_pk_bf16_f32 v107, v108, v109
	v_lshl_add_u64 v[108:109], v[132:133], 1, v[138:139]
	global_store_dwordx2 v[108:109], v[106:107], off offset:160
	v_or_b32_e32 v106, 0x60, v132
	v_add_f32_e32 v102, v102, v236
	v_add_f32_e32 v103, v103, v237
	v_add_f32_e32 v104, v104, v238
	v_add_f32_e32 v105, v105, v239
	v_cvt_pk_bf16_f32 v102, v102, v103
	v_cvt_pk_bf16_f32 v103, v104, v105
	v_lshl_add_u64 v[104:105], v[132:133], 1, v[138:139]
	global_store_dwordx2 v[104:105], v[102:103], off offset:192
	v_or_b32_e32 v102, 0x70, v132
	v_add_f32_e32 v98, v98, v240
	v_add_f32_e32 v99, v99, v241
	v_add_f32_e32 v100, v100, v242
	v_add_f32_e32 v101, v101, v243
	v_cvt_pk_bf16_f32 v98, v98, v99
	v_cvt_pk_bf16_f32 v99, v100, v101
	v_lshl_add_u64 v[100:101], v[132:133], 1, v[138:139]
	global_store_dwordx2 v[100:101], v[98:99], off offset:224
	v_or_b32_e32 v98, 16, v134
	v_ashrrev_i32_e32 v99, 31, v98
	v_lshl_add_u64 v[98:99], v[136:137], 0, v[98:99]
	v_lshlrev_b64 v[98:99], 11, v[98:99]
	v_lshl_add_u64 v[98:99], s[20:21], 0, v[98:99]
	v_add_f32_e32 v94, v94, v196
	v_add_f32_e32 v95, v95, v197
	v_add_f32_e32 v96, v96, v198
	v_add_f32_e32 v97, v97, v199
	v_cvt_pk_bf16_f32 v94, v94, v95
	v_cvt_pk_bf16_f32 v95, v96, v97
	v_lshl_add_u64 v[96:97], v[132:133], 1, v[98:99]
	global_store_dwordx2 v[96:97], v[94:95], off
	v_add_f32_e32 v90, v90, v200
	v_add_f32_e32 v91, v91, v201
	v_add_f32_e32 v92, v92, v202
	v_add_f32_e32 v93, v93, v203
	v_cvt_pk_bf16_f32 v90, v90, v91
	v_cvt_pk_bf16_f32 v91, v92, v93
	v_lshl_add_u64 v[92:93], v[132:133], 1, v[98:99]
	global_store_dwordx2 v[92:93], v[90:91], off offset:32
	v_add_f32_e32 v86, v86, v204
	v_add_f32_e32 v87, v87, v205
	v_add_f32_e32 v88, v88, v206
	v_add_f32_e32 v89, v89, v207
	v_cvt_pk_bf16_f32 v86, v86, v87
	v_cvt_pk_bf16_f32 v87, v88, v89
; __device__ __forceinline__ unsigned pack2(float a, float b) { unsigned r; asm("v_cvt_pk_bf16_f32 %0, %1, %2" : "=v"(r) : "v"(a), "v"(b)); return r; }
;   __device__ __forceinline__ void c4(int g, int rig, int col, f32x4 v) const {
;     const size_t row = (size_t)g * 2048 + rig;
;     const f32x4 b4 = *(const f32x4*)(bias + col);
;     uint2 u; u.x = pack2(v[0] + b4[0], v[1] + b4[1]); u.y = pack2(v[2] + b4[2], v[3] + b4[3]);
;     *(uint2*)(out + row * ld + col) = u;
;   }
; template <bool SWAP, class Epi, bool THIN = false> ...
;     ...
;         } else {
; #pragma unroll
;           for (int n = 0; n < 8; ++n) {
;             const int col = nt * 256 + wc_e * 128 + n * 16 + fq_e * 4;
;             if (col < N) epi.c4(g, rig, col, acc[m][n]);
;           }
	v_lshl_add_u64 v[88:89], v[132:133], 1, v[98:99]
	global_store_dwordx2 v[88:89], v[86:87], off offset:64
	v_add_f32_e32 v82, v82, v208
	v_add_f32_e32 v83, v83, v209
	v_add_f32_e32 v84, v84, v210
	v_add_f32_e32 v85, v85, v211
	v_cvt_pk_bf16_f32 v82, v82, v83
	v_cvt_pk_bf16_f32 v83, v84, v85
	v_lshl_add_u64 v[84:85], v[132:133], 1, v[98:99]
	global_store_dwordx2 v[84:85], v[82:83], off offset:96
	v_add_f32_e32 v78, v78, v228
	v_add_f32_e32 v79, v79, v229
	v_add_f32_e32 v80, v80, v230
	v_add_f32_e32 v81, v81, v231
	v_cvt_pk_bf16_f32 v78, v78, v79
	v_cvt_pk_bf16_f32 v79, v80, v81
	v_lshl_add_u64 v[80:81], v[132:133], 1, v[98:99]
	global_store_dwordx2 v[80:81], v[78:79], off offset:128
	v_add_f32_e32 v70, v70, v232
	v_add_f32_e32 v71, v71, v233
	v_add_f32_e32 v72, v72, v234
	v_add_f32_e32 v73, v73, v235
	v_cvt_pk_bf16_f32 v70, v70, v71
	v_cvt_pk_bf16_f32 v71, v72, v73
	v_lshl_add_u64 v[72:73], v[132:133], 1, v[98:99]
	global_store_dwordx2 v[72:73], v[70:71], off offset:160
	v_add_f32_e32 v70, v74, v236
	v_add_f32_e32 v71, v75, v237
	v_add_f32_e32 v72, v76, v238
	v_add_f32_e32 v73, v77, v239
	v_cvt_pk_bf16_f32 v70, v70, v71
	v_cvt_pk_bf16_f32 v71, v72, v73
	v_lshl_add_u64 v[72:73], v[132:133], 1, v[98:99]
	global_store_dwordx2 v[72:73], v[70:71], off offset:192
	v_add_f32_e32 v66, v66, v240
	v_add_f32_e32 v67, v67, v241
	v_add_f32_e32 v68, v68, v242
	v_add_f32_e32 v69, v69, v243
	v_cvt_pk_bf16_f32 v66, v66, v67
	v_cvt_pk_bf16_f32 v67, v68, v69
	v_lshl_add_u64 v[68:69], v[132:133], 1, v[98:99]
	global_store_dwordx2 v[68:69], v[66:67], off offset:224
	v_or_b32_e32 v66, 32, v134
	v_ashrrev_i32_e32 v67, 31, v66
	v_lshl_add_u64 v[66:67], v[136:137], 0, v[66:67]
	v_lshlrev_b64 v[66:67], 11, v[66:67]
	v_lshl_add_u64 v[66:67], s[20:21], 0, v[66:67]
	v_add_f32_e32 v62, v62, v196
	v_add_f32_e32 v63, v63, v197
	v_add_f32_e32 v64, v64, v198
	v_add_f32_e32 v65, v65, v199
	v_cvt_pk_bf16_f32 v62, v62, v63
	v_cvt_pk_bf16_f32 v63, v64, v65
	v_lshl_add_u64 v[64:65], v[132:133], 1, v[66:67]
	global_store_dwordx2 v[64:65], v[62:63], off
	v_add_f32_e32 v58, v58, v200
	v_add_f32_e32 v59, v59, v201
	v_add_f32_e32 v60, v60, v202
	v_add_f32_e32 v61, v61, v203
	v_cvt_pk_bf16_f32 v58, v58, v59
	v_cvt_pk_bf16_f32 v59, v60, v61
	v_lshl_add_u64 v[60:61], v[132:133], 1, v[66:67]
	global_store_dwordx2 v[60:61], v[58:59], off offset:32
	v_add_f32_e32 v54, v54, v204
	v_add_f32_e32 v55, v55, v205
	v_add_f32_e32 v56, v56, v206
	v_add_f32_e32 v57, v57, v207
	v_cvt_pk_bf16_f32 v54, v54, v55
	v_cvt_pk_bf16_f32 v55, v56, v57
	v_lshl_add_u64 v[56:57], v[132:133], 1, v[66:67]
	global_store_dwordx2 v[56:57], v[54:55], off offset:64
	v_add_f32_e32 v50, v50, v208
	v_add_f32_e32 v51, v51, v209
	v_add_f32_e32 v52, v52, v210
	v_add_f32_e32 v53, v53, v211
	v_cvt_pk_bf16_f32 v50, v50, v51
	v_cvt_pk_bf16_f32 v51, v52, v53
	v_lshl_add_u64 v[52:53], v[132:133], 1, v[66:67]
	global_store_dwordx2 v[52:53], v[50:51], off offset:96
	v_add_f32_e32 v46, v46, v228
	v_add_f32_e32 v47, v47, v229
	v_add_f32_e32 v48, v48, v230
	v_add_f32_e32 v49, v49, v231
	v_cvt_pk_bf16_f32 v46, v46, v47
	v_cvt_pk_bf16_f32 v47, v48, v49
	v_lshl_add_u64 v[48:49], v[132:133], 1, v[66:67]
	global_store_dwordx2 v[48:49], v[46:47], off offset:128
	v_add_f32_e32 v38, v38, v232
	v_add_f32_e32 v39, v39, v233
	v_add_f32_e32 v40, v40, v234
	v_add_f32_e32 v41, v41, v235
	v_cvt_pk_bf16_f32 v38, v38, v39
	v_cvt_pk_bf16_f32 v39, v40, v41
	v_lshl_add_u64 v[40:41], v[132:133], 1, v[66:67]
	global_store_dwordx2 v[40:41], v[38:39], off offset:160
	v_add_f32_e32 v38, v42, v236
	v_add_f32_e32 v39, v43, v237
	v_add_f32_e32 v40, v44, v238
	v_add_f32_e32 v41, v45, v239
	v_cvt_pk_bf16_f32 v38, v38, v39
	v_cvt_pk_bf16_f32 v39, v40, v41
	v_lshl_add_u64 v[40:41], v[132:133], 1, v[66:67]
	global_store_dwordx2 v[40:41], v[38:39], off offset:192
	v_add_f32_e32 v34, v34, v240
	v_add_f32_e32 v35, v35, v241
	v_add_f32_e32 v36, v36, v242
	v_add_f32_e32 v37, v37, v243
	v_cvt_pk_bf16_f32 v34, v34, v35
	v_cvt_pk_bf16_f32 v35, v36, v37
	v_lshl_add_u64 v[36:37], v[132:133], 1, v[66:67]
	global_store_dwordx2 v[36:37], v[34:35], off offset:224
	v_or_b32_e32 v34, 48, v134
	v_ashrrev_i32_e32 v35, 31, v34
	v_lshl_add_u64 v[34:35], v[136:137], 0, v[34:35]
	v_lshlrev_b64 v[34:35], 11, v[34:35]
	v_lshl_add_u64 v[34:35], s[20:21], 0, v[34:35]
	v_add_f32_e32 v30, v30, v196
	v_add_f32_e32 v31, v31, v197
	v_add_f32_e32 v32, v32, v198
	v_add_f32_e32 v33, v33, v199
	v_cvt_pk_bf16_f32 v30, v30, v31
	v_cvt_pk_bf16_f32 v31, v32, v33
	v_lshl_add_u64 v[32:33], v[132:133], 1, v[34:35]
	global_store_dwordx2 v[32:33], v[30:31], off
	v_add_f32_e32 v26, v26, v200
	v_add_f32_e32 v27, v27, v201
	v_add_f32_e32 v28, v28, v202
	v_add_f32_e32 v29, v29, v203
	v_cvt_pk_bf16_f32 v26, v26, v27
	v_cvt_pk_bf16_f32 v27, v28, v29
	v_lshl_add_u64 v[28:29], v[132:133], 1, v[34:35]
	global_store_dwordx2 v[28:29], v[26:27], off offset:32
	v_add_f32_e32 v22, v22, v204
	v_add_f32_e32 v23, v23, v205
	v_add_f32_e32 v24, v24, v206
	v_add_f32_e32 v25, v25, v207
	v_cvt_pk_bf16_f32 v22, v22, v23
	v_cvt_pk_bf16_f32 v23, v24, v25
	v_lshl_add_u64 v[24:25], v[132:133], 1, v[34:35]
	global_store_dwordx2 v[24:25], v[22:23], off offset:64
	v_add_f32_e32 v18, v18, v208
	v_add_f32_e32 v19, v19, v209
	v_add_f32_e32 v20, v20, v210
	v_add_f32_e32 v21, v21, v211
	v_cvt_pk_bf16_f32 v18, v18, v19
	v_cvt_pk_bf16_f32 v19, v20, v21
	v_lshl_add_u64 v[20:21], v[132:133], 1, v[34:35]
	global_store_dwordx2 v[20:21], v[18:19], off offset:96
	v_add_f32_e32 v14, v14, v228
	v_add_f32_e32 v15, v15, v229
	v_add_f32_e32 v16, v16, v230
	v_add_f32_e32 v17, v17, v231
	v_cvt_pk_bf16_f32 v14, v14, v15
	v_cvt_pk_bf16_f32 v15, v16, v17
	v_lshl_add_u64 v[16:17], v[132:133], 1, v[34:35]
	global_store_dwordx2 v[16:17], v[14:15], off offset:128
	v_add_f32_e32 v6, v6, v232
	v_add_f32_e32 v7, v7, v233
	v_add_f32_e32 v8, v8, v234
	v_add_f32_e32 v9, v9, v235
	v_cvt_pk_bf16_f32 v6, v6, v7
	v_cvt_pk_bf16_f32 v7, v8, v9
	v_lshl_add_u64 v[8:9], v[132:133], 1, v[34:35]
	global_store_dwordx2 v[8:9], v[6:7], off offset:160
	v_add_f32_e32 v6, v10, v236
	v_add_f32_e32 v7, v11, v237
	v_add_f32_e32 v8, v12, v238
	v_add_f32_e32 v9, v13, v239
	v_cvt_pk_bf16_f32 v6, v6, v7
	v_cvt_pk_bf16_f32 v7, v8, v9
	v_lshl_add_u64 v[8:9], v[132:133], 1, v[34:35]
	global_store_dwordx2 v[8:9], v[6:7], off offset:192
	v_add_f32_e32 v2, v2, v240
	v_add_f32_e32 v3, v3, v241
	v_add_f32_e32 v4, v4, v242
	v_add_f32_e32 v5, v5, v243
	v_cvt_pk_bf16_f32 v2, v2, v3
	v_cvt_pk_bf16_f32 v3, v4, v5
	v_lshl_add_u64 v[4:5], v[132:133], 1, v[34:35]
	global_store_dwordx2 v[4:5], v[2:3], off offset:224
	s_branch .LBB0_2641

; template <bool SWAP, class Epi, bool THIN = false> ...
;     ...
;     for (int st = 0; st < ns; ++st) {
;       asm volatile("s_waitcnt vmcnt(0)" ::: "memory");
;       __builtin_amdgcn_s_barrier();
;       asm volatile("" ::: "memory");
;       if (st + 1 < ns) {
;         char* nb = smem + ((st + 1) & 1) * 65536;
;         const int ko = (st + 1) * 64;
; #pragma unroll
;         for (int i = 0; i < 4; ++i) { GLDS16(A + (size_t)(ap[i] + ko), nb + tid * 16 + i * 8192); GLDS16(Bt + (size_t)(bp[i] + ko), nb + 32768 + tid * 16 + i * 8192); }
;       }
;       const char* sa = smem + (st & 1) * 65536 + (wr * 64 + fr) * 128;
;       const char* sb = smem + (st & 1) * 65536 + 32768 + (wc * 128 + fr) * 128;
;       if constexpr (THIN) {
;         if (wc == 0) {
; #pragma unroll
;           for (int ks = 0; ks < 2; ++ks) {
;             bf16x8 af[4], bf[2];
; #pragma unroll
;             for (int m = 0; m < 4; ++m) af[m] = *(const bf16x8*)(sa + m * 2048 + (((ks * 4 + fq) ^ swz) << 4));
; #pragma unroll
;             for (int n = 0; n < 2; ++n) bf[n] = *(const bf16x8*)(sb + n * 2048 + (((ks * 4 + fq) ^ swz) << 4));
; #pragma unroll
;             for (int m = 0; m < 4; ++m)
; #pragma unroll
;               for (int n = 0; n < 2; ++n)
;                 acc[m][n] = SWAP ? __builtin_amdgcn_mfma_f32_16x16x32_bf16(bf[n], af[m], acc[m][n], 0, 0, 0)
;                                  : __builtin_amdgcn_mfma_f32_16x16x32_bf16(af[m], bf[n], acc[m][n], 0, 0, 0);
;           }
;         }
;       } else {
;       bf16x8 afA[4], afB[4], bfb[2][2];
; #pragma unroll
;       for (int m = 0; m < 4; ++m) afA[m] = *(const bf16x8*)(sa + m * 2048 + ((fq ^ swz) << 4));
; #pragma unroll
;       for (int n = 0; n < 2; ++n) bfb[0][n] = *(const bf16x8*)(sb + n * 2048 + ((fq ^ swz) << 4));
; #pragma unroll
;       for (int gq = 0; gq < 8; ++gq) {
;         const int ks = gq >> 2, nh = gq & 3;
;         if (gq < 7) {
;           const int ks2 = (gq + 1) >> 2, nh2 = (gq + 1) & 3;
; #pragma unroll
;           for (int n = 0; n < 2; ++n) bfb[(gq + 1) & 1][n] = *(const bf16x8*)(sb + (nh2 * 2 + n) * 2048 + (((ks2 * 4 + fq) ^ swz) << 4));
;         }
;         if (gq == 3) {
; #pragma unroll
;           for (int m = 0; m < 4; ++m) afB[m] = *(const bf16x8*)(sa + m * 2048 + (((4 + fq) ^ swz) << 4));
;         }
;         __builtin_amdgcn_sched_barrier(0);
; #pragma unroll
.LBB0_2714:
	s_add_i32 s8, s7, 0x10000
	s_and_b32 s9, s8, 0x10000
	v_add_u32_e32 v167, s9, v138
	s_nop 0
	v_readfirstlane_b32 s9, v167
	s_waitcnt vmcnt(0)
	s_barrier
	s_and_b32 s7, s7, 0x10000
	v_add_u32_e32 v130, s7, v139
	v_add_u32_e32 v167, v130, v141
	ds_read_b128 v[168:171], v167
	ds_read_b128 v[172:175], v167 offset:2048
	ds_read_b128 v[176:179], v167 offset:4096
	ds_read_b128 v[180:183], v167 offset:6144
	v_or_b32_e32 v167, s7, v140
	v_add_u32_e32 v204, v167, v141
	ds_read_b128 v[184:187], v204 offset:32768
	ds_read_b128 v[188:191], v204 offset:34816
	ds_read_b128 v[192:195], v204 offset:36864
	ds_read_b128 v[196:199], v204 offset:38912
	v_add_u32_e32 v130, v130, v142
	s_waitcnt lgkmcnt(3)
	v_mfma_f32_16x16x32_bf16 v[126:129], v[168:171], v[184:187], v[126:129]
	s_mov_b32 m0, s9
	v_mfma_f32_16x16x32_bf16 v[110:113], v[172:175], v[184:187], v[110:113]
	global_load_lds_dwordx4 v166, s[18:19] sc1
	v_add_u32_e32 v166, 0x80, v166
	v_mfma_f32_16x16x32_bf16 v[82:85], v[176:179], v[184:187], v[82:85]
	v_mfma_f32_16x16x32_bf16 v[50:53], v[180:183], v[184:187], v[50:53]
	ds_read_b128 v[184:187], v204 offset:40960
	ds_read_b128 v[200:203], v204 offset:43008
	s_waitcnt lgkmcnt(4)
	v_mfma_f32_16x16x32_bf16 v[122:125], v[168:171], v[188:191], v[122:125]
	s_add_u32 m0, s9, 0x8000
	v_mfma_f32_16x16x32_bf16 v[106:109], v[172:175], v[188:191], v[106:109]
	global_load_lds_dwordx4 v165, s[24:25] sc1
	v_add_u32_e32 v165, 0x80, v165
	v_mfma_f32_16x16x32_bf16 v[78:81], v[176:179], v[188:191], v[78:81]
	v_mfma_f32_16x16x32_bf16 v[42:45], v[180:183], v[188:191], v[42:45]
	s_waitcnt lgkmcnt(3)
	v_mfma_f32_16x16x32_bf16 v[118:121], v[168:171], v[192:195], v[118:121]
	s_add_u32 m0, s9, 0x2000
	v_mfma_f32_16x16x32_bf16 v[94:97], v[172:175], v[192:195], v[94:97]
	global_load_lds_dwordx4 v164, s[18:19] sc1
	v_add_u32_e32 v164, 0x80, v164
	v_mfma_f32_16x16x32_bf16 v[58:61], v[176:179], v[192:195], v[58:61]
	v_mfma_f32_16x16x32_bf16 v[26:29], v[180:183], v[192:195], v[26:29]
	ds_read_b128 v[188:191], v204 offset:45056
	ds_read_b128 v[192:195], v204 offset:47104
	s_waitcnt lgkmcnt(4)
	v_mfma_f32_16x16x32_bf16 v[114:117], v[168:171], v[196:199], v[114:117]
	s_add_u32 m0, s9, 0xa000
	v_mfma_f32_16x16x32_bf16 v[86:89], v[172:175], v[196:199], v[86:89]
	global_load_lds_dwordx4 v163, s[24:25] sc1
	v_add_u32_e32 v163, 0x80, v163
	v_mfma_f32_16x16x32_bf16 v[54:57], v[176:179], v[196:199], v[54:57]
	v_mfma_f32_16x16x32_bf16 v[22:25], v[180:183], v[196:199], v[22:25]
	v_add_u32_e32 v167, v167, v142
	s_waitcnt lgkmcnt(3)
	v_mfma_f32_16x16x32_bf16 v[102:105], v[168:171], v[184:187], v[102:105]
	ds_read_b128 v[196:199], v167 offset:32768
	ds_read_b128 v[204:207], v167 offset:34816
	s_add_u32 m0, s9, 0x4000
	v_mfma_f32_16x16x32_bf16 v[74:77], v[172:175], v[184:187], v[74:77]
	global_load_lds_dwordx4 v135, s[18:19] sc1
	v_add_u32_e32 v135, 0x80, v135
	v_mfma_f32_16x16x32_bf16 v[46:49], v[176:179], v[184:187], v[46:49]
	v_mfma_f32_16x16x32_bf16 v[10:13], v[180:183], v[184:187], v[10:13]
	ds_read_b128 v[184:187], v130
	ds_read_b128 v[208:211], v130 offset:2048
	ds_read_b128 v[212:215], v130 offset:4096
	ds_read_b128 v[216:219], v130 offset:6144
	s_waitcnt lgkmcnt(8)
	v_mfma_f32_16x16x32_bf16 v[98:101], v[168:171], v[200:203], v[98:101]
	s_add_u32 m0, s9, 0xc000
	v_mfma_f32_16x16x32_bf16 v[66:69], v[172:175], v[200:203], v[66:69]
	global_load_lds_dwordx4 v134, s[24:25] sc1
	v_add_u32_e32 v134, 0x80, v134
	v_mfma_f32_16x16x32_bf16 v[30:33], v[176:179], v[200:203], v[30:33]
	v_mfma_f32_16x16x32_bf16 v[6:9], v[180:183], v[200:203], v[6:9]
	s_waitcnt lgkmcnt(7)
	v_mfma_f32_16x16x32_bf16 v[70:73], v[168:171], v[188:191], v[70:73]
	s_add_u32 m0, s9, 0x6000
	s_waitcnt lgkmcnt(6)
	v_mfma_f32_16x16x32_bf16 v[62:65], v[168:171], v[192:195], v[62:65]
	global_load_lds_dwordx4 v133, s[18:19] sc1
	v_add_u32_e32 v133, 0x80, v133
	v_mfma_f32_16x16x32_bf16 v[38:41], v[172:175], v[188:191], v[38:41]
	v_mfma_f32_16x16x32_bf16 v[34:37], v[172:175], v[192:195], v[34:37]
	ds_read_b128 v[168:171], v167 offset:36864
	ds_read_b128 v[172:175], v167 offset:38912
	v_mfma_f32_16x16x32_bf16 v[18:21], v[176:179], v[188:191], v[18:21]
	s_add_u32 m0, s9, 0xe000
	v_mfma_f32_16x16x32_bf16 v[14:17], v[176:179], v[192:195], v[14:17]
	global_load_lds_dwordx4 v132, s[24:25] sc1
	v_add_u32_e32 v132, 0x80, v132
	v_mfma_f32_16x16x32_bf16 v[2:5], v[180:183], v[188:191], v[2:5]
	v_mfma_f32_16x16x32_bf16 v[90:93], v[180:183], v[192:195], v[90:93]
	ds_read_b128 v[176:179], v167 offset:40960
	ds_read_b128 v[180:183], v167 offset:43008
	s_waitcnt lgkmcnt(7)
	v_mfma_f32_16x16x32_bf16 v[126:129], v[184:187], v[196:199], v[126:129]
	v_mfma_f32_16x16x32_bf16 v[122:125], v[184:187], v[204:207], v[122:125]
	s_waitcnt lgkmcnt(6)
	v_mfma_f32_16x16x32_bf16 v[110:113], v[208:211], v[196:199], v[110:113]
	v_mfma_f32_16x16x32_bf16 v[106:109], v[208:211], v[204:207], v[106:109]
	s_waitcnt lgkmcnt(5)
	v_mfma_f32_16x16x32_bf16 v[82:85], v[212:215], v[196:199], v[82:85]
	v_mfma_f32_16x16x32_bf16 v[78:81], v[212:215], v[204:207], v[78:81]
	s_waitcnt lgkmcnt(4)
	v_mfma_f32_16x16x32_bf16 v[50:53], v[216:219], v[196:199], v[50:53]
	v_mfma_f32_16x16x32_bf16 v[42:45], v[216:219], v[204:207], v[42:45]
	s_waitcnt lgkmcnt(3)
	v_mfma_f32_16x16x32_bf16 v[118:121], v[184:187], v[168:171], v[118:121]
	v_mfma_f32_16x16x32_bf16 v[94:97], v[208:211], v[168:171], v[94:97]
	v_mfma_f32_16x16x32_bf16 v[58:61], v[212:215], v[168:171], v[58:61]
	v_mfma_f32_16x16x32_bf16 v[26:29], v[216:219], v[168:171], v[26:29]
	ds_read_b128 v[168:171], v167 offset:45056
	ds_read_b128 v[188:191], v167 offset:47104
	s_waitcnt lgkmcnt(4)
; template <bool SWAP, class Epi, bool THIN = false> ...
;     ...
;       bf16x8 afA[4], afB[4], bfb[2][2];
; #pragma unroll
;       for (int m = 0; m < 4; ++m) afA[m] = *(const bf16x8*)(sa + m * 2048 + ((fq ^ swz) << 4));
; #pragma unroll
;       for (int n = 0; n < 2; ++n) bfb[0][n] = *(const bf16x8*)(sb + n * 2048 + ((fq ^ swz) << 4));
; #pragma unroll
;       for (int gq = 0; gq < 8; ++gq) {
;         const int ks = gq >> 2, nh = gq & 3;
;         if (gq < 7) {
;           const int ks2 = (gq + 1) >> 2, nh2 = (gq + 1) & 3;
; #pragma unroll
;           for (int n = 0; n < 2; ++n) bfb[(gq + 1) & 1][n] = *(const bf16x8*)(sb + (nh2 * 2 + n) * 2048 + (((ks2 * 4 + fq) ^ swz) << 4));
;         }
;         if (gq == 3) {
; #pragma unroll
;           for (int m = 0; m < 4; ++m) afB[m] = *(const bf16x8*)(sa + m * 2048 + (((4 + fq) ^ swz) << 4));
;         }
;         __builtin_amdgcn_sched_barrier(0);
; #pragma unroll
;         for (int m = 0; m < 4; ++m)
; #pragma unroll
;           for (int n = 0; n < 2; ++n) {
;             const bf16x8 av = ks ? afB[m] : afA[m];
;             acc[m][nh * 2 + n] = SWAP ? __builtin_amdgcn_mfma_f32_16x16x32_bf16(bfb[gq & 1][n], av, acc[m][nh * 2 + n], 0, 0, 0)
;                                       : __builtin_amdgcn_mfma_f32_16x16x32_bf16(av, bfb[gq & 1][n], acc[m][nh * 2 + n], 0, 0, 0);
;           }
;       }
;       }
;     }
;     __syncthreads();
	v_mfma_f32_16x16x32_bf16 v[114:117], v[184:187], v[172:175], v[114:117]
	v_mfma_f32_16x16x32_bf16 v[86:89], v[208:211], v[172:175], v[86:89]
	v_mfma_f32_16x16x32_bf16 v[54:57], v[212:215], v[172:175], v[54:57]
	v_mfma_f32_16x16x32_bf16 v[22:25], v[216:219], v[172:175], v[22:25]
	s_waitcnt lgkmcnt(3)
	v_mfma_f32_16x16x32_bf16 v[102:105], v[184:187], v[176:179], v[102:105]
	s_waitcnt lgkmcnt(2)
	v_mfma_f32_16x16x32_bf16 v[98:101], v[184:187], v[180:183], v[98:101]
	v_mfma_f32_16x16x32_bf16 v[74:77], v[208:211], v[176:179], v[74:77]
	v_mfma_f32_16x16x32_bf16 v[66:69], v[208:211], v[180:183], v[66:69]
	v_mfma_f32_16x16x32_bf16 v[46:49], v[212:215], v[176:179], v[46:49]
	v_mfma_f32_16x16x32_bf16 v[30:33], v[212:215], v[180:183], v[30:33]
	v_mfma_f32_16x16x32_bf16 v[10:13], v[216:219], v[176:179], v[10:13]
	v_mfma_f32_16x16x32_bf16 v[6:9], v[216:219], v[180:183], v[6:9]
	s_waitcnt lgkmcnt(1)
	v_mfma_f32_16x16x32_bf16 v[70:73], v[184:187], v[168:171], v[70:73]
	s_add_i32 s6, s6, 64
	s_cmpk_eq_i32 s6, 0x3c0
	s_mov_b32 s7, s8
	s_waitcnt lgkmcnt(0)
	v_mfma_f32_16x16x32_bf16 v[62:65], v[184:187], v[188:191], v[62:65]
	v_mfma_f32_16x16x32_bf16 v[38:41], v[208:211], v[168:171], v[38:41]
	v_mfma_f32_16x16x32_bf16 v[34:37], v[208:211], v[188:191], v[34:37]
	v_mfma_f32_16x16x32_bf16 v[18:21], v[212:215], v[168:171], v[18:21]
	v_mfma_f32_16x16x32_bf16 v[14:17], v[212:215], v[188:191], v[14:17]
	v_mfma_f32_16x16x32_bf16 v[2:5], v[216:219], v[168:171], v[2:5]
	v_mfma_f32_16x16x32_bf16 v[90:93], v[216:219], v[188:191], v[90:93]
	s_cbranch_scc0 .LBB0_2714
	s_waitcnt vmcnt(0)
	s_barrier
	v_add_u32_e32 v130, v153, v141
	ds_read_b128 v[132:135], v130
	ds_read_b128 v[164:167], v130 offset:2048
	ds_read_b128 v[168:171], v130 offset:4096
	ds_read_b128 v[172:175], v130 offset:6144
	v_add_u32_e32 v130, v154, v141
	ds_read_b128 v[176:179], v130
	ds_read_b128 v[180:183], v130 offset:2048
	ds_read_b128 v[184:187], v130 offset:4096
	ds_read_b128 v[188:191], v130 offset:6144
	s_waitcnt lgkmcnt(0)
	v_mfma_f32_16x16x32_bf16 v[126:129], v[132:135], v[176:179], v[126:129]
	v_mfma_f32_16x16x32_bf16 v[110:113], v[164:167], v[176:179], v[110:113]
	v_mfma_f32_16x16x32_bf16 v[82:85], v[168:171], v[176:179], v[82:85]
	v_mfma_f32_16x16x32_bf16 v[50:53], v[172:175], v[176:179], v[50:53]
	ds_read_b128 v[176:179], v130 offset:8192
	ds_read_b128 v[192:195], v130 offset:10240
	v_mfma_f32_16x16x32_bf16 v[122:125], v[132:135], v[180:183], v[122:125]
	v_mfma_f32_16x16x32_bf16 v[106:109], v[164:167], v[180:183], v[106:109]
	v_mfma_f32_16x16x32_bf16 v[78:81], v[168:171], v[180:183], v[78:81]
	v_mfma_f32_16x16x32_bf16 v[42:45], v[172:175], v[180:183], v[42:45]
	v_mfma_f32_16x16x32_bf16 v[118:121], v[132:135], v[184:187], v[118:121]
	v_mfma_f32_16x16x32_bf16 v[180:183], v[164:167], v[184:187], v[94:97]
	v_mfma_f32_16x16x32_bf16 v[200:203], v[168:171], v[184:187], v[58:61]
	v_mfma_f32_16x16x32_bf16 v[204:207], v[168:171], v[188:191], v[54:57]
	v_mfma_f32_16x16x32_bf16 v[184:187], v[172:175], v[184:187], v[26:29]
	s_nop 2
	ds_read_b128 v[26:29], v130 offset:12288
	ds_read_b128 v[54:57], v130 offset:14336
	v_mfma_f32_16x16x32_bf16 v[114:117], v[132:135], v[188:191], v[114:117]
	v_mfma_f32_16x16x32_bf16 v[196:199], v[164:167], v[188:191], v[86:89]
	v_mfma_f32_16x16x32_bf16 v[188:191], v[172:175], v[188:191], v[22:25]
	v_add_u32_e32 v130, v154, v142
	s_waitcnt lgkmcnt(0)
	v_mfma_f32_16x16x32_bf16 v[208:211], v[168:171], v[192:195], v[30:33]
	ds_read_b128 v[22:25], v130
	ds_read_b128 v[86:89], v130 offset:2048
	s_nop 0
	v_add_u32_e32 v30, v153, v142
	v_mfma_f32_16x16x32_bf16 v[102:105], v[132:135], v[176:179], v[102:105]
	v_mfma_f32_16x16x32_bf16 v[74:77], v[164:167], v[176:179], v[74:77]
	v_mfma_f32_16x16x32_bf16 v[46:49], v[168:171], v[176:179], v[46:49]
	v_mfma_f32_16x16x32_bf16 v[10:13], v[172:175], v[176:179], v[10:13]
	ds_read_b128 v[176:179], v30
	ds_read_b128 v[212:215], v30 offset:2048
	ds_read_b128 v[216:219], v30 offset:4096
	ds_read_b128 v[220:223], v30 offset:6144
	v_mfma_f32_16x16x32_bf16 v[98:101], v[132:135], v[192:195], v[98:101]
	v_mfma_f32_16x16x32_bf16 v[66:69], v[164:167], v[192:195], v[66:69]
	v_mfma_f32_16x16x32_bf16 v[6:9], v[172:175], v[192:195], v[6:9]
	v_mfma_f32_16x16x32_bf16 v[192:195], v[164:167], v[26:29], v[38:41]
	v_mfma_f32_16x16x32_bf16 v[34:37], v[164:167], v[54:57], v[34:37]
	v_mfma_f32_16x16x32_bf16 v[164:167], v[168:171], v[26:29], v[18:21]
	v_mfma_f32_16x16x32_bf16 v[168:171], v[168:171], v[54:57], v[14:17]
	s_nop 2
	ds_read_b128 v[14:17], v130 offset:4096
	ds_read_b128 v[18:21], v130 offset:6144
	v_mfma_f32_16x16x32_bf16 v[70:73], v[132:135], v[26:29], v[70:73]
	v_mfma_f32_16x16x32_bf16 v[132:135], v[132:135], v[54:57], v[62:65]
	v_mfma_f32_16x16x32_bf16 v[2:5], v[172:175], v[26:29], v[2:5]
	v_mfma_f32_16x16x32_bf16 v[172:175], v[172:175], v[54:57], v[90:93]
	ds_read_b128 v[224:227], v130 offset:8192
	ds_read_b128 v[228:231], v130 offset:10240
	s_waitcnt lgkmcnt(0)
	v_mfma_f32_16x16x32_bf16 v[126:129], v[176:179], v[22:25], v[126:129]
	v_mfma_f32_16x16x32_bf16 v[122:125], v[176:179], v[86:89], v[122:125]
	v_mfma_f32_16x16x32_bf16 v[94:97], v[212:215], v[22:25], v[110:113]
	v_mfma_f32_16x16x32_bf16 v[90:93], v[212:215], v[86:89], v[106:109]
	v_mfma_f32_16x16x32_bf16 v[62:65], v[216:219], v[22:25], v[82:85]
	v_mfma_f32_16x16x32_bf16 v[58:61], v[216:219], v[86:89], v[78:81]
	v_mfma_f32_16x16x32_bf16 v[30:33], v[220:223], v[22:25], v[50:53]
	v_mfma_f32_16x16x32_bf16 v[26:29], v[220:223], v[86:89], v[42:45]
	v_mfma_f32_16x16x32_bf16 v[86:89], v[212:215], v[14:17], v[180:183]
	v_mfma_f32_16x16x32_bf16 v[22:25], v[220:223], v[14:17], v[184:187]
	s_nop 1
	ds_read_b128 v[180:183], v130 offset:12288
	ds_read_b128 v[184:187], v130 offset:14336
	v_mfma_f32_16x16x32_bf16 v[118:121], v[176:179], v[14:17], v[118:121]
	v_mfma_f32_16x16x32_bf16 v[114:117], v[176:179], v[18:21], v[114:117]
	v_mfma_f32_16x16x32_bf16 v[82:85], v[212:215], v[18:21], v[196:199]
	v_mfma_f32_16x16x32_bf16 v[54:57], v[216:219], v[14:17], v[200:203]
	v_mfma_f32_16x16x32_bf16 v[50:53], v[216:219], v[18:21], v[204:207]
	v_mfma_f32_16x16x32_bf16 v[18:21], v[220:223], v[18:21], v[188:191]
	v_mfma_f32_16x16x32_bf16 v[110:113], v[176:179], v[224:227], v[102:105]
	v_mfma_f32_16x16x32_bf16 v[106:109], v[176:179], v[228:231], v[98:101]
	v_mfma_f32_16x16x32_bf16 v[78:81], v[212:215], v[224:227], v[74:77]
	v_mfma_f32_16x16x32_bf16 v[74:77], v[212:215], v[228:231], v[66:69]
	v_mfma_f32_16x16x32_bf16 v[46:49], v[216:219], v[224:227], v[46:49]
	v_mfma_f32_16x16x32_bf16 v[38:41], v[216:219], v[228:231], v[208:211]
	v_mfma_f32_16x16x32_bf16 v[14:17], v[220:223], v[224:227], v[10:13]
	v_mfma_f32_16x16x32_bf16 v[6:9], v[220:223], v[228:231], v[6:9]
	v_mov_b32_e32 v130, v1
	s_waitcnt vmcnt(0) lgkmcnt(0)
	s_barrier
; __device__ __forceinline__ int get_tid512() { int t = threadIdx.x; asm volatile("" : "+v"(t)); return t; }
; __device__ __forceinline__ unsigned pack2(float a, float b) { unsigned r; asm("v_cvt_pk_bf16_f32 %0, %1, %2" : "=v"(r) : "v"(a), "v"(b)); return r; }
;   __device__ __forceinline__ void r4(int g, int rig, int col, f32x4 v) const {
;     const float b = bias[col];
;     uint2 u; u.x = pack2(v[0] + b, v[1] + b); u.y = pack2(v[2] + b, v[3] + b);
;     *(uint2*)(out + (size_t)col * 16384 + (size_t)g * 2048 + rig) = u;
;   }
; template <bool SWAP, class Epi, bool THIN = false> ...
;     ...
;     __syncthreads();
;     const int te = get_tid512();
;     const int fr_e = te & 15, fq_e = (te & 63) >> 4, wr_e = te >> 7, wc_e = (te >> 6) & 1;
;     const int sub = 2 * mt + (wr_e >> 1);
;     const int g = sub / tpg, ti = sub - g * tpg;
;     const int rig0 = ti * step - halo;
;     const int rw = (wr_e & 1) * 64;
;     if constexpr (Epi::KIND == 0) {
; #pragma unroll
;       for (int m = 0; m < 4; ++m) {
;         const int rig = rig0 + rw + m * 16 + fr_e;
;         if constexpr (Epi::ROWSUM) {
;           float ss = 0.f;
; #pragma unroll
;           for (int n = 0; n < 8; ++n) {
;             const int col = nt * 256 + wc_e * 128 + n * 16 + fq_e * 4;
;             if (col < N) ss += epi.c4(g, rig, col, acc[m][n]);
;           }
;           ss += __shfl_xor(ss, 16); ss += __shfl_xor(ss, 32);
;           if (fq_e == 0) epi.rowsum(g, rig, nt * 2 + wc_e, ss);
;         } else {
; #pragma unroll
;           for (int n = 0; n < 8; ++n) {
;             const int col = nt * 256 + wc_e * 128 + n * 16 + fq_e * 4;
;             if (col < N) epi.c4(g, rig, col, acc[m][n]);
;           }
;         }
;       }
;     } else if constexpr (Epi::KIND == 1) {
; #pragma unroll
;       for (int m = 0; m < 4; ++m) {
;         const int rig = rig0 + rw + m * 16 + fq_e * 4;
; #pragma unroll
;         for (int n = 0; n < 8; ++n) {
;           const int col = nt * 256 + wc_e * 128 + n * 16 + fr_e;
;           if (col < N) epi.r4(g, rig, col, acc[m][n]);
;         }
;       }
	v_mfma_f32_16x16x32_bf16 v[98:101], v[176:179], v[184:187], v[132:135]
	v_ashrrev_i32_e32 v10, 8, v130
	v_add_u32_e32 v10, s5, v10
	v_ashrrev_i32_e32 v11, 31, v10
	v_lshrrev_b32_e32 v11, 28, v11
	v_add_u32_e32 v11, v10, v11
	v_ashrrev_i32_e32 v132, 4, v11
	v_lshlrev_b32_e32 v11, 11, v132
	v_lshlrev_b32_e32 v10, 7, v10
	v_sub_u32_e32 v10, v10, v11
	v_lshrrev_b32_e32 v11, 1, v130
	v_lshrrev_b32_e32 v12, 2, v130
	v_and_b32_e32 v11, 64, v11
	v_and_b32_e32 v12, 12, v12
	v_mfma_f32_16x16x32_bf16 v[42:45], v[216:219], v[180:183], v[164:167]
	v_and_b32_e32 v133, 15, v130
	s_nop 1
	v_or3_b32 v164, v10, v11, v12
	v_mfma_f32_16x16x32_bf16 v[10:13], v[220:223], v[180:183], v[2:5]
	v_ashrrev_i32_e32 v165, 31, v164
	s_nop 1
	v_lshlrev_b32_e32 v2, 1, v130
	v_and_b32_e32 v2, 0x80, v2
	v_mfma_f32_16x16x32_bf16 v[102:105], v[176:179], v[180:183], v[70:73]
	v_or3_b32 v134, v133, v2, s4
	v_ashrrev_i32_e32 v133, 31, v132
	v_lshlrev_b64 v[132:133], 12, v[132:133]
	v_mfma_f32_16x16x32_bf16 v[70:73], v[212:215], v[180:183], v[192:195]
	v_lshl_add_u64 v[132:133], s[20:21], 0, v[132:133]
	v_lshl_add_u64 v[132:133], v[164:165], 1, v[132:133]
	v_cmp_gt_i32_e32 vcc, s30, v134
	v_mfma_f32_16x16x32_bf16 v[66:69], v[212:215], v[184:187], v[34:37]
	v_ashrrev_i32_e32 v135, 31, v134
	v_mfma_f32_16x16x32_bf16 v[34:37], v[216:219], v[184:187], v[168:171]
	v_mfma_f32_16x16x32_bf16 v[2:5], v[220:223], v[184:187], v[172:175]
	v_lshlrev_b32_e32 v236, 2, v134
	global_load_dword v237, v236, s[22:23]
	global_load_dword v238, v236, s[22:23] offset:64
	global_load_dword v239, v236, s[22:23] offset:128
	global_load_dword v240, v236, s[22:23] offset:192
	global_load_dword v241, v236, s[22:23] offset:256
	global_load_dword v242, v236, s[22:23] offset:320
	global_load_dword v243, v236, s[22:23] offset:384
	global_load_dword v244, v236, s[22:23] offset:448
	s_waitcnt vmcnt(0)
	v_lshl_add_u64 v[164:165], v[134:135], 2, s[22:23]
	v_mov_b32_e32 v130, v237
	v_lshlrev_b64 v[164:165], 15, v[134:135]
	v_add_f32_e32 v126, v126, v130
	v_add_f32_e32 v127, v127, v130
	v_add_f32_e32 v128, v128, v130
	v_add_f32_e32 v129, v129, v130
	v_cvt_pk_bf16_f32 v126, v126, v127
	v_cvt_pk_bf16_f32 v127, v128, v129
	v_lshl_add_u64 v[128:129], v[132:133], 0, v[164:165]
	global_store_dwordx2 v[128:129], v[126:127], off
	v_or_b32_e32 v126, 16, v134
	v_ashrrev_i32_e32 v127, 31, v126
	v_lshl_add_u64 v[128:129], v[126:127], 2, s[22:23]
	v_mov_b32_e32 v130, v238
	v_lshlrev_b64 v[128:129], 15, v[126:127]
	v_add_f32_e32 v122, v122, v130
	v_add_f32_e32 v123, v123, v130
	v_add_f32_e32 v124, v124, v130
	v_add_f32_e32 v125, v125, v130
	v_cvt_pk_bf16_f32 v122, v122, v123
	v_cvt_pk_bf16_f32 v123, v124, v125
	v_lshl_add_u64 v[124:125], v[132:133], 0, v[128:129]
	global_store_dwordx2 v[124:125], v[122:123], off
	v_or_b32_e32 v122, 32, v134
	v_ashrrev_i32_e32 v123, 31, v122
	v_lshl_add_u64 v[124:125], v[122:123], 2, s[22:23]
	v_mov_b32_e32 v128, v239
	v_lshlrev_b64 v[124:125], 15, v[122:123]
	v_add_f32_e32 v118, v118, v128
	v_add_f32_e32 v119, v119, v128
	v_add_f32_e32 v120, v120, v128
	v_add_f32_e32 v121, v121, v128
	v_cvt_pk_bf16_f32 v118, v118, v119
	v_cvt_pk_bf16_f32 v119, v120, v121
	v_lshl_add_u64 v[120:121], v[132:133], 0, v[124:125]
	global_store_dwordx2 v[120:121], v[118:119], off
	v_or_b32_e32 v118, 48, v134
	v_ashrrev_i32_e32 v119, 31, v118
	v_lshl_add_u64 v[120:121], v[118:119], 2, s[22:23]
	v_mov_b32_e32 v124, v240
	v_lshlrev_b64 v[120:121], 15, v[118:119]
	v_add_f32_e32 v114, v114, v124
	v_add_f32_e32 v115, v115, v124
	v_add_f32_e32 v116, v116, v124
	v_add_f32_e32 v117, v117, v124
	v_cvt_pk_bf16_f32 v114, v114, v115
	v_cvt_pk_bf16_f32 v115, v116, v117
	v_lshl_add_u64 v[116:117], v[132:133], 0, v[120:121]
	global_store_dwordx2 v[116:117], v[114:115], off
	v_or_b32_e32 v114, 64, v134
	v_ashrrev_i32_e32 v115, 31, v114
	v_lshl_add_u64 v[116:117], v[114:115], 2, s[22:23]
	v_mov_b32_e32 v120, v241
	v_lshlrev_b64 v[116:117], 15, v[114:115]
	v_add_f32_e32 v110, v110, v120
	v_add_f32_e32 v111, v111, v120
	v_add_f32_e32 v112, v112, v120
	v_add_f32_e32 v113, v113, v120
	v_cvt_pk_bf16_f32 v110, v110, v111
	v_cvt_pk_bf16_f32 v111, v112, v113
	v_lshl_add_u64 v[112:113], v[132:133], 0, v[116:117]
	global_store_dwordx2 v[112:113], v[110:111], off
	v_or_b32_e32 v110, 0x50, v134
	v_ashrrev_i32_e32 v111, 31, v110
	v_lshl_add_u64 v[112:113], v[110:111], 2, s[22:23]
	v_mov_b32_e32 v116, v242
	v_lshlrev_b64 v[112:113], 15, v[110:111]
	v_add_f32_e32 v106, v106, v116
	v_add_f32_e32 v107, v107, v116
	v_add_f32_e32 v108, v108, v116
	v_add_f32_e32 v109, v109, v116
	v_cvt_pk_bf16_f32 v106, v106, v107
	v_cvt_pk_bf16_f32 v107, v108, v109
	v_lshl_add_u64 v[108:109], v[132:133], 0, v[112:113]
	global_store_dwordx2 v[108:109], v[106:107], off
	v_or_b32_e32 v106, 0x60, v134
	v_ashrrev_i32_e32 v107, 31, v106
	v_lshl_add_u64 v[108:109], v[106:107], 2, s[22:23]
	v_mov_b32_e32 v112, v243
	v_lshlrev_b64 v[108:109], 15, v[106:107]
	v_add_f32_e32 v102, v102, v112
	v_add_f32_e32 v103, v103, v112
	v_add_f32_e32 v104, v104, v112
	v_add_f32_e32 v105, v105, v112
	v_cvt_pk_bf16_f32 v102, v102, v103
	v_cvt_pk_bf16_f32 v103, v104, v105
	v_lshl_add_u64 v[104:105], v[132:133], 0, v[108:109]
	global_store_dwordx2 v[104:105], v[102:103], off
	v_or_b32_e32 v102, 0x70, v134
	v_ashrrev_i32_e32 v103, 31, v102
	v_lshl_add_u64 v[104:105], v[102:103], 2, s[22:23]
	v_mov_b32_e32 v108, v244
	v_lshlrev_b64 v[104:105], 15, v[102:103]
	v_add_f32_e32 v98, v98, v108
	v_add_f32_e32 v99, v99, v108
	v_add_f32_e32 v100, v100, v108
	v_add_f32_e32 v101, v101, v108
	v_cvt_pk_bf16_f32 v98, v98, v99
	v_cvt_pk_bf16_f32 v99, v100, v101
	v_lshl_add_u64 v[100:101], v[132:133], 0, v[104:105]
; __device__ __forceinline__ unsigned pack2(float a, float b) { unsigned r; asm("v_cvt_pk_bf16_f32 %0, %1, %2" : "=v"(r) : "v"(a), "v"(b)); return r; }
;   __device__ __forceinline__ void r4(int g, int rig, int col, f32x4 v) const {
;     const float b = bias[col];
;     uint2 u; u.x = pack2(v[0] + b, v[1] + b); u.y = pack2(v[2] + b, v[3] + b);
;     *(uint2*)(out + (size_t)col * 16384 + (size_t)g * 2048 + rig) = u;
;   }
; template <bool SWAP, class Epi, bool THIN = false> ...
;     ...
;     } else if constexpr (Epi::KIND == 1) {
; #pragma unroll
;       for (int m = 0; m < 4; ++m) {
;         const int rig = rig0 + rw + m * 16 + fq_e * 4;
; #pragma unroll
;         for (int n = 0; n < 8; ++n) {
;           const int col = nt * 256 + wc_e * 128 + n * 16 + fr_e;
;           if (col < N) epi.r4(g, rig, col, acc[m][n]);
;         }
;       }
	global_store_dwordx2 v[100:101], v[98:99], off
	v_lshl_add_u64 v[98:99], v[134:135], 2, s[22:23]
	v_mov_b32_e32 v100, v237
	v_lshlrev_b64 v[98:99], 15, v[134:135]
	v_add_f32_e32 v94, v94, v100
	v_add_f32_e32 v95, v95, v100
	v_add_f32_e32 v96, v96, v100
	v_add_f32_e32 v97, v97, v100
	v_cvt_pk_bf16_f32 v94, v94, v95
	v_cvt_pk_bf16_f32 v95, v96, v97
	v_lshl_add_u64 v[96:97], v[132:133], 0, v[98:99]
	global_store_dwordx2 v[96:97], v[94:95], off offset:32
	v_lshl_add_u64 v[94:95], v[126:127], 2, s[22:23]
	v_mov_b32_e32 v96, v238
	v_lshlrev_b64 v[94:95], 15, v[126:127]
	v_add_f32_e32 v90, v90, v96
	v_add_f32_e32 v91, v91, v96
	v_add_f32_e32 v92, v92, v96
	v_add_f32_e32 v93, v93, v96
	v_cvt_pk_bf16_f32 v90, v90, v91
	v_cvt_pk_bf16_f32 v91, v92, v93
	v_lshl_add_u64 v[92:93], v[132:133], 0, v[94:95]
	global_store_dwordx2 v[92:93], v[90:91], off offset:32
	v_lshl_add_u64 v[90:91], v[122:123], 2, s[22:23]
	v_mov_b32_e32 v92, v239
	v_lshlrev_b64 v[90:91], 15, v[122:123]
	v_add_f32_e32 v86, v86, v92
	v_add_f32_e32 v87, v87, v92
	v_add_f32_e32 v88, v88, v92
	v_add_f32_e32 v89, v89, v92
	v_cvt_pk_bf16_f32 v86, v86, v87
	v_cvt_pk_bf16_f32 v87, v88, v89
	v_lshl_add_u64 v[88:89], v[132:133], 0, v[90:91]
	global_store_dwordx2 v[88:89], v[86:87], off offset:32
	v_lshl_add_u64 v[86:87], v[118:119], 2, s[22:23]
	v_mov_b32_e32 v88, v240
	v_lshlrev_b64 v[86:87], 15, v[118:119]
	v_add_f32_e32 v82, v82, v88
	v_add_f32_e32 v83, v83, v88
	v_add_f32_e32 v84, v84, v88
	v_add_f32_e32 v85, v85, v88
	v_cvt_pk_bf16_f32 v82, v82, v83
	v_cvt_pk_bf16_f32 v83, v84, v85
	v_lshl_add_u64 v[84:85], v[132:133], 0, v[86:87]
	global_store_dwordx2 v[84:85], v[82:83], off offset:32
	v_lshl_add_u64 v[82:83], v[114:115], 2, s[22:23]
	v_mov_b32_e32 v84, v241
	v_lshlrev_b64 v[82:83], 15, v[114:115]
	v_add_f32_e32 v78, v78, v84
	v_add_f32_e32 v79, v79, v84
	v_add_f32_e32 v80, v80, v84
	v_add_f32_e32 v81, v81, v84
	v_cvt_pk_bf16_f32 v78, v78, v79
	v_cvt_pk_bf16_f32 v79, v80, v81
	v_lshl_add_u64 v[80:81], v[132:133], 0, v[82:83]
	global_store_dwordx2 v[80:81], v[78:79], off offset:32
	v_lshl_add_u64 v[78:79], v[110:111], 2, s[22:23]
	v_mov_b32_e32 v80, v242
	v_lshlrev_b64 v[78:79], 15, v[110:111]
	v_add_f32_e32 v74, v74, v80
	v_add_f32_e32 v75, v75, v80
	v_add_f32_e32 v76, v76, v80
	v_add_f32_e32 v77, v77, v80
	v_cvt_pk_bf16_f32 v74, v74, v75
	v_cvt_pk_bf16_f32 v75, v76, v77
	v_lshl_add_u64 v[76:77], v[132:133], 0, v[78:79]
	global_store_dwordx2 v[76:77], v[74:75], off offset:32
	v_lshl_add_u64 v[74:75], v[106:107], 2, s[22:23]
	v_mov_b32_e32 v76, v243
	v_lshlrev_b64 v[74:75], 15, v[106:107]
	v_add_f32_e32 v70, v70, v76
	v_add_f32_e32 v71, v71, v76
	v_add_f32_e32 v72, v72, v76
	v_add_f32_e32 v73, v73, v76
	v_cvt_pk_bf16_f32 v70, v70, v71
	v_cvt_pk_bf16_f32 v71, v72, v73
	v_lshl_add_u64 v[72:73], v[132:133], 0, v[74:75]
	global_store_dwordx2 v[72:73], v[70:71], off offset:32
	v_lshl_add_u64 v[70:71], v[102:103], 2, s[22:23]
	v_mov_b32_e32 v72, v244
	v_lshlrev_b64 v[70:71], 15, v[102:103]
	v_add_f32_e32 v66, v66, v72
	v_add_f32_e32 v67, v67, v72
	v_add_f32_e32 v68, v68, v72
	v_add_f32_e32 v69, v69, v72
	v_cvt_pk_bf16_f32 v66, v66, v67
	v_cvt_pk_bf16_f32 v67, v68, v69
	v_lshl_add_u64 v[68:69], v[132:133], 0, v[70:71]
	global_store_dwordx2 v[68:69], v[66:67], off offset:32
	v_lshl_add_u64 v[66:67], v[134:135], 2, s[22:23]
	v_mov_b32_e32 v68, v237
	v_lshlrev_b64 v[66:67], 15, v[134:135]
	v_add_f32_e32 v62, v62, v68
	v_add_f32_e32 v63, v63, v68
	v_add_f32_e32 v64, v64, v68
	v_add_f32_e32 v65, v65, v68
	v_cvt_pk_bf16_f32 v62, v62, v63
	v_cvt_pk_bf16_f32 v63, v64, v65
	v_lshl_add_u64 v[64:65], v[132:133], 0, v[66:67]
	global_store_dwordx2 v[64:65], v[62:63], off offset:64
	v_lshl_add_u64 v[62:63], v[126:127], 2, s[22:23]
	v_mov_b32_e32 v64, v238
	v_lshlrev_b64 v[62:63], 15, v[126:127]
	v_add_f32_e32 v58, v58, v64
	v_add_f32_e32 v59, v59, v64
	v_add_f32_e32 v60, v60, v64
	v_add_f32_e32 v61, v61, v64
	v_cvt_pk_bf16_f32 v58, v58, v59
	v_cvt_pk_bf16_f32 v59, v60, v61
	v_lshl_add_u64 v[60:61], v[132:133], 0, v[62:63]
	global_store_dwordx2 v[60:61], v[58:59], off offset:64
	v_lshl_add_u64 v[58:59], v[122:123], 2, s[22:23]
	v_mov_b32_e32 v60, v239
	v_lshlrev_b64 v[58:59], 15, v[122:123]
	v_add_f32_e32 v54, v54, v60
	v_add_f32_e32 v55, v55, v60
	v_add_f32_e32 v56, v56, v60
	v_add_f32_e32 v57, v57, v60
	v_cvt_pk_bf16_f32 v54, v54, v55
	v_cvt_pk_bf16_f32 v55, v56, v57
	v_lshl_add_u64 v[56:57], v[132:133], 0, v[58:59]
	global_store_dwordx2 v[56:57], v[54:55], off offset:64
	v_lshl_add_u64 v[54:55], v[118:119], 2, s[22:23]
	v_mov_b32_e32 v56, v240
	v_lshlrev_b64 v[54:55], 15, v[118:119]
	v_add_f32_e32 v50, v50, v56
	v_add_f32_e32 v51, v51, v56
	v_add_f32_e32 v52, v52, v56
	v_add_f32_e32 v53, v53, v56
	v_cvt_pk_bf16_f32 v50, v50, v51
	v_cvt_pk_bf16_f32 v51, v52, v53
	v_lshl_add_u64 v[52:53], v[132:133], 0, v[54:55]
; __device__ __forceinline__ unsigned pack2(float a, float b) { unsigned r; asm("v_cvt_pk_bf16_f32 %0, %1, %2" : "=v"(r) : "v"(a), "v"(b)); return r; }
;   __device__ __forceinline__ void r4(int g, int rig, int col, f32x4 v) const {
;     const float b = bias[col];
;     uint2 u; u.x = pack2(v[0] + b, v[1] + b); u.y = pack2(v[2] + b, v[3] + b);
;     *(uint2*)(out + (size_t)col * 16384 + (size_t)g * 2048 + rig) = u;
;   }
; template <bool SWAP, class Epi, bool THIN = false> ...
;     ...
;     } else if constexpr (Epi::KIND == 1) {
; #pragma unroll
;       for (int m = 0; m < 4; ++m) {
;         const int rig = rig0 + rw + m * 16 + fq_e * 4;
; #pragma unroll
;         for (int n = 0; n < 8; ++n) {
;           const int col = nt * 256 + wc_e * 128 + n * 16 + fr_e;
;           if (col < N) epi.r4(g, rig, col, acc[m][n]);
;         }
;       }
	global_store_dwordx2 v[52:53], v[50:51], off offset:64
	v_lshl_add_u64 v[50:51], v[114:115], 2, s[22:23]
	v_mov_b32_e32 v52, v241
	v_lshlrev_b64 v[50:51], 15, v[114:115]
	v_add_f32_e32 v46, v46, v52
	v_add_f32_e32 v47, v47, v52
	v_add_f32_e32 v48, v48, v52
	v_add_f32_e32 v49, v49, v52
	v_cvt_pk_bf16_f32 v46, v46, v47
	v_cvt_pk_bf16_f32 v47, v48, v49
	v_lshl_add_u64 v[48:49], v[132:133], 0, v[50:51]
	global_store_dwordx2 v[48:49], v[46:47], off offset:64
	v_lshl_add_u64 v[46:47], v[110:111], 2, s[22:23]
	v_mov_b32_e32 v48, v242
	v_lshlrev_b64 v[46:47], 15, v[110:111]
	v_add_f32_e32 v38, v38, v48
	v_add_f32_e32 v39, v39, v48
	v_add_f32_e32 v40, v40, v48
	v_add_f32_e32 v41, v41, v48
	v_cvt_pk_bf16_f32 v38, v38, v39
	v_cvt_pk_bf16_f32 v39, v40, v41
	v_lshl_add_u64 v[40:41], v[132:133], 0, v[46:47]
	global_store_dwordx2 v[40:41], v[38:39], off offset:64
	v_lshl_add_u64 v[38:39], v[106:107], 2, s[22:23]
	v_mov_b32_e32 v40, v243
	v_lshlrev_b64 v[38:39], 15, v[106:107]
	v_lshl_add_u64 v[38:39], v[132:133], 0, v[38:39]
	v_add_f32_e32 v41, v42, v40
	v_add_f32_e32 v42, v43, v40
	v_add_f32_e32 v43, v44, v40
	v_add_f32_e32 v44, v45, v40
	v_cvt_pk_bf16_f32 v40, v41, v42
	v_cvt_pk_bf16_f32 v41, v43, v44
	global_store_dwordx2 v[38:39], v[40:41], off offset:64
	v_lshl_add_u64 v[38:39], v[102:103], 2, s[22:23]
	v_mov_b32_e32 v40, v244
	v_lshlrev_b64 v[38:39], 15, v[102:103]
	v_add_f32_e32 v34, v34, v40
	v_add_f32_e32 v35, v35, v40
	v_add_f32_e32 v36, v36, v40
	v_add_f32_e32 v37, v37, v40
	v_cvt_pk_bf16_f32 v34, v34, v35
	v_cvt_pk_bf16_f32 v35, v36, v37
	v_lshl_add_u64 v[36:37], v[132:133], 0, v[38:39]
	global_store_dwordx2 v[36:37], v[34:35], off offset:64
	v_lshl_add_u64 v[34:35], v[134:135], 2, s[22:23]
	v_mov_b32_e32 v36, v237
	v_lshlrev_b64 v[34:35], 15, v[134:135]
	v_add_f32_e32 v30, v30, v36
	v_add_f32_e32 v31, v31, v36
	v_add_f32_e32 v32, v32, v36
	v_add_f32_e32 v33, v33, v36
	v_cvt_pk_bf16_f32 v30, v30, v31
	v_cvt_pk_bf16_f32 v31, v32, v33
	v_lshl_add_u64 v[32:33], v[132:133], 0, v[34:35]
	global_store_dwordx2 v[32:33], v[30:31], off offset:96
	v_lshl_add_u64 v[30:31], v[126:127], 2, s[22:23]
	v_mov_b32_e32 v32, v238
	v_lshlrev_b64 v[30:31], 15, v[126:127]
	v_add_f32_e32 v26, v26, v32
	v_add_f32_e32 v27, v27, v32
	v_add_f32_e32 v28, v28, v32
	v_add_f32_e32 v29, v29, v32
	v_cvt_pk_bf16_f32 v26, v26, v27
	v_cvt_pk_bf16_f32 v27, v28, v29
	v_lshl_add_u64 v[28:29], v[132:133], 0, v[30:31]
	global_store_dwordx2 v[28:29], v[26:27], off offset:96
	v_lshl_add_u64 v[26:27], v[122:123], 2, s[22:23]
	v_mov_b32_e32 v28, v239
	v_lshlrev_b64 v[26:27], 15, v[122:123]
	v_add_f32_e32 v22, v22, v28
	v_add_f32_e32 v23, v23, v28
	v_add_f32_e32 v24, v24, v28
	v_add_f32_e32 v25, v25, v28
	v_cvt_pk_bf16_f32 v22, v22, v23
	v_cvt_pk_bf16_f32 v23, v24, v25
	v_lshl_add_u64 v[24:25], v[132:133], 0, v[26:27]
	global_store_dwordx2 v[24:25], v[22:23], off offset:96
	v_lshl_add_u64 v[22:23], v[118:119], 2, s[22:23]
	v_mov_b32_e32 v24, v240
	v_lshlrev_b64 v[22:23], 15, v[118:119]
	v_add_f32_e32 v18, v18, v24
	v_add_f32_e32 v19, v19, v24
	v_add_f32_e32 v20, v20, v24
	v_add_f32_e32 v21, v21, v24
	v_cvt_pk_bf16_f32 v18, v18, v19
	v_cvt_pk_bf16_f32 v19, v20, v21
	v_lshl_add_u64 v[20:21], v[132:133], 0, v[22:23]
	global_store_dwordx2 v[20:21], v[18:19], off offset:96
	v_lshl_add_u64 v[18:19], v[114:115], 2, s[22:23]
	v_mov_b32_e32 v20, v241
	v_lshlrev_b64 v[18:19], 15, v[114:115]
	v_add_f32_e32 v14, v14, v20
	v_add_f32_e32 v15, v15, v20
	v_add_f32_e32 v16, v16, v20
	v_add_f32_e32 v17, v17, v20
	v_cvt_pk_bf16_f32 v14, v14, v15
	v_cvt_pk_bf16_f32 v15, v16, v17
	v_lshl_add_u64 v[16:17], v[132:133], 0, v[18:19]
	global_store_dwordx2 v[16:17], v[14:15], off offset:96
	v_lshl_add_u64 v[14:15], v[110:111], 2, s[22:23]
	v_mov_b32_e32 v16, v242
	v_lshlrev_b64 v[14:15], 15, v[110:111]
	v_add_f32_e32 v6, v6, v16
	v_add_f32_e32 v7, v7, v16
	v_add_f32_e32 v8, v8, v16
	v_add_f32_e32 v9, v9, v16
	v_cvt_pk_bf16_f32 v6, v6, v7
	v_cvt_pk_bf16_f32 v7, v8, v9
	v_lshl_add_u64 v[8:9], v[132:133], 0, v[14:15]
	global_store_dwordx2 v[8:9], v[6:7], off offset:96
	v_lshl_add_u64 v[6:7], v[106:107], 2, s[22:23]
	v_mov_b32_e32 v8, v243
	v_lshlrev_b64 v[6:7], 15, v[106:107]
	v_lshl_add_u64 v[6:7], v[132:133], 0, v[6:7]
	v_add_f32_e32 v9, v10, v8
	v_add_f32_e32 v10, v11, v8
	v_add_f32_e32 v11, v12, v8
	v_add_f32_e32 v12, v13, v8
	v_cvt_pk_bf16_f32 v8, v9, v10
	v_cvt_pk_bf16_f32 v9, v11, v12
	global_store_dwordx2 v[6:7], v[8:9], off offset:96
	v_lshl_add_u64 v[6:7], v[102:103], 2, s[22:23]
	v_mov_b32_e32 v8, v244
	v_lshlrev_b64 v[6:7], 15, v[102:103]
	v_add_f32_e32 v2, v2, v8
	v_add_f32_e32 v3, v3, v8
	v_add_f32_e32 v4, v4, v8
	v_add_f32_e32 v5, v5, v8
	v_cvt_pk_bf16_f32 v2, v2, v3
	v_cvt_pk_bf16_f32 v3, v4, v5
	v_lshl_add_u64 v[4:5], v[132:133], 0, v[6:7]
	global_store_dwordx2 v[4:5], v[2:3], off offset:96
	s_branch .LBB0_2712

; template <bool SWAP, class Epi, bool THIN = false> ...
;     ...
;     for (int st = 0; st < ns; ++st) {
;       asm volatile("s_waitcnt vmcnt(0)" ::: "memory");
;       __builtin_amdgcn_s_barrier();
;       asm volatile("" ::: "memory");
;       if (st + 1 < ns) {
;         char* nb = smem + ((st + 1) & 1) * 65536;
;         const int ko = (st + 1) * 64;
; #pragma unroll
;         for (int i = 0; i < 4; ++i) { GLDS16(A + (size_t)(ap[i] + ko), nb + tid * 16 + i * 8192); GLDS16(Bt + (size_t)(bp[i] + ko), nb + 32768 + tid * 16 + i * 8192); }
;       }
;       const char* sa = smem + (st & 1) * 65536 + (wr * 64 + fr) * 128;
;       const char* sb = smem + (st & 1) * 65536 + 32768 + (wc * 128 + fr) * 128;
;       if constexpr (THIN) {
;         if (wc == 0) {
; #pragma unroll
;           for (int ks = 0; ks < 2; ++ks) {
;             bf16x8 af[4], bf[2];
; #pragma unroll
;             for (int m = 0; m < 4; ++m) af[m] = *(const bf16x8*)(sa + m * 2048 + (((ks * 4 + fq) ^ swz) << 4));
; #pragma unroll
;             for (int n = 0; n < 2; ++n) bf[n] = *(const bf16x8*)(sb + n * 2048 + (((ks * 4 + fq) ^ swz) << 4));
; #pragma unroll
;             for (int m = 0; m < 4; ++m)
; #pragma unroll
;               for (int n = 0; n < 2; ++n)
;                 acc[m][n] = SWAP ? __builtin_amdgcn_mfma_f32_16x16x32_bf16(bf[n], af[m], acc[m][n], 0, 0, 0)
;                                  : __builtin_amdgcn_mfma_f32_16x16x32_bf16(af[m], bf[n], acc[m][n], 0, 0, 0);
;           }
;         }
;       } else {
;       bf16x8 afA[4], afB[4], bfb[2][2];
; #pragma unroll
;       for (int m = 0; m < 4; ++m) afA[m] = *(const bf16x8*)(sa + m * 2048 + ((fq ^ swz) << 4));
; #pragma unroll
;       for (int n = 0; n < 2; ++n) bfb[0][n] = *(const bf16x8*)(sb + n * 2048 + ((fq ^ swz) << 4));
; #pragma unroll
;       for (int gq = 0; gq < 8; ++gq) {
;         const int ks = gq >> 2, nh = gq & 3;
;         if (gq < 7) {
;           const int ks2 = (gq + 1) >> 2, nh2 = (gq + 1) & 3;
; #pragma unroll
;           for (int n = 0; n < 2; ++n) bfb[(gq + 1) & 1][n] = *(const bf16x8*)(sb + (nh2 * 2 + n) * 2048 + (((ks2 * 4 + fq) ^ swz) << 4));
;         }
;         if (gq == 3) {
; #pragma unroll
;           for (int m = 0; m < 4; ++m) afB[m] = *(const bf16x8*)(sa + m * 2048 + (((4 + fq) ^ swz) << 4));
;         }
;         __builtin_amdgcn_sched_barrier(0);
; #pragma unroll
.LBB0_3112:
	s_add_i32 s9, s7, 0x10000
	s_and_b32 s8, s9, 0x10000
	v_add_u32_e32 v142, s8, v156
	s_nop 0
	v_readfirstlane_b32 s10, v142
	s_waitcnt vmcnt(0)
	s_barrier
	s_and_b32 s7, s7, 0x10000
	v_add_u32_e32 v138, s7, v157
	v_add_u32_e32 v152, v138, v159
	ds_read_b128 v[140:143], v152
	ds_read_b128 v[144:147], v152 offset:2048
	ds_read_b128 v[148:151], v152 offset:4096
	ds_read_b128 v[180:183], v152 offset:6144
	v_or_b32_e32 v152, s7, v158
	v_add_u32_e32 v153, v152, v159
	ds_read_b128 v[184:187], v153 offset:32768
	ds_read_b128 v[188:191], v153 offset:34816
	ds_read_b128 v[192:195], v153 offset:36864
	ds_read_b128 v[196:199], v153 offset:38912
	v_add_u32_e32 v138, v138, v160
	s_waitcnt lgkmcnt(3)
	v_mfma_f32_16x16x32_bf16 v[126:129], v[184:187], v[140:143], v[126:129]
	s_mov_b32 m0, s10
	v_mfma_f32_16x16x32_bf16 v[110:113], v[184:187], v[144:147], v[110:113]
	global_load_lds_dwordx4 v137, s[22:23] sc1
	v_add_u32_e32 v137, 0x80, v137
	v_mfma_f32_16x16x32_bf16 v[82:85], v[184:187], v[148:151], v[82:85]
	v_mfma_f32_16x16x32_bf16 v[50:53], v[184:187], v[180:183], v[50:53]
	ds_read_b128 v[184:187], v153 offset:40960
	ds_read_b128 v[200:203], v153 offset:43008
	s_waitcnt lgkmcnt(4)
	v_mfma_f32_16x16x32_bf16 v[122:125], v[188:191], v[140:143], v[122:125]
	s_add_u32 m0, s10, 0x8000
	v_mfma_f32_16x16x32_bf16 v[106:109], v[188:191], v[144:147], v[106:109]
	global_load_lds_dwordx4 v136, s[28:29] sc1
	v_add_u32_e32 v136, 0x80, v136
	v_mfma_f32_16x16x32_bf16 v[78:81], v[188:191], v[148:151], v[78:81]
	v_mfma_f32_16x16x32_bf16 v[38:41], v[188:191], v[180:183], v[38:41]
	s_waitcnt lgkmcnt(3)
	v_mfma_f32_16x16x32_bf16 v[118:121], v[192:195], v[140:143], v[118:121]
	s_add_u32 m0, s10, 0x2000
	v_mfma_f32_16x16x32_bf16 v[94:97], v[192:195], v[144:147], v[94:97]
	global_load_lds_dwordx4 v135, s[22:23] sc1
	v_add_u32_e32 v135, 0x80, v135
	v_mfma_f32_16x16x32_bf16 v[58:61], v[192:195], v[148:151], v[58:61]
	v_mfma_f32_16x16x32_bf16 v[26:29], v[192:195], v[180:183], v[26:29]
	ds_read_b128 v[188:191], v153 offset:45056
	ds_read_b128 v[192:195], v153 offset:47104
	s_waitcnt lgkmcnt(4)
	v_mfma_f32_16x16x32_bf16 v[114:117], v[196:199], v[140:143], v[114:117]
	s_add_u32 m0, s10, 0xa000
	v_mfma_f32_16x16x32_bf16 v[86:89], v[196:199], v[144:147], v[86:89]
	global_load_lds_dwordx4 v134, s[28:29] sc1
	v_add_u32_e32 v134, 0x80, v134
	v_mfma_f32_16x16x32_bf16 v[54:57], v[196:199], v[148:151], v[54:57]
	v_mfma_f32_16x16x32_bf16 v[22:25], v[196:199], v[180:183], v[22:25]
	v_add_u32_e32 v152, v152, v160
	s_waitcnt lgkmcnt(3)
	v_mfma_f32_16x16x32_bf16 v[102:105], v[184:187], v[140:143], v[102:105]
	ds_read_b128 v[196:199], v152 offset:32768
	ds_read_b128 v[204:207], v152 offset:34816
	s_add_u32 m0, s10, 0x4000
	v_mfma_f32_16x16x32_bf16 v[74:77], v[184:187], v[144:147], v[74:77]
	global_load_lds_dwordx4 v133, s[22:23] sc1
	v_add_u32_e32 v133, 0x80, v133
	v_mfma_f32_16x16x32_bf16 v[46:49], v[184:187], v[148:151], v[46:49]
	v_mfma_f32_16x16x32_bf16 v[10:13], v[184:187], v[180:183], v[10:13]
	ds_read_b128 v[184:187], v138
	ds_read_b128 v[208:211], v138 offset:2048
	ds_read_b128 v[212:215], v138 offset:4096
	ds_read_b128 v[216:219], v138 offset:6144
	s_waitcnt lgkmcnt(8)
	v_mfma_f32_16x16x32_bf16 v[98:101], v[200:203], v[140:143], v[98:101]
	s_add_u32 m0, s10, 0xc000
	v_mfma_f32_16x16x32_bf16 v[66:69], v[200:203], v[144:147], v[66:69]
	global_load_lds_dwordx4 v132, s[28:29] sc1
	v_add_u32_e32 v132, 0x80, v132
	v_mfma_f32_16x16x32_bf16 v[34:37], v[200:203], v[148:151], v[34:37]
	v_mfma_f32_16x16x32_bf16 v[6:9], v[200:203], v[180:183], v[6:9]
	s_waitcnt lgkmcnt(7)
	v_mfma_f32_16x16x32_bf16 v[70:73], v[188:191], v[140:143], v[70:73]
	s_add_u32 m0, s10, 0x6000
	s_waitcnt lgkmcnt(6)
	v_mfma_f32_16x16x32_bf16 v[62:65], v[192:195], v[140:143], v[62:65]
	global_load_lds_dwordx4 v131, s[22:23] sc1
	v_add_u32_e32 v131, 0x80, v131
	v_mfma_f32_16x16x32_bf16 v[42:45], v[188:191], v[144:147], v[42:45]
	v_mfma_f32_16x16x32_bf16 v[30:33], v[192:195], v[144:147], v[30:33]
	ds_read_b128 v[140:143], v152 offset:36864
	ds_read_b128 v[144:147], v152 offset:38912
	v_mfma_f32_16x16x32_bf16 v[18:21], v[188:191], v[148:151], v[18:21]
	s_add_u32 m0, s10, 0xe000
	v_mfma_f32_16x16x32_bf16 v[14:17], v[192:195], v[148:151], v[14:17]
	global_load_lds_dwordx4 v130, s[28:29] sc1
	v_add_u32_e32 v130, 0x80, v130
	v_mfma_f32_16x16x32_bf16 v[2:5], v[188:191], v[180:183], v[2:5]
	v_mfma_f32_16x16x32_bf16 v[90:93], v[192:195], v[180:183], v[90:93]
	ds_read_b128 v[148:151], v152 offset:40960
	ds_read_b128 v[180:183], v152 offset:43008
	s_waitcnt lgkmcnt(7)
	v_mfma_f32_16x16x32_bf16 v[126:129], v[196:199], v[184:187], v[126:129]
	v_mfma_f32_16x16x32_bf16 v[122:125], v[204:207], v[184:187], v[122:125]
	s_waitcnt lgkmcnt(6)
	v_mfma_f32_16x16x32_bf16 v[110:113], v[196:199], v[208:211], v[110:113]
	v_mfma_f32_16x16x32_bf16 v[106:109], v[204:207], v[208:211], v[106:109]
	s_waitcnt lgkmcnt(5)
	v_mfma_f32_16x16x32_bf16 v[82:85], v[196:199], v[212:215], v[82:85]
	v_mfma_f32_16x16x32_bf16 v[78:81], v[204:207], v[212:215], v[78:81]
	s_waitcnt lgkmcnt(4)
	v_mfma_f32_16x16x32_bf16 v[50:53], v[196:199], v[216:219], v[50:53]
	v_mfma_f32_16x16x32_bf16 v[38:41], v[204:207], v[216:219], v[38:41]
	s_waitcnt lgkmcnt(3)
	v_mfma_f32_16x16x32_bf16 v[118:121], v[140:143], v[184:187], v[118:121]
	v_mfma_f32_16x16x32_bf16 v[94:97], v[140:143], v[208:211], v[94:97]
	v_mfma_f32_16x16x32_bf16 v[58:61], v[140:143], v[212:215], v[58:61]
	v_mfma_f32_16x16x32_bf16 v[26:29], v[140:143], v[216:219], v[26:29]
	ds_read_b128 v[140:143], v152 offset:45056
	ds_read_b128 v[188:191], v152 offset:47104
	s_waitcnt lgkmcnt(4)
; template <bool SWAP, class Epi, bool THIN = false> ...
;     ...
;       bf16x8 afA[4], afB[4], bfb[2][2];
; #pragma unroll
;       for (int m = 0; m < 4; ++m) afA[m] = *(const bf16x8*)(sa + m * 2048 + ((fq ^ swz) << 4));
; #pragma unroll
;       for (int n = 0; n < 2; ++n) bfb[0][n] = *(const bf16x8*)(sb + n * 2048 + ((fq ^ swz) << 4));
; #pragma unroll
;       for (int gq = 0; gq < 8; ++gq) {
;         const int ks = gq >> 2, nh = gq & 3;
;         if (gq < 7) {
;           const int ks2 = (gq + 1) >> 2, nh2 = (gq + 1) & 3;
; #pragma unroll
;           for (int n = 0; n < 2; ++n) bfb[(gq + 1) & 1][n] = *(const bf16x8*)(sb + (nh2 * 2 + n) * 2048 + (((ks2 * 4 + fq) ^ swz) << 4));
;         }
;         if (gq == 3) {
; #pragma unroll
;           for (int m = 0; m < 4; ++m) afB[m] = *(const bf16x8*)(sa + m * 2048 + (((4 + fq) ^ swz) << 4));
;         }
;         __builtin_amdgcn_sched_barrier(0);
; #pragma unroll
;         for (int m = 0; m < 4; ++m)
; #pragma unroll
;           for (int n = 0; n < 2; ++n) {
;             const bf16x8 av = ks ? afB[m] : afA[m];
;             acc[m][nh * 2 + n] = SWAP ? __builtin_amdgcn_mfma_f32_16x16x32_bf16(bfb[gq & 1][n], av, acc[m][nh * 2 + n], 0, 0, 0)
;                                       : __builtin_amdgcn_mfma_f32_16x16x32_bf16(av, bfb[gq & 1][n], acc[m][nh * 2 + n], 0, 0, 0);
;           }
;       }
;       }
;     }
;     __syncthreads();
	v_mfma_f32_16x16x32_bf16 v[114:117], v[144:147], v[184:187], v[114:117]
	v_mfma_f32_16x16x32_bf16 v[86:89], v[144:147], v[208:211], v[86:89]
	v_mfma_f32_16x16x32_bf16 v[54:57], v[144:147], v[212:215], v[54:57]
	v_mfma_f32_16x16x32_bf16 v[22:25], v[144:147], v[216:219], v[22:25]
	s_waitcnt lgkmcnt(3)
	v_mfma_f32_16x16x32_bf16 v[102:105], v[148:151], v[184:187], v[102:105]
	s_waitcnt lgkmcnt(2)
	v_mfma_f32_16x16x32_bf16 v[98:101], v[180:183], v[184:187], v[98:101]
	v_mfma_f32_16x16x32_bf16 v[74:77], v[148:151], v[208:211], v[74:77]
	v_mfma_f32_16x16x32_bf16 v[66:69], v[180:183], v[208:211], v[66:69]
	v_mfma_f32_16x16x32_bf16 v[46:49], v[148:151], v[212:215], v[46:49]
	v_mfma_f32_16x16x32_bf16 v[34:37], v[180:183], v[212:215], v[34:37]
	v_mfma_f32_16x16x32_bf16 v[10:13], v[148:151], v[216:219], v[10:13]
	v_mfma_f32_16x16x32_bf16 v[6:9], v[180:183], v[216:219], v[6:9]
	s_waitcnt lgkmcnt(1)
	v_mfma_f32_16x16x32_bf16 v[70:73], v[140:143], v[184:187], v[70:73]
	s_add_i32 s6, s6, 64
	s_cmpk_eq_i32 s6, 0x3c0
	s_mov_b32 s7, s9
	s_waitcnt lgkmcnt(0)
	v_mfma_f32_16x16x32_bf16 v[62:65], v[188:191], v[184:187], v[62:65]
	v_mfma_f32_16x16x32_bf16 v[42:45], v[140:143], v[208:211], v[42:45]
	v_mfma_f32_16x16x32_bf16 v[30:33], v[188:191], v[208:211], v[30:33]
	v_mfma_f32_16x16x32_bf16 v[18:21], v[140:143], v[212:215], v[18:21]
	v_mfma_f32_16x16x32_bf16 v[14:17], v[188:191], v[212:215], v[14:17]
	v_mfma_f32_16x16x32_bf16 v[2:5], v[140:143], v[216:219], v[2:5]
	v_mfma_f32_16x16x32_bf16 v[90:93], v[188:191], v[216:219], v[90:93]
	s_cbranch_scc0 .LBB0_3112
	v_add_u32_e32 v138, s8, v157
	v_add_u32_e32 v152, s8, v158
	s_waitcnt vmcnt(0)
	s_barrier
	v_add_u32_e32 v144, v138, v159
	v_add_u32_e32 v153, v152, v159
	ds_read_b128 v[130:133], v144
	ds_read_b128 v[134:137], v144 offset:2048
	ds_read_b128 v[140:143], v144 offset:4096
	ds_read_b128 v[144:147], v144 offset:6144
	ds_read_b128 v[148:151], v153 offset:32768
	ds_read_b128 v[180:183], v153 offset:34816
	ds_read_b128 v[184:187], v153 offset:36864
	ds_read_b128 v[188:191], v153 offset:38912
	v_add_u32_e32 v138, v138, v160
	s_waitcnt lgkmcnt(0)
	v_mfma_f32_16x16x32_bf16 v[126:129], v[148:151], v[130:133], v[126:129]
	v_mfma_f32_16x16x32_bf16 v[110:113], v[148:151], v[134:137], v[110:113]
	v_mfma_f32_16x16x32_bf16 v[82:85], v[148:151], v[140:143], v[82:85]
	v_mfma_f32_16x16x32_bf16 v[50:53], v[148:151], v[144:147], v[50:53]
	ds_read_b128 v[148:151], v153 offset:40960
	ds_read_b128 v[192:195], v153 offset:43008
	v_mfma_f32_16x16x32_bf16 v[122:125], v[180:183], v[130:133], v[122:125]
	v_mfma_f32_16x16x32_bf16 v[106:109], v[180:183], v[134:137], v[106:109]
	v_mfma_f32_16x16x32_bf16 v[78:81], v[180:183], v[140:143], v[78:81]
	v_mfma_f32_16x16x32_bf16 v[38:41], v[180:183], v[144:147], v[38:41]
	v_mfma_f32_16x16x32_bf16 v[118:121], v[184:187], v[130:133], v[118:121]
	v_mfma_f32_16x16x32_bf16 v[180:183], v[184:187], v[134:137], v[94:97]
	v_mfma_f32_16x16x32_bf16 v[200:203], v[184:187], v[140:143], v[58:61]
	v_mfma_f32_16x16x32_bf16 v[204:207], v[188:191], v[140:143], v[54:57]
	v_mfma_f32_16x16x32_bf16 v[184:187], v[184:187], v[144:147], v[26:29]
	s_nop 2
	ds_read_b128 v[26:29], v153 offset:45056
	ds_read_b128 v[54:57], v153 offset:47104
	v_mfma_f32_16x16x32_bf16 v[114:117], v[188:191], v[130:133], v[114:117]
	v_mfma_f32_16x16x32_bf16 v[196:199], v[188:191], v[134:137], v[86:89]
	v_mfma_f32_16x16x32_bf16 v[188:191], v[188:191], v[144:147], v[22:25]
	v_add_u32_e32 v152, v152, v160
	s_waitcnt lgkmcnt(0)
	v_mfma_f32_16x16x32_bf16 v[102:105], v[148:151], v[130:133], v[102:105]
	ds_read_b128 v[22:25], v152 offset:32768
	ds_read_b128 v[86:89], v152 offset:34816
	v_mfma_f32_16x16x32_bf16 v[74:77], v[148:151], v[134:137], v[74:77]
	v_mfma_f32_16x16x32_bf16 v[46:49], v[148:151], v[140:143], v[46:49]
	v_mfma_f32_16x16x32_bf16 v[10:13], v[148:151], v[144:147], v[10:13]
	ds_read_b128 v[148:151], v138
	ds_read_b128 v[208:211], v138 offset:2048
	ds_read_b128 v[212:215], v138 offset:4096
	ds_read_b128 v[216:219], v138 offset:6144
	v_mfma_f32_16x16x32_bf16 v[98:101], v[192:195], v[130:133], v[98:101]
	v_mfma_f32_16x16x32_bf16 v[66:69], v[192:195], v[134:137], v[66:69]
	v_mfma_f32_16x16x32_bf16 v[34:37], v[192:195], v[140:143], v[34:37]
	v_mfma_f32_16x16x32_bf16 v[6:9], v[192:195], v[144:147], v[6:9]
	v_mfma_f32_16x16x32_bf16 v[220:223], v[26:29], v[140:143], v[18:21]
	v_mfma_f32_16x16x32_bf16 v[140:143], v[54:57], v[140:143], v[14:17]
	s_nop 2
	ds_read_b128 v[14:17], v152 offset:36864
	ds_read_b128 v[18:21], v152 offset:38912
	v_mfma_f32_16x16x32_bf16 v[70:73], v[26:29], v[130:133], v[70:73]
	v_mfma_f32_16x16x32_bf16 v[2:5], v[26:29], v[144:147], v[2:5]
	v_mfma_f32_16x16x32_bf16 v[130:133], v[54:57], v[130:133], v[62:65]
	v_mfma_f32_16x16x32_bf16 v[192:195], v[26:29], v[134:137], v[42:45]
	v_mfma_f32_16x16x32_bf16 v[134:137], v[54:57], v[134:137], v[30:33]
	v_mfma_f32_16x16x32_bf16 v[224:227], v[54:57], v[144:147], v[90:93]
	ds_read_b128 v[144:147], v152 offset:40960
	ds_read_b128 v[228:231], v152 offset:43008
	s_waitcnt lgkmcnt(0)
	v_mfma_f32_16x16x32_bf16 v[126:129], v[22:25], v[148:151], v[126:129]
	v_mfma_f32_16x16x32_bf16 v[122:125], v[86:89], v[148:151], v[122:125]
	v_mfma_f32_16x16x32_bf16 v[94:97], v[22:25], v[208:211], v[110:113]
	v_mfma_f32_16x16x32_bf16 v[90:93], v[86:89], v[208:211], v[106:109]
	v_mfma_f32_16x16x32_bf16 v[62:65], v[22:25], v[212:215], v[82:85]
	v_mfma_f32_16x16x32_bf16 v[58:61], v[86:89], v[212:215], v[78:81]
	v_mfma_f32_16x16x32_bf16 v[30:33], v[22:25], v[216:219], v[50:53]
	v_mfma_f32_16x16x32_bf16 v[26:29], v[86:89], v[216:219], v[38:41]
	v_mfma_f32_16x16x32_bf16 v[86:89], v[14:17], v[208:211], v[180:183]
	v_mfma_f32_16x16x32_bf16 v[22:25], v[14:17], v[216:219], v[184:187]
	s_nop 1
	ds_read_b128 v[180:183], v152 offset:45056
	ds_read_b128 v[184:187], v152 offset:47104
	v_mfma_f32_16x16x32_bf16 v[118:121], v[14:17], v[148:151], v[118:121]
	v_mfma_f32_16x16x32_bf16 v[114:117], v[18:21], v[148:151], v[114:117]
	v_mfma_f32_16x16x32_bf16 v[82:85], v[18:21], v[208:211], v[196:199]
	v_mfma_f32_16x16x32_bf16 v[54:57], v[14:17], v[212:215], v[200:203]
	v_mfma_f32_16x16x32_bf16 v[50:53], v[18:21], v[212:215], v[204:207]
	v_mfma_f32_16x16x32_bf16 v[18:21], v[18:21], v[216:219], v[188:191]
	v_mfma_f32_16x16x32_bf16 v[110:113], v[144:147], v[148:151], v[102:105]
	v_mfma_f32_16x16x32_bf16 v[106:109], v[228:231], v[148:151], v[98:101]
	v_mfma_f32_16x16x32_bf16 v[78:81], v[144:147], v[208:211], v[74:77]
	v_mfma_f32_16x16x32_bf16 v[74:77], v[228:231], v[208:211], v[66:69]
	v_mfma_f32_16x16x32_bf16 v[46:49], v[144:147], v[212:215], v[46:49]
	v_mfma_f32_16x16x32_bf16 v[42:45], v[228:231], v[212:215], v[34:37]
	v_mfma_f32_16x16x32_bf16 v[14:17], v[144:147], v[216:219], v[10:13]
	v_mfma_f32_16x16x32_bf16 v[10:13], v[228:231], v[216:219], v[6:9]
	v_mov_b32_e32 v138, v1
	s_waitcnt vmcnt(0) lgkmcnt(0)
	s_barrier
; __device__ __forceinline__ int get_tid512() { int t = threadIdx.x; asm volatile("" : "+v"(t)); return t; }
; __device__ __forceinline__ float bf2f(bf16_t h) { return __uint_as_float(((unsigned)h) << 16); }
;   __device__ __forceinline__ void c4(int g, int rig, int col, f32x4 v) const {
;     const size_t o = ((size_t)g * 2048 + rig) * 1024 + col;
;     f32x4 bs;
;     if (BASE_F32) bs = __builtin_nontemporal_load((const f32x4*)((const float*)base + o));
;     else {
;       const uint2 u = *(const uint2*)((const bf16_t*)base + o);
;       bs[0] = bf2f((bf16_t)(u.x & 0xffff)); bs[1] = bf2f((bf16_t)(u.x >> 16)); bs[2] = bf2f((bf16_t)(u.y & 0xffff)); bs[3] = bf2f((bf16_t)(u.y >> 16));
;     }
;     const f32x4 gt = *(const f32x4*)(gate + (size_t)g * 6144 + col);
;     f32x4 bi = {0.f, 0.f, 0.f, 0.f};
;     if (bias) bi = *(const f32x4*)(bias + col);
; template <bool SWAP, class Epi, bool THIN = false> ...
;     ...
;     __syncthreads();
;     const int te = get_tid512();
;     const int fr_e = te & 15, fq_e = (te & 63) >> 4, wr_e = te >> 7, wc_e = (te >> 6) & 1;
;     const int sub = 2 * mt + (wr_e >> 1);
;     const int g = sub / tpg, ti = sub - g * tpg;
;     const int rig0 = ti * step - halo;
;     const int rw = (wr_e & 1) * 64;
;     if constexpr (Epi::KIND == 0) {
; #pragma unroll
;       for (int m = 0; m < 4; ++m) {
;         const int rig = rig0 + rw + m * 16 + fr_e;
;         if constexpr (Epi::ROWSUM) {
;           float ss = 0.f;
; #pragma unroll
;           for (int n = 0; n < 8; ++n) {
;             const int col = nt * 256 + wc_e * 128 + n * 16 + fq_e * 4;
;             if (col < N) ss += epi.c4(g, rig, col, acc[m][n]);
;           }
;           ss += __shfl_xor(ss, 16); ss += __shfl_xor(ss, 32);
;           if (fq_e == 0) epi.rowsum(g, rig, nt * 2 + wc_e, ss);
;         } else {
; #pragma unroll
;           for (int n = 0; n < 8; ++n) {
;             const int col = nt * 256 + wc_e * 128 + n * 16 + fq_e * 4;
;             if (col < N) epi.c4(g, rig, col, acc[m][n]);
;           }
	v_mfma_f32_16x16x32_bf16 v[98:101], v[184:187], v[148:151], v[130:133]
	v_ashrrev_i32_e32 v7, 8, v138
	v_add_u32_e32 v7, s5, v7
	v_ashrrev_i32_e32 v8, 31, v7
	v_lshrrev_b32_e32 v8, 28, v8
	v_add_u32_e32 v8, v7, v8
	v_ashrrev_i32_e32 v130, 4, v8
	v_lshlrev_b32_e32 v8, 11, v130
	v_lshlrev_b32_e32 v7, 7, v7
	v_sub_u32_e32 v7, v7, v8
	v_lshrrev_b32_e32 v8, 1, v138
	v_and_b32_e32 v6, 15, v138
	v_and_b32_e32 v8, 64, v8
	v_or3_b32 v144, v7, v8, v6
	v_lshlrev_b32_e32 v6, 1, v138
	v_and_b32_e32 v131, 0x80, v6
	v_mfma_f32_16x16x32_bf16 v[6:9], v[180:183], v[216:219], v[2:5]
	v_ashrrev_i32_e32 v145, 31, v144
	v_lshlrev_b64 v[132:133], 10, v[144:145]
	s_nop 0
	v_lshrrev_b32_e32 v2, 2, v138
	v_and_b32_e32 v2, 12, v2
	v_mfma_f32_16x16x32_bf16 v[102:105], v[180:183], v[148:151], v[70:73]
	v_mfma_f32_16x16x32_bf16 v[70:73], v[180:183], v[208:211], v[192:195]
	v_mfma_f32_16x16x32_bf16 v[66:69], v[184:187], v[208:211], v[134:137]
	v_mfma_f32_16x16x32_bf16 v[38:41], v[180:183], v[212:215], v[220:223]
	v_mfma_f32_16x16x32_bf16 v[34:37], v[184:187], v[212:215], v[140:143]
	s_nop 2
	v_or3_b32 v140, v2, v131, s4
	v_mfma_f32_16x16x32_bf16 v[2:5], v[184:187], v[216:219], v[224:227]
	v_ashrrev_i32_e32 v131, 31, v130
	v_lshlrev_b64 v[146:147], 21, v[130:131]
	v_mad_i64_i32 v[130:131], s[4:5], v130, s39, 0
	v_lshl_add_u64 v[132:133], v[132:133], 0, v[146:147]
	v_lshl_add_u64 v[142:143], s[30:31], 0, v[130:131]
	v_cndmask_b32_e64 v130, 0, 1, s[34:35]
	v_cmp_gt_i32_e64 s[6:7], s40, v140
	v_ashrrev_i32_e32 v141, 31, v140
	v_lshl_add_u64 v[148:149], v[132:133], 1, s[24:25]
	v_cmp_ne_u32_e64 s[4:5], 1, v130
	s_and_saveexec_b64 s[8:9], s[6:7]
	s_cbranch_execz .LBB0_3118
	v_lshl_add_u64 v[150:151], v[140:141], 1, v[148:149]
	v_lshl_add_u64 v[130:131], v[140:141], 2, v[142:143]
	global_load_dwordx2 v[152:153], v[150:151], off
	s_and_b64 vcc, exec, s[4:5]
	global_load_dwordx4 v[130:133], v[130:131], off
	s_cbranch_vccnz .LBB0_3116
	v_lshl_add_u64 v[134:135], v[140:141], 2, s[26:27]
	global_load_dwordx4 v[134:137], v[134:135], off
	s_branch .LBB0_3117

; template <bool SWAP, class Epi, bool THIN = false> ...
;     ...
;     for (int st = 0; st < ns; ++st) {
;       asm volatile("s_waitcnt vmcnt(0)" ::: "memory");
;       __builtin_amdgcn_s_barrier();
;       asm volatile("" ::: "memory");
;       if (st + 1 < ns) {
;         char* nb = smem + ((st + 1) & 1) * 65536;
;         const int ko = (st + 1) * 64;
; #pragma unroll
;         for (int i = 0; i < 4; ++i) { GLDS16(A + (size_t)(ap[i] + ko), nb + tid * 16 + i * 8192); GLDS16(Bt + (size_t)(bp[i] + ko), nb + 32768 + tid * 16 + i * 8192); }
;       }
;       const char* sa = smem + (st & 1) * 65536 + (wr * 64 + fr) * 128;
;       const char* sb = smem + (st & 1) * 65536 + 32768 + (wc * 128 + fr) * 128;
;       if constexpr (THIN) {
;         if (wc == 0) {
; #pragma unroll
;           for (int ks = 0; ks < 2; ++ks) {
;             bf16x8 af[4], bf[2];
; #pragma unroll
;             for (int m = 0; m < 4; ++m) af[m] = *(const bf16x8*)(sa + m * 2048 + (((ks * 4 + fq) ^ swz) << 4));
; #pragma unroll
;             for (int n = 0; n < 2; ++n) bf[n] = *(const bf16x8*)(sb + n * 2048 + (((ks * 4 + fq) ^ swz) << 4));
; #pragma unroll
;             for (int m = 0; m < 4; ++m)
; #pragma unroll
;               for (int n = 0; n < 2; ++n)
;                 acc[m][n] = SWAP ? __builtin_amdgcn_mfma_f32_16x16x32_bf16(bf[n], af[m], acc[m][n], 0, 0, 0)
;                                  : __builtin_amdgcn_mfma_f32_16x16x32_bf16(af[m], bf[n], acc[m][n], 0, 0, 0);
;           }
;         }
;       } else {
;       bf16x8 afA[4], afB[4], bfb[2][2];
; #pragma unroll
;       for (int m = 0; m < 4; ++m) afA[m] = *(const bf16x8*)(sa + m * 2048 + ((fq ^ swz) << 4));
; #pragma unroll
;       for (int n = 0; n < 2; ++n) bfb[0][n] = *(const bf16x8*)(sb + n * 2048 + ((fq ^ swz) << 4));
; #pragma unroll
;       for (int gq = 0; gq < 8; ++gq) {
;         const int ks = gq >> 2, nh = gq & 3;
;         if (gq < 7) {
;           const int ks2 = (gq + 1) >> 2, nh2 = (gq + 1) & 3;
; #pragma unroll
;           for (int n = 0; n < 2; ++n) bfb[(gq + 1) & 1][n] = *(const bf16x8*)(sb + (nh2 * 2 + n) * 2048 + (((ks2 * 4 + fq) ^ swz) << 4));
;         }
;         if (gq == 3) {
; #pragma unroll
;           for (int m = 0; m < 4; ++m) afB[m] = *(const bf16x8*)(sa + m * 2048 + (((4 + fq) ^ swz) << 4));
;         }
;         __builtin_amdgcn_sched_barrier(0);
; #pragma unroll
.LBB0_3424:
	s_add_i32 s8, s7, 0x10000
	s_and_b32 s9, s8, 0x10000
	v_add_u32_e32 v170, s9, v135
	s_nop 0
	v_readfirstlane_b32 s9, v170
	s_waitcnt vmcnt(0)
	s_barrier
	s_and_b32 s7, s7, 0x10000
	v_or_b32_e32 v204, s7, v139
	v_add_u32_e32 v205, v204, v140
	v_add_u32_e32 v136, s7, v138
	v_add_u32_e32 v180, v136, v140
	ds_read_b128 v[168:171], v180
	ds_read_b128 v[172:175], v180 offset:2048
	ds_read_b128 v[176:179], v180 offset:4096
	ds_read_b128 v[180:183], v180 offset:6144
	ds_read_b128 v[184:187], v205 offset:32768
	ds_read_b128 v[188:191], v205 offset:34816
	ds_read_b128 v[192:195], v205 offset:36864
	ds_read_b128 v[196:199], v205 offset:38912
	v_add_u32_e32 v136, v136, v141
	s_waitcnt lgkmcnt(3)
	v_mfma_f32_16x16x32_bf16 v[126:129], v[184:187], v[168:171], v[126:129]
	s_mov_b32 m0, s9
	v_mfma_f32_16x16x32_bf16 v[110:113], v[184:187], v[172:175], v[110:113]
	global_load_lds_dwordx4 v167, s[14:15] sc1
	v_add_u32_e32 v167, 0x80, v167
	v_mfma_f32_16x16x32_bf16 v[82:85], v[184:187], v[176:179], v[82:85]
	v_mfma_f32_16x16x32_bf16 v[50:53], v[184:187], v[180:183], v[50:53]
	ds_read_b128 v[184:187], v205 offset:40960
	ds_read_b128 v[200:203], v205 offset:43008
	s_waitcnt lgkmcnt(4)
	v_mfma_f32_16x16x32_bf16 v[122:125], v[188:191], v[168:171], v[122:125]
	s_add_u32 m0, s9, 0x8000
	v_mfma_f32_16x16x32_bf16 v[106:109], v[188:191], v[172:175], v[106:109]
	global_load_lds_dwordx4 v166, s[10:11] sc1
	v_add_u32_e32 v166, 0x80, v166
	v_mfma_f32_16x16x32_bf16 v[78:81], v[188:191], v[176:179], v[78:81]
	v_mfma_f32_16x16x32_bf16 v[42:45], v[188:191], v[180:183], v[42:45]
	s_waitcnt lgkmcnt(3)
	v_mfma_f32_16x16x32_bf16 v[118:121], v[192:195], v[168:171], v[118:121]
	s_add_u32 m0, s9, 0x2000
	v_mfma_f32_16x16x32_bf16 v[94:97], v[192:195], v[172:175], v[94:97]
	global_load_lds_dwordx4 v165, s[14:15] sc1
	v_add_u32_e32 v165, 0x80, v165
	v_mfma_f32_16x16x32_bf16 v[58:61], v[192:195], v[176:179], v[58:61]
	v_mfma_f32_16x16x32_bf16 v[26:29], v[192:195], v[180:183], v[26:29]
	ds_read_b128 v[188:191], v205 offset:45056
	ds_read_b128 v[192:195], v205 offset:47104
	s_waitcnt lgkmcnt(4)
	v_mfma_f32_16x16x32_bf16 v[114:117], v[196:199], v[168:171], v[114:117]
	s_add_u32 m0, s9, 0xa000
	v_mfma_f32_16x16x32_bf16 v[90:93], v[196:199], v[172:175], v[90:93]
	global_load_lds_dwordx4 v164, s[10:11] sc1
	v_add_u32_e32 v164, 0x80, v164
	v_mfma_f32_16x16x32_bf16 v[54:57], v[196:199], v[176:179], v[54:57]
	v_mfma_f32_16x16x32_bf16 v[22:25], v[196:199], v[180:183], v[22:25]
	v_add_u32_e32 v220, v204, v141
	s_waitcnt lgkmcnt(3)
	v_mfma_f32_16x16x32_bf16 v[102:105], v[184:187], v[168:171], v[102:105]
	ds_read_b128 v[196:199], v220 offset:32768
	ds_read_b128 v[204:207], v220 offset:34816
	s_add_u32 m0, s9, 0x4000
	v_mfma_f32_16x16x32_bf16 v[74:77], v[184:187], v[172:175], v[74:77]
	global_load_lds_dwordx4 v163, s[14:15] sc1
	v_add_u32_e32 v163, 0x80, v163
	v_mfma_f32_16x16x32_bf16 v[46:49], v[184:187], v[176:179], v[46:49]
	v_mfma_f32_16x16x32_bf16 v[10:13], v[184:187], v[180:183], v[10:13]
	ds_read_b128 v[184:187], v136
	ds_read_b128 v[208:211], v136 offset:2048
	ds_read_b128 v[212:215], v136 offset:4096
	ds_read_b128 v[216:219], v136 offset:6144
	s_waitcnt lgkmcnt(8)
	v_mfma_f32_16x16x32_bf16 v[98:101], v[200:203], v[168:171], v[98:101]
	s_add_u32 m0, s9, 0xc000
	v_mfma_f32_16x16x32_bf16 v[66:69], v[200:203], v[172:175], v[66:69]
	global_load_lds_dwordx4 v162, s[10:11] sc1
	v_add_u32_e32 v162, 0x80, v162
	v_mfma_f32_16x16x32_bf16 v[30:33], v[200:203], v[176:179], v[30:33]
	v_mfma_f32_16x16x32_bf16 v[6:9], v[200:203], v[180:183], v[6:9]
	s_waitcnt lgkmcnt(7)
	v_mfma_f32_16x16x32_bf16 v[70:73], v[188:191], v[168:171], v[70:73]
	s_add_u32 m0, s9, 0x6000
	s_waitcnt lgkmcnt(6)
	v_mfma_f32_16x16x32_bf16 v[62:65], v[192:195], v[168:171], v[62:65]
	global_load_lds_dwordx4 v161, s[14:15] sc1
	v_add_u32_e32 v161, 0x80, v161
	v_mfma_f32_16x16x32_bf16 v[38:41], v[188:191], v[172:175], v[38:41]
	v_mfma_f32_16x16x32_bf16 v[34:37], v[192:195], v[172:175], v[34:37]
	ds_read_b128 v[168:171], v220 offset:36864
	ds_read_b128 v[172:175], v220 offset:38912
	v_mfma_f32_16x16x32_bf16 v[18:21], v[188:191], v[176:179], v[18:21]
	s_add_u32 m0, s9, 0xe000
	v_mfma_f32_16x16x32_bf16 v[14:17], v[192:195], v[176:179], v[14:17]
	global_load_lds_dwordx4 v160, s[10:11] sc1
	v_add_u32_e32 v160, 0x80, v160
	v_mfma_f32_16x16x32_bf16 v[2:5], v[188:191], v[180:183], v[2:5]
	v_mfma_f32_16x16x32_bf16 v[86:89], v[192:195], v[180:183], v[86:89]
	ds_read_b128 v[176:179], v220 offset:40960
	ds_read_b128 v[180:183], v220 offset:43008
	s_waitcnt lgkmcnt(7)
	v_mfma_f32_16x16x32_bf16 v[126:129], v[196:199], v[184:187], v[126:129]
	v_mfma_f32_16x16x32_bf16 v[122:125], v[204:207], v[184:187], v[122:125]
	s_waitcnt lgkmcnt(6)
	v_mfma_f32_16x16x32_bf16 v[110:113], v[196:199], v[208:211], v[110:113]
	v_mfma_f32_16x16x32_bf16 v[106:109], v[204:207], v[208:211], v[106:109]
	s_waitcnt lgkmcnt(5)
	v_mfma_f32_16x16x32_bf16 v[82:85], v[196:199], v[212:215], v[82:85]
	v_mfma_f32_16x16x32_bf16 v[78:81], v[204:207], v[212:215], v[78:81]
	s_waitcnt lgkmcnt(4)
	v_mfma_f32_16x16x32_bf16 v[50:53], v[196:199], v[216:219], v[50:53]
	v_mfma_f32_16x16x32_bf16 v[42:45], v[204:207], v[216:219], v[42:45]
	s_waitcnt lgkmcnt(3)
	v_mfma_f32_16x16x32_bf16 v[118:121], v[168:171], v[184:187], v[118:121]
	v_mfma_f32_16x16x32_bf16 v[94:97], v[168:171], v[208:211], v[94:97]
	v_mfma_f32_16x16x32_bf16 v[58:61], v[168:171], v[212:215], v[58:61]
	v_mfma_f32_16x16x32_bf16 v[26:29], v[168:171], v[216:219], v[26:29]
	ds_read_b128 v[168:171], v220 offset:45056
	ds_read_b128 v[188:191], v220 offset:47104
	s_waitcnt lgkmcnt(4)
; template <bool SWAP, class Epi, bool THIN = false> ...
;     ...
;       bf16x8 afA[4], afB[4], bfb[2][2];
; #pragma unroll
;       for (int m = 0; m < 4; ++m) afA[m] = *(const bf16x8*)(sa + m * 2048 + ((fq ^ swz) << 4));
; #pragma unroll
;       for (int n = 0; n < 2; ++n) bfb[0][n] = *(const bf16x8*)(sb + n * 2048 + ((fq ^ swz) << 4));
; #pragma unroll
;       for (int gq = 0; gq < 8; ++gq) {
;         const int ks = gq >> 2, nh = gq & 3;
;         if (gq < 7) {
;           const int ks2 = (gq + 1) >> 2, nh2 = (gq + 1) & 3;
; #pragma unroll
;           for (int n = 0; n < 2; ++n) bfb[(gq + 1) & 1][n] = *(const bf16x8*)(sb + (nh2 * 2 + n) * 2048 + (((ks2 * 4 + fq) ^ swz) << 4));
;         }
;         if (gq == 3) {
; #pragma unroll
;           for (int m = 0; m < 4; ++m) afB[m] = *(const bf16x8*)(sa + m * 2048 + (((4 + fq) ^ swz) << 4));
;         }
;         __builtin_amdgcn_sched_barrier(0);
; #pragma unroll
;         for (int m = 0; m < 4; ++m)
; #pragma unroll
;           for (int n = 0; n < 2; ++n) {
;             const bf16x8 av = ks ? afB[m] : afA[m];
;             acc[m][nh * 2 + n] = SWAP ? __builtin_amdgcn_mfma_f32_16x16x32_bf16(bfb[gq & 1][n], av, acc[m][nh * 2 + n], 0, 0, 0)
;                                       : __builtin_amdgcn_mfma_f32_16x16x32_bf16(av, bfb[gq & 1][n], acc[m][nh * 2 + n], 0, 0, 0);
;           }
;       }
;       }
;     }
;     __syncthreads();
	v_mfma_f32_16x16x32_bf16 v[114:117], v[172:175], v[184:187], v[114:117]
	v_mfma_f32_16x16x32_bf16 v[90:93], v[172:175], v[208:211], v[90:93]
	v_mfma_f32_16x16x32_bf16 v[54:57], v[172:175], v[212:215], v[54:57]
	v_mfma_f32_16x16x32_bf16 v[22:25], v[172:175], v[216:219], v[22:25]
	s_waitcnt lgkmcnt(3)
	v_mfma_f32_16x16x32_bf16 v[102:105], v[176:179], v[184:187], v[102:105]
	s_waitcnt lgkmcnt(2)
	v_mfma_f32_16x16x32_bf16 v[98:101], v[180:183], v[184:187], v[98:101]
	v_mfma_f32_16x16x32_bf16 v[74:77], v[176:179], v[208:211], v[74:77]
	v_mfma_f32_16x16x32_bf16 v[66:69], v[180:183], v[208:211], v[66:69]
	v_mfma_f32_16x16x32_bf16 v[46:49], v[176:179], v[212:215], v[46:49]
	v_mfma_f32_16x16x32_bf16 v[30:33], v[180:183], v[212:215], v[30:33]
	v_mfma_f32_16x16x32_bf16 v[10:13], v[176:179], v[216:219], v[10:13]
	v_mfma_f32_16x16x32_bf16 v[6:9], v[180:183], v[216:219], v[6:9]
	s_waitcnt lgkmcnt(1)
	v_mfma_f32_16x16x32_bf16 v[70:73], v[168:171], v[184:187], v[70:73]
	s_add_i32 s5, s5, 64
	s_cmpk_eq_i32 s5, 0x3c0
	s_mov_b32 s7, s8
	s_waitcnt lgkmcnt(0)
	v_mfma_f32_16x16x32_bf16 v[62:65], v[188:191], v[184:187], v[62:65]
	v_mfma_f32_16x16x32_bf16 v[38:41], v[168:171], v[208:211], v[38:41]
	v_mfma_f32_16x16x32_bf16 v[34:37], v[188:191], v[208:211], v[34:37]
	v_mfma_f32_16x16x32_bf16 v[18:21], v[168:171], v[212:215], v[18:21]
	v_mfma_f32_16x16x32_bf16 v[14:17], v[188:191], v[212:215], v[14:17]
	v_mfma_f32_16x16x32_bf16 v[2:5], v[168:171], v[216:219], v[2:5]
	v_mfma_f32_16x16x32_bf16 v[86:89], v[188:191], v[216:219], v[86:89]
	s_cbranch_scc0 .LBB0_3424
	s_waitcnt vmcnt(0)
	s_barrier
	v_add_u32_e32 v136, v150, v140
	ds_read_b128 v[160:163], v136
	ds_read_b128 v[164:167], v136 offset:2048
	ds_read_b128 v[168:171], v136 offset:4096
	ds_read_b128 v[172:175], v136 offset:6144
	v_add_u32_e32 v136, v151, v140
	ds_read_b128 v[176:179], v136
	ds_read_b128 v[180:183], v136 offset:2048
	ds_read_b128 v[184:187], v136 offset:4096
	ds_read_b128 v[188:191], v136 offset:6144
	s_waitcnt lgkmcnt(0)
	v_mfma_f32_16x16x32_bf16 v[126:129], v[176:179], v[160:163], v[126:129]
	v_mfma_f32_16x16x32_bf16 v[110:113], v[176:179], v[164:167], v[110:113]
	v_mfma_f32_16x16x32_bf16 v[82:85], v[176:179], v[168:171], v[82:85]
	v_mfma_f32_16x16x32_bf16 v[50:53], v[176:179], v[172:175], v[50:53]
	ds_read_b128 v[176:179], v136 offset:8192
	ds_read_b128 v[192:195], v136 offset:10240
	v_mfma_f32_16x16x32_bf16 v[122:125], v[180:183], v[160:163], v[122:125]
	v_mfma_f32_16x16x32_bf16 v[106:109], v[180:183], v[164:167], v[106:109]
	v_mfma_f32_16x16x32_bf16 v[78:81], v[180:183], v[168:171], v[78:81]
	v_mfma_f32_16x16x32_bf16 v[42:45], v[180:183], v[172:175], v[42:45]
	v_mfma_f32_16x16x32_bf16 v[118:121], v[184:187], v[160:163], v[118:121]
	v_mfma_f32_16x16x32_bf16 v[94:97], v[184:187], v[164:167], v[94:97]
	v_mfma_f32_16x16x32_bf16 v[58:61], v[184:187], v[168:171], v[58:61]
	v_mfma_f32_16x16x32_bf16 v[26:29], v[184:187], v[172:175], v[26:29]
	ds_read_b128 v[180:183], v136 offset:12288
	ds_read_b128 v[184:187], v136 offset:14336
	v_mfma_f32_16x16x32_bf16 v[114:117], v[188:191], v[160:163], v[114:117]
	v_mfma_f32_16x16x32_bf16 v[90:93], v[188:191], v[164:167], v[90:93]
	v_mfma_f32_16x16x32_bf16 v[54:57], v[188:191], v[168:171], v[54:57]
	v_mfma_f32_16x16x32_bf16 v[22:25], v[188:191], v[172:175], v[22:25]
	v_add_u32_e32 v136, v151, v141
	v_add_u32_e32 v208, v150, v141
	s_waitcnt lgkmcnt(0)
	v_mfma_f32_16x16x32_bf16 v[102:105], v[176:179], v[160:163], v[102:105]
	v_mfma_f32_16x16x32_bf16 v[74:77], v[176:179], v[164:167], v[74:77]
	v_mfma_f32_16x16x32_bf16 v[188:191], v[192:195], v[164:167], v[66:69]
	v_mfma_f32_16x16x32_bf16 v[196:199], v[176:179], v[168:171], v[46:49]
	s_nop 2
	ds_read_b128 v[46:49], v136
	ds_read_b128 v[66:69], v136 offset:2048
	v_mfma_f32_16x16x32_bf16 v[10:13], v[176:179], v[172:175], v[10:13]
	ds_read_b128 v[176:179], v208
	ds_read_b128 v[200:203], v208 offset:2048
	ds_read_b128 v[204:207], v208 offset:4096
	ds_read_b128 v[208:211], v208 offset:6144
	v_mfma_f32_16x16x32_bf16 v[98:101], v[192:195], v[160:163], v[98:101]
	v_mfma_f32_16x16x32_bf16 v[30:33], v[192:195], v[168:171], v[30:33]
	v_mfma_f32_16x16x32_bf16 v[6:9], v[192:195], v[172:175], v[6:9]
	v_mfma_f32_16x16x32_bf16 v[192:195], v[180:183], v[164:167], v[38:41]
	v_mfma_f32_16x16x32_bf16 v[164:167], v[184:187], v[164:167], v[34:37]
	v_mfma_f32_16x16x32_bf16 v[18:21], v[180:183], v[168:171], v[18:21]
	v_mfma_f32_16x16x32_bf16 v[168:171], v[184:187], v[168:171], v[14:17]
	s_nop 2
	ds_read_b128 v[14:17], v136 offset:4096
	ds_read_b128 v[34:37], v136 offset:6144
	v_mfma_f32_16x16x32_bf16 v[70:73], v[180:183], v[160:163], v[70:73]
	v_mfma_f32_16x16x32_bf16 v[2:5], v[180:183], v[172:175], v[2:5]
	v_mfma_f32_16x16x32_bf16 v[160:163], v[184:187], v[160:163], v[62:65]
	v_mfma_f32_16x16x32_bf16 v[86:89], v[184:187], v[172:175], v[86:89]
	s_waitcnt lgkmcnt(0)
	v_mfma_f32_16x16x32_bf16 v[172:175], v[46:49], v[208:211], v[50:53]
	s_nop 2
	ds_read_b128 v[50:53], v136 offset:8192
	ds_read_b128 v[180:183], v136 offset:10240
	v_mfma_f32_16x16x32_bf16 v[126:129], v[46:49], v[176:179], v[126:129]
	v_mfma_f32_16x16x32_bf16 v[122:125], v[66:69], v[176:179], v[122:125]
	v_mfma_f32_16x16x32_bf16 v[110:113], v[46:49], v[200:203], v[110:113]
	v_mfma_f32_16x16x32_bf16 v[106:109], v[66:69], v[200:203], v[106:109]
	v_mfma_f32_16x16x32_bf16 v[82:85], v[46:49], v[204:207], v[82:85]
	v_mfma_f32_16x16x32_bf16 v[78:81], v[66:69], v[204:207], v[78:81]
	v_mfma_f32_16x16x32_bf16 v[184:187], v[66:69], v[208:211], v[42:45]
	ds_read_b128 v[224:227], v136 offset:12288
	ds_read_b128 v[228:231], v136 offset:14336
	v_mfma_f32_16x16x32_bf16 v[118:121], v[14:17], v[176:179], v[118:121]
	v_mfma_f32_16x16x32_bf16 v[114:117], v[34:37], v[176:179], v[114:117]
	v_mfma_f32_16x16x32_bf16 v[94:97], v[14:17], v[200:203], v[94:97]
	v_mfma_f32_16x16x32_bf16 v[90:93], v[34:37], v[200:203], v[90:93]
	v_mfma_f32_16x16x32_bf16 v[212:215], v[14:17], v[204:207], v[58:61]
	v_mfma_f32_16x16x32_bf16 v[216:219], v[34:37], v[204:207], v[54:57]
	v_mfma_f32_16x16x32_bf16 v[220:223], v[14:17], v[208:211], v[26:29]
	v_mfma_f32_16x16x32_bf16 v[66:69], v[34:37], v[208:211], v[22:25]
	s_waitcnt lgkmcnt(0)
	v_mfma_f32_16x16x32_bf16 v[38:41], v[180:183], v[204:207], v[30:33]
	v_mfma_f32_16x16x32_bf16 v[62:65], v[50:53], v[176:179], v[102:105]
	v_mfma_f32_16x16x32_bf16 v[46:49], v[180:183], v[176:179], v[98:101]
	v_mfma_f32_16x16x32_bf16 v[58:61], v[50:53], v[200:203], v[74:77]
	v_mfma_f32_16x16x32_bf16 v[42:45], v[180:183], v[200:203], v[188:191]
	v_mfma_f32_16x16x32_bf16 v[54:57], v[50:53], v[204:207], v[196:199]
	v_mfma_f32_16x16x32_bf16 v[50:53], v[50:53], v[208:211], v[10:13]
	v_mfma_f32_16x16x32_bf16 v[34:37], v[180:183], v[208:211], v[6:9]
	s_nop 2
	v_mov_b32_e32 v8, v1
	s_waitcnt vmcnt(0)
	s_barrier
; template <bool SWAP, class Epi, bool THIN = false> ...
;     ...
;     __syncthreads();
;     const int te = get_tid512();
;     const int fr_e = te & 15, fq_e = (te & 63) >> 4, wr_e = te >> 7, wc_e = (te >> 6) & 1;
;     const int sub = 2 * mt + (wr_e >> 1);
;     const int g = sub / tpg, ti = sub - g * tpg;
;     const int rig0 = ti * step - halo;
;     const int rw = (wr_e & 1) * 64;
;     if constexpr (Epi::KIND == 0) {
; #pragma unroll
;       for (int m = 0; m < 4; ++m) {
;         const int rig = rig0 + rw + m * 16 + fr_e;
;         if constexpr (Epi::ROWSUM) {
;           float ss = 0.f;
; #pragma unroll
;           for (int n = 0; n < 8; ++n) {
;             const int col = nt * 256 + wc_e * 128 + n * 16 + fq_e * 4;
;             if (col < N) ss += epi.c4(g, rig, col, acc[m][n]);
;           }
;           ss += __shfl_xor(ss, 16); ss += __shfl_xor(ss, 32);
;           if (fq_e == 0) epi.rowsum(g, rig, nt * 2 + wc_e, ss);
;         } else {
; #pragma unroll
;           for (int n = 0; n < 8; ++n) {
;             const int col = nt * 256 + wc_e * 128 + n * 16 + fq_e * 4;
;             if (col < N) epi.c4(g, rig, col, acc[m][n]);
;           }
;         }
;       }
;     } else if constexpr (Epi::KIND == 1) {
; #pragma unroll
;       for (int m = 0; m < 4; ++m) {
;         const int rig = rig0 + rw + m * 16 + fq_e * 4;
; #pragma unroll
;         for (int n = 0; n < 8; ++n) {
;           const int col = nt * 256 + wc_e * 128 + n * 16 + fr_e;
;           if (col < N) epi.r4(g, rig, col, acc[m][n]);
;         }
;       }
;     } else {
;       bf16_t* Zw = (bf16_t*)smem + ((wr_e >> 1) * 2 + wc_e) * (128 * 132);
;       const int nt2w = nt * 2 + wc_e;
; #pragma unroll
;       for (int n = 0; n < 8; ++n) {
;         const int cl = n * 16 + fq_e * 4;
;         f32x4 b4 = {0.f, 0.f, 0.f, 0.f};
;         if (epi.pre_bias) b4 = *(const f32x4*)(epi.pre_bias + epi.norig(nt2w, cl));
; #pragma unroll
;         for (int m = 0; m < 4; ++m) {
;           const int rl = rw + m * 16 + fr_e;
;           const int pos = rig0 + rl;
;           const bool ok = pos >= 0 && pos < grows;
;           f32x4 vv = acc[m][n] + b4;
;           if (!ok) vv = (f32x4){0.f, 0.f, 0.f, 0.f};
;           uint2 u; u.x = pack2(vv[0], vv[1]); u.y = pack2(vv[2], vv[3]);
;           *(uint2*)(Zw + rl * 132 + cl) = u;
;         }
;       }
	v_mfma_f32_16x16x32_bf16 v[30:33], v[224:227], v[176:179], v[70:73]
	v_ashrrev_i32_e32 v98, 8, v8
	v_add_u32_e32 v6, s4, v98
	v_mul_hi_i32 v7, v6, s26
	v_lshrrev_b32_e32 v9, 31, v7
	v_ashrrev_i32_e32 v7, 3, v7
	v_add_u32_e32 v70, v7, v9
	v_and_b32_e32 v71, 15, v8
	v_mad_u64_u32 v[6:7], s[4:5], v70, s27, v[6:7]
	v_lshrrev_b32_e32 v74, 1, v8
	v_bfe_u32 v73, v8, 6, 1
	v_mul_lo_u32 v72, v6, s28
	v_and_or_b32 v71, v74, 64, v71
	v_add_u32_e32 v99, v72, v71
	v_lshl_or_b32 v73, v98, 1, v73
	v_mul_lo_u32 v73, v73, s29
	v_add_u32_e32 v100, -1, v99
	v_and_or_b32 v73, v74, 24, v73
	v_pk_add_f32 v[74:75], v[128:129], 0 op_sel_hi:[1,0]
	v_pk_add_f32 v[76:77], v[126:127], 0 op_sel_hi:[1,0]
	v_cmp_gt_u32_e32 vcc, s30, v100
	v_mfma_f32_16x16x32_bf16 v[22:25], v[224:227], v[204:207], v[18:21]
	v_mad_u32_u24 v71, v71, s31, v73
	v_add_u32_e32 v73, 15, v99
	v_cmp_gt_u32_e64 s[4:5], s30, v73
	v_mfma_f32_16x16x32_bf16 v[18:21], v[224:227], v[208:211], v[2:5]
	s_lshl_b32 s24, s6, 7
	v_cndmask_b32_e32 v75, 0, v75, vcc
	v_pk_add_f32 v[84:85], v[84:85], 0 op_sel_hi:[1,0]
	v_mfma_f32_16x16x32_bf16 v[2:5], v[228:231], v[208:211], v[86:89]
	v_add_f32_e64 v82, v82, 0
	v_add_f32_e64 v83, v83, 0
	v_pk_add_f32 v[66:67], v[66:67], 0 op_sel_hi:[1,0]
	v_pk_add_f32 v[62:63], v[62:63], 0 op_sel_hi:[1,0]
	v_cndmask_b32_e32 v86, 0, v74, vcc
	v_cndmask_b32_e32 v74, 0, v76, vcc
	v_cndmask_b32_e32 v76, 0, v77, vcc
	v_cvt_pk_bf16_f32 v74, v74, v76
	v_pk_add_f32 v[76:77], v[112:113], 0 op_sel_hi:[1,0]
	v_cvt_pk_bf16_f32 v75, v86, v75
	v_pk_add_f32 v[86:87], v[110:111], 0 op_sel_hi:[1,0]
	v_cndmask_b32_e64 v73, 0, v76, s[4:5]
	v_cndmask_b32_e64 v77, 0, v77, s[4:5]
	v_cvt_pk_bf16_f32 v77, v73, v77
	v_add_u32_e32 v73, 31, v99
	v_cmp_gt_u32_e64 s[6:7], s30, v73
	v_cndmask_b32_e64 v76, 0, v86, s[4:5]
	v_cndmask_b32_e64 v86, 0, v87, s[4:5]
	v_cndmask_b32_e64 v73, 0, v84, s[6:7]
	v_cndmask_b32_e64 v82, 0, v82, s[6:7]
	v_cndmask_b32_e64 v83, 0, v83, s[6:7]
	v_cndmask_b32_e64 v84, 0, v85, s[6:7]
	v_cvt_pk_bf16_f32 v82, v82, v83
	v_cvt_pk_bf16_f32 v83, v73, v84
	v_add_u32_e32 v73, 47, v99
	v_cvt_pk_bf16_f32 v76, v76, v86
	v_pk_add_f32 v[84:85], v[174:175], 0 op_sel_hi:[1,0]
	v_pk_add_f32 v[86:87], v[172:173], 0 op_sel_hi:[1,0]
	v_cmp_gt_u32_e64 s[8:9], s30, v73
	v_pk_add_f32 v[88:89], v[122:123], 0 op_sel_hi:[1,0]
	v_mfma_f32_16x16x32_bf16 v[26:29], v[224:227], v[200:203], v[192:195]
	v_cndmask_b32_e64 v73, 0, v84, s[8:9]
	v_cndmask_b32_e64 v84, 0, v86, s[8:9]
	v_cndmask_b32_e64 v86, 0, v87, s[8:9]
	v_cndmask_b32_e64 v85, 0, v85, s[8:9]
	v_cvt_pk_bf16_f32 v84, v84, v86
	v_pk_add_f32 v[86:87], v[124:125], 0 op_sel_hi:[1,0]
	v_cvt_pk_bf16_f32 v85, v73, v85
	v_mfma_f32_16x16x32_bf16 v[14:17], v[228:231], v[176:179], v[160:163]
	v_cndmask_b32_e32 v73, 0, v86, vcc
	v_cndmask_b32_e32 v87, 0, v87, vcc
	v_cndmask_b32_e32 v86, 0, v88, vcc
	v_cndmask_b32_e32 v88, 0, v89, vcc
	v_cvt_pk_bf16_f32 v86, v86, v88
	v_cvt_pk_bf16_f32 v87, v73, v87
	ds_write2_b64 v71, v[74:75], v[86:87] offset1:4
	v_pk_add_f32 v[74:75], v[108:109], 0 op_sel_hi:[1,0]
	v_pk_add_f32 v[86:87], v[106:107], 0 op_sel_hi:[1,0]
	v_cndmask_b32_e64 v73, 0, v74, s[4:5]
	v_cndmask_b32_e64 v75, 0, v75, s[4:5]
	v_cndmask_b32_e64 v74, 0, v86, s[4:5]
	v_cndmask_b32_e64 v86, 0, v87, s[4:5]
	v_cvt_pk_bf16_f32 v74, v74, v86
	v_cvt_pk_bf16_f32 v75, v73, v75
	v_add_u32_e32 v73, 0x1000, v71
	ds_write2_b64 v73, v[76:77], v[74:75] offset0:16 offset1:20
	v_pk_add_f32 v[74:75], v[80:81], 0 op_sel_hi:[1,0]
	v_pk_add_f32 v[76:77], v[78:79], 0 op_sel_hi:[1,0]
	v_cndmask_b32_e64 v78, 0, v74, s[6:7]
	v_cndmask_b32_e64 v75, 0, v75, s[6:7]
	v_cndmask_b32_e64 v74, 0, v76, s[6:7]
	v_cndmask_b32_e64 v76, 0, v77, s[6:7]
	v_cvt_pk_bf16_f32 v74, v74, v76
	v_cvt_pk_bf16_f32 v75, v78, v75
	v_add_u32_e32 v86, 0x2000, v71
	ds_write2_b64 v86, v[82:83], v[74:75] offset0:32 offset1:36
	v_pk_add_f32 v[74:75], v[186:187], 0 op_sel_hi:[1,0]
	v_pk_add_f32 v[76:77], v[184:185], 0 op_sel_hi:[1,0]
	v_cndmask_b32_e64 v78, 0, v74, s[8:9]
	v_cndmask_b32_e64 v75, 0, v75, s[8:9]
	v_cndmask_b32_e64 v74, 0, v76, s[8:9]
	v_cndmask_b32_e64 v76, 0, v77, s[8:9]
	v_cvt_pk_bf16_f32 v74, v74, v76
	v_cvt_pk_bf16_f32 v75, v78, v75
	v_add_u32_e32 v87, 0x3000, v71
	ds_write2_b64 v87, v[84:85], v[74:75] offset0:48 offset1:52
	v_pk_add_f32 v[74:75], v[120:121], 0 op_sel_hi:[1,0]
	v_pk_add_f32 v[76:77], v[118:119], 0 op_sel_hi:[1,0]
	v_cndmask_b32_e32 v78, 0, v74, vcc
	v_cndmask_b32_e32 v75, 0, v75, vcc
	v_cndmask_b32_e32 v74, 0, v76, vcc
	v_cndmask_b32_e32 v76, 0, v77, vcc
	v_cvt_pk_bf16_f32 v74, v74, v76
	v_cvt_pk_bf16_f32 v75, v78, v75
	v_pk_add_f32 v[76:77], v[96:97], 0 op_sel_hi:[1,0]
	v_pk_add_f32 v[78:79], v[94:95], 0 op_sel_hi:[1,0]
	v_cndmask_b32_e64 v80, 0, v76, s[4:5]
	v_cndmask_b32_e64 v77, 0, v77, s[4:5]
	v_cndmask_b32_e64 v76, 0, v78, s[4:5]
	v_cndmask_b32_e64 v78, 0, v79, s[4:5]
	v_cvt_pk_bf16_f32 v76, v76, v78
	v_cvt_pk_bf16_f32 v77, v80, v77
	v_pk_add_f32 v[78:79], v[214:215], 0 op_sel_hi:[1,0]
	v_pk_add_f32 v[80:81], v[212:213], 0 op_sel_hi:[1,0]
	v_cndmask_b32_e64 v82, 0, v78, s[6:7]
	v_cndmask_b32_e64 v79, 0, v79, s[6:7]
	v_cndmask_b32_e64 v78, 0, v80, s[6:7]
	v_cndmask_b32_e64 v80, 0, v81, s[6:7]
	v_cvt_pk_bf16_f32 v78, v78, v80
	v_cvt_pk_bf16_f32 v79, v82, v79
	v_pk_add_f32 v[80:81], v[222:223], 0 op_sel_hi:[1,0]
	v_pk_add_f32 v[82:83], v[220:221], 0 op_sel_hi:[1,0]
	v_cndmask_b32_e64 v84, 0, v80, s[8:9]
	v_cndmask_b32_e64 v81, 0, v81, s[8:9]
	v_cndmask_b32_e64 v80, 0, v82, s[8:9]
	v_cndmask_b32_e64 v82, 0, v83, s[8:9]
	v_cvt_pk_bf16_f32 v80, v80, v82
	v_cvt_pk_bf16_f32 v81, v84, v81
	v_pk_add_f32 v[82:83], v[116:117], 0 op_sel_hi:[1,0]
	v_pk_add_f32 v[84:85], v[114:115], 0 op_sel_hi:[1,0]
; __device__ __forceinline__ unsigned pack2(float a, float b) { unsigned r; asm("v_cvt_pk_bf16_f32 %0, %1, %2" : "=v"(r) : "v"(a), "v"(b)); return r; }
; template <bool SWAP, class Epi, bool THIN = false> ...
;     ...
;       bf16_t* Zw = (bf16_t*)smem + ((wr_e >> 1) * 2 + wc_e) * (128 * 132);
;       const int nt2w = nt * 2 + wc_e;
; #pragma unroll
;       for (int n = 0; n < 8; ++n) {
;         const int cl = n * 16 + fq_e * 4;
;         f32x4 b4 = {0.f, 0.f, 0.f, 0.f};
;         if (epi.pre_bias) b4 = *(const f32x4*)(epi.pre_bias + epi.norig(nt2w, cl));
; #pragma unroll
;         for (int m = 0; m < 4; ++m) {
;           const int rl = rw + m * 16 + fr_e;
;           const int pos = rig0 + rl;
;           const bool ok = pos >= 0 && pos < grows;
;           f32x4 vv = acc[m][n] + b4;
;           if (!ok) vv = (f32x4){0.f, 0.f, 0.f, 0.f};
;           uint2 u; u.x = pack2(vv[0], vv[1]); u.y = pack2(vv[2], vv[3]);
;           *(uint2*)(Zw + rl * 132 + cl) = u;
;         }
;       }
	v_cndmask_b32_e32 v88, 0, v82, vcc
	v_cndmask_b32_e32 v83, 0, v83, vcc
	v_cndmask_b32_e32 v82, 0, v84, vcc
	v_mfma_f32_16x16x32_bf16 v[10:13], v[228:231], v[200:203], v[164:167]
	v_cndmask_b32_e32 v84, 0, v85, vcc
	v_cvt_pk_bf16_f32 v82, v82, v84
	v_cvt_pk_bf16_f32 v83, v88, v83
	v_mfma_f32_16x16x32_bf16 v[6:9], v[228:231], v[204:207], v[168:171]
	ds_write2_b64 v71, v[74:75], v[82:83] offset0:8 offset1:12
	v_pk_add_f32 v[74:75], v[92:93], 0 op_sel_hi:[1,0]
	v_pk_add_f32 v[82:83], v[90:91], 0 op_sel_hi:[1,0]
	v_cndmask_b32_e64 v84, 0, v74, s[4:5]
	v_cndmask_b32_e64 v75, 0, v75, s[4:5]
	v_cndmask_b32_e64 v74, 0, v82, s[4:5]
	v_cndmask_b32_e64 v82, 0, v83, s[4:5]
	v_cvt_pk_bf16_f32 v74, v74, v82
	v_cvt_pk_bf16_f32 v75, v84, v75
	v_pk_add_f32 v[28:29], v[28:29], 0 op_sel_hi:[1,0]
	v_pk_add_f32 v[26:27], v[26:27], 0 op_sel_hi:[1,0]
	ds_write2_b64 v73, v[76:77], v[74:75] offset0:24 offset1:28
	v_pk_add_f32 v[74:75], v[218:219], 0 op_sel_hi:[1,0]
	v_pk_add_f32 v[76:77], v[216:217], 0 op_sel_hi:[1,0]
	v_pk_add_f32 v[58:59], v[58:59], 0 op_sel_hi:[1,0]
	v_pk_add_f32 v[54:55], v[54:55], 0 op_sel_hi:[1,0]
	v_pk_add_f32 v[50:51], v[50:51], 0 op_sel_hi:[1,0]
	v_pk_add_f32 v[46:47], v[46:47], 0 op_sel_hi:[1,0]
	v_pk_add_f32 v[42:43], v[42:43], 0 op_sel_hi:[1,0]
	v_pk_add_f32 v[38:39], v[38:39], 0 op_sel_hi:[1,0]
	v_pk_add_f32 v[34:35], v[34:35], 0 op_sel_hi:[1,0]
	v_pk_add_f32 v[30:31], v[30:31], 0 op_sel_hi:[1,0]
	v_cndmask_b32_e64 v28, 0, v28, s[4:5]
	v_cndmask_b32_e64 v26, 0, v26, s[4:5]
	v_cndmask_b32_e64 v27, 0, v27, s[4:5]
	v_pk_add_f32 v[22:23], v[22:23], 0 op_sel_hi:[1,0]
	v_pk_add_f32 v[18:19], v[18:19], 0 op_sel_hi:[1,0]
	v_pk_add_f32 v[14:15], v[14:15], 0 op_sel_hi:[1,0]
	v_pk_add_f32 v[10:11], v[10:11], 0 op_sel_hi:[1,0]
	v_pk_add_f32 v[6:7], v[6:7], 0 op_sel_hi:[1,0]
	v_pk_add_f32 v[2:3], v[2:3], 0 op_sel_hi:[1,0]
	v_cndmask_b32_e64 v82, 0, v74, s[6:7]
	v_cndmask_b32_e64 v75, 0, v75, s[6:7]
	v_cndmask_b32_e64 v74, 0, v76, s[6:7]
	v_pk_add_f32 v[68:69], v[68:69], 0 op_sel_hi:[1,0]
	v_cndmask_b32_e64 v66, 0, v66, s[8:9]
	v_cndmask_b32_e64 v67, 0, v67, s[8:9]
	v_pk_add_f32 v[64:65], v[64:65], 0 op_sel_hi:[1,0]
	v_cndmask_b32_e32 v62, 0, v62, vcc
	v_cndmask_b32_e32 v63, 0, v63, vcc
	v_pk_add_f32 v[60:61], v[60:61], 0 op_sel_hi:[1,0]
	v_cndmask_b32_e64 v58, 0, v58, s[4:5]
	v_cndmask_b32_e64 v59, 0, v59, s[4:5]
	v_pk_add_f32 v[56:57], v[56:57], 0 op_sel_hi:[1,0]
	v_cndmask_b32_e64 v54, 0, v54, s[6:7]
	v_cndmask_b32_e64 v55, 0, v55, s[6:7]
	v_pk_add_f32 v[52:53], v[52:53], 0 op_sel_hi:[1,0]
	v_cndmask_b32_e64 v50, 0, v50, s[8:9]
	v_cndmask_b32_e64 v51, 0, v51, s[8:9]
	v_pk_add_f32 v[48:49], v[48:49], 0 op_sel_hi:[1,0]
	v_cndmask_b32_e32 v46, 0, v46, vcc
	v_cndmask_b32_e32 v47, 0, v47, vcc
	v_pk_add_f32 v[44:45], v[44:45], 0 op_sel_hi:[1,0]
	v_cndmask_b32_e64 v42, 0, v42, s[4:5]
	v_cndmask_b32_e64 v43, 0, v43, s[4:5]
	v_pk_add_f32 v[40:41], v[40:41], 0 op_sel_hi:[1,0]
	v_cndmask_b32_e64 v38, 0, v38, s[6:7]
	v_cndmask_b32_e64 v39, 0, v39, s[6:7]
	v_pk_add_f32 v[36:37], v[36:37], 0 op_sel_hi:[1,0]
	v_cndmask_b32_e64 v34, 0, v34, s[8:9]
	v_cndmask_b32_e64 v35, 0, v35, s[8:9]
	v_pk_add_f32 v[32:33], v[32:33], 0 op_sel_hi:[1,0]
	v_cndmask_b32_e32 v30, 0, v30, vcc
	v_cndmask_b32_e32 v31, 0, v31, vcc
	v_cndmask_b32_e64 v29, 0, v29, s[4:5]
	v_cvt_pk_bf16_f32 v26, v26, v27
	v_cvt_pk_bf16_f32 v27, v28, v29
	v_pk_add_f32 v[24:25], v[24:25], 0 op_sel_hi:[1,0]
	v_cndmask_b32_e64 v22, 0, v22, s[6:7]
	v_cndmask_b32_e64 v23, 0, v23, s[6:7]
	v_pk_add_f32 v[20:21], v[20:21], 0 op_sel_hi:[1,0]
	v_cndmask_b32_e64 v18, 0, v18, s[8:9]
	v_cndmask_b32_e64 v19, 0, v19, s[8:9]
	v_pk_add_f32 v[16:17], v[16:17], 0 op_sel_hi:[1,0]
	v_cndmask_b32_e32 v14, 0, v14, vcc
	v_cndmask_b32_e32 v15, 0, v15, vcc
	v_pk_add_f32 v[12:13], v[12:13], 0 op_sel_hi:[1,0]
	v_cndmask_b32_e64 v10, 0, v10, s[4:5]
	v_cndmask_b32_e64 v11, 0, v11, s[4:5]
	v_pk_add_f32 v[8:9], v[8:9], 0 op_sel_hi:[1,0]
	v_cndmask_b32_e64 v6, 0, v6, s[6:7]
	v_cndmask_b32_e64 v7, 0, v7, s[6:7]
	v_pk_add_f32 v[4:5], v[4:5], 0 op_sel_hi:[1,0]
	v_cndmask_b32_e64 v2, 0, v2, s[8:9]
	v_cndmask_b32_e64 v3, 0, v3, s[8:9]
	v_mov_b32_e32 v28, v142
	v_cndmask_b32_e64 v76, 0, v77, s[6:7]
	v_cvt_pk_bf16_f32 v74, v74, v76
	v_cvt_pk_bf16_f32 v75, v82, v75
	ds_write2_b64 v86, v[78:79], v[74:75] offset0:40 offset1:44
	v_cndmask_b32_e64 v68, 0, v68, s[8:9]
	v_cndmask_b32_e64 v69, 0, v69, s[8:9]
	v_cvt_pk_bf16_f32 v66, v66, v67
	v_cvt_pk_bf16_f32 v67, v68, v69
	ds_write2_b64 v87, v[80:81], v[66:67] offset0:56 offset1:60
	v_cndmask_b32_e32 v64, 0, v64, vcc
	v_cndmask_b32_e32 v65, 0, v65, vcc
	v_cvt_pk_bf16_f32 v62, v62, v63
	v_cvt_pk_bf16_f32 v63, v64, v65
	v_cndmask_b32_e64 v60, 0, v60, s[4:5]
	v_cndmask_b32_e64 v61, 0, v61, s[4:5]
	v_cvt_pk_bf16_f32 v58, v58, v59
	v_cvt_pk_bf16_f32 v59, v60, v61
	v_cndmask_b32_e64 v56, 0, v56, s[6:7]
	v_cndmask_b32_e64 v57, 0, v57, s[6:7]
	v_cvt_pk_bf16_f32 v54, v54, v55
	v_cvt_pk_bf16_f32 v55, v56, v57
	v_cndmask_b32_e64 v52, 0, v52, s[8:9]
	v_cndmask_b32_e64 v53, 0, v53, s[8:9]
	v_cvt_pk_bf16_f32 v50, v50, v51
	v_cvt_pk_bf16_f32 v51, v52, v53
	v_cndmask_b32_e32 v48, 0, v48, vcc
	v_cndmask_b32_e32 v49, 0, v49, vcc
	v_cvt_pk_bf16_f32 v46, v46, v47
	v_cvt_pk_bf16_f32 v47, v48, v49
	ds_write2_b64 v71, v[62:63], v[46:47] offset0:16 offset1:20
	v_cndmask_b32_e64 v44, 0, v44, s[4:5]
	v_cndmask_b32_e64 v45, 0, v45, s[4:5]
	v_cvt_pk_bf16_f32 v42, v42, v43
; __device__ __forceinline__ unsigned pack2(float a, float b) { unsigned r; asm("v_cvt_pk_bf16_f32 %0, %1, %2" : "=v"(r) : "v"(a), "v"(b)); return r; }
;   template <class F>
;   __device__ __forceinline__ void finish(const bf16_t* Z, int g, int rig0, int nt, F&& pre) const {
;     ...
;     if (MODE == 0 || nt < 8) {
;       if (MODE == 0) {
;         const int f2 = (tid & 31) * 2, q8 = tid >> 5;
;         const int q0 = 1 + 16 * q8, q1 = (q0 + 16 < 127) ? q0 + 16 : 127;
;         const int na = norig(nt, f2), ng = norig(nt, 64 + f2);
;         const f32x2 a0 = *(const f32x2*)(cw + na), a1 = *(const f32x2*)(cw + NC + na), a2 = *(const f32x2*)(cw + 2 * NC + na), ab = *(const f32x2*)(cb + na);
;         const f32x2 g0 = *(const f32x2*)(cw + ng), g1 = *(const f32x2*)(cw + NC + ng), g2 = *(const f32x2*)(cw + 2 * NC + ng), gb = *(const f32x2*)(cb + ng);
;         pre();
;         f32x2 am = ldz(Z, q0 - 1, f2), ac = ldz(Z, q0, f2);
;         f32x2 gm = ldz(Z, q0 - 1, 64 + f2), gc = ldz(Z, q0, 64 + f2);
; template <bool SWAP, class Epi, bool THIN = false> ...
;     ...
;       bf16_t* Zw = (bf16_t*)smem + ((wr_e >> 1) * 2 + wc_e) * (128 * 132);
;       const int nt2w = nt * 2 + wc_e;
; #pragma unroll
;       for (int n = 0; n < 8; ++n) {
;         const int cl = n * 16 + fq_e * 4;
;         f32x4 b4 = {0.f, 0.f, 0.f, 0.f};
;         if (epi.pre_bias) b4 = *(const f32x4*)(epi.pre_bias + epi.norig(nt2w, cl));
; #pragma unroll
;         for (int m = 0; m < 4; ++m) {
;           const int rl = rw + m * 16 + fr_e;
;           const int pos = rig0 + rl;
;           const bool ok = pos >= 0 && pos < grows;
;           f32x4 vv = acc[m][n] + b4;
;           if (!ok) vv = (f32x4){0.f, 0.f, 0.f, 0.f};
;           uint2 u; u.x = pack2(vv[0], vv[1]); u.y = pack2(vv[2], vv[3]);
;           *(uint2*)(Zw + rl * 132 + cl) = u;
;         }
;       }
;       __syncthreads();
;       {
;         auto no_pre = []() {};
;         const bf16_t* Zr = (const bf16_t*)smem + ((wr_e >> 1) * 2) * (128 * 132);
;         epi.finish(Zr, g, rig0, nt * 2, no_pre);
	v_cvt_pk_bf16_f32 v43, v44, v45
	ds_write2_b64 v73, v[58:59], v[42:43] offset0:32 offset1:36
	v_cndmask_b32_e64 v40, 0, v40, s[6:7]
	v_cndmask_b32_e64 v41, 0, v41, s[6:7]
	v_cvt_pk_bf16_f32 v38, v38, v39
	v_cvt_pk_bf16_f32 v39, v40, v41
	ds_write2_b64 v86, v[54:55], v[38:39] offset0:48 offset1:52
	v_cndmask_b32_e64 v36, 0, v36, s[8:9]
	v_cndmask_b32_e64 v37, 0, v37, s[8:9]
	v_cvt_pk_bf16_f32 v34, v34, v35
	v_cvt_pk_bf16_f32 v35, v36, v37
	ds_write2_b64 v87, v[50:51], v[34:35] offset0:64 offset1:68
	v_cndmask_b32_e32 v32, 0, v32, vcc
	v_cndmask_b32_e32 v33, 0, v33, vcc
	v_cvt_pk_bf16_f32 v30, v30, v31
	v_cvt_pk_bf16_f32 v31, v32, v33
	v_cndmask_b32_e64 v24, 0, v24, s[6:7]
	v_cndmask_b32_e64 v25, 0, v25, s[6:7]
	v_cvt_pk_bf16_f32 v22, v22, v23
	v_cvt_pk_bf16_f32 v23, v24, v25
	v_cndmask_b32_e64 v20, 0, v20, s[8:9]
	v_cndmask_b32_e64 v21, 0, v21, s[8:9]
	v_cvt_pk_bf16_f32 v18, v18, v19
	v_cvt_pk_bf16_f32 v19, v20, v21
	v_cndmask_b32_e32 v16, 0, v16, vcc
	v_cndmask_b32_e32 v17, 0, v17, vcc
	v_cvt_pk_bf16_f32 v14, v14, v15
	v_cvt_pk_bf16_f32 v15, v16, v17
	ds_write2_b64 v71, v[30:31], v[14:15] offset0:24 offset1:28
	v_cndmask_b32_e64 v12, 0, v12, s[4:5]
	v_cndmask_b32_e64 v13, 0, v13, s[4:5]
	v_cvt_pk_bf16_f32 v10, v10, v11
	v_cvt_pk_bf16_f32 v11, v12, v13
	ds_write2_b64 v73, v[26:27], v[10:11] offset0:40 offset1:44
	v_cndmask_b32_e64 v8, 0, v8, s[6:7]
	v_cndmask_b32_e64 v9, 0, v9, s[6:7]
	v_cvt_pk_bf16_f32 v6, v6, v7
	v_cvt_pk_bf16_f32 v7, v8, v9
	ds_write2_b64 v86, v[22:23], v[6:7] offset0:56 offset1:60
	v_cndmask_b32_e64 v4, 0, v4, s[8:9]
	v_cndmask_b32_e64 v5, 0, v5, s[8:9]
	v_cvt_pk_bf16_f32 v2, v2, v3
	v_cvt_pk_bf16_f32 v3, v4, v5
	ds_write2_b64 v87, v[18:19], v[2:3] offset0:72 offset1:76
	s_waitcnt lgkmcnt(0)
	s_barrier
	v_mul_i32_i24_e32 v2, 0x10800, v98
	v_ashrrev_i32_e32 v29, 1, v28
	v_and_b32_e32 v38, -16, v29
	v_min_i32_e32 v3, 0x6e, v38
	v_or_b32_e32 v20, 1, v38
	v_add_u32_e32 v3, 17, v3
	v_cmp_lt_i32_e32 vcc, v20, v3
	v_ashrrev_i32_e32 v71, 31, v70
	s_and_saveexec_b64 s[4:5], vcc
	s_cbranch_execz .LBB0_3432
	v_lshlrev_b32_e32 v4, 1, v28
	v_and_b32_e32 v21, 62, v4
	v_or_b32_e32 v4, s24, v21
	s_add_i32 s6, s24, 0xb00
	v_ashrrev_i32_e32 v5, 31, v4
	v_or_b32_e32 v12, s6, v21
	v_lshlrev_b64 v[10:11], 2, v[4:5]
	v_lshl_add_u64 v[14:15], s[16:17], 0, v[10:11]
	v_lshl_add_u64 v[18:19], s[22:23], 0, v[10:11]
	v_ashrrev_i32_e32 v13, 31, v12
	v_lshl_add_u64 v[16:17], s[20:21], 0, v[10:11]
	global_load_dwordx2 v[4:5], v[14:15], off
	global_load_dwordx2 v[6:7], v[16:17], off
	global_load_dwordx2 v[8:9], v[18:19], off
	v_lshlrev_b64 v[18:19], 2, v[12:13]
	v_lshl_add_u64 v[10:11], s[18:19], 0, v[10:11]
	v_lshl_add_u64 v[22:23], s[16:17], 0, v[18:19]
	global_load_dwordx2 v[10:11], v[10:11], off
	v_lshl_add_u64 v[24:25], s[20:21], 0, v[18:19]
	v_lshl_add_u64 v[26:27], s[22:23], 0, v[18:19]
	global_load_dwordx2 v[12:13], v[22:23], off
	global_load_dwordx2 v[14:15], v[24:25], off
	global_load_dwordx2 v[16:17], v[26:27], off
	v_lshl_add_u64 v[18:19], s[18:19], 0, v[18:19]
	global_load_dwordx2 v[18:19], v[18:19], off
	v_mov_b32_e32 v117, 0
	v_lshlrev_b32_e32 v88, 1, v142
	v_and_b32_e32 v105, 62, v88
	v_add3_u32 v88, v105, s24, 64
	s_add_i32 s38, s24, 0xb40
	v_ashrrev_i32_e32 v89, 31, v88
	v_or_b32_e32 v96, s38, v105
	v_lshlrev_b64 v[94:95], 2, v[88:89]
	v_lshl_add_u64 v[98:99], s[16:17], 0, v[94:95]
	v_lshl_add_u64 v[102:103], s[22:23], 0, v[94:95]
	v_ashrrev_i32_e32 v97, 31, v96
	v_lshl_add_u64 v[100:101], s[20:21], 0, v[94:95]
	global_load_dwordx2 v[88:89], v[98:99], off
	global_load_dwordx2 v[90:91], v[100:101], off
	global_load_dwordx2 v[92:93], v[102:103], off
	v_lshlrev_b64 v[102:103], 2, v[96:97]
	v_lshl_add_u64 v[94:95], s[18:19], 0, v[94:95]
	v_lshl_add_u64 v[106:107], s[16:17], 0, v[102:103]
	global_load_dwordx2 v[94:95], v[94:95], off
	v_lshl_add_u64 v[108:109], s[20:21], 0, v[102:103]
	v_lshl_add_u64 v[110:111], s[22:23], 0, v[102:103]
	global_load_dwordx2 v[96:97], v[106:107], off
	global_load_dwordx2 v[98:99], v[108:109], off
	global_load_dwordx2 v[100:101], v[110:111], off
	v_lshl_add_u64 v[102:103], s[18:19], 0, v[102:103]
	global_load_dwordx2 v[102:103], v[102:103], off
	v_lshlrev_b32_e32 v136, 1, v21
	v_mul_lo_u32 v22, v38, s31
	v_mul_lo_u32 v20, v20, s31
	v_add3_u32 v22, v2, v22, v136
	v_add3_u32 v20, v2, v20, v136
	ds_read2_b32 v[22:23], v22 offset1:32
	ds_read2_b32 v[20:21], v20 offset1:32
	s_ashr_i32 s25, s24, 31
	s_lshl_b64 s[6:7], s[24:25], 1
	s_add_u32 s6, s12, s6
	s_addc_u32 s7, s13, s7
	v_lshrrev_b32_e32 v29, 4, v29
	v_and_b32_e32 v28, 31, v28
	s_waitcnt lgkmcnt(1)
	v_lshlrev_b32_e32 v32, 16, v23
	v_and_b32_e32 v33, 0xffff0000, v23
	v_lshlrev_b32_e32 v34, 16, v22
	v_and_b32_e32 v35, 0xffff0000, v22
	v_lshl_add_u64 v[22:23], s[6:7], 0, v[136:137]
	v_mad_u64_u32 v[30:31], s[6:7], v29, s33, v[2:3]
	v_lshlrev_b32_e32 v28, 2, v28
	s_waitcnt lgkmcnt(0)
	v_lshlrev_b32_e32 v24, 16, v21
	v_and_b32_e32 v25, 0xffff0000, v21
	v_lshlrev_b32_e32 v26, 16, v20
	v_and_b32_e32 v27, 0xffff0000, v20
	v_lshlrev_b64 v[20:21], 11, v[70:71]
	v_add3_u32 v39, v30, v28, s34
	s_mov_b32 s98, 0x1600
	s_mov_b32 s99, 0
	v_add_u32_e32 v48, v72, v38
	v_ashrrev_i32_e32 v49, 31, v48
	v_lshl_add_u64 v[48:49], v[20:21], 0, v[48:49]
	v_mad_u64_u32 v[50:51], s[38:39], v48, s35, v[22:23]
	v_mad_i32_i24 v51, v49, s35, v51
	s_mov_b64 s[6:7], 0
	s_waitcnt vmcnt(0)
	ds_read2_b32 v[44:45], v39 offset1:32
	s_branch .LBB0_3428

; template <bool SWAP, class Epi, bool THIN = false> ...
;     ...
;     for (int st = 0; st < ns; ++st) {
;       asm volatile("s_waitcnt vmcnt(0)" ::: "memory");
;       __builtin_amdgcn_s_barrier();
;       asm volatile("" ::: "memory");
;       if (st + 1 < ns) {
;         char* nb = smem + ((st + 1) & 1) * 65536;
;         const int ko = (st + 1) * 64;
; #pragma unroll
;         for (int i = 0; i < 4; ++i) { GLDS16(A + (size_t)(ap[i] + ko), nb + tid * 16 + i * 8192); GLDS16(Bt + (size_t)(bp[i] + ko), nb + 32768 + tid * 16 + i * 8192); }
;       }
;       const char* sa = smem + (st & 1) * 65536 + (wr * 64 + fr) * 128;
;       const char* sb = smem + (st & 1) * 65536 + 32768 + (wc * 128 + fr) * 128;
;       if constexpr (THIN) {
;         if (wc == 0) {
; #pragma unroll
;           for (int ks = 0; ks < 2; ++ks) {
;             bf16x8 af[4], bf[2];
; #pragma unroll
;             for (int m = 0; m < 4; ++m) af[m] = *(const bf16x8*)(sa + m * 2048 + (((ks * 4 + fq) ^ swz) << 4));
; #pragma unroll
;             for (int n = 0; n < 2; ++n) bf[n] = *(const bf16x8*)(sb + n * 2048 + (((ks * 4 + fq) ^ swz) << 4));
; #pragma unroll
;             for (int m = 0; m < 4; ++m)
; #pragma unroll
;               for (int n = 0; n < 2; ++n)
;                 acc[m][n] = SWAP ? __builtin_amdgcn_mfma_f32_16x16x32_bf16(bf[n], af[m], acc[m][n], 0, 0, 0)
;                                  : __builtin_amdgcn_mfma_f32_16x16x32_bf16(af[m], bf[n], acc[m][n], 0, 0, 0);
;           }
;         }
;       } else {
;       bf16x8 afA[4], afB[4], bfb[2][2];
; #pragma unroll
;       for (int m = 0; m < 4; ++m) afA[m] = *(const bf16x8*)(sa + m * 2048 + ((fq ^ swz) << 4));
; #pragma unroll
;       for (int n = 0; n < 2; ++n) bfb[0][n] = *(const bf16x8*)(sb + n * 2048 + ((fq ^ swz) << 4));
; #pragma unroll
;       for (int gq = 0; gq < 8; ++gq) {
;         const int ks = gq >> 2, nh = gq & 3;
;         if (gq < 7) {
;           const int ks2 = (gq + 1) >> 2, nh2 = (gq + 1) & 3;
; #pragma unroll
;           for (int n = 0; n < 2; ++n) bfb[(gq + 1) & 1][n] = *(const bf16x8*)(sb + (nh2 * 2 + n) * 2048 + (((ks2 * 4 + fq) ^ swz) << 4));
;         }
;         if (gq == 3) {
; #pragma unroll
;           for (int m = 0; m < 4; ++m) afB[m] = *(const bf16x8*)(sa + m * 2048 + (((4 + fq) ^ swz) << 4));
;         }
;         __builtin_amdgcn_sched_barrier(0);
; #pragma unroll
.LBB0_3516:
	s_add_i32 s9, s7, 0x10000
	s_and_b32 s8, s9, 0x10000
	v_add_u32_e32 v139, s8, v144
	s_nop 0
	v_readfirstlane_b32 s10, v139
	s_waitcnt vmcnt(0)
	s_barrier
	s_and_b32 s7, s7, 0x10000
	v_add_u32_e32 v130, s7, v145
	v_add_u32_e32 v139, v130, v147
	ds_read_b128 v[168:171], v139
	ds_read_b128 v[172:175], v139 offset:2048
	ds_read_b128 v[176:179], v139 offset:4096
	ds_read_b128 v[180:183], v139 offset:6144
	v_or_b32_e32 v139, s7, v146
	v_add_u32_e32 v141, v139, v147
	ds_read_b128 v[184:187], v141 offset:32768
	ds_read_b128 v[188:191], v141 offset:34816
	ds_read_b128 v[192:195], v141 offset:36864
	ds_read_b128 v[196:199], v141 offset:38912
	v_add_u32_e32 v130, v130, v148
	s_waitcnt lgkmcnt(3)
	v_mfma_f32_16x16x32_bf16 v[126:129], v[184:187], v[168:171], v[126:129]
	s_mov_b32 m0, s10
	v_mfma_f32_16x16x32_bf16 v[110:113], v[184:187], v[172:175], v[110:113]
	global_load_lds_dwordx4 v138, s[24:25] sc1
	v_add_u32_e32 v138, 0x80, v138
	v_mfma_f32_16x16x32_bf16 v[82:85], v[184:187], v[176:179], v[82:85]
	v_mfma_f32_16x16x32_bf16 v[50:53], v[184:187], v[180:183], v[50:53]
	ds_read_b128 v[184:187], v141 offset:40960
	ds_read_b128 v[200:203], v141 offset:43008
	s_waitcnt lgkmcnt(4)
	v_mfma_f32_16x16x32_bf16 v[122:125], v[188:191], v[168:171], v[122:125]
	s_add_u32 m0, s10, 0x8000
	v_mfma_f32_16x16x32_bf16 v[106:109], v[188:191], v[172:175], v[106:109]
	global_load_lds_dwordx4 v137, s[20:21] sc1
	v_add_u32_e32 v137, 0x80, v137
	v_mfma_f32_16x16x32_bf16 v[78:81], v[188:191], v[176:179], v[78:81]
	v_mfma_f32_16x16x32_bf16 v[38:41], v[188:191], v[180:183], v[38:41]
	s_waitcnt lgkmcnt(3)
	v_mfma_f32_16x16x32_bf16 v[118:121], v[192:195], v[168:171], v[118:121]
	s_add_u32 m0, s10, 0x2000
	v_mfma_f32_16x16x32_bf16 v[94:97], v[192:195], v[172:175], v[94:97]
	global_load_lds_dwordx4 v136, s[24:25] sc1
	v_add_u32_e32 v136, 0x80, v136
	v_mfma_f32_16x16x32_bf16 v[58:61], v[192:195], v[176:179], v[58:61]
	v_mfma_f32_16x16x32_bf16 v[26:29], v[192:195], v[180:183], v[26:29]
	ds_read_b128 v[188:191], v141 offset:45056
	ds_read_b128 v[192:195], v141 offset:47104
	s_waitcnt lgkmcnt(4)
	v_mfma_f32_16x16x32_bf16 v[114:117], v[196:199], v[168:171], v[114:117]
	s_add_u32 m0, s10, 0xa000
	v_mfma_f32_16x16x32_bf16 v[86:89], v[196:199], v[172:175], v[86:89]
	global_load_lds_dwordx4 v135, s[20:21] sc1
	v_add_u32_e32 v135, 0x80, v135
	v_mfma_f32_16x16x32_bf16 v[54:57], v[196:199], v[176:179], v[54:57]
	v_mfma_f32_16x16x32_bf16 v[22:25], v[196:199], v[180:183], v[22:25]
	v_add_u32_e32 v139, v139, v148
	s_waitcnt lgkmcnt(3)
	v_mfma_f32_16x16x32_bf16 v[102:105], v[184:187], v[168:171], v[102:105]
	ds_read_b128 v[196:199], v139 offset:32768
	ds_read_b128 v[204:207], v139 offset:34816
	s_add_u32 m0, s10, 0x4000
	v_mfma_f32_16x16x32_bf16 v[74:77], v[184:187], v[172:175], v[74:77]
	global_load_lds_dwordx4 v134, s[24:25] sc1
	v_add_u32_e32 v134, 0x80, v134
	v_mfma_f32_16x16x32_bf16 v[46:49], v[184:187], v[176:179], v[46:49]
	v_mfma_f32_16x16x32_bf16 v[10:13], v[184:187], v[180:183], v[10:13]
	ds_read_b128 v[184:187], v130
	ds_read_b128 v[208:211], v130 offset:2048
	ds_read_b128 v[212:215], v130 offset:4096
	ds_read_b128 v[216:219], v130 offset:6144
	s_waitcnt lgkmcnt(8)
	v_mfma_f32_16x16x32_bf16 v[98:101], v[200:203], v[168:171], v[98:101]
	s_add_u32 m0, s10, 0xc000
	v_mfma_f32_16x16x32_bf16 v[66:69], v[200:203], v[172:175], v[66:69]
	global_load_lds_dwordx4 v133, s[20:21] sc1
	v_add_u32_e32 v133, 0x80, v133
	v_mfma_f32_16x16x32_bf16 v[34:37], v[200:203], v[176:179], v[34:37]
	v_mfma_f32_16x16x32_bf16 v[6:9], v[200:203], v[180:183], v[6:9]
	s_waitcnt lgkmcnt(7)
	v_mfma_f32_16x16x32_bf16 v[70:73], v[188:191], v[168:171], v[70:73]
	s_add_u32 m0, s10, 0x6000
	s_waitcnt lgkmcnt(6)
	v_mfma_f32_16x16x32_bf16 v[62:65], v[192:195], v[168:171], v[62:65]
	global_load_lds_dwordx4 v132, s[24:25] sc1
	v_add_u32_e32 v132, 0x80, v132
	v_mfma_f32_16x16x32_bf16 v[42:45], v[188:191], v[172:175], v[42:45]
	v_mfma_f32_16x16x32_bf16 v[30:33], v[192:195], v[172:175], v[30:33]
	ds_read_b128 v[168:171], v139 offset:36864
	ds_read_b128 v[172:175], v139 offset:38912
	v_mfma_f32_16x16x32_bf16 v[18:21], v[188:191], v[176:179], v[18:21]
	s_add_u32 m0, s10, 0xe000
	v_mfma_f32_16x16x32_bf16 v[14:17], v[192:195], v[176:179], v[14:17]
	global_load_lds_dwordx4 v140, s[20:21] sc1
	v_add_u32_e32 v140, 0x80, v140
	v_mfma_f32_16x16x32_bf16 v[2:5], v[188:191], v[180:183], v[2:5]
	v_mfma_f32_16x16x32_bf16 v[90:93], v[192:195], v[180:183], v[90:93]
	ds_read_b128 v[176:179], v139 offset:40960
	ds_read_b128 v[180:183], v139 offset:43008
	s_waitcnt lgkmcnt(7)
	v_mfma_f32_16x16x32_bf16 v[126:129], v[196:199], v[184:187], v[126:129]
	v_mfma_f32_16x16x32_bf16 v[122:125], v[204:207], v[184:187], v[122:125]
	s_waitcnt lgkmcnt(6)
	v_mfma_f32_16x16x32_bf16 v[110:113], v[196:199], v[208:211], v[110:113]
	v_mfma_f32_16x16x32_bf16 v[106:109], v[204:207], v[208:211], v[106:109]
	s_waitcnt lgkmcnt(5)
	v_mfma_f32_16x16x32_bf16 v[82:85], v[196:199], v[212:215], v[82:85]
	v_mfma_f32_16x16x32_bf16 v[78:81], v[204:207], v[212:215], v[78:81]
	s_waitcnt lgkmcnt(4)
	v_mfma_f32_16x16x32_bf16 v[50:53], v[196:199], v[216:219], v[50:53]
	v_mfma_f32_16x16x32_bf16 v[38:41], v[204:207], v[216:219], v[38:41]
	s_waitcnt lgkmcnt(3)
	v_mfma_f32_16x16x32_bf16 v[118:121], v[168:171], v[184:187], v[118:121]
	v_mfma_f32_16x16x32_bf16 v[94:97], v[168:171], v[208:211], v[94:97]
	v_mfma_f32_16x16x32_bf16 v[58:61], v[168:171], v[212:215], v[58:61]
	v_mfma_f32_16x16x32_bf16 v[26:29], v[168:171], v[216:219], v[26:29]
	ds_read_b128 v[168:171], v139 offset:45056
	ds_read_b128 v[188:191], v139 offset:47104
	s_waitcnt lgkmcnt(4)
; template <bool SWAP, class Epi, bool THIN = false> ...
;     ...
;       bf16x8 afA[4], afB[4], bfb[2][2];
; #pragma unroll
;       for (int m = 0; m < 4; ++m) afA[m] = *(const bf16x8*)(sa + m * 2048 + ((fq ^ swz) << 4));
; #pragma unroll
;       for (int n = 0; n < 2; ++n) bfb[0][n] = *(const bf16x8*)(sb + n * 2048 + ((fq ^ swz) << 4));
; #pragma unroll
;       for (int gq = 0; gq < 8; ++gq) {
;         const int ks = gq >> 2, nh = gq & 3;
;         if (gq < 7) {
;           const int ks2 = (gq + 1) >> 2, nh2 = (gq + 1) & 3;
; #pragma unroll
;           for (int n = 0; n < 2; ++n) bfb[(gq + 1) & 1][n] = *(const bf16x8*)(sb + (nh2 * 2 + n) * 2048 + (((ks2 * 4 + fq) ^ swz) << 4));
;         }
;         if (gq == 3) {
; #pragma unroll
;           for (int m = 0; m < 4; ++m) afB[m] = *(const bf16x8*)(sa + m * 2048 + (((4 + fq) ^ swz) << 4));
;         }
;         __builtin_amdgcn_sched_barrier(0);
; #pragma unroll
;         for (int m = 0; m < 4; ++m)
; #pragma unroll
;           for (int n = 0; n < 2; ++n) {
;             const bf16x8 av = ks ? afB[m] : afA[m];
;             acc[m][nh * 2 + n] = SWAP ? __builtin_amdgcn_mfma_f32_16x16x32_bf16(bfb[gq & 1][n], av, acc[m][nh * 2 + n], 0, 0, 0)
;                                       : __builtin_amdgcn_mfma_f32_16x16x32_bf16(av, bfb[gq & 1][n], acc[m][nh * 2 + n], 0, 0, 0);
;           }
;       }
;       }
;     }
;     __syncthreads();
	v_mfma_f32_16x16x32_bf16 v[114:117], v[172:175], v[184:187], v[114:117]
	v_mfma_f32_16x16x32_bf16 v[86:89], v[172:175], v[208:211], v[86:89]
	v_mfma_f32_16x16x32_bf16 v[54:57], v[172:175], v[212:215], v[54:57]
	v_mfma_f32_16x16x32_bf16 v[22:25], v[172:175], v[216:219], v[22:25]
	s_waitcnt lgkmcnt(3)
	v_mfma_f32_16x16x32_bf16 v[102:105], v[176:179], v[184:187], v[102:105]
	s_waitcnt lgkmcnt(2)
	v_mfma_f32_16x16x32_bf16 v[98:101], v[180:183], v[184:187], v[98:101]
	v_mfma_f32_16x16x32_bf16 v[74:77], v[176:179], v[208:211], v[74:77]
	v_mfma_f32_16x16x32_bf16 v[66:69], v[180:183], v[208:211], v[66:69]
	v_mfma_f32_16x16x32_bf16 v[46:49], v[176:179], v[212:215], v[46:49]
	v_mfma_f32_16x16x32_bf16 v[34:37], v[180:183], v[212:215], v[34:37]
	v_mfma_f32_16x16x32_bf16 v[10:13], v[176:179], v[216:219], v[10:13]
	v_mfma_f32_16x16x32_bf16 v[6:9], v[180:183], v[216:219], v[6:9]
	s_waitcnt lgkmcnt(1)
	v_mfma_f32_16x16x32_bf16 v[70:73], v[168:171], v[184:187], v[70:73]
	s_add_i32 s6, s6, 64
	s_cmpk_eq_i32 s6, 0xac0
	s_mov_b32 s7, s9
	s_waitcnt lgkmcnt(0)
	v_mfma_f32_16x16x32_bf16 v[62:65], v[188:191], v[184:187], v[62:65]
	v_mfma_f32_16x16x32_bf16 v[42:45], v[168:171], v[208:211], v[42:45]
	v_mfma_f32_16x16x32_bf16 v[30:33], v[188:191], v[208:211], v[30:33]
	v_mfma_f32_16x16x32_bf16 v[18:21], v[168:171], v[212:215], v[18:21]
	v_mfma_f32_16x16x32_bf16 v[14:17], v[188:191], v[212:215], v[14:17]
	v_mfma_f32_16x16x32_bf16 v[2:5], v[168:171], v[216:219], v[2:5]
	v_mfma_f32_16x16x32_bf16 v[90:93], v[188:191], v[216:219], v[90:93]
	s_cbranch_scc0 .LBB0_3516
	v_add_u32_e32 v130, s8, v145
	s_waitcnt vmcnt(0)
	s_barrier
	v_add_u32_e32 v140, v130, v147
	ds_read_b128 v[132:135], v140
	ds_read_b128 v[136:139], v140 offset:2048
	ds_read_b128 v[168:171], v140 offset:4096
	ds_read_b128 v[172:175], v140 offset:6144
	v_add_u32_e32 v140, s8, v146
	v_add_u32_e32 v141, v140, v147
	ds_read_b128 v[176:179], v141 offset:32768
	ds_read_b128 v[180:183], v141 offset:34816
	ds_read_b128 v[184:187], v141 offset:36864
	ds_read_b128 v[188:191], v141 offset:38912
	v_add_u32_e32 v130, v130, v148
	s_waitcnt lgkmcnt(0)
	v_mfma_f32_16x16x32_bf16 v[126:129], v[176:179], v[132:135], v[126:129]
	v_mfma_f32_16x16x32_bf16 v[110:113], v[176:179], v[136:139], v[110:113]
	v_mfma_f32_16x16x32_bf16 v[82:85], v[176:179], v[168:171], v[82:85]
	v_mfma_f32_16x16x32_bf16 v[50:53], v[176:179], v[172:175], v[50:53]
	ds_read_b128 v[176:179], v141 offset:40960
	ds_read_b128 v[192:195], v141 offset:43008
	v_mfma_f32_16x16x32_bf16 v[122:125], v[180:183], v[132:135], v[122:125]
	v_mfma_f32_16x16x32_bf16 v[106:109], v[180:183], v[136:139], v[106:109]
	v_mfma_f32_16x16x32_bf16 v[78:81], v[180:183], v[168:171], v[78:81]
	v_mfma_f32_16x16x32_bf16 v[38:41], v[180:183], v[172:175], v[38:41]
	v_mfma_f32_16x16x32_bf16 v[118:121], v[184:187], v[132:135], v[118:121]
	v_mfma_f32_16x16x32_bf16 v[180:183], v[184:187], v[136:139], v[94:97]
	v_mfma_f32_16x16x32_bf16 v[200:203], v[184:187], v[168:171], v[58:61]
	v_mfma_f32_16x16x32_bf16 v[204:207], v[188:191], v[168:171], v[54:57]
	v_mfma_f32_16x16x32_bf16 v[184:187], v[184:187], v[172:175], v[26:29]
	s_nop 2
	ds_read_b128 v[26:29], v141 offset:45056
	ds_read_b128 v[54:57], v141 offset:47104
	v_mfma_f32_16x16x32_bf16 v[114:117], v[188:191], v[132:135], v[114:117]
	v_mfma_f32_16x16x32_bf16 v[196:199], v[188:191], v[136:139], v[86:89]
	v_mfma_f32_16x16x32_bf16 v[188:191], v[188:191], v[172:175], v[22:25]
	v_add_u32_e32 v140, v140, v148
	s_waitcnt lgkmcnt(0)
	v_mfma_f32_16x16x32_bf16 v[102:105], v[176:179], v[132:135], v[102:105]
	ds_read_b128 v[22:25], v140 offset:32768
	ds_read_b128 v[86:89], v140 offset:34816
	v_mfma_f32_16x16x32_bf16 v[74:77], v[176:179], v[136:139], v[74:77]
	v_mfma_f32_16x16x32_bf16 v[46:49], v[176:179], v[168:171], v[46:49]
	v_mfma_f32_16x16x32_bf16 v[10:13], v[176:179], v[172:175], v[10:13]
	ds_read_b128 v[176:179], v130
	ds_read_b128 v[208:211], v130 offset:2048
	ds_read_b128 v[212:215], v130 offset:4096
	ds_read_b128 v[216:219], v130 offset:6144
	v_mfma_f32_16x16x32_bf16 v[98:101], v[192:195], v[132:135], v[98:101]
	v_mfma_f32_16x16x32_bf16 v[66:69], v[192:195], v[136:139], v[66:69]
	v_mfma_f32_16x16x32_bf16 v[34:37], v[192:195], v[168:171], v[34:37]
	v_mfma_f32_16x16x32_bf16 v[6:9], v[192:195], v[172:175], v[6:9]
	v_mfma_f32_16x16x32_bf16 v[220:223], v[26:29], v[168:171], v[18:21]
	v_mfma_f32_16x16x32_bf16 v[168:171], v[54:57], v[168:171], v[14:17]
	s_nop 2
	ds_read_b128 v[14:17], v140 offset:36864
	ds_read_b128 v[18:21], v140 offset:38912
	v_mfma_f32_16x16x32_bf16 v[70:73], v[26:29], v[132:135], v[70:73]
	v_mfma_f32_16x16x32_bf16 v[132:135], v[54:57], v[132:135], v[62:65]
	v_mfma_f32_16x16x32_bf16 v[192:195], v[26:29], v[136:139], v[42:45]
	v_mfma_f32_16x16x32_bf16 v[136:139], v[54:57], v[136:139], v[30:33]
	v_mfma_f32_16x16x32_bf16 v[2:5], v[26:29], v[172:175], v[2:5]
	v_mfma_f32_16x16x32_bf16 v[172:175], v[54:57], v[172:175], v[90:93]
	ds_read_b128 v[224:227], v140 offset:40960
	ds_read_b128 v[228:231], v140 offset:43008
	s_waitcnt lgkmcnt(0)
	v_mfma_f32_16x16x32_bf16 v[126:129], v[22:25], v[176:179], v[126:129]
	v_mfma_f32_16x16x32_bf16 v[122:125], v[86:89], v[176:179], v[122:125]
	v_mfma_f32_16x16x32_bf16 v[94:97], v[22:25], v[208:211], v[110:113]
	v_mfma_f32_16x16x32_bf16 v[90:93], v[86:89], v[208:211], v[106:109]
	v_mfma_f32_16x16x32_bf16 v[62:65], v[22:25], v[212:215], v[82:85]
	v_mfma_f32_16x16x32_bf16 v[58:61], v[86:89], v[212:215], v[78:81]
	v_mfma_f32_16x16x32_bf16 v[30:33], v[22:25], v[216:219], v[50:53]
	v_mfma_f32_16x16x32_bf16 v[26:29], v[86:89], v[216:219], v[38:41]
	v_mfma_f32_16x16x32_bf16 v[86:89], v[14:17], v[208:211], v[180:183]
	v_mfma_f32_16x16x32_bf16 v[22:25], v[14:17], v[216:219], v[184:187]
	s_nop 1
	ds_read_b128 v[180:183], v140 offset:45056
	ds_read_b128 v[184:187], v140 offset:47104
	v_mfma_f32_16x16x32_bf16 v[118:121], v[14:17], v[176:179], v[118:121]
	v_mfma_f32_16x16x32_bf16 v[114:117], v[18:21], v[176:179], v[114:117]
	v_mfma_f32_16x16x32_bf16 v[82:85], v[18:21], v[208:211], v[196:199]
	v_mfma_f32_16x16x32_bf16 v[54:57], v[14:17], v[212:215], v[200:203]
	v_mfma_f32_16x16x32_bf16 v[50:53], v[18:21], v[212:215], v[204:207]
	v_mfma_f32_16x16x32_bf16 v[18:21], v[18:21], v[216:219], v[188:191]
	v_mfma_f32_16x16x32_bf16 v[110:113], v[224:227], v[176:179], v[102:105]
	v_mfma_f32_16x16x32_bf16 v[106:109], v[228:231], v[176:179], v[98:101]
	v_mfma_f32_16x16x32_bf16 v[78:81], v[224:227], v[208:211], v[74:77]
	v_mfma_f32_16x16x32_bf16 v[74:77], v[228:231], v[208:211], v[66:69]
	v_mfma_f32_16x16x32_bf16 v[46:49], v[224:227], v[212:215], v[46:49]
	v_mfma_f32_16x16x32_bf16 v[42:45], v[228:231], v[212:215], v[34:37]
	v_mfma_f32_16x16x32_bf16 v[14:17], v[224:227], v[216:219], v[10:13]
	v_mfma_f32_16x16x32_bf16 v[10:13], v[228:231], v[216:219], v[6:9]
	v_mov_b32_e32 v130, v1
	s_waitcnt vmcnt(0) lgkmcnt(0)
	s_barrier
; __device__ __forceinline__ unsigned pack2(float a, float b) { unsigned r; asm("v_cvt_pk_bf16_f32 %0, %1, %2" : "=v"(r) : "v"(a), "v"(b)); return r; }
; __device__ __forceinline__ float bf2f(bf16_t h) { return __uint_as_float(((unsigned)h) << 16); }
;   __device__ __forceinline__ void c4(int g, int rig, int col, f32x4 v) const {
;     const size_t o = ((size_t)g * 2048 + rig) * 1024 + col;
;     f32x4 bs;
;     if (BASE_F32) bs = __builtin_nontemporal_load((const f32x4*)((const float*)base + o));
;     else {
;       const uint2 u = *(const uint2*)((const bf16_t*)base + o);
;       bs[0] = bf2f((bf16_t)(u.x & 0xffff)); bs[1] = bf2f((bf16_t)(u.x >> 16)); bs[2] = bf2f((bf16_t)(u.y & 0xffff)); bs[3] = bf2f((bf16_t)(u.y >> 16));
;     }
;     const f32x4 gt = *(const f32x4*)(gate + (size_t)g * 6144 + col);
;     f32x4 bi = {0.f, 0.f, 0.f, 0.f};
;     if (bias) bi = *(const f32x4*)(bias + col);
;     f32x4 r;
; #pragma unroll
;     for (int j = 0; j < 4; ++j) r[j] = bs[j] + gt[j] * (v[j] + bi[j]);
;     uint2 w; w.x = pack2(r[0], r[1]); w.y = pack2(r[2], r[3]);
;     *(uint2*)(X16 + o) = w;
;   }
; template <bool SWAP, class Epi, bool THIN = false> ...
;     ...
;     if constexpr (Epi::KIND == 0) {
; #pragma unroll
;       for (int m = 0; m < 4; ++m) {
;         const int rig = rig0 + rw + m * 16 + fr_e;
;         if constexpr (Epi::ROWSUM) {
;           float ss = 0.f;
; #pragma unroll
;           for (int n = 0; n < 8; ++n) {
;             const int col = nt * 256 + wc_e * 128 + n * 16 + fq_e * 4;
;             if (col < N) ss += epi.c4(g, rig, col, acc[m][n]);
;           }
;           ss += __shfl_xor(ss, 16); ss += __shfl_xor(ss, 32);
;           if (fq_e == 0) epi.rowsum(g, rig, nt * 2 + wc_e, ss);
;         } else {
; #pragma unroll
;           for (int n = 0; n < 8; ++n) {
;             const int col = nt * 256 + wc_e * 128 + n * 16 + fq_e * 4;
;             if (col < N) epi.c4(g, rig, col, acc[m][n]);
;           }
;         }
	v_mfma_f32_16x16x32_bf16 v[98:101], v[184:187], v[176:179], v[132:135]
	v_ashrrev_i32_e32 v7, 8, v130
	v_add_u32_e32 v7, s5, v7
	v_ashrrev_i32_e32 v8, 31, v7
	v_lshrrev_b32_e32 v8, 28, v8
	v_add_u32_e32 v8, v7, v8
	v_ashrrev_i32_e32 v134, 4, v8
	v_lshlrev_b32_e32 v8, 11, v134
	v_lshlrev_b32_e32 v7, 7, v7
	v_sub_u32_e32 v7, v7, v8
	v_lshrrev_b32_e32 v8, 1, v130
	v_and_b32_e32 v6, 15, v130
	v_and_b32_e32 v8, 64, v8
	v_mfma_f32_16x16x32_bf16 v[66:69], v[184:187], v[208:211], v[136:139]
	v_ashrrev_i32_e32 v135, 31, v134
	s_nop 1
	v_or3_b32 v136, v7, v8, v6
	v_lshlrev_b32_e32 v6, 1, v130
	v_and_b32_e32 v132, 0x80, v6
	v_mfma_f32_16x16x32_bf16 v[6:9], v[180:183], v[216:219], v[2:5]
	v_ashrrev_i32_e32 v137, 31, v136
	v_lshlrev_b64 v[138:139], 21, v[134:135]
	v_lshlrev_b64 v[140:141], 10, v[136:137]
	v_lshrrev_b32_e32 v2, 2, v130
	v_and_b32_e32 v2, 12, v2
	v_mfma_f32_16x16x32_bf16 v[102:105], v[180:183], v[176:179], v[70:73]
	v_or3_b32 v132, v2, v132, s4
	v_mad_i64_i32 v[134:135], s[4:5], v134, s31, 0
	v_mfma_f32_16x16x32_bf16 v[70:73], v[180:183], v[208:211], v[192:195]
	v_lshl_add_u64 v[140:141], v[140:141], 0, v[138:139]
	v_cmp_gt_i32_e32 vcc, s34, v132
	v_ashrrev_i32_e32 v133, 31, v132
	v_mfma_f32_16x16x32_bf16 v[38:41], v[180:183], v[212:215], v[220:223]
	v_lshl_add_u64 v[134:135], s[22:23], 0, v[134:135]
	v_lshl_add_u64 v[140:141], v[140:141], 1, s[18:19]
	v_mfma_f32_16x16x32_bf16 v[34:37], v[184:187], v[212:215], v[168:171]
	v_mfma_f32_16x16x32_bf16 v[2:5], v[184:187], v[216:219], v[172:175]
	v_lshl_add_u64 v[218:219], v[132:133], 2, v[134:135]
	global_load_dwordx4 v[198:201], v[218:219], off
	global_load_dwordx4 v[202:205], v[218:219], off offset:64
	global_load_dwordx4 v[206:209], v[218:219], off offset:128
	global_load_dwordx4 v[210:213], v[218:219], off offset:192
	global_load_dwordx4 v[214:217], v[218:219], off offset:256
	global_load_dwordx4 v[224:227], v[218:219], off offset:320
	global_load_dwordx4 v[228:231], v[218:219], off offset:384
	global_load_dwordx4 v[232:235], v[218:219], off offset:448
	s_nop 0
	v_lshl_add_u64 v[172:173], v[132:133], 1, v[140:141]
	v_lshl_add_u64 v[196:197], v[132:133], 1, v[140:141]
	global_load_dwordx2 v[176:177], v[196:197], off
	global_load_dwordx2 v[178:179], v[196:197], off offset:32
	global_load_dwordx2 v[180:181], v[196:197], off offset:64
	global_load_dwordx2 v[182:183], v[196:197], off offset:96
	global_load_dwordx2 v[184:185], v[196:197], off offset:128
	global_load_dwordx2 v[186:187], v[196:197], off offset:160
	global_load_dwordx2 v[188:189], v[196:197], off offset:192
	global_load_dwordx2 v[190:191], v[196:197], off offset:224
	v_add_f32_e32 v126, 0, v126
	v_add_f32_e32 v127, 0, v127
	v_add_f32_e32 v128, 0, v128
	v_add_f32_e32 v129, 0, v129
	s_waitcnt vmcnt(7)
	v_lshlrev_b32_e32 v130, 16, v176
	v_and_b32_e32 v137, 0xffff0000, v176
	v_lshlrev_b32_e32 v167, 16, v177
	v_and_b32_e32 v174, 0xffff0000, v177
	v_fmac_f32_e32 v130, v126, v198
	v_fmac_f32_e32 v137, v127, v199
	v_fmac_f32_e32 v167, v128, v200
	v_fmac_f32_e32 v174, v129, v201
	v_cvt_pk_bf16_f32 v126, v130, v137
	v_cvt_pk_bf16_f32 v127, v167, v174
	global_store_dwordx2 v[172:173], v[126:127], off
	v_or_b32_e32 v126, 16, v132
	v_lshl_add_u64 v[168:169], v[132:133], 1, v[140:141]
	v_add_f32_e32 v122, 0, v122
	v_add_f32_e32 v123, 0, v123
	v_add_f32_e32 v124, 0, v124
	v_add_f32_e32 v125, 0, v125
	s_waitcnt vmcnt(7)
	v_lshlrev_b32_e32 v130, 16, v178
	v_and_b32_e32 v137, 0xffff0000, v178
	v_lshlrev_b32_e32 v167, 16, v179
	v_and_b32_e32 v170, 0xffff0000, v179
	v_fmac_f32_e32 v130, v122, v202
	v_fmac_f32_e32 v137, v123, v203
	v_fmac_f32_e32 v167, v124, v204
	v_fmac_f32_e32 v170, v125, v205
	v_cvt_pk_bf16_f32 v122, v130, v137
	v_cvt_pk_bf16_f32 v123, v167, v170
	global_store_dwordx2 v[168:169], v[122:123], off offset:32
	v_or_b32_e32 v122, 32, v132
	v_lshl_add_u64 v[126:127], v[132:133], 1, v[140:141]
	v_add_f32_e32 v118, 0, v118
	v_add_f32_e32 v119, 0, v119
	v_add_f32_e32 v120, 0, v120
	v_add_f32_e32 v121, 0, v121
	s_waitcnt vmcnt(7)
	v_lshlrev_b32_e32 v130, 16, v180
	v_and_b32_e32 v128, 0xffff0000, v180
	v_lshlrev_b32_e32 v137, 16, v181
	v_and_b32_e32 v129, 0xffff0000, v181
	v_fmac_f32_e32 v130, v118, v206
	v_fmac_f32_e32 v128, v119, v207
	v_fmac_f32_e32 v137, v120, v208
	v_fmac_f32_e32 v129, v121, v209
	v_cvt_pk_bf16_f32 v118, v130, v128
	v_cvt_pk_bf16_f32 v119, v137, v129
	global_store_dwordx2 v[126:127], v[118:119], off offset:64
	v_or_b32_e32 v118, 48, v132
	v_lshl_add_u64 v[122:123], v[132:133], 1, v[140:141]
	v_add_f32_e32 v114, 0, v114
	v_add_f32_e32 v115, 0, v115
	v_add_f32_e32 v116, 0, v116
	v_add_f32_e32 v117, 0, v117
	s_waitcnt vmcnt(7)
	v_lshlrev_b32_e32 v126, 16, v182
	v_and_b32_e32 v124, 0xffff0000, v182
	v_lshlrev_b32_e32 v127, 16, v183
	v_and_b32_e32 v125, 0xffff0000, v183
	v_fmac_f32_e32 v126, v114, v210
	v_fmac_f32_e32 v124, v115, v211
	v_fmac_f32_e32 v127, v116, v212
	v_fmac_f32_e32 v125, v117, v213
	v_cvt_pk_bf16_f32 v114, v126, v124
	v_cvt_pk_bf16_f32 v115, v127, v125
	global_store_dwordx2 v[122:123], v[114:115], off offset:96
	v_or_b32_e32 v114, 64, v132
	v_lshl_add_u64 v[118:119], v[132:133], 1, v[140:141]
	v_add_f32_e32 v110, 0, v110
	v_add_f32_e32 v111, 0, v111
	v_add_f32_e32 v112, 0, v112
	v_add_f32_e32 v113, 0, v113
	s_waitcnt vmcnt(7)
	v_lshlrev_b32_e32 v122, 16, v184
	v_and_b32_e32 v120, 0xffff0000, v184
	v_lshlrev_b32_e32 v123, 16, v185
	v_and_b32_e32 v121, 0xffff0000, v185
	v_fmac_f32_e32 v122, v110, v214
	v_fmac_f32_e32 v120, v111, v215
	v_fmac_f32_e32 v123, v112, v216
	v_fmac_f32_e32 v121, v113, v217
	v_cvt_pk_bf16_f32 v110, v122, v120
	v_cvt_pk_bf16_f32 v111, v123, v121
	global_store_dwordx2 v[118:119], v[110:111], off offset:128
	v_or_b32_e32 v110, 0x50, v132
	v_lshl_add_u64 v[114:115], v[132:133], 1, v[140:141]
	v_add_f32_e32 v106, 0, v106
	v_add_f32_e32 v107, 0, v107
	v_add_f32_e32 v108, 0, v108
	v_add_f32_e32 v109, 0, v109
	s_waitcnt vmcnt(7)
; __device__ __forceinline__ unsigned pack2(float a, float b) { unsigned r; asm("v_cvt_pk_bf16_f32 %0, %1, %2" : "=v"(r) : "v"(a), "v"(b)); return r; }
; __device__ __forceinline__ float bf2f(bf16_t h) { return __uint_as_float(((unsigned)h) << 16); }
;   __device__ __forceinline__ void c4(int g, int rig, int col, f32x4 v) const {
;     const size_t o = ((size_t)g * 2048 + rig) * 1024 + col;
;     f32x4 bs;
;     if (BASE_F32) bs = __builtin_nontemporal_load((const f32x4*)((const float*)base + o));
;     else {
;       const uint2 u = *(const uint2*)((const bf16_t*)base + o);
;       bs[0] = bf2f((bf16_t)(u.x & 0xffff)); bs[1] = bf2f((bf16_t)(u.x >> 16)); bs[2] = bf2f((bf16_t)(u.y & 0xffff)); bs[3] = bf2f((bf16_t)(u.y >> 16));
;     }
;     const f32x4 gt = *(const f32x4*)(gate + (size_t)g * 6144 + col);
;     f32x4 bi = {0.f, 0.f, 0.f, 0.f};
;     if (bias) bi = *(const f32x4*)(bias + col);
;     f32x4 r;
; #pragma unroll
;     for (int j = 0; j < 4; ++j) r[j] = bs[j] + gt[j] * (v[j] + bi[j]);
;     uint2 w; w.x = pack2(r[0], r[1]); w.y = pack2(r[2], r[3]);
;     *(uint2*)(X16 + o) = w;
;   }
; template <bool SWAP, class Epi, bool THIN = false> ...
;     ...
;     if constexpr (Epi::KIND == 0) {
; #pragma unroll
;       for (int m = 0; m < 4; ++m) {
;         const int rig = rig0 + rw + m * 16 + fr_e;
;         if constexpr (Epi::ROWSUM) {
;           float ss = 0.f;
; #pragma unroll
;           for (int n = 0; n < 8; ++n) {
;             const int col = nt * 256 + wc_e * 128 + n * 16 + fq_e * 4;
;             if (col < N) ss += epi.c4(g, rig, col, acc[m][n]);
;           }
;           ss += __shfl_xor(ss, 16); ss += __shfl_xor(ss, 32);
;           if (fq_e == 0) epi.rowsum(g, rig, nt * 2 + wc_e, ss);
;         } else {
; #pragma unroll
;           for (int n = 0; n < 8; ++n) {
;             const int col = nt * 256 + wc_e * 128 + n * 16 + fq_e * 4;
;             if (col < N) epi.c4(g, rig, col, acc[m][n]);
;           }
;         }
	v_lshlrev_b32_e32 v118, 16, v186
	v_and_b32_e32 v116, 0xffff0000, v186
	v_lshlrev_b32_e32 v119, 16, v187
	v_and_b32_e32 v117, 0xffff0000, v187
	v_fmac_f32_e32 v118, v106, v224
	v_fmac_f32_e32 v116, v107, v225
	v_fmac_f32_e32 v119, v108, v226
	v_fmac_f32_e32 v117, v109, v227
	v_cvt_pk_bf16_f32 v106, v118, v116
	v_cvt_pk_bf16_f32 v107, v119, v117
	global_store_dwordx2 v[114:115], v[106:107], off offset:160
	v_or_b32_e32 v106, 0x60, v132
	v_lshl_add_u64 v[110:111], v[132:133], 1, v[140:141]
	v_add_f32_e32 v102, 0, v102
	v_add_f32_e32 v103, 0, v103
	v_add_f32_e32 v104, 0, v104
	v_add_f32_e32 v105, 0, v105
	s_waitcnt vmcnt(7)
	v_lshlrev_b32_e32 v114, 16, v188
	v_and_b32_e32 v112, 0xffff0000, v188
	v_lshlrev_b32_e32 v115, 16, v189
	v_and_b32_e32 v113, 0xffff0000, v189
	v_fmac_f32_e32 v114, v102, v228
	v_fmac_f32_e32 v112, v103, v229
	v_fmac_f32_e32 v115, v104, v230
	v_fmac_f32_e32 v113, v105, v231
	v_cvt_pk_bf16_f32 v102, v114, v112
	v_cvt_pk_bf16_f32 v103, v115, v113
	global_store_dwordx2 v[110:111], v[102:103], off offset:192
	v_or_b32_e32 v102, 0x70, v132
	v_lshl_add_u64 v[106:107], v[132:133], 1, v[140:141]
	v_add_f32_e32 v98, 0, v98
	v_add_f32_e32 v99, 0, v99
	v_add_f32_e32 v100, 0, v100
	v_add_f32_e32 v101, 0, v101
	s_waitcnt vmcnt(7)
	v_lshlrev_b32_e32 v110, 16, v190
	v_and_b32_e32 v108, 0xffff0000, v190
	v_lshlrev_b32_e32 v111, 16, v191
	v_and_b32_e32 v109, 0xffff0000, v191
	v_fmac_f32_e32 v110, v98, v232
	v_fmac_f32_e32 v108, v99, v233
	v_fmac_f32_e32 v111, v100, v234
	v_fmac_f32_e32 v109, v101, v235
	v_cvt_pk_bf16_f32 v98, v110, v108
	v_cvt_pk_bf16_f32 v99, v111, v109
	global_store_dwordx2 v[106:107], v[98:99], off offset:224
	v_or_b32_e32 v98, 16, v136
	v_ashrrev_i32_e32 v99, 31, v98
	v_lshlrev_b64 v[98:99], 10, v[98:99]
	v_lshl_add_u64 v[98:99], v[98:99], 0, v[138:139]
	v_lshl_add_u64 v[98:99], v[98:99], 1, s[18:19]
	v_lshl_add_u64 v[104:105], v[132:133], 1, v[98:99]
	v_lshl_add_u64 v[196:197], v[132:133], 1, v[98:99]
	global_load_dwordx2 v[176:177], v[196:197], off
	global_load_dwordx2 v[178:179], v[196:197], off offset:32
	global_load_dwordx2 v[180:181], v[196:197], off offset:64
	global_load_dwordx2 v[182:183], v[196:197], off offset:96
	global_load_dwordx2 v[184:185], v[196:197], off offset:128
	global_load_dwordx2 v[186:187], v[196:197], off offset:160
	global_load_dwordx2 v[188:189], v[196:197], off offset:192
	global_load_dwordx2 v[190:191], v[196:197], off offset:224
	v_add_f32_e32 v94, 0, v94
	v_add_f32_e32 v95, 0, v95
	v_add_f32_e32 v96, 0, v96
	v_add_f32_e32 v97, 0, v97
	s_waitcnt vmcnt(7)
	v_lshlrev_b32_e32 v108, 16, v176
	v_and_b32_e32 v106, 0xffff0000, v176
	v_lshlrev_b32_e32 v109, 16, v177
	v_and_b32_e32 v107, 0xffff0000, v177
	v_fmac_f32_e32 v108, v94, v198
	v_fmac_f32_e32 v106, v95, v199
	v_fmac_f32_e32 v109, v96, v200
	v_fmac_f32_e32 v107, v97, v201
	v_cvt_pk_bf16_f32 v94, v108, v106
	v_cvt_pk_bf16_f32 v95, v109, v107
	global_store_dwordx2 v[104:105], v[94:95], off
	v_lshl_add_u64 v[100:101], v[132:133], 1, v[98:99]
	v_add_f32_e32 v90, 0, v90
	v_add_f32_e32 v91, 0, v91
	v_add_f32_e32 v92, 0, v92
	v_add_f32_e32 v93, 0, v93
	s_waitcnt vmcnt(7)
	v_lshlrev_b32_e32 v104, 16, v178
	v_and_b32_e32 v102, 0xffff0000, v178
	v_lshlrev_b32_e32 v105, 16, v179
	v_and_b32_e32 v103, 0xffff0000, v179
	v_fmac_f32_e32 v104, v90, v202
	v_fmac_f32_e32 v102, v91, v203
	v_fmac_f32_e32 v105, v92, v204
	v_fmac_f32_e32 v103, v93, v205
	v_cvt_pk_bf16_f32 v90, v104, v102
	v_cvt_pk_bf16_f32 v91, v105, v103
	global_store_dwordx2 v[100:101], v[90:91], off offset:32
	v_lshl_add_u64 v[94:95], v[132:133], 1, v[98:99]
	v_add_f32_e32 v86, 0, v86
	v_add_f32_e32 v87, 0, v87
	v_add_f32_e32 v88, 0, v88
	v_add_f32_e32 v89, 0, v89
	s_waitcnt vmcnt(7)
	v_lshlrev_b32_e32 v100, 16, v180
	v_and_b32_e32 v96, 0xffff0000, v180
	v_lshlrev_b32_e32 v101, 16, v181
	v_and_b32_e32 v97, 0xffff0000, v181
	v_fmac_f32_e32 v100, v86, v206
	v_fmac_f32_e32 v96, v87, v207
	v_fmac_f32_e32 v101, v88, v208
	v_fmac_f32_e32 v97, v89, v209
	v_cvt_pk_bf16_f32 v86, v100, v96
	v_cvt_pk_bf16_f32 v87, v101, v97
	global_store_dwordx2 v[94:95], v[86:87], off offset:64
	v_lshl_add_u64 v[90:91], v[132:133], 1, v[98:99]
	v_add_f32_e32 v82, 0, v82
	v_add_f32_e32 v83, 0, v83
	v_add_f32_e32 v84, 0, v84
	v_add_f32_e32 v85, 0, v85
	s_waitcnt vmcnt(7)
	v_lshlrev_b32_e32 v94, 16, v182
	v_and_b32_e32 v92, 0xffff0000, v182
	v_lshlrev_b32_e32 v95, 16, v183
	v_and_b32_e32 v93, 0xffff0000, v183
	v_fmac_f32_e32 v94, v82, v210
	v_fmac_f32_e32 v92, v83, v211
	v_fmac_f32_e32 v95, v84, v212
	v_fmac_f32_e32 v93, v85, v213
	v_cvt_pk_bf16_f32 v82, v94, v92
	v_cvt_pk_bf16_f32 v83, v95, v93
	global_store_dwordx2 v[90:91], v[82:83], off offset:96
	v_lshl_add_u64 v[86:87], v[132:133], 1, v[98:99]
	v_add_f32_e32 v78, 0, v78
	v_add_f32_e32 v79, 0, v79
	v_add_f32_e32 v80, 0, v80
	v_add_f32_e32 v81, 0, v81
	s_waitcnt vmcnt(7)
	v_lshlrev_b32_e32 v90, 16, v184
	v_and_b32_e32 v88, 0xffff0000, v184
	v_lshlrev_b32_e32 v91, 16, v185
	v_and_b32_e32 v89, 0xffff0000, v185
	v_fmac_f32_e32 v90, v78, v214
	v_fmac_f32_e32 v88, v79, v215
	v_fmac_f32_e32 v91, v80, v216
	v_fmac_f32_e32 v89, v81, v217
	v_cvt_pk_bf16_f32 v78, v90, v88
	v_cvt_pk_bf16_f32 v79, v91, v89
	global_store_dwordx2 v[86:87], v[78:79], off offset:128
	v_lshl_add_u64 v[82:83], v[132:133], 1, v[98:99]
	v_add_f32_e32 v74, 0, v74
	v_add_f32_e32 v75, 0, v75
	v_add_f32_e32 v76, 0, v76
	v_add_f32_e32 v77, 0, v77
	s_waitcnt vmcnt(7)
; __device__ __forceinline__ unsigned pack2(float a, float b) { unsigned r; asm("v_cvt_pk_bf16_f32 %0, %1, %2" : "=v"(r) : "v"(a), "v"(b)); return r; }
; __device__ __forceinline__ float bf2f(bf16_t h) { return __uint_as_float(((unsigned)h) << 16); }
;   __device__ __forceinline__ void c4(int g, int rig, int col, f32x4 v) const {
;     const size_t o = ((size_t)g * 2048 + rig) * 1024 + col;
;     f32x4 bs;
;     if (BASE_F32) bs = __builtin_nontemporal_load((const f32x4*)((const float*)base + o));
;     else {
;       const uint2 u = *(const uint2*)((const bf16_t*)base + o);
;       bs[0] = bf2f((bf16_t)(u.x & 0xffff)); bs[1] = bf2f((bf16_t)(u.x >> 16)); bs[2] = bf2f((bf16_t)(u.y & 0xffff)); bs[3] = bf2f((bf16_t)(u.y >> 16));
;     }
;     const f32x4 gt = *(const f32x4*)(gate + (size_t)g * 6144 + col);
;     f32x4 bi = {0.f, 0.f, 0.f, 0.f};
;     if (bias) bi = *(const f32x4*)(bias + col);
;     f32x4 r;
; #pragma unroll
;     for (int j = 0; j < 4; ++j) r[j] = bs[j] + gt[j] * (v[j] + bi[j]);
;     uint2 w; w.x = pack2(r[0], r[1]); w.y = pack2(r[2], r[3]);
;     *(uint2*)(X16 + o) = w;
;   }
; template <bool SWAP, class Epi, bool THIN = false> ...
;     ...
;     if constexpr (Epi::KIND == 0) {
; #pragma unroll
;       for (int m = 0; m < 4; ++m) {
;         const int rig = rig0 + rw + m * 16 + fr_e;
;         if constexpr (Epi::ROWSUM) {
;           float ss = 0.f;
; #pragma unroll
;           for (int n = 0; n < 8; ++n) {
;             const int col = nt * 256 + wc_e * 128 + n * 16 + fq_e * 4;
;             if (col < N) ss += epi.c4(g, rig, col, acc[m][n]);
;           }
;           ss += __shfl_xor(ss, 16); ss += __shfl_xor(ss, 32);
;           if (fq_e == 0) epi.rowsum(g, rig, nt * 2 + wc_e, ss);
;         } else {
; #pragma unroll
;           for (int n = 0; n < 8; ++n) {
;             const int col = nt * 256 + wc_e * 128 + n * 16 + fq_e * 4;
;             if (col < N) epi.c4(g, rig, col, acc[m][n]);
;           }
;         }
	v_lshlrev_b32_e32 v86, 16, v186
	v_and_b32_e32 v84, 0xffff0000, v186
	v_lshlrev_b32_e32 v87, 16, v187
	v_and_b32_e32 v85, 0xffff0000, v187
	v_fmac_f32_e32 v86, v74, v224
	v_fmac_f32_e32 v84, v75, v225
	v_fmac_f32_e32 v87, v76, v226
	v_fmac_f32_e32 v85, v77, v227
	v_cvt_pk_bf16_f32 v74, v86, v84
	v_cvt_pk_bf16_f32 v75, v87, v85
	global_store_dwordx2 v[82:83], v[74:75], off offset:160
	v_lshl_add_u64 v[78:79], v[132:133], 1, v[98:99]
	v_add_f32_e32 v70, 0, v70
	v_add_f32_e32 v71, 0, v71
	v_add_f32_e32 v72, 0, v72
	v_add_f32_e32 v73, 0, v73
	s_waitcnt vmcnt(7)
	v_lshlrev_b32_e32 v82, 16, v188
	v_and_b32_e32 v80, 0xffff0000, v188
	v_lshlrev_b32_e32 v83, 16, v189
	v_and_b32_e32 v81, 0xffff0000, v189
	v_fmac_f32_e32 v82, v70, v228
	v_fmac_f32_e32 v80, v71, v229
	v_fmac_f32_e32 v83, v72, v230
	v_fmac_f32_e32 v81, v73, v231
	v_cvt_pk_bf16_f32 v70, v82, v80
	v_cvt_pk_bf16_f32 v71, v83, v81
	global_store_dwordx2 v[78:79], v[70:71], off offset:192
	v_lshl_add_u64 v[74:75], v[132:133], 1, v[98:99]
	v_add_f32_e32 v66, 0, v66
	v_add_f32_e32 v67, 0, v67
	v_add_f32_e32 v68, 0, v68
	v_add_f32_e32 v69, 0, v69
	s_waitcnt vmcnt(7)
	v_lshlrev_b32_e32 v78, 16, v190
	v_and_b32_e32 v76, 0xffff0000, v190
	v_lshlrev_b32_e32 v79, 16, v191
	v_and_b32_e32 v77, 0xffff0000, v191
	v_fmac_f32_e32 v78, v66, v232
	v_fmac_f32_e32 v76, v67, v233
	v_fmac_f32_e32 v79, v68, v234
	v_fmac_f32_e32 v77, v69, v235
	v_cvt_pk_bf16_f32 v66, v78, v76
	v_cvt_pk_bf16_f32 v67, v79, v77
	global_store_dwordx2 v[74:75], v[66:67], off offset:224
	v_or_b32_e32 v66, 32, v136
	v_ashrrev_i32_e32 v67, 31, v66
	v_lshlrev_b64 v[66:67], 10, v[66:67]
	v_lshl_add_u64 v[66:67], v[66:67], 0, v[138:139]
	v_lshl_add_u64 v[66:67], v[66:67], 1, s[18:19]
	v_lshl_add_u64 v[72:73], v[132:133], 1, v[66:67]
	v_lshl_add_u64 v[196:197], v[132:133], 1, v[66:67]
	global_load_dwordx2 v[176:177], v[196:197], off
	global_load_dwordx2 v[178:179], v[196:197], off offset:32
	global_load_dwordx2 v[180:181], v[196:197], off offset:64
	global_load_dwordx2 v[182:183], v[196:197], off offset:96
	global_load_dwordx2 v[184:185], v[196:197], off offset:128
	global_load_dwordx2 v[186:187], v[196:197], off offset:160
	global_load_dwordx2 v[188:189], v[196:197], off offset:192
	global_load_dwordx2 v[190:191], v[196:197], off offset:224
	v_add_f32_e32 v62, 0, v62
	v_add_f32_e32 v63, 0, v63
	v_add_f32_e32 v64, 0, v64
	v_add_f32_e32 v65, 0, v65
	s_waitcnt vmcnt(7)
	v_lshlrev_b32_e32 v76, 16, v176
	v_and_b32_e32 v74, 0xffff0000, v176
	v_lshlrev_b32_e32 v77, 16, v177
	v_and_b32_e32 v75, 0xffff0000, v177
	v_fmac_f32_e32 v76, v62, v198
	v_fmac_f32_e32 v74, v63, v199
	v_fmac_f32_e32 v77, v64, v200
	v_fmac_f32_e32 v75, v65, v201
	v_cvt_pk_bf16_f32 v62, v76, v74
	v_cvt_pk_bf16_f32 v63, v77, v75
	global_store_dwordx2 v[72:73], v[62:63], off
	v_lshl_add_u64 v[68:69], v[132:133], 1, v[66:67]
	v_add_f32_e32 v58, 0, v58
	v_add_f32_e32 v59, 0, v59
	v_add_f32_e32 v60, 0, v60
	v_add_f32_e32 v61, 0, v61
	s_waitcnt vmcnt(7)
	v_lshlrev_b32_e32 v72, 16, v178
	v_and_b32_e32 v70, 0xffff0000, v178
	v_lshlrev_b32_e32 v73, 16, v179
	v_and_b32_e32 v71, 0xffff0000, v179
	v_fmac_f32_e32 v72, v58, v202
	v_fmac_f32_e32 v70, v59, v203
	v_fmac_f32_e32 v73, v60, v204
	v_fmac_f32_e32 v71, v61, v205
	v_cvt_pk_bf16_f32 v58, v72, v70
	v_cvt_pk_bf16_f32 v59, v73, v71
	global_store_dwordx2 v[68:69], v[58:59], off offset:32
	v_lshl_add_u64 v[62:63], v[132:133], 1, v[66:67]
	v_add_f32_e32 v54, 0, v54
	v_add_f32_e32 v55, 0, v55
	v_add_f32_e32 v56, 0, v56
	v_add_f32_e32 v57, 0, v57
	s_waitcnt vmcnt(7)
	v_lshlrev_b32_e32 v68, 16, v180
	v_and_b32_e32 v64, 0xffff0000, v180
	v_lshlrev_b32_e32 v69, 16, v181
	v_and_b32_e32 v65, 0xffff0000, v181
	v_fmac_f32_e32 v68, v54, v206
	v_fmac_f32_e32 v64, v55, v207
	v_fmac_f32_e32 v69, v56, v208
	v_fmac_f32_e32 v65, v57, v209
	v_cvt_pk_bf16_f32 v54, v68, v64
	v_cvt_pk_bf16_f32 v55, v69, v65
	global_store_dwordx2 v[62:63], v[54:55], off offset:64
	v_lshl_add_u64 v[58:59], v[132:133], 1, v[66:67]
	v_add_f32_e32 v50, 0, v50
	v_add_f32_e32 v51, 0, v51
	v_add_f32_e32 v52, 0, v52
	v_add_f32_e32 v53, 0, v53
	s_waitcnt vmcnt(7)
	v_lshlrev_b32_e32 v62, 16, v182
	v_and_b32_e32 v60, 0xffff0000, v182
	v_lshlrev_b32_e32 v63, 16, v183
	v_and_b32_e32 v61, 0xffff0000, v183
	v_fmac_f32_e32 v62, v50, v210
	v_fmac_f32_e32 v60, v51, v211
	v_fmac_f32_e32 v63, v52, v212
	v_fmac_f32_e32 v61, v53, v213
	v_cvt_pk_bf16_f32 v50, v62, v60
	v_cvt_pk_bf16_f32 v51, v63, v61
	global_store_dwordx2 v[58:59], v[50:51], off offset:96
	v_lshl_add_u64 v[54:55], v[132:133], 1, v[66:67]
	v_add_f32_e32 v46, 0, v46
	v_add_f32_e32 v47, 0, v47
	v_add_f32_e32 v48, 0, v48
	v_add_f32_e32 v49, 0, v49
	s_waitcnt vmcnt(7)
	v_lshlrev_b32_e32 v58, 16, v184
	v_and_b32_e32 v56, 0xffff0000, v184
	v_lshlrev_b32_e32 v59, 16, v185
	v_and_b32_e32 v57, 0xffff0000, v185
	v_fmac_f32_e32 v58, v46, v214
	v_fmac_f32_e32 v56, v47, v215
	v_fmac_f32_e32 v59, v48, v216
	v_fmac_f32_e32 v57, v49, v217
	v_cvt_pk_bf16_f32 v46, v58, v56
	v_cvt_pk_bf16_f32 v47, v59, v57
	global_store_dwordx2 v[54:55], v[46:47], off offset:128
	v_lshl_add_u64 v[50:51], v[132:133], 1, v[66:67]
	v_add_f32_e32 v42, 0, v42
	v_add_f32_e32 v43, 0, v43
	v_add_f32_e32 v44, 0, v44
	v_add_f32_e32 v45, 0, v45
	s_waitcnt vmcnt(7)
	v_lshlrev_b32_e32 v54, 16, v186
	v_and_b32_e32 v52, 0xffff0000, v186
	v_lshlrev_b32_e32 v55, 16, v187
	v_and_b32_e32 v53, 0xffff0000, v187
	v_fmac_f32_e32 v54, v42, v224
	v_fmac_f32_e32 v52, v43, v225
	v_fmac_f32_e32 v55, v44, v226
	v_fmac_f32_e32 v53, v45, v227
	v_cvt_pk_bf16_f32 v42, v54, v52
	v_cvt_pk_bf16_f32 v43, v55, v53
	global_store_dwordx2 v[50:51], v[42:43], off offset:160
	v_lshl_add_u64 v[46:47], v[132:133], 1, v[66:67]
	v_add_f32_e32 v38, 0, v38
	v_add_f32_e32 v39, 0, v39
	v_add_f32_e32 v40, 0, v40
	v_add_f32_e32 v41, 0, v41
	s_waitcnt vmcnt(7)
; __device__ __forceinline__ unsigned pack2(float a, float b) { unsigned r; asm("v_cvt_pk_bf16_f32 %0, %1, %2" : "=v"(r) : "v"(a), "v"(b)); return r; }
; __device__ __forceinline__ float bf2f(bf16_t h) { return __uint_as_float(((unsigned)h) << 16); }
;   __device__ __forceinline__ void c4(int g, int rig, int col, f32x4 v) const {
;     const size_t o = ((size_t)g * 2048 + rig) * 1024 + col;
;     f32x4 bs;
;     if (BASE_F32) bs = __builtin_nontemporal_load((const f32x4*)((const float*)base + o));
;     else {
;       const uint2 u = *(const uint2*)((const bf16_t*)base + o);
;       bs[0] = bf2f((bf16_t)(u.x & 0xffff)); bs[1] = bf2f((bf16_t)(u.x >> 16)); bs[2] = bf2f((bf16_t)(u.y & 0xffff)); bs[3] = bf2f((bf16_t)(u.y >> 16));
;     }
;     const f32x4 gt = *(const f32x4*)(gate + (size_t)g * 6144 + col);
;     f32x4 bi = {0.f, 0.f, 0.f, 0.f};
;     if (bias) bi = *(const f32x4*)(bias + col);
;     f32x4 r;
; #pragma unroll
;     for (int j = 0; j < 4; ++j) r[j] = bs[j] + gt[j] * (v[j] + bi[j]);
;     uint2 w; w.x = pack2(r[0], r[1]); w.y = pack2(r[2], r[3]);
;     *(uint2*)(X16 + o) = w;
;   }
; template <bool SWAP, class Epi, bool THIN = false> ...
;     ...
;     if constexpr (Epi::KIND == 0) {
; #pragma unroll
;       for (int m = 0; m < 4; ++m) {
;         const int rig = rig0 + rw + m * 16 + fr_e;
;         if constexpr (Epi::ROWSUM) {
;           float ss = 0.f;
; #pragma unroll
;           for (int n = 0; n < 8; ++n) {
;             const int col = nt * 256 + wc_e * 128 + n * 16 + fq_e * 4;
;             if (col < N) ss += epi.c4(g, rig, col, acc[m][n]);
;           }
;           ss += __shfl_xor(ss, 16); ss += __shfl_xor(ss, 32);
;           if (fq_e == 0) epi.rowsum(g, rig, nt * 2 + wc_e, ss);
;         } else {
; #pragma unroll
;           for (int n = 0; n < 8; ++n) {
;             const int col = nt * 256 + wc_e * 128 + n * 16 + fq_e * 4;
;             if (col < N) epi.c4(g, rig, col, acc[m][n]);
;           }
;         }
	v_lshlrev_b32_e32 v50, 16, v188
	v_and_b32_e32 v48, 0xffff0000, v188
	v_lshlrev_b32_e32 v51, 16, v189
	v_and_b32_e32 v49, 0xffff0000, v189
	v_fmac_f32_e32 v50, v38, v228
	v_fmac_f32_e32 v48, v39, v229
	v_fmac_f32_e32 v51, v40, v230
	v_fmac_f32_e32 v49, v41, v231
	v_cvt_pk_bf16_f32 v38, v50, v48
	v_cvt_pk_bf16_f32 v39, v51, v49
	global_store_dwordx2 v[46:47], v[38:39], off offset:192
	v_lshl_add_u64 v[42:43], v[132:133], 1, v[66:67]
	v_add_f32_e32 v34, 0, v34
	v_add_f32_e32 v35, 0, v35
	v_add_f32_e32 v36, 0, v36
	v_add_f32_e32 v37, 0, v37
	s_waitcnt vmcnt(7)
	v_lshlrev_b32_e32 v46, 16, v190
	v_and_b32_e32 v44, 0xffff0000, v190
	v_lshlrev_b32_e32 v47, 16, v191
	v_and_b32_e32 v45, 0xffff0000, v191
	v_fmac_f32_e32 v46, v34, v232
	v_fmac_f32_e32 v44, v35, v233
	v_fmac_f32_e32 v47, v36, v234
	v_fmac_f32_e32 v45, v37, v235
	v_cvt_pk_bf16_f32 v34, v46, v44
	v_cvt_pk_bf16_f32 v35, v47, v45
	global_store_dwordx2 v[42:43], v[34:35], off offset:224
	v_or_b32_e32 v34, 48, v136
	v_ashrrev_i32_e32 v35, 31, v34
	v_lshlrev_b64 v[34:35], 10, v[34:35]
	v_lshl_add_u64 v[34:35], v[34:35], 0, v[138:139]
	v_lshl_add_u64 v[34:35], v[34:35], 1, s[18:19]
	v_lshl_add_u64 v[40:41], v[132:133], 1, v[34:35]
	v_lshl_add_u64 v[196:197], v[132:133], 1, v[34:35]
	global_load_dwordx2 v[176:177], v[196:197], off
	global_load_dwordx2 v[178:179], v[196:197], off offset:32
	global_load_dwordx2 v[180:181], v[196:197], off offset:64
	global_load_dwordx2 v[182:183], v[196:197], off offset:96
	global_load_dwordx2 v[184:185], v[196:197], off offset:128
	global_load_dwordx2 v[186:187], v[196:197], off offset:160
	global_load_dwordx2 v[188:189], v[196:197], off offset:192
	global_load_dwordx2 v[190:191], v[196:197], off offset:224
	v_add_f32_e32 v30, 0, v30
	v_add_f32_e32 v31, 0, v31
	v_add_f32_e32 v32, 0, v32
	v_add_f32_e32 v33, 0, v33
	s_waitcnt vmcnt(7)
	v_lshlrev_b32_e32 v44, 16, v176
	v_and_b32_e32 v42, 0xffff0000, v176
	v_lshlrev_b32_e32 v45, 16, v177
	v_and_b32_e32 v43, 0xffff0000, v177
	v_fmac_f32_e32 v44, v30, v198
	v_fmac_f32_e32 v42, v31, v199
	v_fmac_f32_e32 v45, v32, v200
	v_fmac_f32_e32 v43, v33, v201
	v_cvt_pk_bf16_f32 v30, v44, v42
	v_cvt_pk_bf16_f32 v31, v45, v43
	global_store_dwordx2 v[40:41], v[30:31], off
	v_lshl_add_u64 v[36:37], v[132:133], 1, v[34:35]
	v_add_f32_e32 v26, 0, v26
	v_add_f32_e32 v27, 0, v27
	v_add_f32_e32 v28, 0, v28
	v_add_f32_e32 v29, 0, v29
	s_waitcnt vmcnt(7)
	v_lshlrev_b32_e32 v40, 16, v178
	v_and_b32_e32 v38, 0xffff0000, v178
	v_lshlrev_b32_e32 v41, 16, v179
	v_and_b32_e32 v39, 0xffff0000, v179
	v_fmac_f32_e32 v40, v26, v202
	v_fmac_f32_e32 v38, v27, v203
	v_fmac_f32_e32 v41, v28, v204
	v_fmac_f32_e32 v39, v29, v205
	v_cvt_pk_bf16_f32 v26, v40, v38
	v_cvt_pk_bf16_f32 v27, v41, v39
	global_store_dwordx2 v[36:37], v[26:27], off offset:32
	v_lshl_add_u64 v[30:31], v[132:133], 1, v[34:35]
	v_add_f32_e32 v22, 0, v22
	v_add_f32_e32 v23, 0, v23
	v_add_f32_e32 v24, 0, v24
	v_add_f32_e32 v25, 0, v25
	s_waitcnt vmcnt(7)
	v_lshlrev_b32_e32 v36, 16, v180
	v_and_b32_e32 v32, 0xffff0000, v180
	v_lshlrev_b32_e32 v37, 16, v181
	v_and_b32_e32 v33, 0xffff0000, v181
	v_fmac_f32_e32 v36, v22, v206
	v_fmac_f32_e32 v32, v23, v207
	v_fmac_f32_e32 v37, v24, v208
	v_fmac_f32_e32 v33, v25, v209
	v_cvt_pk_bf16_f32 v22, v36, v32
	v_cvt_pk_bf16_f32 v23, v37, v33
	global_store_dwordx2 v[30:31], v[22:23], off offset:64
	v_lshl_add_u64 v[26:27], v[132:133], 1, v[34:35]
	v_add_f32_e32 v18, 0, v18
	v_add_f32_e32 v19, 0, v19
	v_add_f32_e32 v20, 0, v20
	v_add_f32_e32 v21, 0, v21
	s_waitcnt vmcnt(7)
	v_lshlrev_b32_e32 v30, 16, v182
	v_and_b32_e32 v28, 0xffff0000, v182
	v_lshlrev_b32_e32 v31, 16, v183
	v_and_b32_e32 v29, 0xffff0000, v183
	v_fmac_f32_e32 v30, v18, v210
	v_fmac_f32_e32 v28, v19, v211
	v_fmac_f32_e32 v31, v20, v212
	v_fmac_f32_e32 v29, v21, v213
	v_cvt_pk_bf16_f32 v18, v30, v28
	v_cvt_pk_bf16_f32 v19, v31, v29
	global_store_dwordx2 v[26:27], v[18:19], off offset:96
	v_lshl_add_u64 v[22:23], v[132:133], 1, v[34:35]
	v_add_f32_e32 v14, 0, v14
	v_add_f32_e32 v15, 0, v15
	v_add_f32_e32 v16, 0, v16
	v_add_f32_e32 v17, 0, v17
	s_waitcnt vmcnt(7)
	v_lshlrev_b32_e32 v26, 16, v184
	v_and_b32_e32 v24, 0xffff0000, v184
	v_lshlrev_b32_e32 v27, 16, v185
	v_and_b32_e32 v25, 0xffff0000, v185
	v_fmac_f32_e32 v26, v14, v214
	v_fmac_f32_e32 v24, v15, v215
	v_fmac_f32_e32 v27, v16, v216
	v_fmac_f32_e32 v25, v17, v217
	v_cvt_pk_bf16_f32 v14, v26, v24
	v_cvt_pk_bf16_f32 v15, v27, v25
	global_store_dwordx2 v[22:23], v[14:15], off offset:128
	v_lshl_add_u64 v[18:19], v[132:133], 1, v[34:35]
	v_add_f32_e32 v10, 0, v10
	v_add_f32_e32 v11, 0, v11
	v_add_f32_e32 v12, 0, v12
	v_add_f32_e32 v13, 0, v13
	s_waitcnt vmcnt(7)
	v_lshlrev_b32_e32 v22, 16, v186
	v_and_b32_e32 v20, 0xffff0000, v186
	v_lshlrev_b32_e32 v23, 16, v187
	v_and_b32_e32 v21, 0xffff0000, v187
	v_fmac_f32_e32 v22, v10, v224
	v_fmac_f32_e32 v20, v11, v225
	v_fmac_f32_e32 v23, v12, v226
	v_fmac_f32_e32 v21, v13, v227
	v_cvt_pk_bf16_f32 v10, v22, v20
	v_cvt_pk_bf16_f32 v11, v23, v21
	global_store_dwordx2 v[18:19], v[10:11], off offset:160
	v_lshl_add_u64 v[14:15], v[132:133], 1, v[34:35]
	v_add_f32_e32 v6, 0, v6
	v_add_f32_e32 v7, 0, v7
	v_add_f32_e32 v8, 0, v8
	v_add_f32_e32 v9, 0, v9
	s_waitcnt vmcnt(7)
	v_lshlrev_b32_e32 v18, 16, v188
	v_and_b32_e32 v16, 0xffff0000, v188
	v_lshlrev_b32_e32 v19, 16, v189
	v_and_b32_e32 v17, 0xffff0000, v189
	v_fmac_f32_e32 v18, v6, v228
	v_fmac_f32_e32 v16, v7, v229
	v_fmac_f32_e32 v19, v8, v230
	v_fmac_f32_e32 v17, v9, v231
	v_cvt_pk_bf16_f32 v6, v18, v16
	v_cvt_pk_bf16_f32 v7, v19, v17
	global_store_dwordx2 v[14:15], v[6:7], off offset:192
	v_lshl_add_u64 v[10:11], v[132:133], 1, v[34:35]
	v_add_f32_e32 v2, 0, v2
	v_add_f32_e32 v3, 0, v3
	v_add_f32_e32 v4, 0, v4
	v_add_f32_e32 v5, 0, v5
	s_waitcnt vmcnt(7)
	v_lshlrev_b32_e32 v14, 16, v190
	v_and_b32_e32 v12, 0xffff0000, v190
	v_lshlrev_b32_e32 v15, 16, v191
	v_and_b32_e32 v13, 0xffff0000, v191
	v_fmac_f32_e32 v14, v2, v232
	v_fmac_f32_e32 v12, v3, v233
	v_fmac_f32_e32 v15, v4, v234
	v_fmac_f32_e32 v13, v5, v235
	v_cvt_pk_bf16_f32 v2, v14, v12
	v_cvt_pk_bf16_f32 v3, v15, v13
	global_store_dwordx2 v[10:11], v[2:3], off offset:224
	s_branch .LBB0_3514
